# pads after bf16 pack blocks (plain VALU, no hazard) removed; final norm requests later row chunks with the first
# baseline (speedup 1.0000x reference)
.LBB11_78:
	v_lshlrev_b32_e32 v0, 16, v28
	v_and_b32_e32 v1, 0xffff0000, v28
	v_lshlrev_b32_e32 v2, 16, v29
	v_and_b32_e32 v3, 0xffff0000, v29
	v_pk_add_f32 v[14:15], v[12:13], v[2:3]
	v_pk_add_f32 v[12:13], v[8:9], v[0:1]
	v_mul_f32_e32 v1, v14, v14
	v_mul_f32_e32 v0, v13, v13
	v_fmac_f32_e32 v0, v12, v12
	v_fmac_f32_e32 v1, v15, v15
	v_add_f32_e32 v45, v0, v1
	v_lshlrev_b32_e32 v0, 16, v20
	v_and_b32_e32 v1, 0xffff0000, v20
	v_lshlrev_b32_e32 v2, 16, v21
	v_and_b32_e32 v3, 0xffff0000, v21
	v_pk_add_f32 v[10:11], v[32:33], v[2:3]
	v_pk_add_f32 v[8:9], v[30:31], v[0:1]
	v_mul_f32_e32 v1, v10, v10
	v_mul_f32_e32 v0, v9, v9
	v_fmac_f32_e32 v0, v8, v8
	v_fmac_f32_e32 v1, v11, v11
	v_add_f32_e32 v0, v0, v1
	v_add_f32_e32 v30, v45, v0
	v_lshlrev_b32_e32 v0, 16, v24
	v_and_b32_e32 v1, 0xffff0000, v24
	v_lshlrev_b32_e32 v2, 16, v25
	v_and_b32_e32 v3, 0xffff0000, v25
	v_pk_add_f32 v[2:3], v[36:37], v[2:3]
	v_pk_add_f32 v[0:1], v[34:35], v[0:1]
	v_mul_f32_e32 v32, v2, v2
	v_mul_f32_e32 v31, v1, v1
	v_fmac_f32_e32 v31, v0, v0
	v_fmac_f32_e32 v32, v3, v3
	v_add_f32_e32 v31, v31, v32
	v_add_f32_e32 v45, v30, v31
	s_waitcnt vmcnt(0)
	v_cvt_pk_bf16_f32 v30, v4, v5
	v_cvt_pk_bf16_f32 v31, v6, v7
	v_lshlrev_b32_e32 v34, 16, v30
	v_and_b32_e32 v35, 0xffff0000, v30
	v_lshlrev_b32_e32 v36, 16, v31
	v_and_b32_e32 v37, 0xffff0000, v31
	v_sub_f32_e32 v6, v6, v36
	v_sub_f32_e32 v7, v7, v37
	v_sub_f32_e32 v4, v4, v34
	v_sub_f32_e32 v5, v5, v35
	v_cvt_pk_bf16_f32 v32, v4, v5
	v_cvt_pk_bf16_f32 v33, v6, v7
	s_load_dwordx2 s[26:27], s[0:1], 0x140
	v_lshlrev_b32_e32 v4, 16, v32
	v_and_b32_e32 v5, 0xffff0000, v32
	v_lshlrev_b32_e32 v6, 16, v33
	v_and_b32_e32 v7, 0xffff0000, v33
	v_pk_add_f32 v[6:7], v[36:37], v[6:7]
	v_pk_add_f32 v[4:5], v[34:35], v[4:5]
	v_mul_f32_e32 v35, v6, v6
	v_mul_f32_e32 v34, v5, v5
	v_fmac_f32_e32 v34, v4, v4
	v_fmac_f32_e32 v35, v7, v7
	v_add_f32_e32 v34, v34, v35
	v_add_f32_e32 v34, v45, v34
	ds_bpermute_b32 v35, v38, v34
	s_waitcnt lgkmcnt(0)
	s_cmp_eq_u64 s[26:27], 0
	v_add_f32_e32 v34, v34, v35
	ds_bpermute_b32 v35, v39, v34
	s_waitcnt lgkmcnt(0)
	v_add_f32_e32 v34, v34, v35
	ds_bpermute_b32 v35, v40, v34
	s_waitcnt lgkmcnt(0)
	v_add_f32_e32 v34, v34, v35
	ds_bpermute_b32 v35, v41, v34
	s_waitcnt lgkmcnt(0)
	v_add_f32_e32 v34, v34, v35
	ds_bpermute_b32 v35, v42, v34
	s_waitcnt lgkmcnt(0)
	v_add_f32_e32 v36, v34, v35
	ds_bpermute_b32 v37, v43, v36
	s_cbranch_scc1 .LBB11_83
	s_mov_b64 s[8:9], -1
	s_and_b64 vcc, exec, s[24:25]
	s_cbranch_vccz .LBB11_81
	s_add_i32 s8, s3, 0xffffc400
	s_cmpk_lt_u32 s3, 0x4080
	s_cselect_b32 s10, s8, -1
	s_mov_b64 s[8:9], 0

.LBB11_96:
	global_load_dwordx4 v[38:41], v[34:35], off offset:-3072
	global_load_dwordx4 v[42:45], v[34:35], off offset:-2048
	global_load_dwordx4 v[62:65], v[34:35], off offset:-1024
	global_load_dwordx4 v[66:69], v[34:35], off
	global_load_dwordx4 v[46:49], v[2:3], off
	v_lshl_add_u64 v[36:37], s[6:7], 0, v[32:33]
	v_add_co_u32_e32 v70, vcc, s13, v36
	s_add_i32 s19, s19, s12
	s_nop 0
	v_addc_co_u32_e32 v71, vcc, 0, v37, vcc
	v_lshl_add_u64 v[34:35], v[34:35], 0, s[10:11]
	s_waitcnt vmcnt(4)
	v_pk_mul_f32 v[50:51], v[40:41], v[40:41]
	v_pk_mul_f32 v[52:53], v[38:39], v[38:39]
	s_waitcnt vmcnt(3)
	v_pk_mul_f32 v[72:73], v[44:45], v[44:45]
	v_pk_mul_f32 v[74:75], v[42:43], v[42:43]
	v_pk_mov_b32 v[82:83], v[52:53], v[50:51] op_sel:[1,0]
	v_mov_b32_e32 v53, v51
	v_pk_mov_b32 v[50:51], v[74:75], v[72:73] op_sel:[1,0]
	v_mov_b32_e32 v75, v73
	s_waitcnt vmcnt(1)
	v_mul_f32_e32 v81, v68, v68
	v_mul_f32_e32 v78, v63, v63
	v_mul_f32_e32 v80, v65, v65
	v_pk_add_f32 v[52:53], v[82:83], v[52:53]
	v_pk_add_f32 v[50:51], v[50:51], v[74:75]
	v_mul_f32_e32 v61, v66, v66
	v_mul_f32_e32 v77, v67, v67
	v_mul_f32_e32 v84, v69, v69
	v_pk_fma_f32 v[72:73], v[62:63], v[62:63], v[78:79] op_sel_hi:[1,1,0]
	v_pk_fma_f32 v[78:79], v[64:65], v[64:65], v[80:81] op_sel_hi:[1,1,0]
	v_pk_add_f32 v[52:53], v[52:53], v[52:53] op_sel:[0,1] op_sel_hi:[1,0]
	v_pk_add_f32 v[50:51], v[50:51], v[50:51] op_sel:[0,1] op_sel_hi:[1,0]
	v_mov_b32_e32 v73, v81
	v_mov_b32_e32 v79, v84
	v_mov_b32_e32 v53, v61
	v_mov_b32_e32 v51, v77
	v_pk_add_f32 v[72:73], v[72:73], v[78:79]
	v_pk_add_f32 v[50:51], v[52:53], v[50:51]
	s_nop 0
	v_pk_add_f32 v[50:51], v[50:51], v[72:73]
	s_nop 0
	v_add_f32_e32 v50, v50, v51
	ds_bpermute_b32 v51, v54, v50
	s_waitcnt lgkmcnt(0)
	v_add_f32_e32 v50, v50, v51
	ds_bpermute_b32 v51, v55, v50
	s_waitcnt lgkmcnt(0)
	v_add_f32_e32 v50, v50, v51
	ds_bpermute_b32 v51, v56, v50
	s_waitcnt lgkmcnt(0)
	v_add_f32_e32 v50, v50, v51
	ds_bpermute_b32 v51, v57, v50
	s_waitcnt lgkmcnt(0)
	v_add_f32_e32 v50, v50, v51
	ds_bpermute_b32 v51, v58, v50
	s_waitcnt lgkmcnt(0)
	v_add_f32_e32 v50, v50, v51
	ds_bpermute_b32 v51, v59, v50
	s_waitcnt lgkmcnt(0)
	v_add_f32_e32 v50, v50, v51
	v_fmamk_f32 v50, v50, 0x3a800000, v60
	v_mul_f32_e32 v51, 0x4b800000, v50
	v_cmp_gt_f32_e32 vcc, s3, v50
	s_nop 1
	v_cndmask_b32_e32 v50, v50, v51, vcc
	v_rsq_f32_e32 v50, v50
	s_nop 0
	v_mul_f32_e32 v51, 0x45800000, v50
	v_cndmask_b32_e32 v72, v50, v51, vcc
	v_pk_mul_f32 v[50:51], v[38:39], v[72:73] op_sel_hi:[1,0]
	v_pk_mul_f32 v[52:53], v[40:41], v[72:73] op_sel_hi:[1,0]
	s_waitcnt vmcnt(0)
	v_pk_mul_f32 v[40:41], v[46:47], v[50:51]
	v_pk_mul_f32 v[38:39], v[48:49], v[52:53]
	v_cvt_pk_bf16_f32 v40, v40, v41
	v_pk_mul_f32 v[46:47], v[42:43], v[72:73] op_sel_hi:[1,0]
	v_cvt_pk_bf16_f32 v41, v38, v39
	global_store_dwordx2 v[70:71], v[40:41], off
	global_load_dwordx4 v[38:41], v[2:3], off offset:1024
	v_pk_mul_f32 v[48:49], v[44:45], v[72:73] op_sel_hi:[1,0]
	v_pk_mul_f32 v[42:43], v[62:63], v[72:73] op_sel_hi:[1,0]
	v_pk_mul_f32 v[44:45], v[64:65], v[72:73] op_sel_hi:[1,0]
	s_waitcnt vmcnt(0)
	v_pk_mul_f32 v[38:39], v[38:39], v[46:47]
	v_pk_mul_f32 v[40:41], v[40:41], v[48:49]
	v_cvt_pk_bf16_f32 v38, v38, v39
	v_cvt_pk_bf16_f32 v39, v40, v41
	global_store_dwordx2 v[70:71], v[38:39], off offset:512
	global_load_dwordx4 v[38:41], v[2:3], off offset:2048
	s_waitcnt vmcnt(0)
	v_pk_mul_f32 v[38:39], v[38:39], v[42:43]
	v_pk_mul_f32 v[40:41], v[40:41], v[44:45]
	v_cvt_pk_bf16_f32 v38, v38, v39
	v_cvt_pk_bf16_f32 v39, v40, v41
	global_store_dwordx2 v[70:71], v[38:39], off offset:1024
	global_load_dwordx4 v[62:65], v[2:3], off offset:3072
	v_pk_mul_f32 v[38:39], v[66:67], v[72:73] op_sel_hi:[1,0]
	v_pk_mul_f32 v[40:41], v[68:69], v[72:73] op_sel_hi:[1,0]
	v_add_co_u32_e32 v66, vcc, s16, v36
	s_waitcnt vmcnt(0)
	v_pk_mul_f32 v[62:63], v[62:63], v[38:39]
	v_pk_mul_f32 v[64:65], v[64:65], v[40:41]
	v_cvt_pk_bf16_f32 v62, v62, v63
	v_addc_co_u32_e32 v67, vcc, 0, v37, vcc
	v_cvt_pk_bf16_f32 v63, v64, v65
	global_store_dwordx2 v[70:71], v[62:63], off offset:1536
	global_load_dwordx4 v[62:65], v[4:5], off
	s_waitcnt vmcnt(0)
	v_pk_mul_f32 v[62:63], v[50:51], v[62:63]
	v_pk_mul_f32 v[64:65], v[52:53], v[64:65]
	v_cvt_pk_bf16_f32 v62, v62, v63
	v_cvt_pk_bf16_f32 v63, v64, v65
	global_store_dwordx2 v[66:67], v[62:63], off
	global_load_dwordx4 v[62:65], v[6:7], off
	v_lshl_add_u64 v[66:67], s[6:7], 0, v[30:31]
	v_add_co_u32_e32 v68, vcc, s16, v66
	s_waitcnt vmcnt(0)
	v_pk_mul_f32 v[62:63], v[46:47], v[62:63]
	v_addc_co_u32_e32 v69, vcc, 0, v67, vcc
	v_pk_mul_f32 v[64:65], v[48:49], v[64:65]
	v_cvt_pk_bf16_f32 v62, v62, v63
	v_cvt_pk_bf16_f32 v63, v64, v65
	global_store_dwordx2 v[68:69], v[62:63], off
	global_load_dwordx4 v[62:65], v[8:9], off
	v_lshl_add_u64 v[68:69], s[6:7], 0, v[28:29]
	v_add_co_u32_e32 v70, vcc, s16, v68
	s_waitcnt vmcnt(0)
	v_pk_mul_f32 v[62:63], v[42:43], v[62:63]
	v_addc_co_u32_e32 v71, vcc, 0, v69, vcc
	v_pk_mul_f32 v[64:65], v[44:45], v[64:65]
	v_cvt_pk_bf16_f32 v62, v62, v63
	v_cvt_pk_bf16_f32 v63, v64, v65
	global_store_dwordx2 v[70:71], v[62:63], off
	global_load_dwordx4 v[62:65], v[10:11], off
	v_lshl_add_u64 v[70:71], s[6:7], 0, v[26:27]
	v_add_co_u32_e32 v72, vcc, s16, v70
	s_add_u32 s6, s6, s8
	s_nop 0
	v_addc_co_u32_e32 v73, vcc, 0, v71, vcc
	s_addc_u32 s7, s7, s9
	s_cmpk_gt_i32 s19, 0x7ff
	s_waitcnt vmcnt(0)
	v_pk_mul_f32 v[62:63], v[38:39], v[62:63]
	v_pk_mul_f32 v[64:65], v[40:41], v[64:65]
	v_cvt_pk_bf16_f32 v62, v62, v63
	v_cvt_pk_bf16_f32 v63, v64, v65
	global_store_dwordx2 v[72:73], v[62:63], off
	global_load_dwordx4 v[62:65], v[12:13], off
	v_add_co_u32_e32 v72, vcc, s17, v36
	s_waitcnt vmcnt(0)
	v_pk_mul_f32 v[62:63], v[50:51], v[62:63]
	v_addc_co_u32_e32 v73, vcc, 0, v37, vcc
	v_pk_mul_f32 v[64:65], v[52:53], v[64:65]
	v_cvt_pk_bf16_f32 v62, v62, v63
	v_cvt_pk_bf16_f32 v63, v64, v65
	global_store_dwordx2 v[72:73], v[62:63], off
	global_load_dwordx4 v[62:65], v[14:15], off
	v_add_co_u32_e32 v72, vcc, s17, v66
	s_waitcnt vmcnt(0)
	v_pk_mul_f32 v[62:63], v[46:47], v[62:63]
	v_addc_co_u32_e32 v73, vcc, 0, v67, vcc
	v_pk_mul_f32 v[64:65], v[48:49], v[64:65]
	v_cvt_pk_bf16_f32 v62, v62, v63
	v_cvt_pk_bf16_f32 v63, v64, v65
	global_store_dwordx2 v[72:73], v[62:63], off
	global_load_dwordx4 v[62:65], v[16:17], off
	v_add_co_u32_e32 v72, vcc, s17, v68
	s_waitcnt vmcnt(0)
	v_pk_mul_f32 v[62:63], v[42:43], v[62:63]
	v_addc_co_u32_e32 v73, vcc, 0, v69, vcc
	v_pk_mul_f32 v[64:65], v[44:45], v[64:65]
	v_cvt_pk_bf16_f32 v62, v62, v63
	v_cvt_pk_bf16_f32 v63, v64, v65
	global_store_dwordx2 v[72:73], v[62:63], off
	global_load_dwordx4 v[62:65], v[18:19], off
	v_add_co_u32_e32 v72, vcc, s17, v70
	s_waitcnt vmcnt(0)
	v_pk_mul_f32 v[62:63], v[38:39], v[62:63]
	v_addc_co_u32_e32 v73, vcc, 0, v71, vcc
	v_pk_mul_f32 v[64:65], v[40:41], v[64:65]
	v_cvt_pk_bf16_f32 v62, v62, v63
	v_add_co_u32_e32 v36, vcc, s18, v36
	v_cvt_pk_bf16_f32 v63, v64, v65
	global_store_dwordx2 v[72:73], v[62:63], off
	global_load_dwordx4 v[62:65], v[0:1], off
	v_addc_co_u32_e32 v37, vcc, 0, v37, vcc
	s_waitcnt vmcnt(0)
	v_pk_mul_f32 v[50:51], v[50:51], v[62:63]
	v_pk_mul_f32 v[52:53], v[52:53], v[64:65]
	v_cvt_pk_bf16_f32 v50, v50, v51
	v_cvt_pk_bf16_f32 v51, v52, v53
	global_store_dwordx2 v[36:37], v[50:51], off
	global_load_dwordx4 v[50:53], v[20:21], off
	v_add_co_u32_e32 v36, vcc, s18, v66
	s_waitcnt vmcnt(0)
	v_pk_mul_f32 v[46:47], v[46:47], v[50:51]
	v_addc_co_u32_e32 v37, vcc, 0, v67, vcc
	v_pk_mul_f32 v[48:49], v[48:49], v[52:53]
	v_cvt_pk_bf16_f32 v46, v46, v47
	v_cvt_pk_bf16_f32 v47, v48, v49
	global_store_dwordx2 v[36:37], v[46:47], off
	global_load_dwordx4 v[46:49], v[22:23], off
	v_add_co_u32_e32 v36, vcc, s18, v68
	s_waitcnt vmcnt(0)
	v_pk_mul_f32 v[42:43], v[42:43], v[46:47]
	v_addc_co_u32_e32 v37, vcc, 0, v69, vcc
	v_pk_mul_f32 v[44:45], v[44:45], v[48:49]
	v_cvt_pk_bf16_f32 v42, v42, v43
	v_cvt_pk_bf16_f32 v43, v44, v45
	global_store_dwordx2 v[36:37], v[42:43], off
	global_load_dwordx4 v[42:45], v[24:25], off
	v_add_co_u32_e32 v36, vcc, 0xd400000, v70
	s_waitcnt vmcnt(0)
	v_pk_mul_f32 v[38:39], v[38:39], v[42:43]
	v_addc_co_u32_e32 v37, vcc, 0, v71, vcc
	v_pk_mul_f32 v[40:41], v[40:41], v[44:45]
	v_cvt_pk_bf16_f32 v38, v38, v39
	v_cvt_pk_bf16_f32 v39, v40, v41
	global_store_dwordx2 v[36:37], v[38:39], off
	s_cbranch_scc0 .LBB11_96

.LBB11_383:
	s_or_b64 exec, exec, s[10:11]
	v_fmamk_f32 v108, v110, 0x3a800000, v206
	v_mul_f32_e32 v109, 0x4b800000, v108
	v_cmp_gt_f32_e64 s[10:11], s77, v108
	s_nop 1
	v_cndmask_b32_e64 v108, v108, v109, s[10:11]
	v_rsq_f32_e32 v108, v108
	s_nop 0
	v_mul_f32_e32 v109, 0x45800000, v108
	v_cndmask_b32_e64 v114, v108, v109, s[10:11]
	v_pk_mul_f32 v[44:45], v[44:45], v[114:115] op_sel_hi:[1,0]
	v_pk_mul_f32 v[46:47], v[46:47], v[114:115] op_sel_hi:[1,0]
	v_pk_mul_f32 v[108:109], v[40:41], v[44:45]
	v_pk_mul_f32 v[110:111], v[42:43], v[46:47]
	v_pk_mul_f32 v[44:45], v[48:49], v[114:115] op_sel_hi:[1,0]
	v_pk_mul_f32 v[46:47], v[50:51], v[114:115] op_sel_hi:[1,0]
	v_pk_mul_f32 v[48:49], v[36:37], v[44:45]
	v_pk_mul_f32 v[50:51], v[38:39], v[46:47]
	v_cvt_pk_bf16_f32 v44, v108, v109
	v_cvt_pk_bf16_f32 v45, v110, v111
	v_cvt_pk_bf16_f32 v46, v48, v49
	v_cvt_pk_bf16_f32 v47, v50, v51
	s_and_saveexec_b64 s[10:11], vcc
	s_cbranch_execz .LBB11_385
	ds_write_b128 v191, v[108:111] offset:12800
	ds_write_b128 v191, v[48:51] offset:12816
.LBB11_385:
	s_or_b64 exec, exec, s[10:11]
	v_mfma_f32_16x16x32_bf16 v[48:51], v[8:11], v[44:47], 0
	v_add_u32_e32 v220, 0x800, v214
	v_add_u32_e32 v221, 0x1000, v214
	v_add_u32_e32 v222, 0x1800, v214
	v_mfma_f32_16x16x32_bf16 v[108:111], v[4:7], v[44:47], 0
	v_mfma_f32_16x16x32_bf16 v[114:117], v[16:19], v[44:47], 0
	s_nop 2
	ds_write_b128 v213, v[48:51]
	v_mfma_f32_16x16x32_bf16 v[118:121], v[12:15], v[44:47], 0
	s_nop 1
	ds_write_b128 v213, v[108:111] offset:64
	ds_write_b128 v213, v[114:117] offset:128
	s_nop 3
	ds_write_b128 v213, v[118:121] offset:192
	v_mfma_f32_16x16x32_bf16 v[126:129], v[24:27], v[44:47], 0
	v_mfma_f32_16x16x32_bf16 v[48:51], v[20:23], v[44:47], 0
	v_mfma_f32_16x16x32_bf16 v[108:111], v[32:35], v[44:47], 0
	s_nop 5
	ds_write_b128 v213, v[126:129] offset:256
	ds_write_b128 v213, v[48:51] offset:320
	ds_write_b128 v213, v[108:111] offset:384
	v_mfma_f32_16x16x32_bf16 v[44:47], v[28:31], v[44:47], 0
	s_nop 7
	ds_write_b128 v213, v[44:47] offset:448
	v_fmamk_f32 v44, v112, 0x3a800000, v206
	v_mul_f32_e32 v45, 0x4b800000, v44
	v_cmp_gt_f32_e64 s[10:11], s77, v44
	s_waitcnt lgkmcnt(0)
	ds_read2_b64 v[180:183], v214 offset1:66
	ds_read2_b64 v[176:179], v214 offset0:132 offset1:198
	v_cndmask_b32_e64 v44, v44, v45, s[10:11]
	v_rsq_f32_e32 v44, v44
	ds_read2_b64 v[168:171], v220 offset0:8 offset1:74
	ds_read2_b64 v[156:159], v220 offset0:140 offset1:206
	ds_read2_b64 v[144:147], v221 offset0:16 offset1:82
	ds_read2_b64 v[132:135], v221 offset0:148 offset1:214
	ds_read2_b64 v[120:123], v222 offset0:24 offset1:90
	ds_read2_b64 v[116:119], v222 offset0:156 offset1:222
	v_mul_f32_e32 v45, 0x45800000, v44
	s_waitcnt lgkmcnt(0)
	v_cndmask_b32_e64 v44, v44, v45, s[10:11]
	v_pk_mul_f32 v[46:47], v[52:53], v[44:45] op_sel_hi:[1,0]
	v_pk_mul_f32 v[48:49], v[54:55], v[44:45] op_sel_hi:[1,0]
	s_nop 0
	v_pk_mul_f32 v[50:51], v[42:43], v[48:49]
	v_pk_mul_f32 v[48:49], v[40:41], v[46:47]
	v_pk_mul_f32 v[46:47], v[56:57], v[44:45] op_sel_hi:[1,0]
	v_pk_mul_f32 v[44:45], v[58:59], v[44:45] op_sel_hi:[1,0]
	v_pk_mul_f32 v[52:53], v[36:37], v[46:47]
	v_pk_mul_f32 v[54:55], v[38:39], v[44:45]
	v_cvt_pk_bf16_f32 v44, v48, v49
	v_cvt_pk_bf16_f32 v45, v50, v51
	v_cvt_pk_bf16_f32 v46, v52, v53
	v_cvt_pk_bf16_f32 v47, v54, v55
	s_and_saveexec_b64 s[10:11], vcc
	s_cbranch_execz .LBB11_387
	ds_write_b128 v191, v[48:51] offset:12800
	ds_write_b128 v191, v[52:55] offset:12816
.LBB11_387:
	s_or_b64 exec, exec, s[10:11]
	v_mfma_f32_16x16x32_bf16 v[48:51], v[8:11], v[44:47], 0
	v_mfma_f32_16x16x32_bf16 v[52:55], v[4:7], v[44:47], 0
	v_mfma_f32_16x16x32_bf16 v[56:59], v[16:19], v[44:47], 0
	s_nop 5
	ds_write_b128 v213, v[48:51]
	v_mfma_f32_16x16x32_bf16 v[108:111], v[12:15], v[44:47], 0
	ds_write_b128 v213, v[52:55] offset:64
	ds_write_b128 v213, v[56:59] offset:128
	s_nop 5
	ds_write_b128 v213, v[108:111] offset:192
	v_mfma_f32_16x16x32_bf16 v[112:115], v[24:27], v[44:47], 0
	v_mfma_f32_16x16x32_bf16 v[48:51], v[20:23], v[44:47], 0
	v_mfma_f32_16x16x32_bf16 v[52:55], v[32:35], v[44:47], 0
	s_nop 5
	ds_write_b128 v213, v[112:115] offset:256
	ds_write_b128 v213, v[48:51] offset:320
	ds_write_b128 v213, v[52:55] offset:384
	v_mfma_f32_16x16x32_bf16 v[44:47], v[28:31], v[44:47], 0
	s_nop 7
	ds_write_b128 v213, v[44:47] offset:448
	s_waitcnt lgkmcnt(0)
	v_fmamk_f32 v44, v124, 0x3a800000, v206
	v_mul_f32_e32 v45, 0x4b800000, v44
	v_cmp_gt_f32_e64 s[10:11], s77, v44
	ds_read2_b64 v[172:175], v214 offset1:66
	ds_read2_b64 v[164:167], v214 offset0:132 offset1:198
	ds_read2_b64 v[152:155], v220 offset0:8 offset1:74
	ds_read2_b64 v[140:143], v220 offset0:140 offset1:206
	ds_read2_b64 v[128:131], v221 offset0:16 offset1:82
	ds_read2_b64 v[112:115], v221 offset0:148 offset1:214
	ds_read2_b64 v[108:111], v222 offset0:24 offset1:90
	v_cndmask_b32_e64 v44, v44, v45, s[10:11]
	v_rsq_f32_e32 v44, v44
	ds_read2_b64 v[56:59], v222 offset0:156 offset1:222
	s_waitcnt lgkmcnt(0)
	v_mul_f32_e32 v45, 0x45800000, v44
	v_cndmask_b32_e64 v44, v44, v45, s[10:11]
	v_pk_mul_f32 v[46:47], v[68:69], v[44:45] op_sel_hi:[1,0]
	v_pk_mul_f32 v[48:49], v[70:71], v[44:45] op_sel_hi:[1,0]
	s_nop 0
	v_pk_mul_f32 v[50:51], v[42:43], v[48:49]
	v_pk_mul_f32 v[48:49], v[40:41], v[46:47]
	v_pk_mul_f32 v[46:47], v[72:73], v[44:45] op_sel_hi:[1,0]
	v_pk_mul_f32 v[44:45], v[74:75], v[44:45] op_sel_hi:[1,0]
	v_pk_mul_f32 v[52:53], v[36:37], v[46:47]
	v_pk_mul_f32 v[54:55], v[38:39], v[44:45]
	v_cvt_pk_bf16_f32 v44, v48, v49
	v_cvt_pk_bf16_f32 v45, v50, v51
	v_cvt_pk_bf16_f32 v46, v52, v53
	v_cvt_pk_bf16_f32 v47, v54, v55
	s_and_saveexec_b64 s[10:11], vcc
	s_cbranch_execz .LBB11_389
	ds_write_b128 v191, v[48:51] offset:12800
	ds_write_b128 v191, v[52:55] offset:12816
.LBB11_389:
	s_or_b64 exec, exec, s[10:11]
	v_mfma_f32_16x16x32_bf16 v[48:51], v[8:11], v[44:47], 0
	v_mfma_f32_16x16x32_bf16 v[52:55], v[4:7], v[44:47], 0
	v_mfma_f32_16x16x32_bf16 v[68:71], v[16:19], v[44:47], 0
	s_nop 5
	ds_write_b128 v213, v[48:51]
	v_mfma_f32_16x16x32_bf16 v[72:75], v[12:15], v[44:47], 0
	ds_write_b128 v213, v[52:55] offset:64
	ds_write_b128 v213, v[68:71] offset:128
	s_nop 5
	ds_write_b128 v213, v[72:75] offset:192
	v_mfma_f32_16x16x32_bf16 v[124:127], v[24:27], v[44:47], 0
	v_mfma_f32_16x16x32_bf16 v[48:51], v[20:23], v[44:47], 0
	v_mfma_f32_16x16x32_bf16 v[52:55], v[32:35], v[44:47], 0
	s_nop 5
	ds_write_b128 v213, v[124:127] offset:256
	ds_write_b128 v213, v[48:51] offset:320
	ds_write_b128 v213, v[52:55] offset:384
	v_mfma_f32_16x16x32_bf16 v[44:47], v[28:31], v[44:47], 0
	s_nop 7
	ds_write_b128 v213, v[44:47] offset:448
	s_waitcnt lgkmcnt(0)
	v_fmamk_f32 v44, v216, 0x3a800000, v206
	v_mul_f32_e32 v45, 0x4b800000, v44
	v_cmp_gt_f32_e64 s[10:11], s77, v44
	ds_read2_b64 v[160:163], v214 offset1:66
	ds_read2_b64 v[148:151], v214 offset0:132 offset1:198
	ds_read2_b64 v[136:139], v220 offset0:8 offset1:74
	ds_read2_b64 v[124:127], v220 offset0:140 offset1:206
	ds_read2_b64 v[72:75], v221 offset0:16 offset1:82
	ds_read2_b64 v[68:71], v221 offset0:148 offset1:214
	ds_read2_b64 v[48:51], v222 offset0:24 offset1:90
	v_cndmask_b32_e64 v44, v44, v45, s[10:11]
	v_rsq_f32_e32 v52, v44
	ds_read2_b64 v[44:47], v222 offset0:156 offset1:222
	s_waitcnt lgkmcnt(0)
	v_mul_f32_e32 v53, 0x45800000, v52
	v_cndmask_b32_e64 v52, v52, v53, s[10:11]
	v_pk_mul_f32 v[54:55], v[84:85], v[52:53] op_sel_hi:[1,0]
	v_pk_mul_f32 v[84:85], v[86:87], v[52:53] op_sel_hi:[1,0]
	s_nop 0
	v_pk_mul_f32 v[86:87], v[42:43], v[84:85]
	v_pk_mul_f32 v[84:85], v[40:41], v[54:55]
	v_pk_mul_f32 v[54:55], v[88:89], v[52:53] op_sel_hi:[1,0]
	v_pk_mul_f32 v[52:53], v[90:91], v[52:53] op_sel_hi:[1,0]
	v_pk_mul_f32 v[88:89], v[36:37], v[54:55]
	v_pk_mul_f32 v[90:91], v[38:39], v[52:53]
	v_cvt_pk_bf16_f32 v52, v84, v85
	v_cvt_pk_bf16_f32 v53, v86, v87
	v_cvt_pk_bf16_f32 v54, v88, v89
	v_cvt_pk_bf16_f32 v55, v90, v91
	s_and_saveexec_b64 s[10:11], vcc
	s_cbranch_execz .LBB11_380
	ds_write_b128 v191, v[84:87] offset:12800
	ds_write_b128 v191, v[88:91] offset:12816
	s_branch .LBB11_380

.LBB11_689:
	s_or_b64 exec, exec, s[22:23]
	v_fmamk_f32 v128, v130, 0x3a800000, v206
	v_mul_f32_e32 v129, 0x4b800000, v128
	v_cmp_gt_f32_e32 vcc, s77, v128
	s_nop 1
	v_cndmask_b32_e32 v128, v128, v129, vcc
	v_rsq_f32_e32 v128, v128
	s_nop 0
	v_mul_f32_e32 v129, 0x45800000, v128
	v_cndmask_b32_e32 v158, v128, v129, vcc
	v_pk_mul_f32 v[100:101], v[100:101], v[158:159] op_sel_hi:[1,0]
	v_pk_mul_f32 v[102:103], v[102:103], v[158:159] op_sel_hi:[1,0]
	v_pk_mul_f32 v[128:129], v[40:41], v[100:101]
	v_pk_mul_f32 v[130:131], v[42:43], v[102:103]
	v_pk_mul_f32 v[100:101], v[104:105], v[158:159] op_sel_hi:[1,0]
	v_pk_mul_f32 v[102:103], v[106:107], v[158:159] op_sel_hi:[1,0]
	v_pk_mul_f32 v[104:105], v[36:37], v[100:101]
	v_pk_mul_f32 v[106:107], v[38:39], v[102:103]
	v_cvt_pk_bf16_f32 v100, v128, v129
	v_cvt_pk_bf16_f32 v101, v130, v131
	v_cvt_pk_bf16_f32 v102, v104, v105
	v_cvt_pk_bf16_f32 v103, v106, v107
	s_and_saveexec_b64 s[22:23], s[10:11]
	s_cbranch_execz .LBB11_691
	ds_write_b128 v145, v[128:131] offset:12800
	ds_write_b128 v145, v[104:107] offset:12816
.LBB11_691:
	s_or_b64 exec, exec, s[22:23]
	v_mfma_f32_16x16x32_bf16 v[104:107], v[8:11], v[100:103], 0
	v_mul_f32_e32 v182, v135, v143
	v_pk_mul_f32 v[190:191], v[134:135], v[142:143] op_sel:[0,1] op_sel_hi:[1,0]
	v_pk_fma_f32 v[182:183], v[134:135], v[142:143], v[182:183] op_sel_hi:[1,1,0] neg_lo:[0,0,1] neg_hi:[0,0,1]
	v_mfma_f32_16x16x32_bf16 v[128:131], v[4:7], v[100:103], 0
	v_fma_f32 v142, v0, v142, v190
	v_fma_f32 v143, v1, v143, v191
	s_nop 1
	ds_write_b128 v147, v[104:107]
	v_mfma_f32_16x16x32_bf16 v[158:161], v[16:19], v[100:103], 0
	v_mfma_f32_16x16x32_bf16 v[162:165], v[12:15], v[100:103], 0
	s_nop 0
	ds_write_b128 v147, v[128:131] offset:64
	s_nop 4
	ds_write_b128 v147, v[158:161] offset:128
	ds_write_b128 v147, v[162:165] offset:192
	v_mfma_f32_16x16x32_bf16 v[166:169], v[24:27], v[100:103], 0
	v_mfma_f32_16x16x32_bf16 v[104:107], v[20:23], v[100:103], 0
	v_mfma_f32_16x16x32_bf16 v[128:131], v[32:35], v[100:103], 0
	s_nop 5
	ds_write_b128 v147, v[166:169] offset:256
	ds_write_b128 v147, v[104:107] offset:320
	ds_write_b128 v147, v[128:131] offset:384
	v_add_u32_e32 v128, 0x800, v148
	v_mfma_f32_16x16x32_bf16 v[100:103], v[28:31], v[100:103], 0
	v_add_u32_e32 v129, 0x1000, v148
	v_add_u32_e32 v130, 0x1800, v148
	s_nop 5
	ds_write_b128 v147, v[100:103] offset:448
	s_waitcnt lgkmcnt(0)
	ds_read2_b64 v[100:103], v148 offset1:66
	ds_read2_b64 v[104:107], v148 offset0:132 offset1:198
	ds_read2_b64 v[158:161], v128 offset0:8 offset1:74
	ds_read2_b64 v[162:165], v128 offset0:140 offset1:206
	ds_read2_b64 v[166:169], v129 offset0:16 offset1:82
	ds_read2_b64 v[170:173], v129 offset0:148 offset1:214
	ds_read2_b64 v[174:177], v130 offset0:24 offset1:90
	ds_read2_b64 v[178:181], v130 offset0:156 offset1:222
	s_waitcnt lgkmcnt(7)
	v_pk_add_f32 v[182:183], v[182:183], v[100:101]
	v_pk_add_f32 v[100:101], v[142:143], v[100:101] op_sel:[0,1] op_sel_hi:[1,0]
	s_nop 0
	v_pk_mul_f32 v[142:143], v[0:1], v[100:101]
	v_cvt_pk_bf16_f32 v131, v182, v100
	ds_write_b32 v149, v131 offset:8448
	v_pk_fma_f32 v[142:143], v[134:135], v[182:183], v[142:143] neg_lo:[0,0,1] neg_hi:[0,0,1]
	v_pk_mul_f32 v[182:183], v[0:1], v[182:183]
	v_pk_add_f32 v[142:143], v[102:103], v[142:143]
	v_pk_fma_f32 v[100:101], v[134:135], v[100:101], v[182:183]
	s_nop 0
	v_pk_add_f32 v[100:101], v[102:103], v[100:101] op_sel:[1,0] op_sel_hi:[0,1]
	v_cvt_pk_bf16_f32 v102, v142, v100
	ds_write_b32 v149, v102 offset:8720
	v_pk_mul_f32 v[102:103], v[0:1], v[100:101]
	s_nop 0
	v_pk_fma_f32 v[102:103], v[134:135], v[142:143], v[102:103] neg_lo:[0,0,1] neg_hi:[0,0,1]
	v_pk_mul_f32 v[142:143], v[0:1], v[142:143]
	s_waitcnt lgkmcnt(8)
	v_pk_add_f32 v[102:103], v[104:105], v[102:103]
	v_pk_fma_f32 v[100:101], v[134:135], v[100:101], v[142:143]
	s_nop 0
	v_pk_add_f32 v[100:101], v[104:105], v[100:101] op_sel:[1,0] op_sel_hi:[0,1]
	v_cvt_pk_bf16_f32 v104, v102, v100
	ds_write_b32 v149, v104 offset:8992
	v_pk_mul_f32 v[104:105], v[0:1], v[100:101]
	s_nop 0
	v_pk_fma_f32 v[104:105], v[134:135], v[102:103], v[104:105] neg_lo:[0,0,1] neg_hi:[0,0,1]
	v_pk_mul_f32 v[102:103], v[0:1], v[102:103]
	v_pk_add_f32 v[104:105], v[106:107], v[104:105]
	v_pk_fma_f32 v[100:101], v[134:135], v[100:101], v[102:103]
	s_nop 0
	v_pk_add_f32 v[100:101], v[106:107], v[100:101] op_sel:[1,0] op_sel_hi:[0,1]
	v_cvt_pk_bf16_f32 v102, v104, v100
	ds_write_b32 v149, v102 offset:9264
	v_pk_mul_f32 v[102:103], v[0:1], v[100:101]
	s_nop 0
	v_pk_fma_f32 v[102:103], v[134:135], v[104:105], v[102:103] neg_lo:[0,0,1] neg_hi:[0,0,1]
	v_pk_mul_f32 v[104:105], v[0:1], v[104:105]
	s_waitcnt lgkmcnt(9)
	v_pk_add_f32 v[102:103], v[158:159], v[102:103]
	v_pk_fma_f32 v[100:101], v[134:135], v[100:101], v[104:105]
	s_nop 0
	v_pk_add_f32 v[100:101], v[158:159], v[100:101] op_sel:[1,0] op_sel_hi:[0,1]
	v_cvt_pk_bf16_f32 v104, v102, v100
	ds_write_b32 v149, v104 offset:9536
	v_pk_mul_f32 v[104:105], v[0:1], v[100:101]
	s_nop 0
	v_pk_fma_f32 v[104:105], v[134:135], v[102:103], v[104:105] neg_lo:[0,0,1] neg_hi:[0,0,1]
	v_pk_mul_f32 v[102:103], v[0:1], v[102:103]
	v_pk_add_f32 v[104:105], v[160:161], v[104:105]
	v_pk_fma_f32 v[100:101], v[134:135], v[100:101], v[102:103]
	s_nop 0
	v_pk_add_f32 v[100:101], v[160:161], v[100:101] op_sel:[1,0] op_sel_hi:[0,1]
	v_cvt_pk_bf16_f32 v102, v104, v100
	ds_write_b32 v149, v102 offset:9808
	v_pk_mul_f32 v[102:103], v[0:1], v[100:101]
	s_nop 0
	v_pk_fma_f32 v[102:103], v[134:135], v[104:105], v[102:103] neg_lo:[0,0,1] neg_hi:[0,0,1]
	v_pk_mul_f32 v[104:105], v[0:1], v[104:105]
	s_waitcnt lgkmcnt(10)
	v_pk_add_f32 v[102:103], v[162:163], v[102:103]
	v_pk_fma_f32 v[100:101], v[134:135], v[100:101], v[104:105]
	s_nop 0
	v_pk_add_f32 v[100:101], v[162:163], v[100:101] op_sel:[1,0] op_sel_hi:[0,1]
	v_cvt_pk_bf16_f32 v104, v102, v100
	ds_write_b32 v149, v104 offset:10080
	v_pk_mul_f32 v[104:105], v[0:1], v[100:101]
	s_nop 0
	v_pk_fma_f32 v[104:105], v[134:135], v[102:103], v[104:105] neg_lo:[0,0,1] neg_hi:[0,0,1]
	v_pk_mul_f32 v[102:103], v[0:1], v[102:103]
	v_pk_add_f32 v[104:105], v[164:165], v[104:105]
	v_pk_fma_f32 v[100:101], v[134:135], v[100:101], v[102:103]
	s_nop 0
	v_pk_add_f32 v[100:101], v[164:165], v[100:101] op_sel:[1,0] op_sel_hi:[0,1]
	v_cvt_pk_bf16_f32 v102, v104, v100
	ds_write_b32 v149, v102 offset:10352
	v_pk_mul_f32 v[102:103], v[0:1], v[100:101]
	s_nop 0
	v_pk_fma_f32 v[102:103], v[134:135], v[104:105], v[102:103] neg_lo:[0,0,1] neg_hi:[0,0,1]
	v_pk_mul_f32 v[104:105], v[0:1], v[104:105]
	s_waitcnt lgkmcnt(11)
	v_pk_add_f32 v[102:103], v[166:167], v[102:103]
	v_pk_fma_f32 v[100:101], v[134:135], v[100:101], v[104:105]
	s_nop 0
	v_pk_add_f32 v[100:101], v[166:167], v[100:101] op_sel:[1,0] op_sel_hi:[0,1]
	v_cvt_pk_bf16_f32 v104, v102, v100
	ds_write_b32 v149, v104 offset:10624
	v_pk_mul_f32 v[104:105], v[0:1], v[100:101]
	s_nop 0
	v_pk_fma_f32 v[104:105], v[134:135], v[102:103], v[104:105] neg_lo:[0,0,1] neg_hi:[0,0,1]
	v_pk_mul_f32 v[102:103], v[0:1], v[102:103]
	v_pk_add_f32 v[104:105], v[168:169], v[104:105]
	v_pk_fma_f32 v[100:101], v[134:135], v[100:101], v[102:103]
	s_nop 0
	v_pk_add_f32 v[100:101], v[168:169], v[100:101] op_sel:[1,0] op_sel_hi:[0,1]
	v_cvt_pk_bf16_f32 v102, v104, v100
	ds_write_b32 v149, v102 offset:10896
	v_pk_mul_f32 v[102:103], v[0:1], v[100:101]
	s_nop 0
	v_pk_fma_f32 v[102:103], v[134:135], v[104:105], v[102:103] neg_lo:[0,0,1] neg_hi:[0,0,1]
	v_pk_mul_f32 v[104:105], v[0:1], v[104:105]
	s_waitcnt lgkmcnt(12)
	v_pk_add_f32 v[102:103], v[170:171], v[102:103]
	v_pk_fma_f32 v[100:101], v[134:135], v[100:101], v[104:105]
	s_nop 0
	v_pk_add_f32 v[100:101], v[170:171], v[100:101] op_sel:[1,0] op_sel_hi:[0,1]
	v_cvt_pk_bf16_f32 v104, v102, v100
	ds_write_b32 v149, v104 offset:11168
	v_pk_mul_f32 v[104:105], v[0:1], v[100:101]
	s_nop 0
	v_pk_fma_f32 v[104:105], v[134:135], v[102:103], v[104:105] neg_lo:[0,0,1] neg_hi:[0,0,1]
	v_pk_mul_f32 v[102:103], v[0:1], v[102:103]
	v_pk_add_f32 v[104:105], v[172:173], v[104:105]
	v_pk_fma_f32 v[100:101], v[134:135], v[100:101], v[102:103]
	s_nop 0
	v_pk_add_f32 v[100:101], v[172:173], v[100:101] op_sel:[1,0] op_sel_hi:[0,1]
	v_cvt_pk_bf16_f32 v102, v104, v100
	ds_write_b32 v149, v102 offset:11440
	v_pk_mul_f32 v[102:103], v[0:1], v[100:101]
	s_nop 0
	v_pk_fma_f32 v[102:103], v[134:135], v[104:105], v[102:103] neg_lo:[0,0,1] neg_hi:[0,0,1]
	v_pk_mul_f32 v[104:105], v[0:1], v[104:105]
	s_waitcnt lgkmcnt(13)
	v_pk_add_f32 v[102:103], v[174:175], v[102:103]
	v_pk_fma_f32 v[100:101], v[134:135], v[100:101], v[104:105]
	s_nop 0
	v_pk_add_f32 v[100:101], v[174:175], v[100:101] op_sel:[1,0] op_sel_hi:[0,1]
	v_cvt_pk_bf16_f32 v104, v102, v100
	ds_write_b32 v149, v104 offset:11712
	v_pk_mul_f32 v[104:105], v[0:1], v[100:101]
	s_nop 0
	v_pk_fma_f32 v[104:105], v[134:135], v[102:103], v[104:105] neg_lo:[0,0,1] neg_hi:[0,0,1]
	v_pk_mul_f32 v[102:103], v[0:1], v[102:103]
	v_pk_add_f32 v[104:105], v[176:177], v[104:105]
	v_pk_fma_f32 v[100:101], v[134:135], v[100:101], v[102:103]
	s_nop 0
	v_pk_add_f32 v[100:101], v[176:177], v[100:101] op_sel:[1,0] op_sel_hi:[0,1]
	v_cvt_pk_bf16_f32 v102, v104, v100
	ds_write_b32 v149, v102 offset:11984
	v_pk_mul_f32 v[102:103], v[0:1], v[100:101]
	s_nop 0
	v_pk_fma_f32 v[102:103], v[134:135], v[104:105], v[102:103] neg_lo:[0,0,1] neg_hi:[0,0,1]
	v_pk_mul_f32 v[104:105], v[0:1], v[104:105]
	s_waitcnt lgkmcnt(14)
	v_pk_add_f32 v[102:103], v[178:179], v[102:103]
	v_pk_fma_f32 v[100:101], v[134:135], v[100:101], v[104:105]
	s_nop 0
	v_pk_add_f32 v[100:101], v[178:179], v[100:101] op_sel:[1,0] op_sel_hi:[0,1]
	v_cvt_pk_bf16_f32 v104, v102, v100
	ds_write_b32 v149, v104 offset:12256
	v_pk_mul_f32 v[104:105], v[0:1], v[100:101]
	s_nop 0
	v_pk_fma_f32 v[104:105], v[134:135], v[102:103], v[104:105] neg_lo:[0,0,1] neg_hi:[0,0,1]
	v_pk_mul_f32 v[102:103], v[0:1], v[102:103]
	v_pk_add_f32 v[104:105], v[180:181], v[104:105]
	v_pk_fma_f32 v[100:101], v[134:135], v[100:101], v[102:103]
	s_nop 0
	v_pk_add_f32 v[106:107], v[180:181], v[100:101] op_sel:[1,0] op_sel_hi:[0,1]
	v_cvt_pk_bf16_f32 v100, v104, v106
	ds_write_b32 v149, v100 offset:12528
	s_waitcnt lgkmcnt(0)
	ds_read_b128 v[100:103], v150 offset:8448
	ds_read_b128 v[158:161], v150 offset:8512
	s_waitcnt lgkmcnt(1)
	v_mfma_f32_16x16x32_bf16 v[100:103], v[52:55], v[100:103], 0
	s_waitcnt lgkmcnt(0)
	v_mfma_f32_16x16x32_bf16 v[100:103], v[44:47], v[158:161], v[100:103]
	ds_read_b128 v[158:161], v150 offset:8576
	ds_read_b128 v[162:165], v150 offset:8640
	s_waitcnt lgkmcnt(1)
	v_mfma_f32_16x16x32_bf16 v[100:103], v[48:51], v[158:161], v[100:103]
	ds_read_b128 v[158:161], v151 offset:12800
	s_waitcnt lgkmcnt(1)
	v_mfma_f32_16x16x32_bf16 v[100:103], v[56:59], v[162:165], v[100:103]
	s_waitcnt lgkmcnt(0)
	s_nop 6
	v_pk_fma_f32 v[100:101], v[60:61], v[158:159], v[100:101]
	v_pk_fma_f32 v[102:103], v[62:63], v[160:161], v[102:103]
	v_mul_f32_e32 v131, 0x3d922279, v100
	v_fmaak_f32 v131, v100, v131, 0x3fcc422a
	v_mul_f32_e32 v131, v100, v131
	v_mul_f32_e32 v131, 0xbfb8aa3b, v131
	v_exp_f32_e32 v131, v131
	v_mul_f32_e32 v141, 0x3d922279, v101
	v_fmaak_f32 v141, v101, v141, 0x3fcc422a
	v_mul_f32_e32 v141, v101, v141
	v_add_f32_e32 v131, 1.0, v131
	v_mul_f32_e32 v141, 0xbfb8aa3b, v141
	v_rcp_f32_e32 v131, v131
	v_exp_f32_e32 v141, v141
	v_mul_f32_e32 v142, 0x3d922279, v103
	v_fmaak_f32 v142, v103, v142, 0x3fcc422a
	v_mul_f32_e32 v100, v100, v131
	v_add_f32_e32 v131, 1.0, v141
	v_mul_f32_e32 v141, 0x3d922279, v102
	v_fmaak_f32 v141, v102, v141, 0x3fcc422a
	v_mul_f32_e32 v141, v102, v141
	v_mul_f32_e32 v142, v103, v142
	v_mul_f32_e32 v141, 0xbfb8aa3b, v141
	v_mul_f32_e32 v142, 0xbfb8aa3b, v142
	v_exp_f32_e32 v141, v141
	v_exp_f32_e32 v142, v142
	v_rcp_f32_e32 v131, v131
	v_add_f32_e32 v141, 1.0, v141
	v_add_f32_e32 v142, 1.0, v142
	v_rcp_f32_e32 v141, v141
	v_rcp_f32_e32 v142, v142
	v_mul_f32_e32 v101, v101, v131
	v_cvt_pk_bf16_f32 v100, v100, v101
	v_mul_f32_e32 v101, v102, v141
	v_mul_f32_e32 v102, v103, v142
	v_ashrrev_i32_e32 v141, 31, v140
	v_fmamk_f32 v131, v152, 0x3a800000, v206
	v_cvt_pk_bf16_f32 v101, v101, v102
	v_lshlrev_b64 v[102:103], 11, v[140:141]
	v_mul_f32_e32 v141, 0x4b800000, v131
	v_cmp_gt_f32_e32 vcc, s77, v131
	v_lshl_add_u64 v[102:103], v[2:3], 0, v[102:103]
	global_store_dwordx2 v[102:103], v[100:101], off
	v_cndmask_b32_e32 v131, v131, v141, vcc
	v_rsq_f32_e32 v131, v131
	s_waitcnt lgkmcnt(0)
	s_nop 0
	v_mul_f32_e32 v100, 0x45800000, v131
	v_cndmask_b32_e32 v142, v131, v100, vcc
	v_pk_mul_f32 v[88:89], v[88:89], v[142:143] op_sel_hi:[1,0]
	v_pk_mul_f32 v[90:91], v[90:91], v[142:143] op_sel_hi:[1,0]
	v_pk_mul_f32 v[100:101], v[40:41], v[88:89]
	v_pk_mul_f32 v[102:103], v[42:43], v[90:91]
	v_pk_mul_f32 v[88:89], v[92:93], v[142:143] op_sel_hi:[1,0]
	v_pk_mul_f32 v[90:91], v[94:95], v[142:143] op_sel_hi:[1,0]
	v_pk_mul_f32 v[92:93], v[36:37], v[88:89]
	v_pk_mul_f32 v[94:95], v[38:39], v[90:91]
	v_cvt_pk_bf16_f32 v88, v100, v101
	v_cvt_pk_bf16_f32 v89, v102, v103
	v_cvt_pk_bf16_f32 v90, v92, v93
	v_cvt_pk_bf16_f32 v91, v94, v95
	s_and_saveexec_b64 s[22:23], s[10:11]
	s_cbranch_execz .LBB11_693
	ds_write_b128 v145, v[100:103] offset:12800
	ds_write_b128 v145, v[92:95] offset:12816
.LBB11_693:
	s_or_b64 exec, exec, s[22:23]
	v_mfma_f32_16x16x32_bf16 v[92:95], v[8:11], v[88:91], 0
	v_mul_f32_e64 v142, v0, v106
	v_mul_f32_e64 v143, v1, v107
	v_pk_fma_f32 v[142:143], v[134:135], v[104:105], v[142:143] neg_lo:[0,0,1] neg_hi:[0,0,1]
	v_mfma_f32_16x16x32_bf16 v[100:103], v[4:7], v[88:91], 0
	v_mul_f32_e64 v104, v0, v104
	v_mul_f32_e64 v105, v1, v105
	s_nop 1
	ds_write_b128 v147, v[92:95]
	v_pk_fma_f32 v[104:105], v[134:135], v[106:107], v[104:105]
	v_mfma_f32_16x16x32_bf16 v[158:161], v[16:19], v[88:91], 0
	v_mfma_f32_16x16x32_bf16 v[162:165], v[12:15], v[88:91], 0
	ds_write_b128 v147, v[100:103] offset:64
	s_nop 5
	ds_write_b128 v147, v[158:161] offset:128
	ds_write_b128 v147, v[162:165] offset:192
	v_mfma_f32_16x16x32_bf16 v[166:169], v[24:27], v[88:91], 0
	v_mfma_f32_16x16x32_bf16 v[92:95], v[20:23], v[88:91], 0
	v_mfma_f32_16x16x32_bf16 v[100:103], v[32:35], v[88:91], 0
	s_nop 5
	ds_write_b128 v147, v[166:169] offset:256
	ds_write_b128 v147, v[92:95] offset:320
	ds_write_b128 v147, v[100:103] offset:384
	v_mfma_f32_16x16x32_bf16 v[88:91], v[28:31], v[88:91], 0
	s_nop 7
	ds_write_b128 v147, v[88:91] offset:448
	s_waitcnt lgkmcnt(0)
	ds_read2_b64 v[88:91], v148 offset1:66
	ds_read2_b64 v[92:95], v148 offset0:132 offset1:198
	ds_read2_b64 v[100:103], v128 offset0:8 offset1:74
	ds_read2_b64 v[158:161], v128 offset0:140 offset1:206
	ds_read2_b64 v[162:165], v129 offset0:16 offset1:82
	ds_read2_b64 v[166:169], v129 offset0:148 offset1:214
	ds_read2_b64 v[170:173], v130 offset0:24 offset1:90
	ds_read2_b64 v[174:177], v130 offset0:156 offset1:222
	s_waitcnt lgkmcnt(7)
	v_pk_add_f32 v[142:143], v[142:143], v[88:89]
	v_pk_add_f32 v[88:89], v[104:105], v[88:89] op_sel:[0,1] op_sel_hi:[1,0]
	v_pk_mul_f32 v[106:107], v[0:1], v[142:143]
	v_cvt_pk_bf16_f32 v104, v142, v88
	ds_write_b32 v149, v104 offset:8448
	v_pk_mul_f32 v[104:105], v[0:1], v[88:89]
	v_pk_fma_f32 v[88:89], v[134:135], v[88:89], v[106:107]
	v_pk_fma_f32 v[104:105], v[134:135], v[142:143], v[104:105] neg_lo:[0,0,1] neg_hi:[0,0,1]
	v_pk_add_f32 v[88:89], v[90:91], v[88:89] op_sel:[1,0] op_sel_hi:[0,1]
	v_pk_add_f32 v[104:105], v[90:91], v[104:105]
	s_nop 0
	v_cvt_pk_bf16_f32 v90, v104, v88
	ds_write_b32 v149, v90 offset:8720
	v_pk_mul_f32 v[90:91], v[0:1], v[88:89]
	s_nop 0
	v_pk_fma_f32 v[90:91], v[134:135], v[104:105], v[90:91] neg_lo:[0,0,1] neg_hi:[0,0,1]
	v_pk_mul_f32 v[104:105], v[0:1], v[104:105]
	s_waitcnt lgkmcnt(8)
	v_pk_add_f32 v[90:91], v[92:93], v[90:91]
	v_pk_fma_f32 v[88:89], v[134:135], v[88:89], v[104:105]
	s_nop 0
	v_pk_add_f32 v[88:89], v[92:93], v[88:89] op_sel:[1,0] op_sel_hi:[0,1]
	v_cvt_pk_bf16_f32 v92, v90, v88
	ds_write_b32 v149, v92 offset:8992
	v_pk_mul_f32 v[92:93], v[0:1], v[88:89]
	s_nop 0
	v_pk_fma_f32 v[92:93], v[134:135], v[90:91], v[92:93] neg_lo:[0,0,1] neg_hi:[0,0,1]
	v_pk_mul_f32 v[90:91], v[0:1], v[90:91]
	v_pk_add_f32 v[92:93], v[94:95], v[92:93]
	v_pk_fma_f32 v[88:89], v[134:135], v[88:89], v[90:91]
	s_nop 0
	v_pk_add_f32 v[88:89], v[94:95], v[88:89] op_sel:[1,0] op_sel_hi:[0,1]
	v_cvt_pk_bf16_f32 v90, v92, v88
	ds_write_b32 v149, v90 offset:9264
	v_pk_mul_f32 v[90:91], v[0:1], v[88:89]
	s_nop 0
	v_pk_fma_f32 v[90:91], v[134:135], v[92:93], v[90:91] neg_lo:[0,0,1] neg_hi:[0,0,1]
	v_pk_mul_f32 v[92:93], v[0:1], v[92:93]
	s_waitcnt lgkmcnt(9)
	v_pk_add_f32 v[90:91], v[100:101], v[90:91]
	v_pk_fma_f32 v[88:89], v[134:135], v[88:89], v[92:93]
	s_nop 0
	v_pk_add_f32 v[88:89], v[100:101], v[88:89] op_sel:[1,0] op_sel_hi:[0,1]
	v_cvt_pk_bf16_f32 v92, v90, v88
	ds_write_b32 v149, v92 offset:9536
	v_pk_mul_f32 v[92:93], v[0:1], v[88:89]
	s_nop 0
	v_pk_fma_f32 v[92:93], v[134:135], v[90:91], v[92:93] neg_lo:[0,0,1] neg_hi:[0,0,1]
	v_pk_mul_f32 v[90:91], v[0:1], v[90:91]
	v_pk_add_f32 v[92:93], v[102:103], v[92:93]
	v_pk_fma_f32 v[88:89], v[134:135], v[88:89], v[90:91]
	s_nop 0
	v_pk_add_f32 v[88:89], v[102:103], v[88:89] op_sel:[1,0] op_sel_hi:[0,1]
	v_cvt_pk_bf16_f32 v90, v92, v88
	ds_write_b32 v149, v90 offset:9808
	v_pk_mul_f32 v[90:91], v[0:1], v[88:89]
	s_nop 0
	v_pk_fma_f32 v[90:91], v[134:135], v[92:93], v[90:91] neg_lo:[0,0,1] neg_hi:[0,0,1]
	v_pk_mul_f32 v[92:93], v[0:1], v[92:93]
	s_waitcnt lgkmcnt(10)
	v_pk_add_f32 v[90:91], v[158:159], v[90:91]
	v_pk_fma_f32 v[88:89], v[134:135], v[88:89], v[92:93]
	s_nop 0
	v_pk_add_f32 v[88:89], v[158:159], v[88:89] op_sel:[1,0] op_sel_hi:[0,1]
	v_cvt_pk_bf16_f32 v92, v90, v88
	ds_write_b32 v149, v92 offset:10080
	v_pk_mul_f32 v[92:93], v[0:1], v[88:89]
	s_nop 0
	v_pk_fma_f32 v[92:93], v[134:135], v[90:91], v[92:93] neg_lo:[0,0,1] neg_hi:[0,0,1]
	v_pk_mul_f32 v[90:91], v[0:1], v[90:91]
	v_pk_add_f32 v[92:93], v[160:161], v[92:93]
	v_pk_fma_f32 v[88:89], v[134:135], v[88:89], v[90:91]
	s_nop 0
	v_pk_add_f32 v[88:89], v[160:161], v[88:89] op_sel:[1,0] op_sel_hi:[0,1]
	v_cvt_pk_bf16_f32 v90, v92, v88
	ds_write_b32 v149, v90 offset:10352
	v_pk_mul_f32 v[90:91], v[0:1], v[88:89]
	s_nop 0
	v_pk_fma_f32 v[90:91], v[134:135], v[92:93], v[90:91] neg_lo:[0,0,1] neg_hi:[0,0,1]
	v_pk_mul_f32 v[92:93], v[0:1], v[92:93]
	s_waitcnt lgkmcnt(11)
	v_pk_add_f32 v[90:91], v[162:163], v[90:91]
	v_pk_fma_f32 v[88:89], v[134:135], v[88:89], v[92:93]
	s_nop 0
	v_pk_add_f32 v[88:89], v[162:163], v[88:89] op_sel:[1,0] op_sel_hi:[0,1]
	v_cvt_pk_bf16_f32 v92, v90, v88
	ds_write_b32 v149, v92 offset:10624
	v_pk_mul_f32 v[92:93], v[0:1], v[88:89]
	s_nop 0
	v_pk_fma_f32 v[92:93], v[134:135], v[90:91], v[92:93] neg_lo:[0,0,1] neg_hi:[0,0,1]
	v_pk_mul_f32 v[90:91], v[0:1], v[90:91]
	v_pk_add_f32 v[92:93], v[164:165], v[92:93]
	v_pk_fma_f32 v[88:89], v[134:135], v[88:89], v[90:91]
	s_nop 0
	v_pk_add_f32 v[88:89], v[164:165], v[88:89] op_sel:[1,0] op_sel_hi:[0,1]
	v_cvt_pk_bf16_f32 v90, v92, v88
	ds_write_b32 v149, v90 offset:10896
	v_pk_mul_f32 v[90:91], v[0:1], v[88:89]
	s_nop 0
	v_pk_fma_f32 v[90:91], v[134:135], v[92:93], v[90:91] neg_lo:[0,0,1] neg_hi:[0,0,1]
	v_pk_mul_f32 v[92:93], v[0:1], v[92:93]
	s_waitcnt lgkmcnt(12)
	v_pk_add_f32 v[90:91], v[166:167], v[90:91]
	v_pk_fma_f32 v[88:89], v[134:135], v[88:89], v[92:93]
	s_nop 0
	v_pk_add_f32 v[88:89], v[166:167], v[88:89] op_sel:[1,0] op_sel_hi:[0,1]
	v_cvt_pk_bf16_f32 v92, v90, v88
	ds_write_b32 v149, v92 offset:11168
	v_pk_mul_f32 v[92:93], v[0:1], v[88:89]
	s_nop 0
	v_pk_fma_f32 v[92:93], v[134:135], v[90:91], v[92:93] neg_lo:[0,0,1] neg_hi:[0,0,1]
	v_pk_mul_f32 v[90:91], v[0:1], v[90:91]
	v_pk_add_f32 v[92:93], v[168:169], v[92:93]
	v_pk_fma_f32 v[88:89], v[134:135], v[88:89], v[90:91]
	s_nop 0
	v_pk_add_f32 v[88:89], v[168:169], v[88:89] op_sel:[1,0] op_sel_hi:[0,1]
	v_cvt_pk_bf16_f32 v90, v92, v88
	ds_write_b32 v149, v90 offset:11440
	v_pk_mul_f32 v[90:91], v[0:1], v[88:89]
	s_nop 0
	v_pk_fma_f32 v[90:91], v[134:135], v[92:93], v[90:91] neg_lo:[0,0,1] neg_hi:[0,0,1]
	v_pk_mul_f32 v[92:93], v[0:1], v[92:93]
	s_waitcnt lgkmcnt(13)
	v_pk_add_f32 v[90:91], v[170:171], v[90:91]
	v_pk_fma_f32 v[88:89], v[134:135], v[88:89], v[92:93]
	s_nop 0
	v_pk_add_f32 v[88:89], v[170:171], v[88:89] op_sel:[1,0] op_sel_hi:[0,1]
	v_cvt_pk_bf16_f32 v92, v90, v88
	ds_write_b32 v149, v92 offset:11712
	v_pk_mul_f32 v[92:93], v[0:1], v[88:89]
	s_nop 0
	v_pk_fma_f32 v[92:93], v[134:135], v[90:91], v[92:93] neg_lo:[0,0,1] neg_hi:[0,0,1]
	v_pk_mul_f32 v[90:91], v[0:1], v[90:91]
	v_pk_add_f32 v[92:93], v[172:173], v[92:93]
	v_pk_fma_f32 v[88:89], v[134:135], v[88:89], v[90:91]
	s_nop 0
	v_pk_add_f32 v[88:89], v[172:173], v[88:89] op_sel:[1,0] op_sel_hi:[0,1]
	v_cvt_pk_bf16_f32 v90, v92, v88
	ds_write_b32 v149, v90 offset:11984
	v_pk_mul_f32 v[90:91], v[0:1], v[88:89]
	s_nop 0
	v_pk_fma_f32 v[90:91], v[134:135], v[92:93], v[90:91] neg_lo:[0,0,1] neg_hi:[0,0,1]
	v_pk_mul_f32 v[92:93], v[0:1], v[92:93]
	s_waitcnt lgkmcnt(14)
	v_pk_add_f32 v[90:91], v[174:175], v[90:91]
	v_pk_fma_f32 v[88:89], v[134:135], v[88:89], v[92:93]
	s_nop 0
	v_pk_add_f32 v[88:89], v[174:175], v[88:89] op_sel:[1,0] op_sel_hi:[0,1]
	v_cvt_pk_bf16_f32 v92, v90, v88
	ds_write_b32 v149, v92 offset:12256
	v_pk_mul_f32 v[92:93], v[0:1], v[88:89]
	s_nop 0
	v_pk_fma_f32 v[92:93], v[134:135], v[90:91], v[92:93] neg_lo:[0,0,1] neg_hi:[0,0,1]
	v_pk_mul_f32 v[90:91], v[0:1], v[90:91]
	v_pk_add_f32 v[92:93], v[176:177], v[92:93]
	v_pk_fma_f32 v[88:89], v[134:135], v[88:89], v[90:91]
	s_nop 0
	v_pk_add_f32 v[94:95], v[176:177], v[88:89] op_sel:[1,0] op_sel_hi:[0,1]
	v_cvt_pk_bf16_f32 v88, v92, v94
	ds_write_b32 v149, v88 offset:12528
	s_waitcnt lgkmcnt(0)
	ds_read_b128 v[88:91], v150 offset:8448
	ds_read_b128 v[100:103], v150 offset:8512
	s_waitcnt lgkmcnt(1)
	v_mfma_f32_16x16x32_bf16 v[88:91], v[52:55], v[88:91], 0
	s_waitcnt lgkmcnt(0)
	v_mfma_f32_16x16x32_bf16 v[88:91], v[44:47], v[100:103], v[88:91]
	ds_read_b128 v[100:103], v150 offset:8576
	ds_read_b128 v[104:107], v150 offset:8640
	s_waitcnt lgkmcnt(1)
	v_mfma_f32_16x16x32_bf16 v[88:91], v[48:51], v[100:103], v[88:91]
	ds_read_b128 v[100:103], v151 offset:12800
	s_waitcnt lgkmcnt(1)
	v_mfma_f32_16x16x32_bf16 v[88:91], v[56:59], v[104:107], v[88:91]
	s_waitcnt lgkmcnt(0)
	s_nop 6
	v_pk_fma_f32 v[88:89], v[60:61], v[100:101], v[88:89]
	v_pk_fma_f32 v[90:91], v[62:63], v[102:103], v[90:91]
	v_mul_f32_e32 v100, 0x3d922279, v88
	v_fmaak_f32 v100, v88, v100, 0x3fcc422a
	v_mul_f32_e32 v100, v88, v100
	v_mul_f32_e32 v100, 0xbfb8aa3b, v100
	v_exp_f32_e32 v100, v100
	v_mul_f32_e32 v101, 0x3d922279, v89
	v_fmaak_f32 v101, v89, v101, 0x3fcc422a
	v_mul_f32_e32 v101, v89, v101
	v_add_f32_e32 v100, 1.0, v100
	v_mul_f32_e32 v101, 0xbfb8aa3b, v101
	v_rcp_f32_e32 v100, v100
	v_exp_f32_e32 v101, v101
	v_mul_f32_e32 v102, 0x3d922279, v91
	v_fmaak_f32 v102, v91, v102, 0x3fcc422a
	v_mul_f32_e32 v88, v88, v100
	v_add_f32_e32 v100, 1.0, v101
	v_mul_f32_e32 v101, 0x3d922279, v90
	v_fmaak_f32 v101, v90, v101, 0x3fcc422a
	v_mul_f32_e32 v101, v90, v101
	v_mul_f32_e32 v101, 0xbfb8aa3b, v101
	v_mul_f32_e32 v102, v91, v102
	v_exp_f32_e32 v101, v101
	v_mul_f32_e32 v102, 0xbfb8aa3b, v102
	v_exp_f32_e32 v102, v102
	v_rcp_f32_e32 v100, v100
	v_add_f32_e32 v101, 1.0, v101
	v_rcp_f32_e32 v101, v101
	v_add_f32_e32 v102, 1.0, v102
	v_rcp_f32_e32 v102, v102
	v_mul_f32_e32 v89, v89, v100
	v_fmamk_f32 v100, v154, 0x3a800000, v206
	v_cvt_pk_bf16_f32 v88, v88, v89
	v_mul_f32_e32 v89, v90, v101
	v_mul_f32_e32 v101, 0x4b800000, v100
	v_cmp_gt_f32_e32 vcc, s77, v100
	v_mul_f32_e32 v90, v91, v102
	v_cvt_pk_bf16_f32 v89, v89, v90
	v_add_u32_e32 v90, 16, v140
	v_cndmask_b32_e32 v100, v100, v101, vcc
	v_rsq_f32_e32 v100, v100
	v_ashrrev_i32_e32 v91, 31, v90
	v_lshlrev_b64 v[90:91], 11, v[90:91]
	v_lshl_add_u64 v[90:91], v[2:3], 0, v[90:91]
	global_store_dwordx2 v[90:91], v[88:89], off
	v_mul_f32_e32 v88, 0x45800000, v100
	s_waitcnt lgkmcnt(0)
	v_cndmask_b32_e32 v100, v100, v88, vcc
	v_pk_mul_f32 v[72:73], v[72:73], v[100:101] op_sel_hi:[1,0]
	v_pk_mul_f32 v[74:75], v[74:75], v[100:101] op_sel_hi:[1,0]
	v_pk_mul_f32 v[88:89], v[40:41], v[72:73]
	v_pk_mul_f32 v[90:91], v[42:43], v[74:75]
	v_pk_mul_f32 v[72:73], v[76:77], v[100:101] op_sel_hi:[1,0]
	v_pk_mul_f32 v[74:75], v[78:79], v[100:101] op_sel_hi:[1,0]
	v_pk_mul_f32 v[76:77], v[36:37], v[72:73]
	v_pk_mul_f32 v[78:79], v[38:39], v[74:75]
	v_cvt_pk_bf16_f32 v72, v88, v89
	v_cvt_pk_bf16_f32 v73, v90, v91
	v_cvt_pk_bf16_f32 v74, v76, v77
	v_cvt_pk_bf16_f32 v75, v78, v79
	s_and_saveexec_b64 s[22:23], s[10:11]
	s_cbranch_execz .LBB11_695
	ds_write_b128 v145, v[88:91] offset:12800
	ds_write_b128 v145, v[76:79] offset:12816
.LBB11_695:
	s_or_b64 exec, exec, s[22:23]
	v_mfma_f32_16x16x32_bf16 v[76:79], v[8:11], v[72:75], 0
	v_mul_f32_e64 v142, v0, v94
	v_mul_f32_e64 v143, v1, v95
	v_pk_fma_f32 v[142:143], v[134:135], v[92:93], v[142:143] neg_lo:[0,0,1] neg_hi:[0,0,1]
	v_mfma_f32_16x16x32_bf16 v[88:91], v[4:7], v[72:75], 0
	v_mul_f32_e64 v92, v0, v92
	v_mul_f32_e64 v93, v1, v93
	s_nop 1
	ds_write_b128 v147, v[76:79]
	v_pk_fma_f32 v[92:93], v[134:135], v[94:95], v[92:93]
	v_mfma_f32_16x16x32_bf16 v[100:103], v[16:19], v[72:75], 0
	v_mfma_f32_16x16x32_bf16 v[104:107], v[12:15], v[72:75], 0
	ds_write_b128 v147, v[88:91] offset:64
	s_nop 5
	ds_write_b128 v147, v[100:103] offset:128
	ds_write_b128 v147, v[104:107] offset:192
	v_mfma_f32_16x16x32_bf16 v[158:161], v[24:27], v[72:75], 0
	v_mfma_f32_16x16x32_bf16 v[76:79], v[20:23], v[72:75], 0
	v_mfma_f32_16x16x32_bf16 v[88:91], v[32:35], v[72:75], 0
	s_nop 5
	ds_write_b128 v147, v[158:161] offset:256
	ds_write_b128 v147, v[76:79] offset:320
	ds_write_b128 v147, v[88:91] offset:384
	v_mfma_f32_16x16x32_bf16 v[72:75], v[28:31], v[72:75], 0
	s_nop 7
	ds_write_b128 v147, v[72:75] offset:448
	s_waitcnt lgkmcnt(0)
	ds_read2_b64 v[72:75], v148 offset1:66
	ds_read2_b64 v[76:79], v148 offset0:132 offset1:198
	ds_read2_b64 v[88:91], v128 offset0:8 offset1:74
	ds_read2_b64 v[100:103], v128 offset0:140 offset1:206
	ds_read2_b64 v[104:107], v129 offset0:16 offset1:82
	ds_read2_b64 v[158:161], v129 offset0:148 offset1:214
	ds_read2_b64 v[162:165], v130 offset0:24 offset1:90
	ds_read2_b64 v[166:169], v130 offset0:156 offset1:222
	s_waitcnt lgkmcnt(7)
	v_pk_add_f32 v[142:143], v[142:143], v[72:73]
	v_pk_add_f32 v[72:73], v[92:93], v[72:73] op_sel:[0,1] op_sel_hi:[1,0]
	v_pk_mul_f32 v[94:95], v[0:1], v[142:143]
	v_cvt_pk_bf16_f32 v92, v142, v72
	ds_write_b32 v149, v92 offset:8448
	v_pk_mul_f32 v[92:93], v[0:1], v[72:73]
	v_pk_fma_f32 v[72:73], v[134:135], v[72:73], v[94:95]
	v_pk_fma_f32 v[92:93], v[134:135], v[142:143], v[92:93] neg_lo:[0,0,1] neg_hi:[0,0,1]
	v_pk_add_f32 v[72:73], v[74:75], v[72:73] op_sel:[1,0] op_sel_hi:[0,1]
	v_pk_add_f32 v[92:93], v[74:75], v[92:93]
	s_nop 0
	v_cvt_pk_bf16_f32 v74, v92, v72
	ds_write_b32 v149, v74 offset:8720
	v_pk_mul_f32 v[74:75], v[0:1], v[72:73]
	s_nop 0
	v_pk_fma_f32 v[74:75], v[134:135], v[92:93], v[74:75] neg_lo:[0,0,1] neg_hi:[0,0,1]
	v_pk_mul_f32 v[92:93], v[0:1], v[92:93]
	s_waitcnt lgkmcnt(8)
	v_pk_add_f32 v[74:75], v[76:77], v[74:75]
	v_pk_fma_f32 v[72:73], v[134:135], v[72:73], v[92:93]
	s_nop 0
	v_pk_add_f32 v[72:73], v[76:77], v[72:73] op_sel:[1,0] op_sel_hi:[0,1]
	v_cvt_pk_bf16_f32 v76, v74, v72
	ds_write_b32 v149, v76 offset:8992
	v_pk_mul_f32 v[76:77], v[0:1], v[72:73]
	s_nop 0
	v_pk_fma_f32 v[76:77], v[134:135], v[74:75], v[76:77] neg_lo:[0,0,1] neg_hi:[0,0,1]
	v_pk_mul_f32 v[74:75], v[0:1], v[74:75]
	v_pk_add_f32 v[76:77], v[78:79], v[76:77]
	v_pk_fma_f32 v[72:73], v[134:135], v[72:73], v[74:75]
	s_nop 0
	v_pk_add_f32 v[72:73], v[78:79], v[72:73] op_sel:[1,0] op_sel_hi:[0,1]
	v_cvt_pk_bf16_f32 v74, v76, v72
	ds_write_b32 v149, v74 offset:9264
	v_pk_mul_f32 v[74:75], v[0:1], v[72:73]
	s_nop 0
	v_pk_fma_f32 v[74:75], v[134:135], v[76:77], v[74:75] neg_lo:[0,0,1] neg_hi:[0,0,1]
	v_pk_mul_f32 v[76:77], v[0:1], v[76:77]
	s_waitcnt lgkmcnt(9)
	v_pk_add_f32 v[74:75], v[88:89], v[74:75]
	v_pk_fma_f32 v[72:73], v[134:135], v[72:73], v[76:77]
	s_nop 0
	v_pk_add_f32 v[72:73], v[88:89], v[72:73] op_sel:[1,0] op_sel_hi:[0,1]
	v_cvt_pk_bf16_f32 v76, v74, v72
	ds_write_b32 v149, v76 offset:9536
	v_pk_mul_f32 v[76:77], v[0:1], v[72:73]
	s_nop 0
	v_pk_fma_f32 v[76:77], v[134:135], v[74:75], v[76:77] neg_lo:[0,0,1] neg_hi:[0,0,1]
	v_pk_mul_f32 v[74:75], v[0:1], v[74:75]
	v_pk_add_f32 v[76:77], v[90:91], v[76:77]
	v_pk_fma_f32 v[72:73], v[134:135], v[72:73], v[74:75]
	s_nop 0
	v_pk_add_f32 v[72:73], v[90:91], v[72:73] op_sel:[1,0] op_sel_hi:[0,1]
	v_cvt_pk_bf16_f32 v74, v76, v72
	ds_write_b32 v149, v74 offset:9808
	v_pk_mul_f32 v[74:75], v[0:1], v[72:73]
	s_nop 0
	v_pk_fma_f32 v[74:75], v[134:135], v[76:77], v[74:75] neg_lo:[0,0,1] neg_hi:[0,0,1]
	v_pk_mul_f32 v[76:77], v[0:1], v[76:77]
	s_waitcnt lgkmcnt(10)
	v_pk_add_f32 v[74:75], v[100:101], v[74:75]
	v_pk_fma_f32 v[72:73], v[134:135], v[72:73], v[76:77]
	s_nop 0
	v_pk_add_f32 v[72:73], v[100:101], v[72:73] op_sel:[1,0] op_sel_hi:[0,1]
	v_cvt_pk_bf16_f32 v76, v74, v72
	ds_write_b32 v149, v76 offset:10080
	v_pk_mul_f32 v[76:77], v[0:1], v[72:73]
	s_nop 0
	v_pk_fma_f32 v[76:77], v[134:135], v[74:75], v[76:77] neg_lo:[0,0,1] neg_hi:[0,0,1]
	v_pk_mul_f32 v[74:75], v[0:1], v[74:75]
	v_pk_add_f32 v[76:77], v[102:103], v[76:77]
	v_pk_fma_f32 v[72:73], v[134:135], v[72:73], v[74:75]
	s_nop 0
	v_pk_add_f32 v[72:73], v[102:103], v[72:73] op_sel:[1,0] op_sel_hi:[0,1]
	v_cvt_pk_bf16_f32 v74, v76, v72
	ds_write_b32 v149, v74 offset:10352
	v_pk_mul_f32 v[74:75], v[0:1], v[72:73]
	s_nop 0
	v_pk_fma_f32 v[74:75], v[134:135], v[76:77], v[74:75] neg_lo:[0,0,1] neg_hi:[0,0,1]
	v_pk_mul_f32 v[76:77], v[0:1], v[76:77]
	s_waitcnt lgkmcnt(11)
	v_pk_add_f32 v[74:75], v[104:105], v[74:75]
	v_pk_fma_f32 v[72:73], v[134:135], v[72:73], v[76:77]
	s_nop 0
	v_pk_add_f32 v[72:73], v[104:105], v[72:73] op_sel:[1,0] op_sel_hi:[0,1]
	v_cvt_pk_bf16_f32 v76, v74, v72
	ds_write_b32 v149, v76 offset:10624
	v_pk_mul_f32 v[76:77], v[0:1], v[72:73]
	s_nop 0
	v_pk_fma_f32 v[76:77], v[134:135], v[74:75], v[76:77] neg_lo:[0,0,1] neg_hi:[0,0,1]
	v_pk_mul_f32 v[74:75], v[0:1], v[74:75]
	v_pk_add_f32 v[76:77], v[106:107], v[76:77]
	v_pk_fma_f32 v[72:73], v[134:135], v[72:73], v[74:75]
	s_nop 0
	v_pk_add_f32 v[72:73], v[106:107], v[72:73] op_sel:[1,0] op_sel_hi:[0,1]
	v_cvt_pk_bf16_f32 v74, v76, v72
	ds_write_b32 v149, v74 offset:10896
	v_pk_mul_f32 v[74:75], v[0:1], v[72:73]
	s_nop 0
	v_pk_fma_f32 v[74:75], v[134:135], v[76:77], v[74:75] neg_lo:[0,0,1] neg_hi:[0,0,1]
	v_pk_mul_f32 v[76:77], v[0:1], v[76:77]
	s_waitcnt lgkmcnt(12)
	v_pk_add_f32 v[74:75], v[158:159], v[74:75]
	v_pk_fma_f32 v[72:73], v[134:135], v[72:73], v[76:77]
	s_nop 0
	v_pk_add_f32 v[72:73], v[158:159], v[72:73] op_sel:[1,0] op_sel_hi:[0,1]
	v_cvt_pk_bf16_f32 v76, v74, v72
	ds_write_b32 v149, v76 offset:11168
	v_pk_mul_f32 v[76:77], v[0:1], v[72:73]
	s_nop 0
	v_pk_fma_f32 v[76:77], v[134:135], v[74:75], v[76:77] neg_lo:[0,0,1] neg_hi:[0,0,1]
	v_pk_mul_f32 v[74:75], v[0:1], v[74:75]
	v_pk_add_f32 v[76:77], v[160:161], v[76:77]
	v_pk_fma_f32 v[72:73], v[134:135], v[72:73], v[74:75]
	s_nop 0
	v_pk_add_f32 v[72:73], v[160:161], v[72:73] op_sel:[1,0] op_sel_hi:[0,1]
	v_cvt_pk_bf16_f32 v74, v76, v72
	ds_write_b32 v149, v74 offset:11440
	v_pk_mul_f32 v[74:75], v[0:1], v[72:73]
	s_nop 0
	v_pk_fma_f32 v[74:75], v[134:135], v[76:77], v[74:75] neg_lo:[0,0,1] neg_hi:[0,0,1]
	v_pk_mul_f32 v[76:77], v[0:1], v[76:77]
	s_waitcnt lgkmcnt(13)
	v_pk_add_f32 v[74:75], v[162:163], v[74:75]
	v_pk_fma_f32 v[72:73], v[134:135], v[72:73], v[76:77]
	s_nop 0
	v_pk_add_f32 v[72:73], v[162:163], v[72:73] op_sel:[1,0] op_sel_hi:[0,1]
	v_cvt_pk_bf16_f32 v76, v74, v72
	ds_write_b32 v149, v76 offset:11712
	v_pk_mul_f32 v[76:77], v[0:1], v[72:73]
	s_nop 0
	v_pk_fma_f32 v[76:77], v[134:135], v[74:75], v[76:77] neg_lo:[0,0,1] neg_hi:[0,0,1]
	v_pk_mul_f32 v[74:75], v[0:1], v[74:75]
	v_pk_add_f32 v[76:77], v[164:165], v[76:77]
	v_pk_fma_f32 v[72:73], v[134:135], v[72:73], v[74:75]
	s_nop 0
	v_pk_add_f32 v[72:73], v[164:165], v[72:73] op_sel:[1,0] op_sel_hi:[0,1]
	v_cvt_pk_bf16_f32 v74, v76, v72
	ds_write_b32 v149, v74 offset:11984
	v_pk_mul_f32 v[74:75], v[0:1], v[72:73]
	s_nop 0
	v_pk_fma_f32 v[74:75], v[134:135], v[76:77], v[74:75] neg_lo:[0,0,1] neg_hi:[0,0,1]
	v_pk_mul_f32 v[76:77], v[0:1], v[76:77]
	s_waitcnt lgkmcnt(14)
	v_pk_add_f32 v[74:75], v[166:167], v[74:75]
	v_pk_fma_f32 v[72:73], v[134:135], v[72:73], v[76:77]
	s_nop 0
	v_pk_add_f32 v[72:73], v[166:167], v[72:73] op_sel:[1,0] op_sel_hi:[0,1]
	v_cvt_pk_bf16_f32 v76, v74, v72
	ds_write_b32 v149, v76 offset:12256
	v_pk_mul_f32 v[76:77], v[0:1], v[72:73]
	s_nop 0
	v_pk_fma_f32 v[76:77], v[134:135], v[74:75], v[76:77] neg_lo:[0,0,1] neg_hi:[0,0,1]
	v_pk_mul_f32 v[74:75], v[0:1], v[74:75]
	v_pk_add_f32 v[76:77], v[168:169], v[76:77]
	v_pk_fma_f32 v[72:73], v[134:135], v[72:73], v[74:75]
	s_nop 0
	v_pk_add_f32 v[78:79], v[168:169], v[72:73] op_sel:[1,0] op_sel_hi:[0,1]
	v_cvt_pk_bf16_f32 v72, v76, v78
	ds_write_b32 v149, v72 offset:12528
	s_waitcnt lgkmcnt(0)
	ds_read_b128 v[72:75], v150 offset:8448
	ds_read_b128 v[88:91], v150 offset:8512
	s_waitcnt lgkmcnt(1)
	v_mfma_f32_16x16x32_bf16 v[72:75], v[52:55], v[72:75], 0
	s_waitcnt lgkmcnt(0)
	v_mfma_f32_16x16x32_bf16 v[72:75], v[44:47], v[88:91], v[72:75]
	ds_read_b128 v[88:91], v150 offset:8576
	ds_read_b128 v[92:95], v150 offset:8640
	s_waitcnt lgkmcnt(1)
	v_mfma_f32_16x16x32_bf16 v[72:75], v[48:51], v[88:91], v[72:75]
	ds_read_b128 v[88:91], v151 offset:12800
	s_waitcnt lgkmcnt(1)
	v_mfma_f32_16x16x32_bf16 v[72:75], v[56:59], v[92:95], v[72:75]
	s_waitcnt lgkmcnt(0)
	s_nop 6
	v_pk_fma_f32 v[72:73], v[60:61], v[88:89], v[72:73]
	v_pk_fma_f32 v[74:75], v[62:63], v[90:91], v[74:75]
	v_mul_f32_e32 v88, 0x3d922279, v72
	v_fmaak_f32 v88, v72, v88, 0x3fcc422a
	v_mul_f32_e32 v88, v72, v88
	v_mul_f32_e32 v88, 0xbfb8aa3b, v88
	v_exp_f32_e32 v88, v88
	v_mul_f32_e32 v89, 0x3d922279, v73
	v_fmaak_f32 v89, v73, v89, 0x3fcc422a
	v_mul_f32_e32 v89, v73, v89
	v_add_f32_e32 v88, 1.0, v88
	v_mul_f32_e32 v89, 0xbfb8aa3b, v89
	v_rcp_f32_e32 v88, v88
	v_exp_f32_e32 v89, v89
	v_mul_f32_e32 v90, 0x3d922279, v75
	v_fmaak_f32 v90, v75, v90, 0x3fcc422a
	v_mul_f32_e32 v72, v72, v88
	v_add_f32_e32 v88, 1.0, v89
	v_mul_f32_e32 v89, 0x3d922279, v74
	v_fmaak_f32 v89, v74, v89, 0x3fcc422a
	v_mul_f32_e32 v89, v74, v89
	v_mul_f32_e32 v89, 0xbfb8aa3b, v89
	v_mul_f32_e32 v90, v75, v90
	v_exp_f32_e32 v89, v89
	v_mul_f32_e32 v90, 0xbfb8aa3b, v90
	v_exp_f32_e32 v90, v90
	v_rcp_f32_e32 v88, v88
	v_add_f32_e32 v89, 1.0, v89
	v_rcp_f32_e32 v89, v89
	v_add_f32_e32 v90, 1.0, v90
	v_rcp_f32_e32 v90, v90
	v_mul_f32_e32 v73, v73, v88
	v_fmamk_f32 v88, v144, 0x3a800000, v206
	v_cvt_pk_bf16_f32 v72, v72, v73
	v_mul_f32_e32 v73, v74, v89
	v_mul_f32_e32 v89, 0x4b800000, v88
	v_cmp_gt_f32_e32 vcc, s77, v88
	v_mul_f32_e32 v74, v75, v90
	v_cvt_pk_bf16_f32 v73, v73, v74
	v_add_u32_e32 v74, 32, v140
	v_cndmask_b32_e32 v88, v88, v89, vcc
	v_rsq_f32_e32 v88, v88
	v_ashrrev_i32_e32 v75, 31, v74
	v_lshlrev_b64 v[74:75], 11, v[74:75]
	v_lshl_add_u64 v[74:75], v[2:3], 0, v[74:75]
	global_store_dwordx2 v[74:75], v[72:73], off
	v_mul_f32_e32 v72, 0x45800000, v88
	s_waitcnt lgkmcnt(0)
	v_cndmask_b32_e32 v88, v88, v72, vcc
	v_pk_mul_f32 v[64:65], v[64:65], v[88:89] op_sel_hi:[1,0]
	v_pk_mul_f32 v[66:67], v[66:67], v[88:89] op_sel_hi:[1,0]
	v_pk_mul_f32 v[72:73], v[40:41], v[64:65]
	v_pk_mul_f32 v[74:75], v[42:43], v[66:67]
	v_pk_mul_f32 v[64:65], v[68:69], v[88:89] op_sel_hi:[1,0]
	v_pk_mul_f32 v[66:67], v[70:71], v[88:89] op_sel_hi:[1,0]
	v_pk_mul_f32 v[68:69], v[36:37], v[64:65]
	v_pk_mul_f32 v[70:71], v[38:39], v[66:67]
	v_cvt_pk_bf16_f32 v64, v72, v73
	v_cvt_pk_bf16_f32 v65, v74, v75
	v_cvt_pk_bf16_f32 v66, v68, v69
	v_cvt_pk_bf16_f32 v67, v70, v71
	s_and_saveexec_b64 s[22:23], s[10:11]
	s_cbranch_execz .LBB11_697
	ds_write_b128 v145, v[72:75] offset:12800
	ds_write_b128 v145, v[68:71] offset:12816

.LBB11_929:
	v_mov_b32_e32 v148, v158
	v_mov_b32_e32 v130, v160
	s_lshl_b32 s22, s7, 8
	v_mul_f32_e32 v122, 0xbfb8aa3b, v122
	v_add_u32_e32 v150, s22, v148
	v_lshl_add_u32 v130, s6, 7, v130
	v_ashrrev_i32_e32 v151, 31, v150
	v_ashrrev_i32_e32 v131, 31, v130
	v_lshlrev_b64 v[132:133], 11, v[150:151]
	v_lshl_add_u64 v[134:135], s[66:67], 0, v[132:133]
	v_lshlrev_b64 v[152:153], 1, v[130:131]
	v_lshl_add_u64 v[156:157], v[134:135], 0, v[152:153]
	v_lshl_add_u64 v[130:131], s[64:65], 0, v[132:133]
	v_lshl_add_u64 v[154:155], v[130:131], 0, v[152:153]
	v_lshl_add_u32 v249, v150, 11, v152
	global_load_dwordx4 v[170:173], v249, s[66:67]
	global_load_dwordx4 v[174:177], v249, s[64:65]
	v_add_u32_e32 v250, 0x8000, v249
	global_load_dwordx4 v[178:181], v250, s[66:67]
	global_load_dwordx4 v[190:193], v250, s[64:65]
	v_add_u32_e32 v251, 0x10000, v249
	global_load_dwordx4 v[194:197], v251, s[66:67]
	global_load_dwordx4 v[214:217], v251, s[64:65]
	v_add_u32_e32 v250, 0x18000, v249
	global_load_dwordx4 v[218:221], v250, s[66:67]
	global_load_dwordx4 v[222:225], v250, s[64:65]
	v_add_u32_e32 v251, 0x40000, v249
	global_load_dwordx4 v[226:229], v251, s[66:67]
	global_load_dwordx4 v[230:233], v251, s[64:65]
	v_mul_f32_e32 v123, 0xbfb8aa3b, v123
	v_exp_f32_e32 v122, v122
	v_exp_f32_e32 v123, v123
	v_mul_f32_e32 v118, 0xbfb8aa3b, v118
	v_mul_f32_e32 v119, 0xbfb8aa3b, v119
	v_exp_f32_e32 v118, v118
	v_exp_f32_e32 v119, v119
	v_add_f32_e32 v122, 1.0, v122
	v_add_f32_e32 v123, 1.0, v123
	v_rcp_f32_e32 v122, v122
	v_rcp_f32_e32 v123, v123
	v_add_f32_e32 v118, 1.0, v118
	v_add_f32_e32 v119, 1.0, v119
	v_rcp_f32_e32 v118, v118
	v_rcp_f32_e32 v119, v119
	v_mul_f32_e32 v121, 0xbfb8aa3b, v121
	v_exp_f32_e32 v121, v121
	v_mul_f32_e32 v106, 0xbfb8aa3b, v106
	v_mul_f32_e32 v107, 0xbfb8aa3b, v107
	v_exp_f32_e32 v106, v106
	v_add_f32_e32 v121, 1.0, v121
	v_rcp_f32_e32 v121, v121
	v_exp_f32_e32 v107, v107
	v_mul_f32_e32 v102, 0xbfb8aa3b, v102
	v_mul_f32_e32 v103, 0xbfb8aa3b, v103
	v_exp_f32_e32 v102, v102
	v_exp_f32_e32 v103, v103
	v_add_f32_e32 v106, 1.0, v106
	v_add_f32_e32 v107, 1.0, v107
	v_rcp_f32_e32 v106, v106
	v_rcp_f32_e32 v107, v107
	v_add_f32_e32 v102, 1.0, v102
	v_add_f32_e32 v103, 1.0, v103
	v_rcp_f32_e32 v102, v102
	v_rcp_f32_e32 v103, v103
	v_mul_f32_e32 v105, 0xbfb8aa3b, v105
	v_exp_f32_e32 v105, v105
	v_mul_f32_e32 v90, 0xbfb8aa3b, v90
	v_mul_f32_e32 v91, 0xbfb8aa3b, v91
	v_exp_f32_e32 v90, v90
	v_add_f32_e32 v105, 1.0, v105
	v_rcp_f32_e32 v105, v105
	v_exp_f32_e32 v91, v91
	v_mul_f32_e32 v86, 0xbfb8aa3b, v86
	v_mul_f32_e32 v87, 0xbfb8aa3b, v87
	v_exp_f32_e32 v86, v86
	v_exp_f32_e32 v87, v87
	v_add_f32_e32 v90, 1.0, v90
	v_add_f32_e32 v91, 1.0, v91
	v_rcp_f32_e32 v90, v90
	v_rcp_f32_e32 v91, v91
	v_add_f32_e32 v86, 1.0, v86
	v_add_f32_e32 v87, 1.0, v87
	v_rcp_f32_e32 v86, v86
	v_rcp_f32_e32 v87, v87
	v_mul_f32_e32 v89, 0xbfb8aa3b, v89
	v_exp_f32_e32 v89, v89
	v_mul_f32_e32 v74, 0xbfb8aa3b, v74
	v_mul_f32_e32 v75, 0xbfb8aa3b, v75
	v_exp_f32_e32 v74, v74
	v_add_f32_e32 v89, 1.0, v89
	v_rcp_f32_e32 v89, v89
	v_exp_f32_e32 v75, v75
	v_mul_f32_e32 v70, 0xbfb8aa3b, v70
	v_mul_f32_e32 v71, 0xbfb8aa3b, v71
	v_exp_f32_e32 v70, v70
	v_exp_f32_e32 v71, v71
	v_add_f32_e32 v74, 1.0, v74
	v_add_f32_e32 v75, 1.0, v75
	v_rcp_f32_e32 v74, v74
	v_rcp_f32_e32 v75, v75
	v_add_f32_e32 v70, 1.0, v70
	v_add_f32_e32 v71, 1.0, v71
	v_rcp_f32_e32 v70, v70
	v_rcp_f32_e32 v71, v71
	v_mul_f32_e32 v73, 0xbfb8aa3b, v73
	v_exp_f32_e32 v73, v73
	v_mul_f32_e32 v58, 0xbfb8aa3b, v58
	s_waitcnt vmcnt(8)
	v_lshlrev_b32_e32 v162, 16, v170
	v_and_b32_e32 v163, 0xffff0000, v170
	v_lshlrev_b32_e32 v164, 16, v174
	v_and_b32_e32 v165, 0xffff0000, v174
	v_pk_add_f32 v[162:163], v[162:163], v[164:165]
	v_add_f32_e32 v73, 1.0, v73
	v_pk_fma_f32 v[122:123], v[126:127], v[122:123], v[162:163]
	v_lshlrev_b32_e32 v126, 16, v172
	v_and_b32_e32 v127, 0xffff0000, v172
	v_lshlrev_b32_e32 v162, 16, v176
	v_and_b32_e32 v163, 0xffff0000, v176
	v_pk_add_f32 v[126:127], v[126:127], v[162:163]
	v_rcp_f32_e32 v73, v73
	v_pk_fma_f32 v[114:115], v[114:115], v[118:119], v[126:127]
	v_mul_f32_e32 v119, 0xbfb8aa3b, v120
	v_exp_f32_e32 v119, v119
	v_mul_f32_e32 v118, 0xbfb8aa3b, v124
	v_exp_f32_e32 v118, v118
	v_lshlrev_b32_e32 v124, 16, v171
	v_add_f32_e32 v119, 1.0, v119
	v_rcp_f32_e32 v120, v119
	v_mul_f32_e32 v119, 0xbfb8aa3b, v125
	v_exp_f32_e32 v119, v119
	v_add_f32_e32 v118, 1.0, v118
	v_rcp_f32_e32 v118, v118
	v_and_b32_e32 v125, 0xffff0000, v171
	v_add_f32_e32 v119, 1.0, v119
	v_rcp_f32_e32 v119, v119
	v_lshlrev_b32_e32 v126, 16, v175
	v_and_b32_e32 v127, 0xffff0000, v175
	v_pk_add_f32 v[124:125], v[124:125], v[126:127]
	v_lshlrev_b32_e32 v126, 16, v177
	v_pk_fma_f32 v[118:119], v[128:129], v[118:119], v[124:125]
	v_lshlrev_b32_e32 v124, 16, v173
	v_and_b32_e32 v125, 0xffff0000, v173
	v_and_b32_e32 v127, 0xffff0000, v177
	v_add_u32_e32 v250, 0x48000, v249
	global_load_dwordx4 v[170:173], v250, s[66:67]
	global_load_dwordx4 v[174:177], v250, s[64:65]
	v_pk_add_f32 v[124:125], v[124:125], v[126:127]
	v_mul_f32_e32 v59, 0xbfb8aa3b, v59
	v_pk_fma_f32 v[124:125], v[116:117], v[120:121], v[124:125]
	v_cvt_pk_bf16_f32 v116, v122, v123
	v_cvt_pk_bf16_f32 v117, v118, v119
	v_exp_f32_e32 v58, v58
	v_lshlrev_b32_e32 v126, 16, v116
	v_and_b32_e32 v127, 0xffff0000, v116
	v_lshlrev_b32_e32 v128, 16, v117
	v_and_b32_e32 v129, 0xffff0000, v117
	v_sub_f32_e32 v118, v118, v128
	v_sub_f32_e32 v119, v119, v129
	v_sub_f32_e32 v120, v122, v126
	v_sub_f32_e32 v121, v123, v127
	v_cvt_pk_bf16_f32 v120, v120, v121
	v_cvt_pk_bf16_f32 v121, v118, v119
	v_exp_f32_e32 v59, v59
	v_lshlrev_b32_e32 v118, 16, v120
	v_and_b32_e32 v119, 0xffff0000, v120
	v_pk_add_f32 v[126:127], v[126:127], v[118:119]
	v_cvt_pk_bf16_f32 v118, v114, v115
	v_lshlrev_b32_e32 v122, 16, v121
	v_lshlrev_b32_e32 v130, 16, v118
	v_and_b32_e32 v131, 0xffff0000, v118
	v_and_b32_e32 v123, 0xffff0000, v121
	v_cvt_pk_bf16_f32 v119, v124, v125
	v_sub_f32_e32 v114, v114, v130
	v_lshlrev_b32_e32 v132, 16, v119
	v_sub_f32_e32 v115, v115, v131
	v_pk_add_f32 v[128:129], v[128:129], v[122:123]
	v_and_b32_e32 v133, 0xffff0000, v119
	v_sub_f32_e32 v123, v124, v132
	v_cvt_pk_bf16_f32 v122, v114, v115
	v_sub_f32_e32 v124, v125, v133
	v_lshlrev_b32_e32 v114, 16, v122
	v_and_b32_e32 v115, 0xffff0000, v122
	v_cvt_pk_bf16_f32 v123, v123, v124
	v_pk_add_f32 v[114:115], v[130:131], v[114:115]
	global_store_dwordx4 v[156:157], v[116:119], off
	global_store_dwordx4 v[154:155], v[120:123], off
	v_lshlrev_b32_e32 v124, 16, v123
	v_mul_f32_e32 v116, v127, v127
	v_mul_f32_e32 v117, v129, v129
	v_and_b32_e32 v125, 0xffff0000, v123
	v_fmac_f32_e32 v116, v126, v126
	v_fmac_f32_e32 v117, v128, v128
	v_mul_f32_e32 v115, v115, v115
	v_pk_add_f32 v[124:125], v[132:133], v[124:125]
	v_add_f32_e32 v116, v116, v117
	v_fmac_f32_e32 v115, v114, v114
	v_add_f32_e32 v114, v116, v115
	v_mul_f32_e32 v115, v125, v125
	v_fmac_f32_e32 v115, v124, v124
	v_add_f32_e32 v114, v115, v114
	ds_bpermute_b32 v115, v204, v114
	v_mul_f32_e32 v54, 0xbfb8aa3b, v54
	v_mul_f32_e32 v55, 0xbfb8aa3b, v55
	v_exp_f32_e32 v54, v54
	s_waitcnt lgkmcnt(0)
	v_add_f32_e32 v126, v114, v115
	v_add_u32_e32 v114, 16, v150
	v_ashrrev_i32_e32 v115, 31, v114
	v_lshlrev_b64 v[114:115], 11, v[114:115]
	v_lshl_add_u64 v[116:117], s[66:67], 0, v[114:115]
	v_lshl_add_u64 v[124:125], v[116:117], 0, v[152:153]
	v_lshl_add_u64 v[114:115], s[64:65], 0, v[114:115]
	v_lshl_add_u64 v[122:123], v[114:115], 0, v[152:153]
	v_exp_f32_e32 v55, v55
	v_add_f32_e32 v58, 1.0, v58
	v_add_f32_e32 v59, 1.0, v59
	v_rcp_f32_e32 v58, v58
	v_rcp_f32_e32 v59, v59
	v_add_f32_e32 v54, 1.0, v54
	v_add_f32_e32 v55, 1.0, v55
	v_rcp_f32_e32 v54, v54
	v_rcp_f32_e32 v55, v55
	v_mul_f32_e32 v57, 0xbfb8aa3b, v57
	v_exp_f32_e32 v57, v57
	v_mul_f32_e32 v42, 0xbfb8aa3b, v42
	v_mul_f32_e32 v43, 0xbfb8aa3b, v43
	v_exp_f32_e32 v42, v42
	v_add_f32_e32 v57, 1.0, v57
	v_rcp_f32_e32 v57, v57
	v_exp_f32_e32 v43, v43
	v_mul_f32_e32 v34, 0xbfb8aa3b, v34
	v_mul_f32_e32 v35, 0xbfb8aa3b, v35
	v_exp_f32_e32 v34, v34
	v_exp_f32_e32 v35, v35
	v_add_f32_e32 v42, 1.0, v42
	v_add_f32_e32 v43, 1.0, v43
	v_rcp_f32_e32 v42, v42
	v_rcp_f32_e32 v43, v43
	v_add_f32_e32 v34, 1.0, v34
	v_add_f32_e32 v35, 1.0, v35
	v_rcp_f32_e32 v34, v34
	v_rcp_f32_e32 v35, v35
	v_mul_f32_e32 v26, 0xbfb8aa3b, v26
	v_mul_f32_e32 v27, 0xbfb8aa3b, v27
	v_exp_f32_e32 v26, v26
	v_exp_f32_e32 v27, v27
	v_mul_f32_e32 v18, 0xbfb8aa3b, v18
	v_mul_f32_e32 v19, 0xbfb8aa3b, v19
	v_exp_f32_e32 v18, v18
	v_exp_f32_e32 v19, v19
	v_add_f32_e32 v26, 1.0, v26
	v_add_f32_e32 v27, 1.0, v27
	v_rcp_f32_e32 v26, v26
	v_rcp_f32_e32 v27, v27
	v_add_f32_e32 v18, 1.0, v18
	v_add_f32_e32 v19, 1.0, v19
	v_rcp_f32_e32 v18, v18
	v_rcp_f32_e32 v19, v19
	v_mul_f32_e32 v10, 0xbfb8aa3b, v10
	v_mul_f32_e32 v11, 0xbfb8aa3b, v11
	v_exp_f32_e32 v10, v10
	v_exp_f32_e32 v11, v11
	v_mul_f32_e32 v2, 0xbfb8aa3b, v2
	v_mul_f32_e32 v3, 0xbfb8aa3b, v3
	v_exp_f32_e32 v2, v2
	v_exp_f32_e32 v3, v3
	v_add_f32_e32 v10, 1.0, v10
	v_add_f32_e32 v11, 1.0, v11
	v_rcp_f32_e32 v10, v10
	v_rcp_f32_e32 v11, v11
	v_add_f32_e32 v2, 1.0, v2
	v_add_f32_e32 v3, 1.0, v3
	v_rcp_f32_e32 v2, v2
	v_rcp_f32_e32 v3, v3
	ds_bpermute_b32 v127, v205, v126
	s_waitcnt vmcnt(10)
	v_lshlrev_b32_e32 v128, 16, v178
	v_and_b32_e32 v129, 0xffff0000, v178
	v_lshlrev_b32_e32 v130, 16, v190
	v_and_b32_e32 v131, 0xffff0000, v190
	v_pk_add_f32 v[128:129], v[128:129], v[130:131]
	s_nop 0
	v_pk_fma_f32 v[106:107], v[110:111], v[106:107], v[128:129]
	v_lshlrev_b32_e32 v110, 16, v180
	v_and_b32_e32 v111, 0xffff0000, v180
	v_lshlrev_b32_e32 v128, 16, v192
	v_and_b32_e32 v129, 0xffff0000, v192
	v_pk_add_f32 v[110:111], v[110:111], v[128:129]
	s_nop 0
	v_pk_fma_f32 v[98:99], v[98:99], v[102:103], v[110:111]
	v_mul_f32_e32 v103, 0xbfb8aa3b, v104
	v_exp_f32_e32 v103, v103
	v_mul_f32_e32 v102, 0xbfb8aa3b, v108
	v_exp_f32_e32 v102, v102
	v_lshlrev_b32_e32 v108, 16, v179
	v_add_f32_e32 v103, 1.0, v103
	v_rcp_f32_e32 v104, v103
	v_mul_f32_e32 v103, 0xbfb8aa3b, v109
	v_exp_f32_e32 v103, v103
	v_add_f32_e32 v102, 1.0, v102
	v_rcp_f32_e32 v102, v102
	v_and_b32_e32 v109, 0xffff0000, v179
	v_add_f32_e32 v103, 1.0, v103
	v_rcp_f32_e32 v103, v103
	v_lshlrev_b32_e32 v110, 16, v191
	v_and_b32_e32 v111, 0xffff0000, v191
	v_pk_add_f32 v[108:109], v[108:109], v[110:111]
	v_lshlrev_b32_e32 v110, 16, v193
	v_pk_fma_f32 v[102:103], v[112:113], v[102:103], v[108:109]
	v_lshlrev_b32_e32 v108, 16, v181
	v_and_b32_e32 v109, 0xffff0000, v181
	v_and_b32_e32 v111, 0xffff0000, v193
	v_add_u32_e32 v251, 0x50000, v249
	global_load_dwordx4 v[178:181], v251, s[66:67]
	global_load_dwordx4 v[190:193], v251, s[64:65]
	v_pk_add_f32 v[108:109], v[108:109], v[110:111]
	s_nop 0
	v_pk_fma_f32 v[108:109], v[100:101], v[104:105], v[108:109]
	v_cvt_pk_bf16_f32 v100, v106, v107
	v_cvt_pk_bf16_f32 v101, v102, v103
	v_lshlrev_b32_e32 v110, 16, v100
	v_and_b32_e32 v111, 0xffff0000, v100
	v_lshlrev_b32_e32 v112, 16, v101
	v_and_b32_e32 v113, 0xffff0000, v101
	v_sub_f32_e32 v102, v102, v112
	v_sub_f32_e32 v103, v103, v113
	v_sub_f32_e32 v104, v106, v110
	v_sub_f32_e32 v105, v107, v111
	v_cvt_pk_bf16_f32 v104, v104, v105
	v_cvt_pk_bf16_f32 v105, v102, v103
	v_lshlrev_b32_e32 v102, 16, v104
	v_and_b32_e32 v103, 0xffff0000, v104
	v_pk_add_f32 v[110:111], v[110:111], v[102:103]
	v_cvt_pk_bf16_f32 v102, v98, v99
	v_lshlrev_b32_e32 v106, 16, v105
	v_lshlrev_b32_e32 v114, 16, v102
	v_and_b32_e32 v115, 0xffff0000, v102
	v_and_b32_e32 v107, 0xffff0000, v105
	v_cvt_pk_bf16_f32 v103, v108, v109
	v_sub_f32_e32 v98, v98, v114
	v_lshlrev_b32_e32 v116, 16, v103
	v_sub_f32_e32 v99, v99, v115
	v_pk_add_f32 v[112:113], v[112:113], v[106:107]
	v_and_b32_e32 v117, 0xffff0000, v103
	v_sub_f32_e32 v107, v108, v116
	v_cvt_pk_bf16_f32 v106, v98, v99
	v_sub_f32_e32 v108, v109, v117
	v_lshlrev_b32_e32 v98, 16, v106
	v_and_b32_e32 v99, 0xffff0000, v106
	v_cvt_pk_bf16_f32 v107, v107, v108
	v_pk_add_f32 v[98:99], v[114:115], v[98:99]
	global_store_dwordx4 v[124:125], v[100:103], off
	global_store_dwordx4 v[122:123], v[104:107], off
	v_lshlrev_b32_e32 v108, 16, v107
	v_mul_f32_e32 v100, v111, v111
	v_mul_f32_e32 v101, v113, v113
	v_and_b32_e32 v109, 0xffff0000, v107
	v_fmac_f32_e32 v100, v110, v110
	v_fmac_f32_e32 v101, v112, v112
	v_mul_f32_e32 v99, v99, v99
	v_pk_add_f32 v[108:109], v[116:117], v[108:109]
	v_add_f32_e32 v100, v100, v101
	v_fmac_f32_e32 v99, v98, v98
	v_add_f32_e32 v98, v100, v99
	v_mul_f32_e32 v99, v109, v109
	v_fmac_f32_e32 v99, v108, v108
	v_add_f32_e32 v98, v99, v98
	ds_bpermute_b32 v99, v204, v98
	s_waitcnt lgkmcnt(0)
	v_add_f32_e32 v110, v98, v99
	v_add_u32_e32 v98, 32, v150
	v_ashrrev_i32_e32 v99, 31, v98
	v_lshlrev_b64 v[98:99], 11, v[98:99]
	v_lshl_add_u64 v[100:101], s[66:67], 0, v[98:99]
	v_lshl_add_u64 v[108:109], v[100:101], 0, v[152:153]
	v_lshl_add_u64 v[98:99], s[64:65], 0, v[98:99]
	v_lshl_add_u64 v[106:107], v[98:99], 0, v[152:153]
	ds_bpermute_b32 v111, v205, v110
	s_waitcnt vmcnt(12)
	v_lshlrev_b32_e32 v112, 16, v194
	v_and_b32_e32 v113, 0xffff0000, v194
	v_lshlrev_b32_e32 v114, 16, v214
	v_and_b32_e32 v115, 0xffff0000, v214
	v_pk_add_f32 v[112:113], v[112:113], v[114:115]
	s_nop 0
	v_pk_fma_f32 v[90:91], v[94:95], v[90:91], v[112:113]
	v_lshlrev_b32_e32 v94, 16, v196
	v_and_b32_e32 v95, 0xffff0000, v196
	v_lshlrev_b32_e32 v112, 16, v216
	v_and_b32_e32 v113, 0xffff0000, v216
	v_pk_add_f32 v[94:95], v[94:95], v[112:113]
	s_nop 0
	v_pk_fma_f32 v[82:83], v[82:83], v[86:87], v[94:95]
	v_mul_f32_e32 v87, 0xbfb8aa3b, v88
	v_exp_f32_e32 v87, v87
	v_mul_f32_e32 v86, 0xbfb8aa3b, v92
	v_exp_f32_e32 v86, v86
	v_lshlrev_b32_e32 v92, 16, v195
	v_add_f32_e32 v87, 1.0, v87
	v_rcp_f32_e32 v88, v87
	v_mul_f32_e32 v87, 0xbfb8aa3b, v93
	v_exp_f32_e32 v87, v87
	v_add_f32_e32 v86, 1.0, v86
	v_rcp_f32_e32 v86, v86
	v_and_b32_e32 v93, 0xffff0000, v195
	v_add_f32_e32 v87, 1.0, v87
	v_rcp_f32_e32 v87, v87
	v_lshlrev_b32_e32 v94, 16, v215
	v_and_b32_e32 v95, 0xffff0000, v215
	v_pk_add_f32 v[92:93], v[92:93], v[94:95]
	v_lshlrev_b32_e32 v94, 16, v217
	v_pk_fma_f32 v[86:87], v[96:97], v[86:87], v[92:93]
	v_lshlrev_b32_e32 v92, 16, v197
	v_and_b32_e32 v93, 0xffff0000, v197
	v_and_b32_e32 v95, 0xffff0000, v217
	v_add_u32_e32 v250, 0x58000, v249
	global_load_dwordx4 v[194:197], v250, s[66:67]
	global_load_dwordx4 v[214:217], v250, s[64:65]
	v_pk_add_f32 v[92:93], v[92:93], v[94:95]
	s_nop 0
	v_pk_fma_f32 v[92:93], v[84:85], v[88:89], v[92:93]
	v_cvt_pk_bf16_f32 v84, v90, v91
	v_cvt_pk_bf16_f32 v85, v86, v87
	v_lshlrev_b32_e32 v94, 16, v84
	v_and_b32_e32 v95, 0xffff0000, v84
	v_lshlrev_b32_e32 v96, 16, v85
	v_and_b32_e32 v97, 0xffff0000, v85
	v_sub_f32_e32 v86, v86, v96
	v_sub_f32_e32 v87, v87, v97
	v_sub_f32_e32 v88, v90, v94
	v_sub_f32_e32 v89, v91, v95
	v_cvt_pk_bf16_f32 v88, v88, v89
	v_cvt_pk_bf16_f32 v89, v86, v87
	v_lshlrev_b32_e32 v86, 16, v88
	v_and_b32_e32 v87, 0xffff0000, v88
	v_pk_add_f32 v[94:95], v[94:95], v[86:87]
	v_cvt_pk_bf16_f32 v86, v82, v83
	v_lshlrev_b32_e32 v90, 16, v89
	v_lshlrev_b32_e32 v98, 16, v86
	v_and_b32_e32 v99, 0xffff0000, v86
	v_and_b32_e32 v91, 0xffff0000, v89
	v_cvt_pk_bf16_f32 v87, v92, v93
	v_sub_f32_e32 v82, v82, v98
	v_lshlrev_b32_e32 v100, 16, v87
	v_sub_f32_e32 v83, v83, v99
	v_pk_add_f32 v[96:97], v[96:97], v[90:91]
	v_and_b32_e32 v101, 0xffff0000, v87
	v_sub_f32_e32 v91, v92, v100
	v_cvt_pk_bf16_f32 v90, v82, v83
	v_sub_f32_e32 v92, v93, v101
	v_lshlrev_b32_e32 v82, 16, v90
	v_and_b32_e32 v83, 0xffff0000, v90
	v_cvt_pk_bf16_f32 v91, v91, v92
	v_pk_add_f32 v[82:83], v[98:99], v[82:83]
	global_store_dwordx4 v[108:109], v[84:87], off
	global_store_dwordx4 v[106:107], v[88:91], off
	v_lshlrev_b32_e32 v92, 16, v91
	v_mul_f32_e32 v84, v95, v95
	v_mul_f32_e32 v85, v97, v97
	v_and_b32_e32 v93, 0xffff0000, v91
	v_fmac_f32_e32 v84, v94, v94
	v_fmac_f32_e32 v85, v96, v96
	v_mul_f32_e32 v83, v83, v83
	v_pk_add_f32 v[92:93], v[100:101], v[92:93]
	v_add_f32_e32 v84, v84, v85
	v_fmac_f32_e32 v83, v82, v82
	v_add_f32_e32 v82, v84, v83
	v_mul_f32_e32 v83, v93, v93
	v_fmac_f32_e32 v83, v92, v92
	v_add_f32_e32 v82, v83, v82
	ds_bpermute_b32 v83, v204, v82
	s_waitcnt lgkmcnt(0)
	v_add_f32_e32 v94, v82, v83
	v_add_u32_e32 v82, 48, v150
	v_ashrrev_i32_e32 v83, 31, v82
	v_lshlrev_b64 v[82:83], 11, v[82:83]
	v_lshl_add_u64 v[84:85], s[66:67], 0, v[82:83]
	v_lshl_add_u64 v[92:93], v[84:85], 0, v[152:153]
	v_lshl_add_u64 v[82:83], s[64:65], 0, v[82:83]
	v_lshl_add_u64 v[90:91], v[82:83], 0, v[152:153]
	ds_bpermute_b32 v95, v205, v94
	s_waitcnt vmcnt(14)
	v_lshlrev_b32_e32 v96, 16, v218
	v_and_b32_e32 v97, 0xffff0000, v218
	v_lshlrev_b32_e32 v98, 16, v222
	v_and_b32_e32 v99, 0xffff0000, v222
	v_pk_add_f32 v[96:97], v[96:97], v[98:99]
	s_nop 0
	v_pk_fma_f32 v[74:75], v[78:79], v[74:75], v[96:97]
	v_lshlrev_b32_e32 v78, 16, v220
	v_and_b32_e32 v79, 0xffff0000, v220
	v_lshlrev_b32_e32 v96, 16, v224
	v_and_b32_e32 v97, 0xffff0000, v224
	v_pk_add_f32 v[78:79], v[78:79], v[96:97]
	s_nop 0
	v_pk_fma_f32 v[66:67], v[66:67], v[70:71], v[78:79]
	v_mul_f32_e32 v71, 0xbfb8aa3b, v72
	v_exp_f32_e32 v71, v71
	v_mul_f32_e32 v70, 0xbfb8aa3b, v76
	v_exp_f32_e32 v70, v70
	v_lshlrev_b32_e32 v76, 16, v219
	v_add_f32_e32 v71, 1.0, v71
	v_rcp_f32_e32 v72, v71
	v_mul_f32_e32 v71, 0xbfb8aa3b, v77
	v_exp_f32_e32 v71, v71
	v_add_f32_e32 v70, 1.0, v70
	v_rcp_f32_e32 v70, v70
	v_and_b32_e32 v77, 0xffff0000, v219
	v_add_f32_e32 v71, 1.0, v71
	v_rcp_f32_e32 v71, v71
	v_lshlrev_b32_e32 v78, 16, v223
	v_and_b32_e32 v79, 0xffff0000, v223
	v_pk_add_f32 v[76:77], v[76:77], v[78:79]
	v_lshlrev_b32_e32 v78, 16, v225
	v_pk_fma_f32 v[70:71], v[80:81], v[70:71], v[76:77]
	v_lshlrev_b32_e32 v76, 16, v221
	v_and_b32_e32 v77, 0xffff0000, v221
	v_and_b32_e32 v79, 0xffff0000, v225
	v_pk_add_f32 v[76:77], v[76:77], v[78:79]
	s_nop 0
	v_pk_fma_f32 v[76:77], v[68:69], v[72:73], v[76:77]
	v_cvt_pk_bf16_f32 v68, v74, v75
	v_cvt_pk_bf16_f32 v69, v70, v71
	v_lshlrev_b32_e32 v78, 16, v68
	v_and_b32_e32 v79, 0xffff0000, v68
	v_lshlrev_b32_e32 v80, 16, v69
	v_and_b32_e32 v81, 0xffff0000, v69
	v_sub_f32_e32 v70, v70, v80
	v_sub_f32_e32 v71, v71, v81
	v_sub_f32_e32 v72, v74, v78
	v_sub_f32_e32 v73, v75, v79
	v_cvt_pk_bf16_f32 v72, v72, v73
	v_cvt_pk_bf16_f32 v73, v70, v71
	v_lshlrev_b32_e32 v70, 16, v72
	v_and_b32_e32 v71, 0xffff0000, v72
	v_pk_add_f32 v[78:79], v[78:79], v[70:71]
	v_cvt_pk_bf16_f32 v70, v66, v67
	v_lshlrev_b32_e32 v74, 16, v73
	v_lshlrev_b32_e32 v82, 16, v70
	v_and_b32_e32 v83, 0xffff0000, v70
	v_and_b32_e32 v75, 0xffff0000, v73
	v_cvt_pk_bf16_f32 v71, v76, v77
	v_sub_f32_e32 v66, v66, v82
	v_lshlrev_b32_e32 v84, 16, v71
	v_sub_f32_e32 v67, v67, v83
	v_pk_add_f32 v[80:81], v[80:81], v[74:75]
	v_and_b32_e32 v85, 0xffff0000, v71
	v_sub_f32_e32 v75, v76, v84
	v_cvt_pk_bf16_f32 v74, v66, v67
	v_sub_f32_e32 v76, v77, v85
	v_lshlrev_b32_e32 v66, 16, v74
	v_and_b32_e32 v67, 0xffff0000, v74
	v_cvt_pk_bf16_f32 v75, v75, v76
	v_pk_add_f32 v[66:67], v[82:83], v[66:67]
	global_store_dwordx4 v[92:93], v[68:71], off
	global_store_dwordx4 v[90:91], v[72:75], off
	v_lshlrev_b32_e32 v76, 16, v75
	v_mul_f32_e32 v68, v79, v79
	v_mul_f32_e32 v69, v81, v81
	v_and_b32_e32 v77, 0xffff0000, v75
	v_fmac_f32_e32 v68, v78, v78
	v_fmac_f32_e32 v69, v80, v80
	v_mul_f32_e32 v67, v67, v67
	v_pk_add_f32 v[76:77], v[84:85], v[76:77]
	v_add_f32_e32 v68, v68, v69
	v_fmac_f32_e32 v67, v66, v66
	v_add_f32_e32 v66, v68, v67
	v_mul_f32_e32 v67, v77, v77
	v_fmac_f32_e32 v67, v76, v76
	v_add_f32_e32 v66, v67, v66
	ds_bpermute_b32 v67, v204, v66
	s_waitcnt lgkmcnt(0)
	v_add_f32_e32 v78, v66, v67
	v_add_u32_e32 v66, 0x80, v150
	v_ashrrev_i32_e32 v67, 31, v66
	v_lshlrev_b64 v[66:67], 11, v[66:67]
	v_lshl_add_u64 v[68:69], s[66:67], 0, v[66:67]
	v_lshl_add_u64 v[76:77], v[68:69], 0, v[152:153]
	v_lshl_add_u64 v[66:67], s[64:65], 0, v[66:67]
	v_lshl_add_u64 v[74:75], v[66:67], 0, v[152:153]
	ds_bpermute_b32 v79, v205, v78
	s_waitcnt vmcnt(14)
	v_lshlrev_b32_e32 v80, 16, v226
	v_and_b32_e32 v81, 0xffff0000, v226
	v_lshlrev_b32_e32 v82, 16, v230
	v_and_b32_e32 v83, 0xffff0000, v230
	v_pk_add_f32 v[80:81], v[80:81], v[82:83]
	s_nop 0
	v_pk_fma_f32 v[58:59], v[62:63], v[58:59], v[80:81]
	v_lshlrev_b32_e32 v62, 16, v228
	v_and_b32_e32 v63, 0xffff0000, v228
	v_lshlrev_b32_e32 v80, 16, v232
	v_and_b32_e32 v81, 0xffff0000, v232
	v_pk_add_f32 v[62:63], v[62:63], v[80:81]
	s_nop 0
	v_pk_fma_f32 v[50:51], v[50:51], v[54:55], v[62:63]
	v_mul_f32_e32 v55, 0xbfb8aa3b, v56
	v_exp_f32_e32 v55, v55
	v_mul_f32_e32 v54, 0xbfb8aa3b, v60
	v_exp_f32_e32 v54, v54
	v_lshlrev_b32_e32 v60, 16, v227
	v_add_f32_e32 v55, 1.0, v55
	v_rcp_f32_e32 v56, v55
	v_mul_f32_e32 v55, 0xbfb8aa3b, v61
	v_exp_f32_e32 v55, v55
	v_add_f32_e32 v54, 1.0, v54
	v_rcp_f32_e32 v54, v54
	v_and_b32_e32 v61, 0xffff0000, v227
	v_add_f32_e32 v55, 1.0, v55
	v_rcp_f32_e32 v55, v55
	v_lshlrev_b32_e32 v62, 16, v231
	v_and_b32_e32 v63, 0xffff0000, v231
	v_pk_add_f32 v[60:61], v[60:61], v[62:63]
	v_lshlrev_b32_e32 v62, 16, v233
	v_pk_fma_f32 v[54:55], v[64:65], v[54:55], v[60:61]
	v_lshlrev_b32_e32 v60, 16, v229
	v_and_b32_e32 v61, 0xffff0000, v229
	v_and_b32_e32 v63, 0xffff0000, v233
	v_pk_add_f32 v[60:61], v[60:61], v[62:63]
	s_nop 0
	v_pk_fma_f32 v[60:61], v[52:53], v[56:57], v[60:61]
	v_cvt_pk_bf16_f32 v52, v58, v59
	v_cvt_pk_bf16_f32 v53, v54, v55
	v_lshlrev_b32_e32 v62, 16, v52
	v_and_b32_e32 v63, 0xffff0000, v52
	v_lshlrev_b32_e32 v64, 16, v53
	v_and_b32_e32 v65, 0xffff0000, v53
	v_sub_f32_e32 v54, v54, v64
	v_sub_f32_e32 v55, v55, v65
	v_sub_f32_e32 v56, v58, v62
	v_sub_f32_e32 v57, v59, v63
	v_cvt_pk_bf16_f32 v56, v56, v57
	v_cvt_pk_bf16_f32 v57, v54, v55
	v_lshlrev_b32_e32 v54, 16, v56
	v_and_b32_e32 v55, 0xffff0000, v56
	v_pk_add_f32 v[62:63], v[62:63], v[54:55]
	v_cvt_pk_bf16_f32 v54, v50, v51
	v_lshlrev_b32_e32 v58, 16, v57
	v_lshlrev_b32_e32 v66, 16, v54
	v_and_b32_e32 v67, 0xffff0000, v54
	v_and_b32_e32 v59, 0xffff0000, v57
	v_cvt_pk_bf16_f32 v55, v60, v61
	v_sub_f32_e32 v50, v50, v66
	v_lshlrev_b32_e32 v68, 16, v55
	v_sub_f32_e32 v51, v51, v67
	v_pk_add_f32 v[64:65], v[64:65], v[58:59]
	v_and_b32_e32 v69, 0xffff0000, v55
	v_sub_f32_e32 v59, v60, v68
	v_cvt_pk_bf16_f32 v58, v50, v51
	v_sub_f32_e32 v60, v61, v69
	v_lshlrev_b32_e32 v50, 16, v58
	v_and_b32_e32 v51, 0xffff0000, v58
	v_cvt_pk_bf16_f32 v59, v59, v60
	v_pk_add_f32 v[50:51], v[66:67], v[50:51]
	global_store_dwordx4 v[76:77], v[52:55], off
	global_store_dwordx4 v[74:75], v[56:59], off
	v_lshlrev_b32_e32 v60, 16, v59
	v_mul_f32_e32 v52, v63, v63
	v_mul_f32_e32 v53, v65, v65
	v_and_b32_e32 v61, 0xffff0000, v59
	v_fmac_f32_e32 v52, v62, v62
	v_fmac_f32_e32 v53, v64, v64
	v_mul_f32_e32 v51, v51, v51
	v_pk_add_f32 v[60:61], v[68:69], v[60:61]
	v_add_f32_e32 v52, v52, v53
	v_fmac_f32_e32 v51, v50, v50
	v_add_f32_e32 v50, v52, v51
	v_mul_f32_e32 v51, v61, v61
	v_fmac_f32_e32 v51, v60, v60
	v_add_f32_e32 v50, v51, v50
	ds_bpermute_b32 v51, v204, v50
	s_waitcnt lgkmcnt(0)
	v_add_f32_e32 v62, v50, v51
	v_add_u32_e32 v50, 0x90, v150
	v_ashrrev_i32_e32 v51, 31, v50
	v_lshlrev_b64 v[50:51], 11, v[50:51]
	v_lshl_add_u64 v[52:53], s[66:67], 0, v[50:51]
	v_lshl_add_u64 v[60:61], v[52:53], 0, v[152:153]
	v_lshl_add_u64 v[50:51], s[64:65], 0, v[50:51]
	v_lshl_add_u64 v[58:59], v[50:51], 0, v[152:153]
	ds_bpermute_b32 v63, v205, v62
	s_waitcnt vmcnt(14)
	v_lshlrev_b32_e32 v64, 16, v170
	v_and_b32_e32 v65, 0xffff0000, v170
	v_lshlrev_b32_e32 v66, 16, v174
	v_and_b32_e32 v67, 0xffff0000, v174
	v_pk_add_f32 v[64:65], v[64:65], v[66:67]
	s_nop 0
	v_pk_fma_f32 v[42:43], v[46:47], v[42:43], v[64:65]
	v_lshlrev_b32_e32 v46, 16, v172
	v_and_b32_e32 v47, 0xffff0000, v172
	v_lshlrev_b32_e32 v64, 16, v176
	v_and_b32_e32 v65, 0xffff0000, v176
	v_pk_add_f32 v[46:47], v[46:47], v[64:65]
	s_nop 0
	v_pk_fma_f32 v[46:47], v[38:39], v[34:35], v[46:47]
	v_mul_f32_e32 v35, 0xbfb8aa3b, v36
	v_exp_f32_e32 v35, v35
	v_mul_f32_e32 v34, 0xbfb8aa3b, v44
	v_exp_f32_e32 v34, v34
	v_lshlrev_b32_e32 v38, 16, v171
	v_add_f32_e32 v35, 1.0, v35
	v_rcp_f32_e32 v36, v35
	v_mul_f32_e32 v35, 0xbfb8aa3b, v45
	v_exp_f32_e32 v35, v35
	v_add_f32_e32 v34, 1.0, v34
	v_rcp_f32_e32 v34, v34
	v_and_b32_e32 v39, 0xffff0000, v171
	v_add_f32_e32 v35, 1.0, v35
	v_rcp_f32_e32 v35, v35
	v_lshlrev_b32_e32 v44, 16, v175
	v_and_b32_e32 v45, 0xffff0000, v175
	v_pk_add_f32 v[38:39], v[38:39], v[44:45]
	v_lshlrev_b32_e32 v44, 16, v177
	v_pk_fma_f32 v[38:39], v[48:49], v[34:35], v[38:39]
	v_mul_f32_e32 v34, 0xbfb8aa3b, v37
	v_exp_f32_e32 v34, v34
	v_and_b32_e32 v35, 0xffff0000, v173
	v_and_b32_e32 v45, 0xffff0000, v177
	v_add_f32_e32 v34, 1.0, v34
	v_rcp_f32_e32 v37, v34
	v_lshlrev_b32_e32 v34, 16, v173
	v_pk_add_f32 v[34:35], v[34:35], v[44:45]
	s_nop 0
	v_pk_fma_f32 v[40:41], v[40:41], v[36:37], v[34:35]
	v_cvt_pk_bf16_f32 v34, v42, v43
	v_cvt_pk_bf16_f32 v35, v38, v39
	v_lshlrev_b32_e32 v36, 16, v34
	v_and_b32_e32 v37, 0xffff0000, v34
	v_lshlrev_b32_e32 v44, 16, v35
	v_and_b32_e32 v45, 0xffff0000, v35
	v_sub_f32_e32 v48, v38, v44
	v_sub_f32_e32 v39, v39, v45
	v_sub_f32_e32 v38, v42, v36
	v_sub_f32_e32 v42, v43, v37
	v_cvt_pk_bf16_f32 v38, v38, v42
	v_cvt_pk_bf16_f32 v39, v48, v39
	v_lshlrev_b32_e32 v42, 16, v38
	v_and_b32_e32 v43, 0xffff0000, v38
	v_lshlrev_b32_e32 v48, 16, v39
	v_and_b32_e32 v49, 0xffff0000, v39
	v_pk_add_f32 v[44:45], v[44:45], v[48:49]
	v_pk_add_f32 v[42:43], v[36:37], v[42:43]
	v_cvt_pk_bf16_f32 v36, v46, v47
	v_cvt_pk_bf16_f32 v37, v40, v41
	v_lshlrev_b32_e32 v48, 16, v36
	v_and_b32_e32 v49, 0xffff0000, v36
	v_lshlrev_b32_e32 v50, 16, v37
	v_and_b32_e32 v51, 0xffff0000, v37
	v_sub_f32_e32 v52, v40, v50
	v_sub_f32_e32 v41, v41, v51
	v_sub_f32_e32 v40, v46, v48
	v_sub_f32_e32 v46, v47, v49
	v_cvt_pk_bf16_f32 v40, v40, v46
	v_cvt_pk_bf16_f32 v41, v52, v41
	global_store_dwordx4 v[60:61], v[34:37], off
	global_store_dwordx4 v[58:59], v[38:41], off
	v_lshlrev_b32_e32 v46, 16, v40
	v_and_b32_e32 v47, 0xffff0000, v40
	v_mul_f32_e32 v34, v43, v43
	v_mul_f32_e32 v35, v45, v45
	v_pk_add_f32 v[46:47], v[48:49], v[46:47]
	v_fmac_f32_e32 v34, v42, v42
	v_fmac_f32_e32 v35, v44, v44
	v_lshlrev_b32_e32 v52, 16, v41
	v_and_b32_e32 v53, 0xffff0000, v41
	v_add_f32_e32 v34, v34, v35
	v_mul_f32_e32 v35, v47, v47
	v_pk_add_f32 v[50:51], v[50:51], v[52:53]
	v_fmac_f32_e32 v35, v46, v46
	v_add_f32_e32 v34, v34, v35
	v_mul_f32_e32 v35, v51, v51
	v_fmac_f32_e32 v35, v50, v50
	v_add_f32_e32 v34, v35, v34
	ds_bpermute_b32 v35, v204, v34
	s_waitcnt lgkmcnt(0)
	v_add_f32_e32 v46, v34, v35
	v_add_u32_e32 v34, 0xa0, v150
	v_ashrrev_i32_e32 v35, 31, v34
	v_lshlrev_b64 v[34:35], 11, v[34:35]
	v_lshl_add_u64 v[36:37], s[66:67], 0, v[34:35]
	v_lshl_add_u64 v[44:45], v[36:37], 0, v[152:153]
	v_lshl_add_u64 v[34:35], s[64:65], 0, v[34:35]
	v_lshl_add_u64 v[42:43], v[34:35], 0, v[152:153]
	ds_bpermute_b32 v47, v205, v46
	s_waitcnt vmcnt(12)
	v_lshlrev_b32_e32 v48, 16, v178
	v_and_b32_e32 v49, 0xffff0000, v178
	v_lshlrev_b32_e32 v50, 16, v190
	v_and_b32_e32 v51, 0xffff0000, v190
	v_pk_add_f32 v[48:49], v[48:49], v[50:51]
	s_nop 0
	v_pk_fma_f32 v[26:27], v[30:31], v[26:27], v[48:49]
	v_lshlrev_b32_e32 v30, 16, v180
	v_and_b32_e32 v31, 0xffff0000, v180
	v_lshlrev_b32_e32 v48, 16, v192
	v_and_b32_e32 v49, 0xffff0000, v192
	v_pk_add_f32 v[30:31], v[30:31], v[48:49]
	s_nop 0
	v_pk_fma_f32 v[30:31], v[22:23], v[18:19], v[30:31]
	v_mul_f32_e32 v19, 0xbfb8aa3b, v20
	v_exp_f32_e32 v19, v19
	v_mul_f32_e32 v18, 0xbfb8aa3b, v28
	v_exp_f32_e32 v18, v18
	v_lshlrev_b32_e32 v22, 16, v179
	v_add_f32_e32 v19, 1.0, v19
	v_rcp_f32_e32 v20, v19
	v_mul_f32_e32 v19, 0xbfb8aa3b, v29
	v_exp_f32_e32 v19, v19
	v_add_f32_e32 v18, 1.0, v18
	v_rcp_f32_e32 v18, v18
	v_and_b32_e32 v23, 0xffff0000, v179
	v_add_f32_e32 v19, 1.0, v19
	v_rcp_f32_e32 v19, v19
	v_lshlrev_b32_e32 v28, 16, v191
	v_and_b32_e32 v29, 0xffff0000, v191
	v_pk_add_f32 v[22:23], v[22:23], v[28:29]
	v_lshlrev_b32_e32 v28, 16, v193
	v_pk_fma_f32 v[22:23], v[32:33], v[18:19], v[22:23]
	v_mul_f32_e32 v18, 0xbfb8aa3b, v21
	v_exp_f32_e32 v18, v18
	v_and_b32_e32 v19, 0xffff0000, v181
	v_and_b32_e32 v29, 0xffff0000, v193
	v_add_f32_e32 v18, 1.0, v18
	v_rcp_f32_e32 v21, v18
	v_lshlrev_b32_e32 v18, 16, v181
	v_pk_add_f32 v[18:19], v[18:19], v[28:29]
	s_nop 0
	v_pk_fma_f32 v[24:25], v[24:25], v[20:21], v[18:19]
	v_cvt_pk_bf16_f32 v18, v26, v27
	v_cvt_pk_bf16_f32 v19, v22, v23
	v_lshlrev_b32_e32 v20, 16, v18
	v_and_b32_e32 v21, 0xffff0000, v18
	v_lshlrev_b32_e32 v28, 16, v19
	v_and_b32_e32 v29, 0xffff0000, v19
	v_sub_f32_e32 v32, v22, v28
	v_sub_f32_e32 v23, v23, v29
	v_sub_f32_e32 v22, v26, v20
	v_sub_f32_e32 v26, v27, v21
	v_cvt_pk_bf16_f32 v22, v22, v26
	v_cvt_pk_bf16_f32 v23, v32, v23
	v_lshlrev_b32_e32 v26, 16, v22
	v_and_b32_e32 v27, 0xffff0000, v22
	v_lshlrev_b32_e32 v32, 16, v23
	v_and_b32_e32 v33, 0xffff0000, v23
	v_pk_add_f32 v[28:29], v[28:29], v[32:33]
	v_pk_add_f32 v[26:27], v[20:21], v[26:27]
	v_cvt_pk_bf16_f32 v20, v30, v31
	v_cvt_pk_bf16_f32 v21, v24, v25
	v_lshlrev_b32_e32 v32, 16, v20
	v_and_b32_e32 v33, 0xffff0000, v20
	v_lshlrev_b32_e32 v34, 16, v21
	v_and_b32_e32 v35, 0xffff0000, v21
	v_sub_f32_e32 v36, v24, v34
	v_sub_f32_e32 v25, v25, v35
	v_sub_f32_e32 v24, v30, v32
	v_sub_f32_e32 v30, v31, v33
	v_cvt_pk_bf16_f32 v24, v24, v30
	v_cvt_pk_bf16_f32 v25, v36, v25
	global_store_dwordx4 v[44:45], v[18:21], off
	global_store_dwordx4 v[42:43], v[22:25], off
	v_lshlrev_b32_e32 v30, 16, v24
	v_and_b32_e32 v31, 0xffff0000, v24
	v_mul_f32_e32 v18, v27, v27
	v_mul_f32_e32 v19, v29, v29
	v_pk_add_f32 v[30:31], v[32:33], v[30:31]
	v_fmac_f32_e32 v18, v26, v26
	v_fmac_f32_e32 v19, v28, v28
	v_lshlrev_b32_e32 v36, 16, v25
	v_and_b32_e32 v37, 0xffff0000, v25
	v_add_f32_e32 v18, v18, v19
	v_mul_f32_e32 v19, v31, v31
	v_pk_add_f32 v[34:35], v[34:35], v[36:37]
	v_fmac_f32_e32 v19, v30, v30
	v_add_f32_e32 v18, v18, v19
	v_mul_f32_e32 v19, v35, v35
	v_fmac_f32_e32 v19, v34, v34
	v_add_f32_e32 v18, v19, v18
	ds_bpermute_b32 v19, v204, v18
	s_waitcnt lgkmcnt(0)
	v_add_f32_e32 v30, v18, v19
	v_add_u32_e32 v18, 0xb0, v150
	v_ashrrev_i32_e32 v19, 31, v18
	v_lshlrev_b64 v[18:19], 11, v[18:19]
	v_lshl_add_u64 v[20:21], s[66:67], 0, v[18:19]
	v_lshl_add_u64 v[26:27], v[20:21], 0, v[152:153]
	v_lshl_add_u64 v[18:19], s[64:65], 0, v[18:19]
	v_lshl_add_u64 v[28:29], v[18:19], 0, v[152:153]
	ds_bpermute_b32 v31, v205, v30
	s_waitcnt vmcnt(10)
	v_lshlrev_b32_e32 v32, 16, v194
	v_and_b32_e32 v33, 0xffff0000, v194
	v_lshlrev_b32_e32 v34, 16, v214
	v_and_b32_e32 v35, 0xffff0000, v214
	v_pk_add_f32 v[32:33], v[32:33], v[34:35]
	s_nop 0
	v_pk_fma_f32 v[10:11], v[14:15], v[10:11], v[32:33]
	v_lshlrev_b32_e32 v14, 16, v196
	v_and_b32_e32 v15, 0xffff0000, v196
	v_lshlrev_b32_e32 v32, 16, v216
	v_and_b32_e32 v33, 0xffff0000, v216
	v_pk_add_f32 v[14:15], v[14:15], v[32:33]
	s_nop 0
	v_pk_fma_f32 v[14:15], v[6:7], v[2:3], v[14:15]
	v_mul_f32_e32 v3, 0xbfb8aa3b, v4
	v_exp_f32_e32 v3, v3
	v_mul_f32_e32 v2, 0xbfb8aa3b, v12
	v_exp_f32_e32 v2, v2
	v_lshlrev_b32_e32 v6, 16, v195
	v_add_f32_e32 v3, 1.0, v3
	v_rcp_f32_e32 v4, v3
	v_mul_f32_e32 v3, 0xbfb8aa3b, v13
	v_exp_f32_e32 v3, v3
	v_add_f32_e32 v2, 1.0, v2
	v_rcp_f32_e32 v2, v2
	v_and_b32_e32 v7, 0xffff0000, v195
	v_add_f32_e32 v3, 1.0, v3
	v_rcp_f32_e32 v3, v3
	v_lshlrev_b32_e32 v12, 16, v215
	v_and_b32_e32 v13, 0xffff0000, v215
	v_pk_add_f32 v[6:7], v[6:7], v[12:13]
	v_lshlrev_b32_e32 v12, 16, v217
	v_pk_fma_f32 v[6:7], v[16:17], v[2:3], v[6:7]
	v_mul_f32_e32 v2, 0xbfb8aa3b, v5
	v_exp_f32_e32 v2, v2
	v_and_b32_e32 v3, 0xffff0000, v197
	v_and_b32_e32 v13, 0xffff0000, v217
	v_add_f32_e32 v2, 1.0, v2
	v_rcp_f32_e32 v5, v2
	v_lshlrev_b32_e32 v2, 16, v197
	v_pk_add_f32 v[2:3], v[2:3], v[12:13]
	s_nop 0
	v_pk_fma_f32 v[8:9], v[8:9], v[4:5], v[2:3]
	v_cvt_pk_bf16_f32 v2, v10, v11
	v_cvt_pk_bf16_f32 v3, v6, v7
	v_lshlrev_b32_e32 v4, 16, v2
	v_and_b32_e32 v5, 0xffff0000, v2
	v_lshlrev_b32_e32 v12, 16, v3
	v_and_b32_e32 v13, 0xffff0000, v3
	v_sub_f32_e32 v16, v6, v12
	v_sub_f32_e32 v7, v7, v13
	v_sub_f32_e32 v6, v10, v4
	v_sub_f32_e32 v10, v11, v5
	v_cvt_pk_bf16_f32 v6, v6, v10
	v_cvt_pk_bf16_f32 v7, v16, v7
	v_lshlrev_b32_e32 v10, 16, v6
	v_and_b32_e32 v11, 0xffff0000, v6
	v_lshlrev_b32_e32 v16, 16, v7
	v_and_b32_e32 v17, 0xffff0000, v7
	v_pk_add_f32 v[12:13], v[12:13], v[16:17]
	v_pk_add_f32 v[10:11], v[4:5], v[10:11]
	v_cvt_pk_bf16_f32 v4, v14, v15
	v_cvt_pk_bf16_f32 v5, v8, v9
	v_lshlrev_b32_e32 v16, 16, v4
	v_and_b32_e32 v17, 0xffff0000, v4
	v_lshlrev_b32_e32 v18, 16, v5
	v_and_b32_e32 v19, 0xffff0000, v5
	v_sub_f32_e32 v20, v8, v18
	v_sub_f32_e32 v9, v9, v19
	v_sub_f32_e32 v8, v14, v16
	v_sub_f32_e32 v14, v15, v17
	v_cvt_pk_bf16_f32 v8, v8, v14
	v_cvt_pk_bf16_f32 v9, v20, v9
	global_store_dwordx4 v[26:27], v[2:5], off
	global_store_dwordx4 v[28:29], v[6:9], off
	v_lshlrev_b32_e32 v14, 16, v8
	v_and_b32_e32 v15, 0xffff0000, v8
	v_mul_f32_e32 v2, v11, v11
	v_mul_f32_e32 v3, v13, v13
	v_pk_add_f32 v[14:15], v[16:17], v[14:15]
	v_fmac_f32_e32 v2, v10, v10
	v_fmac_f32_e32 v3, v12, v12
	v_lshlrev_b32_e32 v20, 16, v9
	v_and_b32_e32 v21, 0xffff0000, v9
	v_add_f32_e32 v2, v2, v3
	v_mul_f32_e32 v3, v15, v15
	v_pk_add_f32 v[18:19], v[18:19], v[20:21]
	v_fmac_f32_e32 v3, v14, v14
	v_add_f32_e32 v2, v2, v3
	v_mul_f32_e32 v3, v19, v19
	v_fmac_f32_e32 v3, v18, v18
	v_add_f32_e32 v2, v3, v2
	ds_bpermute_b32 v3, v204, v2
	s_waitcnt lgkmcnt(0)
	v_add_f32_e32 v2, v2, v3
	ds_bpermute_b32 v3, v205, v2
	s_and_saveexec_b64 s[24:25], s[10:11]
	s_cbranch_execz .LBB11_931
	s_ashr_i32 s23, s22, 31
	s_lshl_b64 s[0:1], s[22:23], 2
	s_add_u32 s0, s28, s0
	v_ashrrev_i32_e32 v149, 31, v148
	s_addc_u32 s1, s29, s1
	s_waitcnt lgkmcnt(0)
	v_add_f32_e32 v4, v2, v3
	v_add_f32_e32 v11, v126, v127
	v_lshl_add_u64 v[2:3], v[148:149], 2, s[0:1]
	v_add_f32_e32 v5, v30, v31
	v_add_f32_e32 v6, v46, v47
	v_add_f32_e32 v7, v62, v63
	v_add_f32_e32 v8, v78, v79
	v_add_f32_e32 v9, v94, v95
	v_add_f32_e32 v10, v110, v111
	global_atomic_add_f32 v[2:3], v11, off
	global_atomic_add_f32 v[2:3], v10, off offset:64
	global_atomic_add_f32 v[2:3], v9, off offset:128
	global_atomic_add_f32 v[2:3], v8, off offset:192
	global_atomic_add_f32 v[2:3], v7, off offset:512
	global_atomic_add_f32 v[2:3], v6, off offset:576
	global_atomic_add_f32 v[2:3], v5, off offset:640
	global_atomic_add_f32 v[2:3], v4, off offset:704

.LBB11_1059:
	s_or_b64 exec, exec, s[30:31]
	s_waitcnt lgkmcnt(0)
	s_waitcnt lgkmcnt(0)
	s_barrier
	ds_read_b128 v[108:111], v106
	ds_read_b128 v[112:115], v106 offset:33024
	v_readlane_b32 s0, v245, 5
	s_andn2_b64 vcc, exec, s[2:3]
	s_waitcnt vmcnt(7) lgkmcnt(1)
	v_mfma_f32_16x16x32_bf16 v[108:111], v[108:111], v[62:65], 0
	v_add_u32_e32 v0, s0, v86
	s_waitcnt lgkmcnt(0)
	v_mfma_f32_16x16x32_bf16 v[62:65], v[112:115], v[62:65], 0
	ds_read_b128 v[112:115], v106 offset:64
	s_waitcnt vmcnt(6) lgkmcnt(0)
	v_mfma_f32_16x16x32_bf16 v[108:111], v[112:115], v[58:61], v[108:111]
	ds_read_b128 v[112:115], v106 offset:33088
	s_waitcnt lgkmcnt(0)
	v_mfma_f32_16x16x32_bf16 v[58:61], v[112:115], v[58:61], v[62:65]
	s_nop 2
	ds_read_b128 v[62:65], v106 offset:128
	s_waitcnt vmcnt(5) lgkmcnt(0)
	v_mfma_f32_16x16x32_bf16 v[62:65], v[62:65], v[54:57], v[108:111]
	s_nop 2
	ds_read_b128 v[108:111], v106 offset:33152
	s_waitcnt lgkmcnt(0)
	v_mfma_f32_16x16x32_bf16 v[54:57], v[108:111], v[54:57], v[58:61]
	s_nop 2
	ds_read_b128 v[58:61], v106 offset:192
	s_waitcnt vmcnt(4) lgkmcnt(0)
	v_mfma_f32_16x16x32_bf16 v[58:61], v[58:61], v[50:53], v[62:65]
	s_nop 2
	ds_read_b128 v[62:65], v106 offset:33216
	s_waitcnt lgkmcnt(0)
	v_mfma_f32_16x16x32_bf16 v[50:53], v[62:65], v[50:53], v[54:57]
	s_nop 2
	ds_read_b128 v[54:57], v106 offset:256
	s_waitcnt vmcnt(3) lgkmcnt(0)
	v_mfma_f32_16x16x32_bf16 v[54:57], v[54:57], v[46:49], v[58:61]
	s_nop 2
	ds_read_b128 v[58:61], v106 offset:33280
	s_waitcnt lgkmcnt(0)
	v_mfma_f32_16x16x32_bf16 v[46:49], v[58:61], v[46:49], v[50:53]
	s_nop 2
	ds_read_b128 v[50:53], v106 offset:320
	s_waitcnt vmcnt(2) lgkmcnt(0)
	v_mfma_f32_16x16x32_bf16 v[50:53], v[50:53], v[42:45], v[54:57]
	s_nop 2
	ds_read_b128 v[54:57], v106 offset:33344
	s_waitcnt lgkmcnt(0)
	v_mfma_f32_16x16x32_bf16 v[42:45], v[54:57], v[42:45], v[46:49]
	s_nop 2
	ds_read_b128 v[46:49], v106 offset:384
	s_waitcnt vmcnt(1) lgkmcnt(0)
	v_mfma_f32_16x16x32_bf16 v[46:49], v[46:49], v[38:41], v[50:53]
	s_nop 2
	ds_read_b128 v[50:53], v106 offset:33408
	s_waitcnt lgkmcnt(0)
	v_mfma_f32_16x16x32_bf16 v[42:45], v[50:53], v[38:41], v[42:45]
	ds_read_b128 v[38:41], v106 offset:448
	s_waitcnt vmcnt(0) lgkmcnt(0)
	v_mfma_f32_16x16x32_bf16 v[38:41], v[38:41], v[34:37], v[46:49]
	s_nop 2
	ds_read_b128 v[46:49], v106 offset:33472
	s_waitcnt lgkmcnt(0)
	v_mfma_f32_16x16x32_bf16 v[34:37], v[46:49], v[34:37], v[42:45]
	s_nop 1
	ds_write_b128 v0, v[38:41]
	s_nop 4
	ds_write_b128 v0, v[34:37] offset:1024
	s_waitcnt lgkmcnt(0)
	s_waitcnt lgkmcnt(0)
	s_barrier
	s_cbranch_vccnz .LBB11_1026
	v_readlane_b32 s0, v245, 6
	s_nop 1
	v_add_u32_e32 v0, s0, v86
	ds_read_b128 v[42:45], v0 offset:4096
	s_lshl_b32 s0, s9, 17
	s_waitcnt lgkmcnt(0)
	v_pk_add_f32 v[44:45], v[40:41], v[44:45]
	v_pk_add_f32 v[42:43], v[38:39], v[42:43]
	ds_read_b128 v[38:41], v0 offset:5120
	s_waitcnt lgkmcnt(0)
	v_pk_add_f32 v[40:41], v[36:37], v[40:41]
	v_pk_add_f32 v[38:39], v[34:35], v[38:39]
	ds_read_b128 v[34:37], v0 offset:8192
	s_waitcnt lgkmcnt(0)
	v_pk_add_f32 v[44:45], v[44:45], v[36:37]
	v_pk_add_f32 v[42:43], v[42:43], v[34:35]
	ds_read_b128 v[34:37], v0 offset:9216
	s_waitcnt lgkmcnt(0)
	v_pk_add_f32 v[40:41], v[40:41], v[36:37]
	v_pk_add_f32 v[46:47], v[38:39], v[34:35]
	ds_read_b128 v[36:39], v0 offset:12288
	s_waitcnt lgkmcnt(0)
	v_pk_add_f32 v[34:35], v[44:45], v[38:39]
	v_pk_add_f32 v[42:43], v[42:43], v[36:37]
	ds_read_b128 v[36:39], v0 offset:13312
	v_subrev_u32_e32 v0, s0, v97
	s_waitcnt lgkmcnt(0)
	v_pk_add_f32 v[44:45], v[46:47], v[36:37]
	v_add_u32_e32 v36, s34, v87
	v_pk_add_f32 v[40:41], v[40:41], v[38:39]
	v_ashrrev_i32_e32 v37, 31, v36
	v_lshlrev_b64 v[38:39], 1, v[0:1]
	v_lshl_add_u64 v[46:47], s[66:67], 0, v[38:39]
	v_lshlrev_b64 v[48:49], 1, v[36:37]
	v_lshl_add_u64 v[36:37], v[46:47], 0, v[48:49]
	v_lshl_add_u64 v[38:39], s[64:65], 0, v[38:39]
	v_lshl_add_u64 v[38:39], v[38:39], 0, v[48:49]
	global_load_dwordx2 v[46:47], v[36:37], off
	global_load_dwordx2 v[48:49], v[38:39], off
	v_mul_f32_e32 v0, 0xbfb8aa3b, v44
	v_exp_f32_e32 v0, v0
	s_waitcnt vmcnt(1)
	v_lshlrev_b32_e32 v50, 16, v46
	v_add_f32_e32 v0, 1.0, v0
	v_rcp_f32_e32 v44, v0
	v_mul_f32_e32 v0, 0xbfb8aa3b, v45
	v_exp_f32_e32 v0, v0
	v_and_b32_e32 v51, 0xffff0000, v46
	s_waitcnt vmcnt(0)
	v_lshlrev_b32_e32 v52, 16, v48
	v_and_b32_e32 v53, 0xffff0000, v48
	v_add_f32_e32 v0, 1.0, v0
	v_rcp_f32_e32 v45, v0
	v_mul_f32_e32 v0, 0xbfb8aa3b, v40
	v_exp_f32_e32 v0, v0
	v_pk_add_f32 v[50:51], v[50:51], v[52:53]
	v_lshlrev_b32_e32 v46, 16, v49
	v_pk_fma_f32 v[42:43], v[42:43], v[44:45], v[50:51]
	v_add_f32_e32 v0, 1.0, v0
	v_rcp_f32_e32 v40, v0
	v_mul_f32_e32 v0, 0xbfb8aa3b, v41
	v_exp_f32_e32 v0, v0
	v_lshlrev_b32_e32 v44, 16, v47
	v_and_b32_e32 v45, 0xffff0000, v47
	v_and_b32_e32 v47, 0xffff0000, v49
	v_add_f32_e32 v0, 1.0, v0
	v_rcp_f32_e32 v41, v0
	v_pk_add_f32 v[44:45], v[44:45], v[46:47]
	s_nop 0
	v_pk_fma_f32 v[34:35], v[34:35], v[40:41], v[44:45]
	v_cvt_pk_bf16_f32 v40, v42, v43
	v_cvt_pk_bf16_f32 v41, v34, v35
	v_lshlrev_b32_e32 v44, 16, v40
	v_and_b32_e32 v45, 0xffff0000, v40
	v_lshlrev_b32_e32 v46, 16, v41
	v_and_b32_e32 v47, 0xffff0000, v41
	v_sub_f32_e32 v0, v34, v46
	v_sub_f32_e32 v35, v35, v47
	v_sub_f32_e32 v34, v42, v44
	v_sub_f32_e32 v42, v43, v45
	v_cvt_pk_bf16_f32 v34, v34, v42
	v_cvt_pk_bf16_f32 v35, v0, v35
	global_store_dwordx2 v[36:37], v[40:41], off sc1
	global_store_dwordx2 v[38:39], v[34:35], off sc1
	v_lshlrev_b32_e32 v42, 16, v34
	v_and_b32_e32 v43, 0xffff0000, v34
	v_lshlrev_b32_e32 v48, 16, v35
	v_and_b32_e32 v49, 0xffff0000, v35
	v_pk_add_f32 v[46:47], v[46:47], v[48:49]
	v_pk_add_f32 v[42:43], v[44:45], v[42:43]
	v_mul_f32_e32 v34, v47, v47
	v_mul_f32_e32 v0, v43, v43
	v_fmac_f32_e32 v0, v42, v42
	v_fmac_f32_e32 v34, v46, v46
	v_add_f32_e32 v0, v0, v34
	ds_bpermute_b32 v34, v204, v0
	s_waitcnt lgkmcnt(0)
	v_add_f32_e32 v34, v0, v34
	ds_bpermute_b32 v35, v205, v34
	s_and_saveexec_b64 s[30:31], s[10:11]
	s_cbranch_execz .LBB11_1025
	v_add_u32_e32 v0, 0x4000, v84
	v_lshl_add_u64 v[36:37], v[0:1], 2, s[28:29]
	s_waitcnt lgkmcnt(0)
	v_add_f32_e32 v0, v34, v35
	global_atomic_add_f32 v[36:37], v0, off
	s_branch .LBB11_1025

.LBB11_1181:
	ds_read_b32 v122, v151 offset:64
	v_add_u32_e32 v114, 16, v142
	s_waitcnt lgkmcnt(0)
	v_ashrrev_i32_e32 v115, 31, v114
	v_lshlrev_b64 v[116:117], 13, v[114:115]
	v_lshl_add_u64 v[116:117], s[62:63], 0, v[116:117]
	v_mul_f32_e32 v110, v110, v122
	v_mul_f32_e32 v115, 0x3d922279, v110
	v_fmaak_f32 v115, v110, v115, 0x3fcc422a
	v_mul_f32_e32 v115, v110, v115
	v_mul_f32_e32 v115, 0xbfb8aa3b, v115
	v_exp_f32_e32 v115, v115
	v_mul_f32_e32 v111, v111, v122
	v_mul_f32_e32 v112, v112, v122
	v_mul_f32_e32 v113, v113, v122
	v_add_f32_e32 v115, 1.0, v115
	v_rcp_f32_e32 v115, v115
	v_mul_f32_e32 v106, v106, v122
	v_mul_f32_e32 v107, v107, v122
	v_mul_f32_e32 v108, v108, v122
	v_mul_f32_e32 v110, v110, v115
	v_mul_f32_e32 v115, 0x3d922279, v111
	v_fmaak_f32 v115, v111, v115, 0x3fcc422a
	v_mul_f32_e32 v115, v111, v115
	v_mul_f32_e32 v115, 0xbfb8aa3b, v115
	v_exp_f32_e32 v115, v115
	v_mul_f32_e32 v109, v109, v122
	v_mul_f32_e32 v102, v102, v122
	v_mul_f32_e32 v103, v103, v122
	v_add_f32_e32 v115, 1.0, v115
	v_rcp_f32_e32 v115, v115
	v_mul_f32_e32 v104, v104, v122
	v_mul_f32_e32 v105, v105, v122
	v_mul_f32_e32 v98, v98, v122
	v_mul_f32_e32 v111, v111, v115
	v_mul_f32_e32 v115, 0x3d922279, v112
	v_fmaak_f32 v115, v112, v115, 0x3fcc422a
	v_mul_f32_e32 v115, v112, v115
	v_mul_f32_e32 v115, 0xbfb8aa3b, v115
	v_exp_f32_e32 v115, v115
	v_mul_f32_e32 v99, v99, v122
	v_mul_f32_e32 v100, v100, v122
	v_mul_f32_e32 v101, v101, v122
	v_add_f32_e32 v115, 1.0, v115
	v_rcp_f32_e32 v115, v115
	v_lshl_add_u64 v[116:117], s[28:29], 1, v[116:117]
	v_lshl_add_u64 v[120:121], v[140:141], 1, v[116:117]
	v_cvt_pk_bf16_f32 v116, v110, v111
	v_mul_f32_e32 v112, v112, v115
	v_mul_f32_e32 v115, 0x3d922279, v113
	v_fmaak_f32 v115, v113, v115, 0x3fcc422a
	v_mul_f32_e32 v115, v113, v115
	v_mul_f32_e32 v115, 0xbfb8aa3b, v115
	v_exp_f32_e32 v115, v115
	s_andn2_b64 vcc, exec, s[38:39]
	v_add_f32_e32 v115, 1.0, v115
	v_rcp_f32_e32 v115, v115
	s_nop 0
	v_mul_f32_e32 v113, v113, v115
	v_mul_f32_e32 v115, 0x3d922279, v106
	v_fmaak_f32 v115, v106, v115, 0x3fcc422a
	v_mul_f32_e32 v115, v106, v115
	v_mul_f32_e32 v115, 0xbfb8aa3b, v115
	v_exp_f32_e32 v115, v115
	v_cvt_pk_bf16_f32 v117, v112, v113
	v_add_f32_e32 v115, 1.0, v115
	v_rcp_f32_e32 v115, v115
	s_nop 0
	v_mul_f32_e32 v106, v106, v115
	v_mul_f32_e32 v115, 0x3d922279, v107
	v_fmaak_f32 v115, v107, v115, 0x3fcc422a
	v_mul_f32_e32 v115, v107, v115
	v_mul_f32_e32 v115, 0xbfb8aa3b, v115
	v_exp_f32_e32 v115, v115
	s_nop 0
	v_add_f32_e32 v115, 1.0, v115
	v_rcp_f32_e32 v115, v115
	s_nop 0
	v_mul_f32_e32 v107, v107, v115
	v_mul_f32_e32 v115, 0x3d922279, v108
	v_fmaak_f32 v115, v108, v115, 0x3fcc422a
	v_mul_f32_e32 v115, v108, v115
	v_mul_f32_e32 v115, 0xbfb8aa3b, v115
	v_exp_f32_e32 v115, v115
	v_cvt_pk_bf16_f32 v118, v106, v107
	v_add_f32_e32 v115, 1.0, v115
	v_rcp_f32_e32 v115, v115
	s_nop 0
	v_mul_f32_e32 v108, v108, v115
	v_mul_f32_e32 v115, 0x3d922279, v109
	v_fmaak_f32 v115, v109, v115, 0x3fcc422a
	v_mul_f32_e32 v115, v109, v115
	v_mul_f32_e32 v115, 0xbfb8aa3b, v115
	v_exp_f32_e32 v115, v115
	s_nop 0
	v_add_f32_e32 v115, 1.0, v115
	v_rcp_f32_e32 v115, v115
	s_nop 0
	v_mul_f32_e32 v109, v109, v115
	v_mul_f32_e32 v115, 0x3d922279, v102
	v_fmaak_f32 v115, v102, v115, 0x3fcc422a
	v_mul_f32_e32 v115, v102, v115
	v_mul_f32_e32 v115, 0xbfb8aa3b, v115
	v_exp_f32_e32 v115, v115
	v_cvt_pk_bf16_f32 v119, v108, v109
	global_store_dwordx4 v[120:121], v[116:119], off
	v_add_f32_e32 v115, 1.0, v115
	v_rcp_f32_e32 v115, v115
	s_nop 0
	v_mul_f32_e32 v102, v102, v115
	v_mul_f32_e32 v115, 0x3d922279, v103
	v_fmaak_f32 v115, v103, v115, 0x3fcc422a
	v_mul_f32_e32 v115, v103, v115
	v_mul_f32_e32 v115, 0xbfb8aa3b, v115
	v_exp_f32_e32 v115, v115
	s_nop 0
	v_add_f32_e32 v115, 1.0, v115
	v_rcp_f32_e32 v115, v115
	s_nop 0
	v_mul_f32_e32 v103, v103, v115
	v_mul_f32_e32 v115, 0x3d922279, v104
	v_fmaak_f32 v115, v104, v115, 0x3fcc422a
	v_mul_f32_e32 v115, v104, v115
	v_mul_f32_e32 v115, 0xbfb8aa3b, v115
	v_exp_f32_e32 v115, v115
	v_cvt_pk_bf16_f32 v116, v102, v103
	v_add_f32_e32 v115, 1.0, v115
	v_rcp_f32_e32 v115, v115
	s_nop 0
	v_mul_f32_e32 v104, v104, v115
	v_mul_f32_e32 v115, 0x3d922279, v105
	v_fmaak_f32 v115, v105, v115, 0x3fcc422a
	v_mul_f32_e32 v115, v105, v115
	v_mul_f32_e32 v115, 0xbfb8aa3b, v115
	v_exp_f32_e32 v115, v115
	s_nop 0
	v_add_f32_e32 v115, 1.0, v115
	v_rcp_f32_e32 v115, v115
	s_nop 0
	v_mul_f32_e32 v105, v105, v115
	v_mul_f32_e32 v115, 0x3d922279, v98
	v_fmaak_f32 v115, v98, v115, 0x3fcc422a
	v_mul_f32_e32 v115, v98, v115
	v_mul_f32_e32 v115, 0xbfb8aa3b, v115
	v_exp_f32_e32 v115, v115
	v_cvt_pk_bf16_f32 v117, v104, v105
	v_add_f32_e32 v115, 1.0, v115
	v_rcp_f32_e32 v115, v115
	s_nop 0
	v_mul_f32_e32 v98, v98, v115
	v_mul_f32_e32 v115, 0x3d922279, v99
	v_fmaak_f32 v115, v99, v115, 0x3fcc422a
	v_mul_f32_e32 v115, v99, v115
	v_mul_f32_e32 v115, 0xbfb8aa3b, v115
	v_exp_f32_e32 v115, v115
	s_nop 0
	v_add_f32_e32 v115, 1.0, v115
	v_rcp_f32_e32 v115, v115
	s_nop 0
	v_mul_f32_e32 v99, v99, v115
	v_mul_f32_e32 v115, 0x3d922279, v100
	v_fmaak_f32 v115, v100, v115, 0x3fcc422a
	v_mul_f32_e32 v115, v100, v115
	v_mul_f32_e32 v115, 0xbfb8aa3b, v115
	v_exp_f32_e32 v115, v115
	v_cvt_pk_bf16_f32 v118, v98, v99
	v_add_f32_e32 v115, 1.0, v115
	v_rcp_f32_e32 v115, v115
	s_nop 0
	v_mul_f32_e32 v100, v100, v115
	v_mul_f32_e32 v115, 0x3d922279, v101
	v_fmaak_f32 v115, v101, v115, 0x3fcc422a
	v_mul_f32_e32 v115, v101, v115
	v_mul_f32_e32 v115, 0xbfb8aa3b, v115
	v_exp_f32_e32 v115, v115
	s_nop 0
	v_add_f32_e32 v115, 1.0, v115
	v_rcp_f32_e32 v115, v115
	s_nop 0
	v_mul_f32_e32 v101, v101, v115
	v_cndmask_b32_e64 v115, 0, 1, s[38:39]
	v_cmp_ne_u32_e64 s[16:17], 1, v115
	v_cvt_pk_bf16_f32 v119, v100, v101
	global_store_dwordx4 v[120:121], v[116:119], off offset:256
	s_cbranch_vccnz .LBB11_1185
	v_mul_f32_e32 v115, v111, v111
	v_fmac_f32_e32 v115, v110, v110
	v_add_f32_e32 v110, 0, v110
	v_add_f32_e32 v110, v111, v110
	v_fmac_f32_e32 v115, v112, v112
	v_add_f32_e32 v110, v112, v110
	v_fmac_f32_e32 v115, v113, v113
	v_add_f32_e32 v110, v113, v110
	v_fmac_f32_e32 v115, v106, v106
	v_add_f32_e32 v106, v106, v110
	v_fmac_f32_e32 v115, v107, v107
	v_add_f32_e32 v106, v107, v106
	v_fmac_f32_e32 v115, v108, v108
	v_add_f32_e32 v106, v108, v106
	v_fmac_f32_e32 v115, v109, v109
	v_add_f32_e32 v106, v109, v106
	v_fmac_f32_e32 v115, v102, v102
	v_add_f32_e32 v102, v102, v106
	v_fmac_f32_e32 v115, v103, v103
	v_add_f32_e32 v102, v103, v102
	v_fmac_f32_e32 v115, v104, v104
	v_add_f32_e32 v102, v104, v102
	v_fmac_f32_e32 v115, v105, v105
	v_add_f32_e32 v102, v105, v102
	v_fmac_f32_e32 v115, v98, v98
	v_add_f32_e32 v98, v98, v102
	v_fmac_f32_e32 v115, v99, v99
	v_add_f32_e32 v98, v99, v98
	v_fmac_f32_e32 v115, v100, v100
	v_add_f32_e32 v98, v100, v98
	v_add_f32_e32 v98, v101, v98
	v_fmac_f32_e32 v115, v101, v101
	ds_bpermute_b32 v99, v204, v98
	ds_bpermute_b32 v100, v204, v115
	s_waitcnt lgkmcnt(0)
	v_add_f32_e32 v98, v98, v99
	v_add_f32_e32 v100, v115, v100
	ds_bpermute_b32 v99, v205, v98
	ds_bpermute_b32 v101, v205, v100
	s_and_saveexec_b64 s[38:39], s[14:15]
	s_cbranch_execz .LBB11_1184
	v_lshlrev_b32_e32 v102, 1, v114
	v_ashrrev_i32_e32 v103, 31, v102
	v_lshl_add_u64 v[102:103], v[102:103], 2, s[34:35]
	s_waitcnt lgkmcnt(0)
	v_add_f32_e32 v98, v98, v99
	v_add_f32_e32 v99, v100, v101
	global_atomic_add_f32 v[102:103], v98, off
	global_atomic_add_f32 v[102:103], v99, off offset:4

.LBB11_1185:
	ds_read_b32 v106, v151 offset:128
	v_add_u32_e32 v98, 32, v142
	s_waitcnt lgkmcnt(0)
	v_ashrrev_i32_e32 v99, 31, v98
	v_lshlrev_b64 v[100:101], 13, v[98:99]
	v_lshl_add_u64 v[100:101], s[62:63], 0, v[100:101]
	v_mul_f32_e32 v94, v94, v106
	v_mul_f32_e32 v99, 0x3d922279, v94
	v_fmaak_f32 v99, v94, v99, 0x3fcc422a
	v_mul_f32_e32 v99, v94, v99
	v_mul_f32_e32 v99, 0xbfb8aa3b, v99
	v_exp_f32_e32 v99, v99
	v_mul_f32_e32 v95, v95, v106
	v_mul_f32_e32 v96, v96, v106
	v_mul_f32_e32 v97, v97, v106
	v_add_f32_e32 v99, 1.0, v99
	v_rcp_f32_e32 v99, v99
	v_mul_f32_e32 v90, v90, v106
	v_mul_f32_e32 v91, v91, v106
	v_mul_f32_e32 v92, v92, v106
	v_mul_f32_e32 v94, v94, v99
	v_mul_f32_e32 v99, 0x3d922279, v95
	v_fmaak_f32 v99, v95, v99, 0x3fcc422a
	v_mul_f32_e32 v99, v95, v99
	v_mul_f32_e32 v99, 0xbfb8aa3b, v99
	v_exp_f32_e32 v99, v99
	v_mul_f32_e32 v93, v93, v106
	v_mul_f32_e32 v86, v86, v106
	v_mul_f32_e32 v87, v87, v106
	v_add_f32_e32 v99, 1.0, v99
	v_rcp_f32_e32 v99, v99
	v_mul_f32_e32 v88, v88, v106
	v_mul_f32_e32 v89, v89, v106
	v_mul_f32_e32 v82, v82, v106
	v_mul_f32_e32 v95, v95, v99
	v_mul_f32_e32 v99, 0x3d922279, v96
	v_fmaak_f32 v99, v96, v99, 0x3fcc422a
	v_mul_f32_e32 v99, v96, v99
	v_mul_f32_e32 v99, 0xbfb8aa3b, v99
	v_exp_f32_e32 v99, v99
	v_mul_f32_e32 v83, v83, v106
	v_mul_f32_e32 v84, v84, v106
	v_mul_f32_e32 v85, v85, v106
	v_add_f32_e32 v99, 1.0, v99
	v_rcp_f32_e32 v99, v99
	v_lshl_add_u64 v[100:101], s[28:29], 1, v[100:101]
	v_lshl_add_u64 v[104:105], v[140:141], 1, v[100:101]
	v_cvt_pk_bf16_f32 v100, v94, v95
	v_mul_f32_e32 v96, v96, v99
	v_mul_f32_e32 v99, 0x3d922279, v97
	v_fmaak_f32 v99, v97, v99, 0x3fcc422a
	v_mul_f32_e32 v99, v97, v99
	v_mul_f32_e32 v99, 0xbfb8aa3b, v99
	v_exp_f32_e32 v99, v99
	s_and_b64 vcc, exec, s[16:17]
	v_add_f32_e32 v99, 1.0, v99
	v_rcp_f32_e32 v99, v99
	s_nop 0
	v_mul_f32_e32 v97, v97, v99
	v_mul_f32_e32 v99, 0x3d922279, v90
	v_fmaak_f32 v99, v90, v99, 0x3fcc422a
	v_mul_f32_e32 v99, v90, v99
	v_mul_f32_e32 v99, 0xbfb8aa3b, v99
	v_exp_f32_e32 v99, v99
	v_cvt_pk_bf16_f32 v101, v96, v97
	v_add_f32_e32 v99, 1.0, v99
	v_rcp_f32_e32 v99, v99
	s_nop 0
	v_mul_f32_e32 v90, v90, v99
	v_mul_f32_e32 v99, 0x3d922279, v91
	v_fmaak_f32 v99, v91, v99, 0x3fcc422a
	v_mul_f32_e32 v99, v91, v99
	v_mul_f32_e32 v99, 0xbfb8aa3b, v99
	v_exp_f32_e32 v99, v99
	s_nop 0
	v_add_f32_e32 v99, 1.0, v99
	v_rcp_f32_e32 v99, v99
	s_nop 0
	v_mul_f32_e32 v91, v91, v99
	v_mul_f32_e32 v99, 0x3d922279, v92
	v_fmaak_f32 v99, v92, v99, 0x3fcc422a
	v_mul_f32_e32 v99, v92, v99
	v_mul_f32_e32 v99, 0xbfb8aa3b, v99
	v_exp_f32_e32 v99, v99
	v_cvt_pk_bf16_f32 v102, v90, v91
	v_add_f32_e32 v99, 1.0, v99
	v_rcp_f32_e32 v99, v99
	s_nop 0
	v_mul_f32_e32 v92, v92, v99
	v_mul_f32_e32 v99, 0x3d922279, v93
	v_fmaak_f32 v99, v93, v99, 0x3fcc422a
	v_mul_f32_e32 v99, v93, v99
	v_mul_f32_e32 v99, 0xbfb8aa3b, v99
	v_exp_f32_e32 v99, v99
	s_nop 0
	v_add_f32_e32 v99, 1.0, v99
	v_rcp_f32_e32 v99, v99
	s_nop 0
	v_mul_f32_e32 v93, v93, v99
	v_mul_f32_e32 v99, 0x3d922279, v86
	v_fmaak_f32 v99, v86, v99, 0x3fcc422a
	v_mul_f32_e32 v99, v86, v99
	v_mul_f32_e32 v99, 0xbfb8aa3b, v99
	v_exp_f32_e32 v99, v99
	v_cvt_pk_bf16_f32 v103, v92, v93
	global_store_dwordx4 v[104:105], v[100:103], off
	v_add_f32_e32 v99, 1.0, v99
	v_rcp_f32_e32 v99, v99
	s_nop 0
	v_mul_f32_e32 v86, v86, v99
	v_mul_f32_e32 v99, 0x3d922279, v87
	v_fmaak_f32 v99, v87, v99, 0x3fcc422a
	v_mul_f32_e32 v99, v87, v99
	v_mul_f32_e32 v99, 0xbfb8aa3b, v99
	v_exp_f32_e32 v99, v99
	s_nop 0
	v_add_f32_e32 v99, 1.0, v99
	v_rcp_f32_e32 v99, v99
	s_nop 0
	v_mul_f32_e32 v87, v87, v99
	v_mul_f32_e32 v99, 0x3d922279, v88
	v_fmaak_f32 v99, v88, v99, 0x3fcc422a
	v_mul_f32_e32 v99, v88, v99
	v_mul_f32_e32 v99, 0xbfb8aa3b, v99
	v_exp_f32_e32 v99, v99
	v_cvt_pk_bf16_f32 v100, v86, v87
	v_add_f32_e32 v99, 1.0, v99
	v_rcp_f32_e32 v99, v99
	s_nop 0
	v_mul_f32_e32 v88, v88, v99
	v_mul_f32_e32 v99, 0x3d922279, v89
	v_fmaak_f32 v99, v89, v99, 0x3fcc422a
	v_mul_f32_e32 v99, v89, v99
	v_mul_f32_e32 v99, 0xbfb8aa3b, v99
	v_exp_f32_e32 v99, v99
	s_nop 0
	v_add_f32_e32 v99, 1.0, v99
	v_rcp_f32_e32 v99, v99
	s_nop 0
	v_mul_f32_e32 v89, v89, v99
	v_mul_f32_e32 v99, 0x3d922279, v82
	v_fmaak_f32 v99, v82, v99, 0x3fcc422a
	v_mul_f32_e32 v99, v82, v99
	v_mul_f32_e32 v99, 0xbfb8aa3b, v99
	v_exp_f32_e32 v99, v99
	v_cvt_pk_bf16_f32 v101, v88, v89
	v_add_f32_e32 v99, 1.0, v99
	v_rcp_f32_e32 v99, v99
	s_nop 0
	v_mul_f32_e32 v82, v82, v99
	v_mul_f32_e32 v99, 0x3d922279, v83
	v_fmaak_f32 v99, v83, v99, 0x3fcc422a
	v_mul_f32_e32 v99, v83, v99
	v_mul_f32_e32 v99, 0xbfb8aa3b, v99
	v_exp_f32_e32 v99, v99
	s_nop 0
	v_add_f32_e32 v99, 1.0, v99
	v_rcp_f32_e32 v99, v99
	s_nop 0
	v_mul_f32_e32 v83, v83, v99
	v_mul_f32_e32 v99, 0x3d922279, v84
	v_fmaak_f32 v99, v84, v99, 0x3fcc422a
	v_mul_f32_e32 v99, v84, v99
	v_mul_f32_e32 v99, 0xbfb8aa3b, v99
	v_exp_f32_e32 v99, v99
	v_cvt_pk_bf16_f32 v102, v82, v83
	v_add_f32_e32 v99, 1.0, v99
	v_rcp_f32_e32 v99, v99
	s_nop 0
	v_mul_f32_e32 v84, v84, v99
	v_mul_f32_e32 v99, 0x3d922279, v85
	v_fmaak_f32 v99, v85, v99, 0x3fcc422a
	v_mul_f32_e32 v99, v85, v99
	v_mul_f32_e32 v99, 0xbfb8aa3b, v99
	v_exp_f32_e32 v99, v99
	s_nop 0
	v_add_f32_e32 v99, 1.0, v99
	v_rcp_f32_e32 v99, v99
	s_nop 0
	v_mul_f32_e32 v85, v85, v99
	v_cvt_pk_bf16_f32 v103, v84, v85
	global_store_dwordx4 v[104:105], v[100:103], off offset:256
	s_cbranch_vccnz .LBB11_1189
	v_mul_f32_e32 v99, v95, v95
	v_fmac_f32_e32 v99, v94, v94
	v_add_f32_e32 v94, 0, v94
	v_add_f32_e32 v94, v95, v94
	v_fmac_f32_e32 v99, v96, v96
	v_add_f32_e32 v94, v96, v94
	v_fmac_f32_e32 v99, v97, v97
	v_add_f32_e32 v94, v97, v94
	v_fmac_f32_e32 v99, v90, v90
	v_add_f32_e32 v90, v90, v94
	v_fmac_f32_e32 v99, v91, v91
	v_add_f32_e32 v90, v91, v90
	v_fmac_f32_e32 v99, v92, v92
	v_add_f32_e32 v90, v92, v90
	v_fmac_f32_e32 v99, v93, v93
	v_add_f32_e32 v90, v93, v90
	v_fmac_f32_e32 v99, v86, v86
	v_add_f32_e32 v86, v86, v90
	v_fmac_f32_e32 v99, v87, v87
	v_add_f32_e32 v86, v87, v86
	v_fmac_f32_e32 v99, v88, v88
	v_add_f32_e32 v86, v88, v86
	v_fmac_f32_e32 v99, v89, v89
	v_add_f32_e32 v86, v89, v86
	v_fmac_f32_e32 v99, v82, v82
	v_add_f32_e32 v82, v82, v86
	v_fmac_f32_e32 v99, v83, v83
	v_add_f32_e32 v82, v83, v82
	v_fmac_f32_e32 v99, v84, v84
	v_add_f32_e32 v82, v84, v82
	v_add_f32_e32 v82, v85, v82
	v_fmac_f32_e32 v99, v85, v85
	ds_bpermute_b32 v83, v204, v82
	ds_bpermute_b32 v84, v204, v99
	s_waitcnt lgkmcnt(0)
	v_add_f32_e32 v82, v82, v83
	v_add_f32_e32 v84, v99, v84
	ds_bpermute_b32 v83, v205, v82
	ds_bpermute_b32 v85, v205, v84
	s_and_saveexec_b64 s[38:39], s[14:15]
	s_cbranch_execz .LBB11_1188
	v_lshlrev_b32_e32 v86, 1, v98
	v_ashrrev_i32_e32 v87, 31, v86
	v_lshl_add_u64 v[86:87], v[86:87], 2, s[34:35]
	s_waitcnt lgkmcnt(0)
	v_add_f32_e32 v82, v82, v83
	v_add_f32_e32 v83, v84, v85
	global_atomic_add_f32 v[86:87], v82, off
	global_atomic_add_f32 v[86:87], v83, off offset:4

.LBB11_1189:
	ds_read_b32 v90, v151 offset:192
	v_add_u32_e32 v82, 48, v142
	s_waitcnt lgkmcnt(0)
	v_ashrrev_i32_e32 v83, 31, v82
	v_lshlrev_b64 v[84:85], 13, v[82:83]
	v_lshl_add_u64 v[84:85], s[62:63], 0, v[84:85]
	v_mul_f32_e32 v78, v78, v90
	v_mul_f32_e32 v83, 0x3d922279, v78
	v_fmaak_f32 v83, v78, v83, 0x3fcc422a
	v_mul_f32_e32 v83, v78, v83
	v_mul_f32_e32 v83, 0xbfb8aa3b, v83
	v_exp_f32_e32 v83, v83
	v_mul_f32_e32 v79, v79, v90
	v_mul_f32_e32 v80, v80, v90
	v_mul_f32_e32 v81, v81, v90
	v_add_f32_e32 v83, 1.0, v83
	v_rcp_f32_e32 v83, v83
	v_mul_f32_e32 v74, v74, v90
	v_mul_f32_e32 v75, v75, v90
	v_mul_f32_e32 v76, v76, v90
	v_mul_f32_e32 v78, v78, v83
	v_mul_f32_e32 v83, 0x3d922279, v79
	v_fmaak_f32 v83, v79, v83, 0x3fcc422a
	v_mul_f32_e32 v83, v79, v83
	v_mul_f32_e32 v83, 0xbfb8aa3b, v83
	v_exp_f32_e32 v83, v83
	v_mul_f32_e32 v77, v77, v90
	v_mul_f32_e32 v70, v70, v90
	v_mul_f32_e32 v71, v71, v90
	v_add_f32_e32 v83, 1.0, v83
	v_rcp_f32_e32 v83, v83
	v_mul_f32_e32 v72, v72, v90
	v_mul_f32_e32 v73, v73, v90
	v_mul_f32_e32 v66, v66, v90
	v_mul_f32_e32 v79, v79, v83
	v_mul_f32_e32 v83, 0x3d922279, v80
	v_fmaak_f32 v83, v80, v83, 0x3fcc422a
	v_mul_f32_e32 v83, v80, v83
	v_mul_f32_e32 v83, 0xbfb8aa3b, v83
	v_exp_f32_e32 v83, v83
	v_mul_f32_e32 v67, v67, v90
	v_mul_f32_e32 v68, v68, v90
	v_mul_f32_e32 v69, v69, v90
	v_add_f32_e32 v83, 1.0, v83
	v_rcp_f32_e32 v83, v83
	v_lshl_add_u64 v[84:85], s[28:29], 1, v[84:85]
	v_lshl_add_u64 v[88:89], v[140:141], 1, v[84:85]
	v_cvt_pk_bf16_f32 v84, v78, v79
	v_mul_f32_e32 v80, v80, v83
	v_mul_f32_e32 v83, 0x3d922279, v81
	v_fmaak_f32 v83, v81, v83, 0x3fcc422a
	v_mul_f32_e32 v83, v81, v83
	v_mul_f32_e32 v83, 0xbfb8aa3b, v83
	v_exp_f32_e32 v83, v83
	s_and_b64 vcc, exec, s[16:17]
	v_add_f32_e32 v83, 1.0, v83
	v_rcp_f32_e32 v83, v83
	s_nop 0
	v_mul_f32_e32 v81, v81, v83
	v_mul_f32_e32 v83, 0x3d922279, v74
	v_fmaak_f32 v83, v74, v83, 0x3fcc422a
	v_mul_f32_e32 v83, v74, v83
	v_mul_f32_e32 v83, 0xbfb8aa3b, v83
	v_exp_f32_e32 v83, v83
	v_cvt_pk_bf16_f32 v85, v80, v81
	v_add_f32_e32 v83, 1.0, v83
	v_rcp_f32_e32 v83, v83
	s_nop 0
	v_mul_f32_e32 v74, v74, v83
	v_mul_f32_e32 v83, 0x3d922279, v75
	v_fmaak_f32 v83, v75, v83, 0x3fcc422a
	v_mul_f32_e32 v83, v75, v83
	v_mul_f32_e32 v83, 0xbfb8aa3b, v83
	v_exp_f32_e32 v83, v83
	s_nop 0
	v_add_f32_e32 v83, 1.0, v83
	v_rcp_f32_e32 v83, v83
	s_nop 0
	v_mul_f32_e32 v75, v75, v83
	v_mul_f32_e32 v83, 0x3d922279, v76
	v_fmaak_f32 v83, v76, v83, 0x3fcc422a
	v_mul_f32_e32 v83, v76, v83
	v_mul_f32_e32 v83, 0xbfb8aa3b, v83
	v_exp_f32_e32 v83, v83
	v_cvt_pk_bf16_f32 v86, v74, v75
	v_add_f32_e32 v83, 1.0, v83
	v_rcp_f32_e32 v83, v83
	s_nop 0
	v_mul_f32_e32 v76, v76, v83
	v_mul_f32_e32 v83, 0x3d922279, v77
	v_fmaak_f32 v83, v77, v83, 0x3fcc422a
	v_mul_f32_e32 v83, v77, v83
	v_mul_f32_e32 v83, 0xbfb8aa3b, v83
	v_exp_f32_e32 v83, v83
	s_nop 0
	v_add_f32_e32 v83, 1.0, v83
	v_rcp_f32_e32 v83, v83
	s_nop 0
	v_mul_f32_e32 v77, v77, v83
	v_mul_f32_e32 v83, 0x3d922279, v70
	v_fmaak_f32 v83, v70, v83, 0x3fcc422a
	v_mul_f32_e32 v83, v70, v83
	v_mul_f32_e32 v83, 0xbfb8aa3b, v83
	v_exp_f32_e32 v83, v83
	v_cvt_pk_bf16_f32 v87, v76, v77
	global_store_dwordx4 v[88:89], v[84:87], off
	v_add_f32_e32 v83, 1.0, v83
	v_rcp_f32_e32 v83, v83
	s_nop 0
	v_mul_f32_e32 v70, v70, v83
	v_mul_f32_e32 v83, 0x3d922279, v71
	v_fmaak_f32 v83, v71, v83, 0x3fcc422a
	v_mul_f32_e32 v83, v71, v83
	v_mul_f32_e32 v83, 0xbfb8aa3b, v83
	v_exp_f32_e32 v83, v83
	s_nop 0
	v_add_f32_e32 v83, 1.0, v83
	v_rcp_f32_e32 v83, v83
	s_nop 0
	v_mul_f32_e32 v71, v71, v83
	v_mul_f32_e32 v83, 0x3d922279, v72
	v_fmaak_f32 v83, v72, v83, 0x3fcc422a
	v_mul_f32_e32 v83, v72, v83
	v_mul_f32_e32 v83, 0xbfb8aa3b, v83
	v_exp_f32_e32 v83, v83
	v_cvt_pk_bf16_f32 v84, v70, v71
	v_add_f32_e32 v83, 1.0, v83
	v_rcp_f32_e32 v83, v83
	s_nop 0
	v_mul_f32_e32 v72, v72, v83
	v_mul_f32_e32 v83, 0x3d922279, v73
	v_fmaak_f32 v83, v73, v83, 0x3fcc422a
	v_mul_f32_e32 v83, v73, v83
	v_mul_f32_e32 v83, 0xbfb8aa3b, v83
	v_exp_f32_e32 v83, v83
	s_nop 0
	v_add_f32_e32 v83, 1.0, v83
	v_rcp_f32_e32 v83, v83
	s_nop 0
	v_mul_f32_e32 v73, v73, v83
	v_mul_f32_e32 v83, 0x3d922279, v66
	v_fmaak_f32 v83, v66, v83, 0x3fcc422a
	v_mul_f32_e32 v83, v66, v83
	v_mul_f32_e32 v83, 0xbfb8aa3b, v83
	v_exp_f32_e32 v83, v83
	v_cvt_pk_bf16_f32 v85, v72, v73
	v_add_f32_e32 v83, 1.0, v83
	v_rcp_f32_e32 v83, v83
	s_nop 0
	v_mul_f32_e32 v66, v66, v83
	v_mul_f32_e32 v83, 0x3d922279, v67
	v_fmaak_f32 v83, v67, v83, 0x3fcc422a
	v_mul_f32_e32 v83, v67, v83
	v_mul_f32_e32 v83, 0xbfb8aa3b, v83
	v_exp_f32_e32 v83, v83
	s_nop 0
	v_add_f32_e32 v83, 1.0, v83
	v_rcp_f32_e32 v83, v83
	s_nop 0
	v_mul_f32_e32 v67, v67, v83
	v_mul_f32_e32 v83, 0x3d922279, v68
	v_fmaak_f32 v83, v68, v83, 0x3fcc422a
	v_mul_f32_e32 v83, v68, v83
	v_mul_f32_e32 v83, 0xbfb8aa3b, v83
	v_exp_f32_e32 v83, v83
	v_cvt_pk_bf16_f32 v86, v66, v67
	v_add_f32_e32 v83, 1.0, v83
	v_rcp_f32_e32 v83, v83
	s_nop 0
	v_mul_f32_e32 v68, v68, v83
	v_mul_f32_e32 v83, 0x3d922279, v69
	v_fmaak_f32 v83, v69, v83, 0x3fcc422a
	v_mul_f32_e32 v83, v69, v83
	v_mul_f32_e32 v83, 0xbfb8aa3b, v83
	v_exp_f32_e32 v83, v83
	s_nop 0
	v_add_f32_e32 v83, 1.0, v83
	v_rcp_f32_e32 v83, v83
	s_nop 0
	v_mul_f32_e32 v69, v69, v83
	v_cvt_pk_bf16_f32 v87, v68, v69
	global_store_dwordx4 v[88:89], v[84:87], off offset:256
	s_cbranch_vccnz .LBB11_1193
	v_mul_f32_e32 v83, v79, v79
	v_fmac_f32_e32 v83, v78, v78
	v_add_f32_e32 v78, 0, v78
	v_add_f32_e32 v78, v79, v78
	v_fmac_f32_e32 v83, v80, v80
	v_add_f32_e32 v78, v80, v78
	v_fmac_f32_e32 v83, v81, v81
	v_add_f32_e32 v78, v81, v78
	v_fmac_f32_e32 v83, v74, v74
	v_add_f32_e32 v74, v74, v78
	v_fmac_f32_e32 v83, v75, v75
	v_add_f32_e32 v74, v75, v74
	v_fmac_f32_e32 v83, v76, v76
	v_add_f32_e32 v74, v76, v74
	v_fmac_f32_e32 v83, v77, v77
	v_add_f32_e32 v74, v77, v74
	v_fmac_f32_e32 v83, v70, v70
	v_add_f32_e32 v70, v70, v74
	v_fmac_f32_e32 v83, v71, v71
	v_add_f32_e32 v70, v71, v70
	v_fmac_f32_e32 v83, v72, v72
	v_add_f32_e32 v70, v72, v70
	v_fmac_f32_e32 v83, v73, v73
	v_add_f32_e32 v70, v73, v70
	v_fmac_f32_e32 v83, v66, v66
	v_add_f32_e32 v66, v66, v70
	v_fmac_f32_e32 v83, v67, v67
	v_add_f32_e32 v66, v67, v66
	v_fmac_f32_e32 v83, v68, v68
	v_add_f32_e32 v66, v68, v66
	v_add_f32_e32 v66, v69, v66
	v_fmac_f32_e32 v83, v69, v69
	ds_bpermute_b32 v67, v204, v66
	ds_bpermute_b32 v68, v204, v83
	s_waitcnt lgkmcnt(0)
	v_add_f32_e32 v66, v66, v67
	v_add_f32_e32 v68, v83, v68
	ds_bpermute_b32 v67, v205, v66
	ds_bpermute_b32 v69, v205, v68
	s_and_saveexec_b64 s[38:39], s[14:15]
	s_cbranch_execz .LBB11_1192
	v_lshlrev_b32_e32 v70, 1, v82
	v_ashrrev_i32_e32 v71, 31, v70
	v_lshl_add_u64 v[70:71], v[70:71], 2, s[34:35]
	s_waitcnt lgkmcnt(0)
	v_add_f32_e32 v66, v66, v67
	v_add_f32_e32 v67, v68, v69
	global_atomic_add_f32 v[70:71], v66, off
	global_atomic_add_f32 v[70:71], v67, off offset:4

.LBB11_1193:
	ds_read_b32 v74, v151 offset:512
	v_add_u32_e32 v66, 0x80, v142
	s_waitcnt lgkmcnt(0)
	v_ashrrev_i32_e32 v67, 31, v66
	v_lshlrev_b64 v[68:69], 13, v[66:67]
	v_lshl_add_u64 v[68:69], s[62:63], 0, v[68:69]
	v_mul_f32_e32 v62, v62, v74
	v_mul_f32_e32 v67, 0x3d922279, v62
	v_fmaak_f32 v67, v62, v67, 0x3fcc422a
	v_mul_f32_e32 v67, v62, v67
	v_mul_f32_e32 v67, 0xbfb8aa3b, v67
	v_exp_f32_e32 v67, v67
	v_mul_f32_e32 v63, v63, v74
	v_mul_f32_e32 v64, v64, v74
	v_mul_f32_e32 v65, v65, v74
	v_add_f32_e32 v67, 1.0, v67
	v_rcp_f32_e32 v67, v67
	v_mul_f32_e32 v58, v58, v74
	v_mul_f32_e32 v59, v59, v74
	v_mul_f32_e32 v60, v60, v74
	v_mul_f32_e32 v62, v62, v67
	v_mul_f32_e32 v67, 0x3d922279, v63
	v_fmaak_f32 v67, v63, v67, 0x3fcc422a
	v_mul_f32_e32 v67, v63, v67
	v_mul_f32_e32 v67, 0xbfb8aa3b, v67
	v_exp_f32_e32 v67, v67
	v_mul_f32_e32 v61, v61, v74
	v_mul_f32_e32 v54, v54, v74
	v_mul_f32_e32 v55, v55, v74
	v_add_f32_e32 v67, 1.0, v67
	v_rcp_f32_e32 v67, v67
	v_mul_f32_e32 v56, v56, v74
	v_mul_f32_e32 v57, v57, v74
	v_mul_f32_e32 v50, v50, v74
	v_mul_f32_e32 v63, v63, v67
	v_mul_f32_e32 v67, 0x3d922279, v64
	v_fmaak_f32 v67, v64, v67, 0x3fcc422a
	v_mul_f32_e32 v67, v64, v67
	v_mul_f32_e32 v67, 0xbfb8aa3b, v67
	v_exp_f32_e32 v67, v67
	v_mul_f32_e32 v51, v51, v74
	v_mul_f32_e32 v52, v52, v74
	v_mul_f32_e32 v53, v53, v74
	v_add_f32_e32 v67, 1.0, v67
	v_rcp_f32_e32 v67, v67
	v_lshl_add_u64 v[68:69], s[28:29], 1, v[68:69]
	v_lshl_add_u64 v[72:73], v[140:141], 1, v[68:69]
	v_cvt_pk_bf16_f32 v68, v62, v63
	v_mul_f32_e32 v64, v64, v67
	v_mul_f32_e32 v67, 0x3d922279, v65
	v_fmaak_f32 v67, v65, v67, 0x3fcc422a
	v_mul_f32_e32 v67, v65, v67
	v_mul_f32_e32 v67, 0xbfb8aa3b, v67
	v_exp_f32_e32 v67, v67
	s_and_b64 vcc, exec, s[16:17]
	v_add_f32_e32 v67, 1.0, v67
	v_rcp_f32_e32 v67, v67
	s_nop 0
	v_mul_f32_e32 v65, v65, v67
	v_mul_f32_e32 v67, 0x3d922279, v58
	v_fmaak_f32 v67, v58, v67, 0x3fcc422a
	v_mul_f32_e32 v67, v58, v67
	v_mul_f32_e32 v67, 0xbfb8aa3b, v67
	v_exp_f32_e32 v67, v67
	v_cvt_pk_bf16_f32 v69, v64, v65
	v_add_f32_e32 v67, 1.0, v67
	v_rcp_f32_e32 v67, v67
	s_nop 0
	v_mul_f32_e32 v58, v58, v67
	v_mul_f32_e32 v67, 0x3d922279, v59
	v_fmaak_f32 v67, v59, v67, 0x3fcc422a
	v_mul_f32_e32 v67, v59, v67
	v_mul_f32_e32 v67, 0xbfb8aa3b, v67
	v_exp_f32_e32 v67, v67
	s_nop 0
	v_add_f32_e32 v67, 1.0, v67
	v_rcp_f32_e32 v67, v67
	s_nop 0
	v_mul_f32_e32 v59, v59, v67
	v_mul_f32_e32 v67, 0x3d922279, v60
	v_fmaak_f32 v67, v60, v67, 0x3fcc422a
	v_mul_f32_e32 v67, v60, v67
	v_mul_f32_e32 v67, 0xbfb8aa3b, v67
	v_exp_f32_e32 v67, v67
	v_cvt_pk_bf16_f32 v70, v58, v59
	v_add_f32_e32 v67, 1.0, v67
	v_rcp_f32_e32 v67, v67
	s_nop 0
	v_mul_f32_e32 v60, v60, v67
	v_mul_f32_e32 v67, 0x3d922279, v61
	v_fmaak_f32 v67, v61, v67, 0x3fcc422a
	v_mul_f32_e32 v67, v61, v67
	v_mul_f32_e32 v67, 0xbfb8aa3b, v67
	v_exp_f32_e32 v67, v67
	s_nop 0
	v_add_f32_e32 v67, 1.0, v67
	v_rcp_f32_e32 v67, v67
	s_nop 0
	v_mul_f32_e32 v61, v61, v67
	v_mul_f32_e32 v67, 0x3d922279, v54
	v_fmaak_f32 v67, v54, v67, 0x3fcc422a
	v_mul_f32_e32 v67, v54, v67
	v_mul_f32_e32 v67, 0xbfb8aa3b, v67
	v_exp_f32_e32 v67, v67
	v_cvt_pk_bf16_f32 v71, v60, v61
	global_store_dwordx4 v[72:73], v[68:71], off
	v_add_f32_e32 v67, 1.0, v67
	v_rcp_f32_e32 v67, v67
	s_nop 0
	v_mul_f32_e32 v54, v54, v67
	v_mul_f32_e32 v67, 0x3d922279, v55
	v_fmaak_f32 v67, v55, v67, 0x3fcc422a
	v_mul_f32_e32 v67, v55, v67
	v_mul_f32_e32 v67, 0xbfb8aa3b, v67
	v_exp_f32_e32 v67, v67
	s_nop 0
	v_add_f32_e32 v67, 1.0, v67
	v_rcp_f32_e32 v67, v67
	s_nop 0
	v_mul_f32_e32 v55, v55, v67
	v_mul_f32_e32 v67, 0x3d922279, v56
	v_fmaak_f32 v67, v56, v67, 0x3fcc422a
	v_mul_f32_e32 v67, v56, v67
	v_mul_f32_e32 v67, 0xbfb8aa3b, v67
	v_exp_f32_e32 v67, v67
	v_cvt_pk_bf16_f32 v68, v54, v55
	v_add_f32_e32 v67, 1.0, v67
	v_rcp_f32_e32 v67, v67
	s_nop 0
	v_mul_f32_e32 v56, v56, v67
	v_mul_f32_e32 v67, 0x3d922279, v57
	v_fmaak_f32 v67, v57, v67, 0x3fcc422a
	v_mul_f32_e32 v67, v57, v67
	v_mul_f32_e32 v67, 0xbfb8aa3b, v67
	v_exp_f32_e32 v67, v67
	s_nop 0
	v_add_f32_e32 v67, 1.0, v67
	v_rcp_f32_e32 v67, v67
	s_nop 0
	v_mul_f32_e32 v57, v57, v67
	v_mul_f32_e32 v67, 0x3d922279, v50
	v_fmaak_f32 v67, v50, v67, 0x3fcc422a
	v_mul_f32_e32 v67, v50, v67
	v_mul_f32_e32 v67, 0xbfb8aa3b, v67
	v_exp_f32_e32 v67, v67
	v_cvt_pk_bf16_f32 v69, v56, v57
	v_add_f32_e32 v67, 1.0, v67
	v_rcp_f32_e32 v67, v67
	s_nop 0
	v_mul_f32_e32 v50, v50, v67
	v_mul_f32_e32 v67, 0x3d922279, v51
	v_fmaak_f32 v67, v51, v67, 0x3fcc422a
	v_mul_f32_e32 v67, v51, v67
	v_mul_f32_e32 v67, 0xbfb8aa3b, v67
	v_exp_f32_e32 v67, v67
	s_nop 0
	v_add_f32_e32 v67, 1.0, v67
	v_rcp_f32_e32 v67, v67
	s_nop 0
	v_mul_f32_e32 v51, v51, v67
	v_mul_f32_e32 v67, 0x3d922279, v52
	v_fmaak_f32 v67, v52, v67, 0x3fcc422a
	v_mul_f32_e32 v67, v52, v67
	v_mul_f32_e32 v67, 0xbfb8aa3b, v67
	v_exp_f32_e32 v67, v67
	v_cvt_pk_bf16_f32 v70, v50, v51
	v_add_f32_e32 v67, 1.0, v67
	v_rcp_f32_e32 v67, v67
	s_nop 0
	v_mul_f32_e32 v52, v52, v67
	v_mul_f32_e32 v67, 0x3d922279, v53
	v_fmaak_f32 v67, v53, v67, 0x3fcc422a
	v_mul_f32_e32 v67, v53, v67
	v_mul_f32_e32 v67, 0xbfb8aa3b, v67
	v_exp_f32_e32 v67, v67
	s_nop 0
	v_add_f32_e32 v67, 1.0, v67
	v_rcp_f32_e32 v67, v67
	s_nop 0
	v_mul_f32_e32 v53, v53, v67
	v_cvt_pk_bf16_f32 v71, v52, v53
	global_store_dwordx4 v[72:73], v[68:71], off offset:256
	s_cbranch_vccnz .LBB11_1197
	v_mul_f32_e32 v67, v63, v63
	v_fmac_f32_e32 v67, v62, v62
	v_add_f32_e32 v62, 0, v62
	v_add_f32_e32 v62, v63, v62
	v_fmac_f32_e32 v67, v64, v64
	v_add_f32_e32 v62, v64, v62
	v_fmac_f32_e32 v67, v65, v65
	v_add_f32_e32 v62, v65, v62
	v_fmac_f32_e32 v67, v58, v58
	v_add_f32_e32 v58, v58, v62
	v_fmac_f32_e32 v67, v59, v59
	v_add_f32_e32 v58, v59, v58
	v_fmac_f32_e32 v67, v60, v60
	v_add_f32_e32 v58, v60, v58
	v_fmac_f32_e32 v67, v61, v61
	v_add_f32_e32 v58, v61, v58
	v_fmac_f32_e32 v67, v54, v54
	v_add_f32_e32 v54, v54, v58
	v_fmac_f32_e32 v67, v55, v55
	v_add_f32_e32 v54, v55, v54
	v_fmac_f32_e32 v67, v56, v56
	v_add_f32_e32 v54, v56, v54
	v_fmac_f32_e32 v67, v57, v57
	v_add_f32_e32 v54, v57, v54
	v_fmac_f32_e32 v67, v50, v50
	v_add_f32_e32 v50, v50, v54
	v_fmac_f32_e32 v67, v51, v51
	v_add_f32_e32 v50, v51, v50
	v_fmac_f32_e32 v67, v52, v52
	v_add_f32_e32 v50, v52, v50
	v_add_f32_e32 v50, v53, v50
	v_fmac_f32_e32 v67, v53, v53
	ds_bpermute_b32 v51, v204, v50
	ds_bpermute_b32 v52, v204, v67
	s_waitcnt lgkmcnt(0)
	v_add_f32_e32 v50, v50, v51
	v_add_f32_e32 v52, v67, v52
	ds_bpermute_b32 v51, v205, v50
	ds_bpermute_b32 v53, v205, v52
	s_and_saveexec_b64 s[38:39], s[14:15]
	s_cbranch_execz .LBB11_1196
	v_lshlrev_b32_e32 v54, 1, v66
	v_ashrrev_i32_e32 v55, 31, v54
	v_lshl_add_u64 v[54:55], v[54:55], 2, s[34:35]
	s_waitcnt lgkmcnt(0)
	v_add_f32_e32 v50, v50, v51
	v_add_f32_e32 v51, v52, v53
	global_atomic_add_f32 v[54:55], v50, off
	global_atomic_add_f32 v[54:55], v51, off offset:4

.LBB11_1197:
	ds_read_b32 v58, v151 offset:576
	v_add_u32_e32 v50, 0x90, v142
	s_waitcnt lgkmcnt(0)
	v_ashrrev_i32_e32 v51, 31, v50
	v_lshlrev_b64 v[52:53], 13, v[50:51]
	v_lshl_add_u64 v[52:53], s[62:63], 0, v[52:53]
	v_mul_f32_e32 v46, v46, v58
	v_mul_f32_e32 v51, 0x3d922279, v46
	v_fmaak_f32 v51, v46, v51, 0x3fcc422a
	v_mul_f32_e32 v51, v46, v51
	v_mul_f32_e32 v51, 0xbfb8aa3b, v51
	v_exp_f32_e32 v51, v51
	v_mul_f32_e32 v47, v47, v58
	v_mul_f32_e32 v48, v48, v58
	v_mul_f32_e32 v49, v49, v58
	v_add_f32_e32 v51, 1.0, v51
	v_rcp_f32_e32 v51, v51
	v_mul_f32_e32 v42, v42, v58
	v_mul_f32_e32 v43, v43, v58
	v_mul_f32_e32 v44, v44, v58
	v_mul_f32_e32 v46, v46, v51
	v_mul_f32_e32 v51, 0x3d922279, v47
	v_fmaak_f32 v51, v47, v51, 0x3fcc422a
	v_mul_f32_e32 v51, v47, v51
	v_mul_f32_e32 v51, 0xbfb8aa3b, v51
	v_exp_f32_e32 v51, v51
	v_mul_f32_e32 v45, v45, v58
	v_mul_f32_e32 v38, v38, v58
	v_mul_f32_e32 v39, v39, v58
	v_add_f32_e32 v51, 1.0, v51
	v_rcp_f32_e32 v51, v51
	v_mul_f32_e32 v40, v40, v58
	v_mul_f32_e32 v41, v41, v58
	v_mul_f32_e32 v34, v34, v58
	v_mul_f32_e32 v47, v47, v51
	v_mul_f32_e32 v51, 0x3d922279, v48
	v_fmaak_f32 v51, v48, v51, 0x3fcc422a
	v_mul_f32_e32 v51, v48, v51
	v_mul_f32_e32 v51, 0xbfb8aa3b, v51
	v_exp_f32_e32 v51, v51
	v_mul_f32_e32 v35, v35, v58
	v_mul_f32_e32 v36, v36, v58
	v_mul_f32_e32 v37, v37, v58
	v_add_f32_e32 v51, 1.0, v51
	v_rcp_f32_e32 v51, v51
	v_lshl_add_u64 v[52:53], s[28:29], 1, v[52:53]
	v_lshl_add_u64 v[56:57], v[140:141], 1, v[52:53]
	v_cvt_pk_bf16_f32 v52, v46, v47
	v_mul_f32_e32 v48, v48, v51
	v_mul_f32_e32 v51, 0x3d922279, v49
	v_fmaak_f32 v51, v49, v51, 0x3fcc422a
	v_mul_f32_e32 v51, v49, v51
	v_mul_f32_e32 v51, 0xbfb8aa3b, v51
	v_exp_f32_e32 v51, v51
	s_and_b64 vcc, exec, s[16:17]
	v_add_f32_e32 v51, 1.0, v51
	v_rcp_f32_e32 v51, v51
	s_nop 0
	v_mul_f32_e32 v49, v49, v51
	v_mul_f32_e32 v51, 0x3d922279, v42
	v_fmaak_f32 v51, v42, v51, 0x3fcc422a
	v_mul_f32_e32 v51, v42, v51
	v_mul_f32_e32 v51, 0xbfb8aa3b, v51
	v_exp_f32_e32 v51, v51
	v_cvt_pk_bf16_f32 v53, v48, v49
	v_add_f32_e32 v51, 1.0, v51
	v_rcp_f32_e32 v51, v51
	s_nop 0
	v_mul_f32_e32 v42, v42, v51
	v_mul_f32_e32 v51, 0x3d922279, v43
	v_fmaak_f32 v51, v43, v51, 0x3fcc422a
	v_mul_f32_e32 v51, v43, v51
	v_mul_f32_e32 v51, 0xbfb8aa3b, v51
	v_exp_f32_e32 v51, v51
	s_nop 0
	v_add_f32_e32 v51, 1.0, v51
	v_rcp_f32_e32 v51, v51
	s_nop 0
	v_mul_f32_e32 v43, v43, v51
	v_mul_f32_e32 v51, 0x3d922279, v44
	v_fmaak_f32 v51, v44, v51, 0x3fcc422a
	v_mul_f32_e32 v51, v44, v51
	v_mul_f32_e32 v51, 0xbfb8aa3b, v51
	v_exp_f32_e32 v51, v51
	v_cvt_pk_bf16_f32 v54, v42, v43
	v_add_f32_e32 v51, 1.0, v51
	v_rcp_f32_e32 v51, v51
	s_nop 0
	v_mul_f32_e32 v44, v44, v51
	v_mul_f32_e32 v51, 0x3d922279, v45
	v_fmaak_f32 v51, v45, v51, 0x3fcc422a
	v_mul_f32_e32 v51, v45, v51
	v_mul_f32_e32 v51, 0xbfb8aa3b, v51
	v_exp_f32_e32 v51, v51
	s_nop 0
	v_add_f32_e32 v51, 1.0, v51
	v_rcp_f32_e32 v51, v51
	s_nop 0
	v_mul_f32_e32 v45, v45, v51
	v_mul_f32_e32 v51, 0x3d922279, v38
	v_fmaak_f32 v51, v38, v51, 0x3fcc422a
	v_mul_f32_e32 v51, v38, v51
	v_mul_f32_e32 v51, 0xbfb8aa3b, v51
	v_exp_f32_e32 v51, v51
	v_cvt_pk_bf16_f32 v55, v44, v45
	global_store_dwordx4 v[56:57], v[52:55], off
	v_add_f32_e32 v51, 1.0, v51
	v_rcp_f32_e32 v51, v51
	s_nop 0
	v_mul_f32_e32 v38, v38, v51
	v_mul_f32_e32 v51, 0x3d922279, v39
	v_fmaak_f32 v51, v39, v51, 0x3fcc422a
	v_mul_f32_e32 v51, v39, v51
	v_mul_f32_e32 v51, 0xbfb8aa3b, v51
	v_exp_f32_e32 v51, v51
	s_nop 0
	v_add_f32_e32 v51, 1.0, v51
	v_rcp_f32_e32 v51, v51
	s_nop 0
	v_mul_f32_e32 v39, v39, v51
	v_mul_f32_e32 v51, 0x3d922279, v40
	v_fmaak_f32 v51, v40, v51, 0x3fcc422a
	v_mul_f32_e32 v51, v40, v51
	v_mul_f32_e32 v51, 0xbfb8aa3b, v51
	v_exp_f32_e32 v51, v51
	v_cvt_pk_bf16_f32 v52, v38, v39
	v_add_f32_e32 v51, 1.0, v51
	v_rcp_f32_e32 v51, v51
	s_nop 0
	v_mul_f32_e32 v40, v40, v51
	v_mul_f32_e32 v51, 0x3d922279, v41
	v_fmaak_f32 v51, v41, v51, 0x3fcc422a
	v_mul_f32_e32 v51, v41, v51
	v_mul_f32_e32 v51, 0xbfb8aa3b, v51
	v_exp_f32_e32 v51, v51
	s_nop 0
	v_add_f32_e32 v51, 1.0, v51
	v_rcp_f32_e32 v51, v51
	s_nop 0
	v_mul_f32_e32 v41, v41, v51
	v_mul_f32_e32 v51, 0x3d922279, v34
	v_fmaak_f32 v51, v34, v51, 0x3fcc422a
	v_mul_f32_e32 v51, v34, v51
	v_mul_f32_e32 v51, 0xbfb8aa3b, v51
	v_exp_f32_e32 v51, v51
	v_cvt_pk_bf16_f32 v53, v40, v41
	v_add_f32_e32 v51, 1.0, v51
	v_rcp_f32_e32 v51, v51
	s_nop 0
	v_mul_f32_e32 v34, v34, v51
	v_mul_f32_e32 v51, 0x3d922279, v35
	v_fmaak_f32 v51, v35, v51, 0x3fcc422a
	v_mul_f32_e32 v51, v35, v51
	v_mul_f32_e32 v51, 0xbfb8aa3b, v51
	v_exp_f32_e32 v51, v51
	s_nop 0
	v_add_f32_e32 v51, 1.0, v51
	v_rcp_f32_e32 v51, v51
	s_nop 0
	v_mul_f32_e32 v35, v35, v51
	v_mul_f32_e32 v51, 0x3d922279, v36
	v_fmaak_f32 v51, v36, v51, 0x3fcc422a
	v_mul_f32_e32 v51, v36, v51
	v_mul_f32_e32 v51, 0xbfb8aa3b, v51
	v_exp_f32_e32 v51, v51
	v_cvt_pk_bf16_f32 v54, v34, v35
	v_add_f32_e32 v51, 1.0, v51
	v_rcp_f32_e32 v51, v51
	s_nop 0
	v_mul_f32_e32 v36, v36, v51
	v_mul_f32_e32 v51, 0x3d922279, v37
	v_fmaak_f32 v51, v37, v51, 0x3fcc422a
	v_mul_f32_e32 v51, v37, v51
	v_mul_f32_e32 v51, 0xbfb8aa3b, v51
	v_exp_f32_e32 v51, v51
	s_nop 0
	v_add_f32_e32 v51, 1.0, v51
	v_rcp_f32_e32 v51, v51
	s_nop 0
	v_mul_f32_e32 v37, v37, v51
	v_cvt_pk_bf16_f32 v55, v36, v37
	global_store_dwordx4 v[56:57], v[52:55], off offset:256
	s_cbranch_vccnz .LBB11_1201
	v_mul_f32_e32 v51, v47, v47
	v_fmac_f32_e32 v51, v46, v46
	v_add_f32_e32 v46, 0, v46
	v_add_f32_e32 v46, v47, v46
	v_fmac_f32_e32 v51, v48, v48
	v_add_f32_e32 v46, v48, v46
	v_fmac_f32_e32 v51, v49, v49
	v_add_f32_e32 v46, v49, v46
	v_fmac_f32_e32 v51, v42, v42
	v_add_f32_e32 v42, v42, v46
	v_fmac_f32_e32 v51, v43, v43
	v_add_f32_e32 v42, v43, v42
	v_fmac_f32_e32 v51, v44, v44
	v_add_f32_e32 v42, v44, v42
	v_fmac_f32_e32 v51, v45, v45
	v_add_f32_e32 v42, v45, v42
	v_fmac_f32_e32 v51, v38, v38
	v_add_f32_e32 v38, v38, v42
	v_fmac_f32_e32 v51, v39, v39
	v_add_f32_e32 v38, v39, v38
	v_fmac_f32_e32 v51, v40, v40
	v_add_f32_e32 v38, v40, v38
	v_fmac_f32_e32 v51, v41, v41
	v_add_f32_e32 v38, v41, v38
	v_fmac_f32_e32 v51, v34, v34
	v_add_f32_e32 v34, v34, v38
	v_fmac_f32_e32 v51, v35, v35
	v_add_f32_e32 v34, v35, v34
	v_fmac_f32_e32 v51, v36, v36
	v_add_f32_e32 v34, v36, v34
	v_add_f32_e32 v34, v37, v34
	v_fmac_f32_e32 v51, v37, v37
	ds_bpermute_b32 v35, v204, v34
	ds_bpermute_b32 v36, v204, v51
	s_waitcnt lgkmcnt(0)
	v_add_f32_e32 v34, v34, v35
	v_add_f32_e32 v36, v51, v36
	ds_bpermute_b32 v35, v205, v34
	ds_bpermute_b32 v37, v205, v36
	s_and_saveexec_b64 s[38:39], s[14:15]
	s_cbranch_execz .LBB11_1200
	v_lshlrev_b32_e32 v38, 1, v50
	v_ashrrev_i32_e32 v39, 31, v38
	v_lshl_add_u64 v[38:39], v[38:39], 2, s[34:35]
	s_waitcnt lgkmcnt(0)
	v_add_f32_e32 v34, v34, v35
	v_add_f32_e32 v35, v36, v37
	global_atomic_add_f32 v[38:39], v34, off
	global_atomic_add_f32 v[38:39], v35, off offset:4

.LBB11_1201:
	ds_read_b32 v42, v151 offset:640
	v_add_u32_e32 v34, 0xa0, v142
	s_waitcnt lgkmcnt(0)
	v_ashrrev_i32_e32 v35, 31, v34
	v_lshlrev_b64 v[36:37], 13, v[34:35]
	v_lshl_add_u64 v[36:37], s[62:63], 0, v[36:37]
	v_mul_f32_e32 v30, v30, v42
	v_mul_f32_e32 v35, 0x3d922279, v30
	v_fmaak_f32 v35, v30, v35, 0x3fcc422a
	v_mul_f32_e32 v35, v30, v35
	v_mul_f32_e32 v35, 0xbfb8aa3b, v35
	v_exp_f32_e32 v35, v35
	v_mul_f32_e32 v31, v31, v42
	v_mul_f32_e32 v32, v32, v42
	v_mul_f32_e32 v33, v33, v42
	v_add_f32_e32 v35, 1.0, v35
	v_rcp_f32_e32 v35, v35
	v_mul_f32_e32 v26, v26, v42
	v_mul_f32_e32 v27, v27, v42
	v_mul_f32_e32 v28, v28, v42
	v_mul_f32_e32 v30, v30, v35
	v_mul_f32_e32 v35, 0x3d922279, v31
	v_fmaak_f32 v35, v31, v35, 0x3fcc422a
	v_mul_f32_e32 v35, v31, v35
	v_mul_f32_e32 v35, 0xbfb8aa3b, v35
	v_exp_f32_e32 v35, v35
	v_mul_f32_e32 v29, v29, v42
	v_mul_f32_e32 v22, v22, v42
	v_mul_f32_e32 v23, v23, v42
	v_add_f32_e32 v35, 1.0, v35
	v_rcp_f32_e32 v35, v35
	v_mul_f32_e32 v24, v24, v42
	v_mul_f32_e32 v25, v25, v42
	v_mul_f32_e32 v18, v18, v42
	v_mul_f32_e32 v31, v31, v35
	v_mul_f32_e32 v35, 0x3d922279, v32
	v_fmaak_f32 v35, v32, v35, 0x3fcc422a
	v_mul_f32_e32 v35, v32, v35
	v_mul_f32_e32 v35, 0xbfb8aa3b, v35
	v_exp_f32_e32 v35, v35
	v_mul_f32_e32 v19, v19, v42
	v_mul_f32_e32 v20, v20, v42
	v_mul_f32_e32 v21, v21, v42
	v_add_f32_e32 v35, 1.0, v35
	v_rcp_f32_e32 v35, v35
	v_lshl_add_u64 v[36:37], s[28:29], 1, v[36:37]
	v_lshl_add_u64 v[40:41], v[140:141], 1, v[36:37]
	v_cvt_pk_bf16_f32 v36, v30, v31
	v_mul_f32_e32 v32, v32, v35
	v_mul_f32_e32 v35, 0x3d922279, v33
	v_fmaak_f32 v35, v33, v35, 0x3fcc422a
	v_mul_f32_e32 v35, v33, v35
	v_mul_f32_e32 v35, 0xbfb8aa3b, v35
	v_exp_f32_e32 v35, v35
	s_and_b64 vcc, exec, s[16:17]
	v_add_f32_e32 v35, 1.0, v35
	v_rcp_f32_e32 v35, v35
	s_nop 0
	v_mul_f32_e32 v33, v33, v35
	v_mul_f32_e32 v35, 0x3d922279, v26
	v_fmaak_f32 v35, v26, v35, 0x3fcc422a
	v_mul_f32_e32 v35, v26, v35
	v_mul_f32_e32 v35, 0xbfb8aa3b, v35
	v_exp_f32_e32 v35, v35
	v_cvt_pk_bf16_f32 v37, v32, v33
	v_add_f32_e32 v35, 1.0, v35
	v_rcp_f32_e32 v35, v35
	s_nop 0
	v_mul_f32_e32 v26, v26, v35
	v_mul_f32_e32 v35, 0x3d922279, v27
	v_fmaak_f32 v35, v27, v35, 0x3fcc422a
	v_mul_f32_e32 v35, v27, v35
	v_mul_f32_e32 v35, 0xbfb8aa3b, v35
	v_exp_f32_e32 v35, v35
	s_nop 0
	v_add_f32_e32 v35, 1.0, v35
	v_rcp_f32_e32 v35, v35
	s_nop 0
	v_mul_f32_e32 v27, v27, v35
	v_mul_f32_e32 v35, 0x3d922279, v28
	v_fmaak_f32 v35, v28, v35, 0x3fcc422a
	v_mul_f32_e32 v35, v28, v35
	v_mul_f32_e32 v35, 0xbfb8aa3b, v35
	v_exp_f32_e32 v35, v35
	v_cvt_pk_bf16_f32 v38, v26, v27
	v_add_f32_e32 v35, 1.0, v35
	v_rcp_f32_e32 v35, v35
	s_nop 0
	v_mul_f32_e32 v28, v28, v35
	v_mul_f32_e32 v35, 0x3d922279, v29
	v_fmaak_f32 v35, v29, v35, 0x3fcc422a
	v_mul_f32_e32 v35, v29, v35
	v_mul_f32_e32 v35, 0xbfb8aa3b, v35
	v_exp_f32_e32 v35, v35
	s_nop 0
	v_add_f32_e32 v35, 1.0, v35
	v_rcp_f32_e32 v35, v35
	s_nop 0
	v_mul_f32_e32 v29, v29, v35
	v_mul_f32_e32 v35, 0x3d922279, v22
	v_fmaak_f32 v35, v22, v35, 0x3fcc422a
	v_mul_f32_e32 v35, v22, v35
	v_mul_f32_e32 v35, 0xbfb8aa3b, v35
	v_exp_f32_e32 v35, v35
	v_cvt_pk_bf16_f32 v39, v28, v29
	global_store_dwordx4 v[40:41], v[36:39], off
	v_add_f32_e32 v35, 1.0, v35
	v_rcp_f32_e32 v35, v35
	s_nop 0
	v_mul_f32_e32 v22, v22, v35
	v_mul_f32_e32 v35, 0x3d922279, v23
	v_fmaak_f32 v35, v23, v35, 0x3fcc422a
	v_mul_f32_e32 v35, v23, v35
	v_mul_f32_e32 v35, 0xbfb8aa3b, v35
	v_exp_f32_e32 v35, v35
	s_nop 0
	v_add_f32_e32 v35, 1.0, v35
	v_rcp_f32_e32 v35, v35
	s_nop 0
	v_mul_f32_e32 v23, v23, v35
	v_mul_f32_e32 v35, 0x3d922279, v24
	v_fmaak_f32 v35, v24, v35, 0x3fcc422a
	v_mul_f32_e32 v35, v24, v35
	v_mul_f32_e32 v35, 0xbfb8aa3b, v35
	v_exp_f32_e32 v35, v35
	v_cvt_pk_bf16_f32 v36, v22, v23
	v_add_f32_e32 v35, 1.0, v35
	v_rcp_f32_e32 v35, v35
	s_nop 0
	v_mul_f32_e32 v24, v24, v35
	v_mul_f32_e32 v35, 0x3d922279, v25
	v_fmaak_f32 v35, v25, v35, 0x3fcc422a
	v_mul_f32_e32 v35, v25, v35
	v_mul_f32_e32 v35, 0xbfb8aa3b, v35
	v_exp_f32_e32 v35, v35
	s_nop 0
	v_add_f32_e32 v35, 1.0, v35
	v_rcp_f32_e32 v35, v35
	s_nop 0
	v_mul_f32_e32 v25, v25, v35
	v_mul_f32_e32 v35, 0x3d922279, v18
	v_fmaak_f32 v35, v18, v35, 0x3fcc422a
	v_mul_f32_e32 v35, v18, v35
	v_mul_f32_e32 v35, 0xbfb8aa3b, v35
	v_exp_f32_e32 v35, v35
	v_cvt_pk_bf16_f32 v37, v24, v25
	v_add_f32_e32 v35, 1.0, v35
	v_rcp_f32_e32 v35, v35
	s_nop 0
	v_mul_f32_e32 v18, v18, v35
	v_mul_f32_e32 v35, 0x3d922279, v19
	v_fmaak_f32 v35, v19, v35, 0x3fcc422a
	v_mul_f32_e32 v35, v19, v35
	v_mul_f32_e32 v35, 0xbfb8aa3b, v35
	v_exp_f32_e32 v35, v35
	s_nop 0
	v_add_f32_e32 v35, 1.0, v35
	v_rcp_f32_e32 v35, v35
	s_nop 0
	v_mul_f32_e32 v19, v19, v35
	v_mul_f32_e32 v35, 0x3d922279, v20
	v_fmaak_f32 v35, v20, v35, 0x3fcc422a
	v_mul_f32_e32 v35, v20, v35
	v_mul_f32_e32 v35, 0xbfb8aa3b, v35
	v_exp_f32_e32 v35, v35
	v_cvt_pk_bf16_f32 v38, v18, v19
	v_add_f32_e32 v35, 1.0, v35
	v_rcp_f32_e32 v35, v35
	s_nop 0
	v_mul_f32_e32 v20, v20, v35
	v_mul_f32_e32 v35, 0x3d922279, v21
	v_fmaak_f32 v35, v21, v35, 0x3fcc422a
	v_mul_f32_e32 v35, v21, v35
	v_mul_f32_e32 v35, 0xbfb8aa3b, v35
	v_exp_f32_e32 v35, v35
	s_nop 0
	v_add_f32_e32 v35, 1.0, v35
	v_rcp_f32_e32 v35, v35
	s_nop 0
	v_mul_f32_e32 v21, v21, v35
	v_cvt_pk_bf16_f32 v39, v20, v21
	global_store_dwordx4 v[40:41], v[36:39], off offset:256
	s_cbranch_vccnz .LBB11_1205
	v_mul_f32_e32 v35, v31, v31
	v_fmac_f32_e32 v35, v30, v30
	v_add_f32_e32 v30, 0, v30
	v_add_f32_e32 v30, v31, v30
	v_fmac_f32_e32 v35, v32, v32
	v_add_f32_e32 v30, v32, v30
	v_fmac_f32_e32 v35, v33, v33
	v_add_f32_e32 v30, v33, v30
	v_fmac_f32_e32 v35, v26, v26
	v_add_f32_e32 v26, v26, v30
	v_fmac_f32_e32 v35, v27, v27
	v_add_f32_e32 v26, v27, v26
	v_fmac_f32_e32 v35, v28, v28
	v_add_f32_e32 v26, v28, v26
	v_fmac_f32_e32 v35, v29, v29
	v_add_f32_e32 v26, v29, v26
	v_fmac_f32_e32 v35, v22, v22
	v_add_f32_e32 v22, v22, v26
	v_fmac_f32_e32 v35, v23, v23
	v_add_f32_e32 v22, v23, v22
	v_fmac_f32_e32 v35, v24, v24
	v_add_f32_e32 v22, v24, v22
	v_fmac_f32_e32 v35, v25, v25
	v_add_f32_e32 v22, v25, v22
	v_fmac_f32_e32 v35, v18, v18
	v_add_f32_e32 v18, v18, v22
	v_fmac_f32_e32 v35, v19, v19
	v_add_f32_e32 v18, v19, v18
	v_fmac_f32_e32 v35, v20, v20
	v_add_f32_e32 v18, v20, v18
	v_add_f32_e32 v18, v21, v18
	v_fmac_f32_e32 v35, v21, v21
	ds_bpermute_b32 v19, v204, v18
	ds_bpermute_b32 v20, v204, v35
	s_waitcnt lgkmcnt(0)
	v_add_f32_e32 v18, v18, v19
	v_add_f32_e32 v20, v35, v20
	ds_bpermute_b32 v19, v205, v18
	ds_bpermute_b32 v21, v205, v20
	s_and_saveexec_b64 s[38:39], s[14:15]
	s_cbranch_execz .LBB11_1204
	v_lshlrev_b32_e32 v22, 1, v34
	v_ashrrev_i32_e32 v23, 31, v22
	v_lshl_add_u64 v[22:23], v[22:23], 2, s[34:35]
	s_waitcnt lgkmcnt(0)
	v_add_f32_e32 v18, v18, v19
	v_add_f32_e32 v19, v20, v21
	global_atomic_add_f32 v[22:23], v18, off
	global_atomic_add_f32 v[22:23], v19, off offset:4

.LBB11_1205:
	ds_read_b32 v26, v151 offset:704
	v_add_u32_e32 v18, 0xb0, v142
	s_waitcnt lgkmcnt(0)
	v_ashrrev_i32_e32 v19, 31, v18
	v_lshlrev_b64 v[20:21], 13, v[18:19]
	v_lshl_add_u64 v[20:21], s[62:63], 0, v[20:21]
	v_mul_f32_e32 v14, v14, v26
	v_mul_f32_e32 v19, 0x3d922279, v14
	v_fmaak_f32 v19, v14, v19, 0x3fcc422a
	v_mul_f32_e32 v19, v14, v19
	v_mul_f32_e32 v19, 0xbfb8aa3b, v19
	v_exp_f32_e32 v19, v19
	v_mul_f32_e32 v15, v15, v26
	v_mul_f32_e32 v16, v16, v26
	v_mul_f32_e32 v17, v17, v26
	v_add_f32_e32 v19, 1.0, v19
	v_rcp_f32_e32 v19, v19
	v_mul_f32_e32 v10, v10, v26
	v_mul_f32_e32 v11, v11, v26
	v_mul_f32_e32 v12, v12, v26
	v_mul_f32_e32 v14, v14, v19
	v_mul_f32_e32 v19, 0x3d922279, v15
	v_fmaak_f32 v19, v15, v19, 0x3fcc422a
	v_mul_f32_e32 v19, v15, v19
	v_mul_f32_e32 v19, 0xbfb8aa3b, v19
	v_exp_f32_e32 v19, v19
	v_mul_f32_e32 v13, v13, v26
	v_mul_f32_e32 v6, v6, v26
	v_mul_f32_e32 v7, v7, v26
	v_add_f32_e32 v19, 1.0, v19
	v_rcp_f32_e32 v19, v19
	v_mul_f32_e32 v8, v8, v26
	v_mul_f32_e32 v9, v9, v26
	v_mul_f32_e32 v2, v2, v26
	v_mul_f32_e32 v15, v15, v19
	v_mul_f32_e32 v19, 0x3d922279, v16
	v_fmaak_f32 v19, v16, v19, 0x3fcc422a
	v_mul_f32_e32 v19, v16, v19
	v_mul_f32_e32 v19, 0xbfb8aa3b, v19
	v_exp_f32_e32 v19, v19
	v_mul_f32_e32 v3, v3, v26
	v_mul_f32_e32 v4, v4, v26
	v_mul_f32_e32 v5, v5, v26
	v_add_f32_e32 v19, 1.0, v19
	v_rcp_f32_e32 v19, v19
	v_lshl_add_u64 v[20:21], s[28:29], 1, v[20:21]
	v_lshl_add_u64 v[24:25], v[140:141], 1, v[20:21]
	v_cvt_pk_bf16_f32 v20, v14, v15
	v_mul_f32_e32 v16, v16, v19
	v_mul_f32_e32 v19, 0x3d922279, v17
	v_fmaak_f32 v19, v17, v19, 0x3fcc422a
	v_mul_f32_e32 v19, v17, v19
	v_mul_f32_e32 v19, 0xbfb8aa3b, v19
	v_exp_f32_e32 v19, v19
	s_and_b64 vcc, exec, s[16:17]
	v_add_f32_e32 v19, 1.0, v19
	v_rcp_f32_e32 v19, v19
	s_nop 0
	v_mul_f32_e32 v17, v17, v19
	v_mul_f32_e32 v19, 0x3d922279, v10
	v_fmaak_f32 v19, v10, v19, 0x3fcc422a
	v_mul_f32_e32 v19, v10, v19
	v_mul_f32_e32 v19, 0xbfb8aa3b, v19
	v_exp_f32_e32 v19, v19
	v_cvt_pk_bf16_f32 v21, v16, v17
	v_add_f32_e32 v19, 1.0, v19
	v_rcp_f32_e32 v19, v19
	s_nop 0
	v_mul_f32_e32 v10, v10, v19
	v_mul_f32_e32 v19, 0x3d922279, v11
	v_fmaak_f32 v19, v11, v19, 0x3fcc422a
	v_mul_f32_e32 v19, v11, v19
	v_mul_f32_e32 v19, 0xbfb8aa3b, v19
	v_exp_f32_e32 v19, v19
	s_nop 0
	v_add_f32_e32 v19, 1.0, v19
	v_rcp_f32_e32 v19, v19
	s_nop 0
	v_mul_f32_e32 v11, v11, v19
	v_mul_f32_e32 v19, 0x3d922279, v12
	v_fmaak_f32 v19, v12, v19, 0x3fcc422a
	v_mul_f32_e32 v19, v12, v19
	v_mul_f32_e32 v19, 0xbfb8aa3b, v19
	v_exp_f32_e32 v19, v19
	v_cvt_pk_bf16_f32 v22, v10, v11
	v_add_f32_e32 v19, 1.0, v19
	v_rcp_f32_e32 v19, v19
	s_nop 0
	v_mul_f32_e32 v12, v12, v19
	v_mul_f32_e32 v19, 0x3d922279, v13
	v_fmaak_f32 v19, v13, v19, 0x3fcc422a
	v_mul_f32_e32 v19, v13, v19
	v_mul_f32_e32 v19, 0xbfb8aa3b, v19
	v_exp_f32_e32 v19, v19
	s_nop 0
	v_add_f32_e32 v19, 1.0, v19
	v_rcp_f32_e32 v19, v19
	s_nop 0
	v_mul_f32_e32 v13, v13, v19
	v_mul_f32_e32 v19, 0x3d922279, v6
	v_fmaak_f32 v19, v6, v19, 0x3fcc422a
	v_mul_f32_e32 v19, v6, v19
	v_mul_f32_e32 v19, 0xbfb8aa3b, v19
	v_exp_f32_e32 v19, v19
	v_cvt_pk_bf16_f32 v23, v12, v13
	global_store_dwordx4 v[24:25], v[20:23], off
	v_add_f32_e32 v19, 1.0, v19
	v_rcp_f32_e32 v19, v19
	s_nop 0
	v_mul_f32_e32 v6, v6, v19
	v_mul_f32_e32 v19, 0x3d922279, v7
	v_fmaak_f32 v19, v7, v19, 0x3fcc422a
	v_mul_f32_e32 v19, v7, v19
	v_mul_f32_e32 v19, 0xbfb8aa3b, v19
	v_exp_f32_e32 v19, v19
	s_nop 0
	v_add_f32_e32 v19, 1.0, v19
	v_rcp_f32_e32 v19, v19
	s_nop 0
	v_mul_f32_e32 v7, v7, v19
	v_mul_f32_e32 v19, 0x3d922279, v8
	v_fmaak_f32 v19, v8, v19, 0x3fcc422a
	v_mul_f32_e32 v19, v8, v19
	v_mul_f32_e32 v19, 0xbfb8aa3b, v19
	v_exp_f32_e32 v19, v19
	v_cvt_pk_bf16_f32 v20, v6, v7
	v_add_f32_e32 v19, 1.0, v19
	v_rcp_f32_e32 v19, v19
	s_nop 0
	v_mul_f32_e32 v8, v8, v19
	v_mul_f32_e32 v19, 0x3d922279, v9
	v_fmaak_f32 v19, v9, v19, 0x3fcc422a
	v_mul_f32_e32 v19, v9, v19
	v_mul_f32_e32 v19, 0xbfb8aa3b, v19
	v_exp_f32_e32 v19, v19
	s_nop 0
	v_add_f32_e32 v19, 1.0, v19
	v_rcp_f32_e32 v19, v19
	s_nop 0
	v_mul_f32_e32 v9, v9, v19
	v_mul_f32_e32 v19, 0x3d922279, v2
	v_fmaak_f32 v19, v2, v19, 0x3fcc422a
	v_mul_f32_e32 v19, v2, v19
	v_mul_f32_e32 v19, 0xbfb8aa3b, v19
	v_exp_f32_e32 v19, v19
	v_cvt_pk_bf16_f32 v21, v8, v9
	v_add_f32_e32 v19, 1.0, v19
	v_rcp_f32_e32 v19, v19
	s_nop 0
	v_mul_f32_e32 v2, v2, v19
	v_mul_f32_e32 v19, 0x3d922279, v3
	v_fmaak_f32 v19, v3, v19, 0x3fcc422a
	v_mul_f32_e32 v19, v3, v19
	v_mul_f32_e32 v19, 0xbfb8aa3b, v19
	v_exp_f32_e32 v19, v19
	s_nop 0
	v_add_f32_e32 v19, 1.0, v19
	v_rcp_f32_e32 v19, v19
	s_nop 0
	v_mul_f32_e32 v3, v3, v19
	v_mul_f32_e32 v19, 0x3d922279, v4
	v_fmaak_f32 v19, v4, v19, 0x3fcc422a
	v_mul_f32_e32 v19, v4, v19
	v_mul_f32_e32 v19, 0xbfb8aa3b, v19
	v_exp_f32_e32 v19, v19
	v_cvt_pk_bf16_f32 v22, v2, v3
	v_add_f32_e32 v19, 1.0, v19
	v_rcp_f32_e32 v19, v19
	s_nop 0
	v_mul_f32_e32 v4, v4, v19
	v_mul_f32_e32 v19, 0x3d922279, v5
	v_fmaak_f32 v19, v5, v19, 0x3fcc422a
	v_mul_f32_e32 v19, v5, v19
	v_mul_f32_e32 v19, 0xbfb8aa3b, v19
	v_exp_f32_e32 v19, v19
	s_nop 0
	v_add_f32_e32 v19, 1.0, v19
	v_rcp_f32_e32 v19, v19
	s_nop 0
	v_mul_f32_e32 v5, v5, v19
	v_cvt_pk_bf16_f32 v23, v4, v5
	global_store_dwordx4 v[24:25], v[20:23], off offset:256
	s_cbranch_vccnz .LBB11_1210
	v_mul_f32_e32 v19, v15, v15
	v_fmac_f32_e32 v19, v14, v14
	v_add_f32_e32 v14, 0, v14
	v_add_f32_e32 v14, v15, v14
	v_fmac_f32_e32 v19, v16, v16
	v_add_f32_e32 v14, v16, v14
	v_fmac_f32_e32 v19, v17, v17
	v_add_f32_e32 v14, v17, v14
	v_fmac_f32_e32 v19, v10, v10
	v_add_f32_e32 v10, v10, v14
	v_fmac_f32_e32 v19, v11, v11
	v_add_f32_e32 v10, v11, v10
	v_fmac_f32_e32 v19, v12, v12
	v_add_f32_e32 v10, v12, v10
	v_fmac_f32_e32 v19, v13, v13
	v_add_f32_e32 v10, v13, v10
	v_fmac_f32_e32 v19, v6, v6
	v_add_f32_e32 v6, v6, v10
	v_fmac_f32_e32 v19, v7, v7
	v_add_f32_e32 v6, v7, v6
	v_fmac_f32_e32 v19, v8, v8
	v_add_f32_e32 v6, v8, v6
	v_fmac_f32_e32 v19, v9, v9
	v_add_f32_e32 v6, v9, v6
	v_fmac_f32_e32 v19, v2, v2
	v_add_f32_e32 v2, v2, v6
	v_fmac_f32_e32 v19, v3, v3
	v_add_f32_e32 v2, v3, v2
	v_fmac_f32_e32 v19, v4, v4
	v_add_f32_e32 v2, v4, v2
	v_add_f32_e32 v2, v5, v2
	v_fmac_f32_e32 v19, v5, v5
	ds_bpermute_b32 v3, v204, v2
	ds_bpermute_b32 v4, v204, v19
	s_waitcnt lgkmcnt(0)
	v_add_f32_e32 v2, v2, v3
	v_add_f32_e32 v4, v19, v4
	ds_bpermute_b32 v3, v205, v2
	ds_bpermute_b32 v5, v205, v4
	s_and_saveexec_b64 s[16:17], s[14:15]
	s_cbranch_execz .LBB11_1208
	v_lshlrev_b32_e32 v6, 1, v18
	v_ashrrev_i32_e32 v7, 31, v6
	v_lshl_add_u64 v[6:7], v[6:7], 2, s[34:35]
	s_waitcnt lgkmcnt(0)
	v_add_f32_e32 v2, v2, v3
	v_add_f32_e32 v3, v4, v5
	global_atomic_add_f32 v[6:7], v2, off
	global_atomic_add_f32 v[6:7], v3, off offset:4

.LBB11_1526:
	s_or_b64 exec, exec, s[10:11]
	v_readlane_b32 s0, v245, 25
	v_readlane_b32 s10, v248, 14
	v_readlane_b32 s1, v245, 26
	v_readlane_b32 s11, v248, 15
	v_mov_b32_e32 v0, v199
	v_mov_b32_e32 v2, v198
	s_andn2_b64 vcc, exec, s[0:1]
	s_barrier
	s_cbranch_vccnz .LBB11_1528
	s_load_dwordx8 s[12:19], s[10:11], 0x68
	s_load_dwordx4 s[20:23], s[10:11], 0x130
	s_lshl_b32 s60, s94, 10
	s_lshl_b64 s[0:1], s[60:61], 2
	v_lshlrev_b32_e32 v4, 2, v0
	s_waitcnt lgkmcnt(0)
	s_add_u32 s0, s18, s0
	s_addc_u32 s1, s19, s1
	s_lshl_b32 s60, s94, 11
	s_lshl_b64 s[6:7], s[60:61], 2
	s_add_u32 s8, s14, s6
	s_addc_u32 s9, s15, s7
	s_add_u32 s6, s12, s6
	s_addc_u32 s7, s13, s7
	s_add_u32 s12, s22, s44
	s_addc_u32 s13, s23, s43
	v_readlane_b32 s10, v245, 28
	v_readlane_b32 s11, v245, 29
	s_add_u32 s10, s22, s10
	v_ashrrev_i32_e32 v5, 31, v4
	s_addc_u32 s11, s23, s11
	v_lshlrev_b64 v[2:3], 1, v[4:5]
	v_lshl_add_u64 v[12:13], s[10:11], 0, v[2:3]
	s_mov_b32 s10, 0x1b401000
	v_add_co_u32_e32 v6, vcc, s10, v12
	v_readlane_b32 s10, v242, 24
	v_readlane_b32 s11, v242, 25
	s_add_u32 s10, s12, s10
	s_addc_u32 s11, s13, s11
	v_addc_co_u32_e32 v7, vcc, 0, v13, vcc
	global_load_dwordx2 v[16:17], v[6:7], off
	s_nop 0
	global_load_dwordx2 v[14:15], v211, s[10:11]
	v_lshlrev_b64 v[18:19], 2, v[4:5]
	v_lshl_add_u64 v[4:5], s[8:9], 0, v[18:19]
	v_lshl_add_u64 v[8:9], s[6:7], 0, v[18:19]
	global_load_dwordx4 v[4:7], v[4:5], off
	v_ashrrev_i32_e32 v20, 6, v0
	global_load_dwordx4 v[8:11], v[8:9], off
	v_lshlrev_b32_e32 v22, 7, v20
	v_ashrrev_i32_e32 v23, 31, v22
	v_lshl_add_u64 v[22:23], v[22:23], 2, s[0:1]
	s_mov_b32 s0, 0x1b400000
	v_add_co_u32_e32 v12, vcc, s0, v12
	s_lshl_b64 s[0:1], s[94:95], 20
	s_add_u32 s0, s20, s0
	s_addc_u32 s1, s21, s1
	v_readlane_b32 s6, v245, 27
	s_add_u32 s0, s0, s6
	s_addc_u32 s1, s1, 0
	s_lshl_b64 s[6:7], s[94:95], 19
	v_ashrrev_i32_e32 v21, 31, v20
	v_addc_co_u32_e32 v13, vcc, 0, v13, vcc
	v_lshl_add_u64 v[18:19], s[0:1], 0, v[18:19]
	s_add_u32 s0, s16, s6
	s_mov_b32 s1, 0x8900000
	v_lshlrev_b64 v[20:21], 16, v[20:21]
	v_add_co_u32_e32 v18, vcc, s1, v18
	s_addc_u32 s1, s17, s7
	v_lshl_add_u64 v[20:21], s[0:1], 0, v[20:21]
	s_mov_b32 s0, 0x3a000000
	v_addc_co_u32_e32 v19, vcc, 0, v19, vcc
	global_load_dwordx2 v[12:13], v[12:13], off
	s_waitcnt vmcnt(4)
	v_lshlrev_b32_e32 v24, 16, v16
	s_waitcnt vmcnt(3)
	v_pk_mul_f32 v[14:15], v[14:15], s[0:1] op_sel_hi:[1,0]
	v_readlane_b32 s0, v245, 30
	v_fma_f32 v0, -v14, v14, v15
	v_max_f32_e32 v0, 0, v0
	v_add_f32_e32 v0, 0x358637bd, v0
	v_cmp_gt_f32_e32 vcc, s77, v0
	v_mul_f32_e32 v25, 0x4b800000, v0
	v_and_b32_e32 v15, 0xffff0000, v16
	v_cndmask_b32_e32 v0, v0, v25, vcc
	v_rsq_f32_e32 v0, v0
	v_lshlrev_b32_e32 v16, 16, v17
	v_and_b32_e32 v17, 0xffff0000, v17
	v_sub_f32_e32 v17, v17, v14
	v_sub_f32_e32 v16, v16, v14
	v_sub_f32_e32 v15, v15, v14
	v_sub_f32_e32 v14, v24, v14
	v_mul_f32_e32 v24, 0x45800000, v0
	v_cndmask_b32_e32 v0, v0, v24, vcc
	v_pk_mul_f32 v[14:15], v[14:15], v[0:1] op_sel_hi:[1,0]
	v_pk_mul_f32 v[16:17], v[16:17], v[0:1] op_sel_hi:[1,0]
	s_waitcnt vmcnt(1)
	v_pk_fma_f32 v[4:5], v[8:9], v[14:15], v[4:5]
	v_pk_fma_f32 v[6:7], v[10:11], v[16:17], v[6:7]
	global_store_dwordx4 v[18:19], v[4:7], off sc1
	global_load_dword v0, v[20:21], off
	global_load_dword v8, v[22:23], off
	v_readlane_b32 s1, v245, 31
	s_add_u32 s0, s22, s0
	s_addc_u32 s1, s23, s1
	v_lshl_add_u64 v[2:3], s[0:1], 0, v[2:3]
	v_add_co_u32_e32 v2, vcc, 0x23600000, v2
	s_waitcnt vmcnt(3)
	v_lshlrev_b32_e32 v10, 16, v12
	v_and_b32_e32 v11, 0xffff0000, v12
	v_lshlrev_b32_e32 v12, 16, v13
	v_and_b32_e32 v13, 0xffff0000, v13
	v_addc_co_u32_e32 v3, vcc, 0, v3, vcc
	s_waitcnt vmcnt(0)
	v_pk_fma_f32 v[4:5], v[0:1], v[4:5], v[8:9] op_sel_hi:[0,1,0]
	v_pk_fma_f32 v[6:7], v[0:1], v[6:7], v[8:9] op_sel_hi:[0,1,0]
	v_pk_mul_f32 v[4:5], v[4:5], v[10:11]
	v_pk_mul_f32 v[6:7], v[6:7], v[12:13]
	v_cvt_pk_bf16_f32 v4, v4, v5
	v_cvt_pk_bf16_f32 v5, v6, v7
	global_store_dwordx2 v[2:3], v[4:5], off sc1

.LBB11_1632:
	v_mov_b32_e32 v141, v152
	v_mov_b32_e32 v140, v150
	s_lshl_b32 s22, s7, 8
	s_nop 0
	v_add_u32_e32 v144, s22, v140
	v_lshl_add_u32 v142, s6, 8, v141
	v_ashrrev_i32_e32 v145, 31, v144
	v_lshlrev_b64 v[148:149], 11, v[144:145]
	v_ashrrev_i32_e32 v143, 31, v142
	v_lshl_add_u64 v[146:147], s[66:67], 0, v[148:149]
	v_lshlrev_b64 v[142:143], 1, v[142:143]
	v_lshl_add_u64 v[146:147], v[146:147], 0, v[142:143]
	v_lshl_add_u64 v[148:149], s[64:65], 0, v[148:149]
	v_lshl_add_u64 v[148:149], v[148:149], 0, v[142:143]
	v_lshl_add_u32 v249, v144, 11, v142
	global_load_dwordx4 v[170:173], v249, s[66:67]
	global_load_dwordx4 v[174:177], v249, s[64:65]
	global_load_dwordx4 v[178:181], v249, s[66:67] offset:256
	global_load_dwordx4 v[190:193], v249, s[64:65] offset:256
	v_add_u32_e32 v251, 0x8000, v249
	global_load_dwordx4 v[194:197], v251, s[66:67]
	global_load_dwordx4 v[214:217], v251, s[64:65]
	v_add_u32_e32 v250, 0x8000, v249
	global_load_dwordx4 v[218:221], v250, s[66:67] offset:256
	global_load_dwordx4 v[222:225], v250, s[64:65] offset:256
	v_add_u32_e32 v251, 0x10000, v249
	global_load_dwordx4 v[226:229], v251, s[66:67]
	global_load_dwordx4 v[230:233], v251, s[64:65]
	s_waitcnt vmcnt(8)
	v_lshlrev_b32_e32 v162, 16, v170
	v_and_b32_e32 v163, 0xffff0000, v170
	v_lshlrev_b32_e32 v164, 16, v174
	v_and_b32_e32 v165, 0xffff0000, v174
	v_lshlrev_b32_e32 v154, 16, v171
	v_and_b32_e32 v155, 0xffff0000, v171
	v_lshlrev_b32_e32 v158, 16, v175
	v_and_b32_e32 v159, 0xffff0000, v175
	v_pk_add_f32 v[162:163], v[162:163], v[164:165]
	v_pk_add_f32 v[154:155], v[154:155], v[158:159]
	v_lshlrev_b32_e32 v158, 16, v172
	v_and_b32_e32 v159, 0xffff0000, v172
	v_lshlrev_b32_e32 v164, 16, v176
	v_and_b32_e32 v165, 0xffff0000, v176
	v_lshlrev_b32_e32 v156, 16, v173
	v_and_b32_e32 v157, 0xffff0000, v173
	v_lshlrev_b32_e32 v160, 16, v177
	v_and_b32_e32 v161, 0xffff0000, v177
	v_add_u32_e32 v250, 0x10000, v249
	global_load_dwordx4 v[170:173], v250, s[66:67] offset:256
	global_load_dwordx4 v[174:177], v250, s[64:65] offset:256
	v_pk_add_f32 v[158:159], v[158:159], v[164:165]
	v_pk_add_f32 v[156:157], v[156:157], v[160:161]
	v_pk_add_f32 v[128:129], v[128:129], v[154:155]
	v_pk_add_f32 v[126:127], v[126:127], v[162:163]
	v_pk_add_f32 v[154:155], v[124:125], v[156:157]
	v_pk_add_f32 v[156:157], v[122:123], v[158:159]
	v_cvt_pk_bf16_f32 v122, v126, v127
	v_cvt_pk_bf16_f32 v123, v128, v129
	v_lshlrev_b32_e32 v124, 16, v122
	v_and_b32_e32 v125, 0xffff0000, v122
	v_lshlrev_b32_e32 v158, 16, v123
	v_and_b32_e32 v159, 0xffff0000, v123
	v_sub_f32_e32 v128, v128, v158
	v_sub_f32_e32 v129, v129, v159
	v_sub_f32_e32 v126, v126, v124
	v_sub_f32_e32 v127, v127, v125
	v_cvt_pk_bf16_f32 v126, v126, v127
	v_cvt_pk_bf16_f32 v127, v128, v129
	v_lshlrev_b32_e32 v128, 16, v126
	v_and_b32_e32 v129, 0xffff0000, v126
	v_lshlrev_b32_e32 v160, 16, v127
	v_and_b32_e32 v161, 0xffff0000, v127
	v_pk_add_f32 v[158:159], v[158:159], v[160:161]
	v_pk_add_f32 v[160:161], v[124:125], v[128:129]
	v_cvt_pk_bf16_f32 v124, v156, v157
	v_cvt_pk_bf16_f32 v125, v154, v155
	v_lshlrev_b32_e32 v162, 16, v124
	v_lshlrev_b32_e32 v164, 16, v125
	v_and_b32_e32 v163, 0xffff0000, v124
	v_and_b32_e32 v165, 0xffff0000, v125
	v_sub_f32_e32 v129, v154, v164
	v_sub_f32_e32 v128, v156, v162
	v_sub_f32_e32 v141, v155, v165
	v_sub_f32_e32 v145, v157, v163
	v_cvt_pk_bf16_f32 v128, v128, v145
	v_cvt_pk_bf16_f32 v129, v129, v141
	global_store_dwordx4 v[146:147], v[122:125], off
	global_store_dwordx4 v[148:149], v[126:129], off
	v_lshlrev_b32_e32 v154, 16, v128
	v_and_b32_e32 v155, 0xffff0000, v128
	v_mul_f32_e32 v122, v161, v161
	v_mul_f32_e32 v123, v159, v159
	v_pk_add_f32 v[154:155], v[162:163], v[154:155]
	v_fmac_f32_e32 v122, v160, v160
	v_fmac_f32_e32 v123, v158, v158
	v_lshlrev_b32_e32 v156, 16, v129
	v_and_b32_e32 v157, 0xffff0000, v129
	v_add_f32_e32 v122, v122, v123
	v_mul_f32_e32 v123, v155, v155
	v_pk_add_f32 v[156:157], v[164:165], v[156:157]
	v_fmac_f32_e32 v123, v154, v154
	v_add_f32_e32 v122, v122, v123
	v_mul_f32_e32 v123, v157, v157
	v_fmac_f32_e32 v123, v156, v156
	v_add_f32_e32 v141, v123, v122
	s_waitcnt vmcnt(10)
	v_lshlrev_b32_e32 v154, 16, v178
	v_and_b32_e32 v155, 0xffff0000, v178
	v_lshlrev_b32_e32 v156, 16, v190
	v_and_b32_e32 v157, 0xffff0000, v190
	v_lshlrev_b32_e32 v122, 16, v179
	v_and_b32_e32 v123, 0xffff0000, v179
	v_lshlrev_b32_e32 v126, 16, v191
	v_and_b32_e32 v127, 0xffff0000, v191
	v_pk_add_f32 v[154:155], v[154:155], v[156:157]
	v_pk_add_f32 v[122:123], v[122:123], v[126:127]
	v_lshlrev_b32_e32 v126, 16, v180
	v_and_b32_e32 v127, 0xffff0000, v180
	v_lshlrev_b32_e32 v156, 16, v192
	v_and_b32_e32 v157, 0xffff0000, v192
	v_lshlrev_b32_e32 v124, 16, v181
	v_and_b32_e32 v125, 0xffff0000, v181
	v_lshlrev_b32_e32 v128, 16, v193
	v_and_b32_e32 v129, 0xffff0000, v193
	v_add_u32_e32 v251, 0x18000, v249
	global_load_dwordx4 v[178:181], v251, s[66:67]
	global_load_dwordx4 v[190:193], v251, s[64:65]
	v_pk_add_f32 v[126:127], v[126:127], v[156:157]
	v_pk_add_f32 v[124:125], v[124:125], v[128:129]
	v_pk_add_f32 v[120:121], v[120:121], v[122:123]
	v_pk_add_f32 v[118:119], v[118:119], v[154:155]
	v_pk_add_f32 v[122:123], v[116:117], v[124:125]
	v_pk_add_f32 v[124:125], v[114:115], v[126:127]
	v_cvt_pk_bf16_f32 v114, v118, v119
	v_cvt_pk_bf16_f32 v115, v120, v121
	v_lshlrev_b32_e32 v116, 16, v114
	v_and_b32_e32 v117, 0xffff0000, v114
	v_lshlrev_b32_e32 v126, 16, v115
	v_and_b32_e32 v127, 0xffff0000, v115
	v_sub_f32_e32 v120, v120, v126
	v_sub_f32_e32 v121, v121, v127
	v_sub_f32_e32 v118, v118, v116
	v_sub_f32_e32 v119, v119, v117
	v_cvt_pk_bf16_f32 v118, v118, v119
	v_cvt_pk_bf16_f32 v119, v120, v121
	v_lshlrev_b32_e32 v120, 16, v118
	v_and_b32_e32 v121, 0xffff0000, v118
	v_lshlrev_b32_e32 v128, 16, v119
	v_and_b32_e32 v129, 0xffff0000, v119
	v_pk_add_f32 v[126:127], v[126:127], v[128:129]
	v_pk_add_f32 v[128:129], v[116:117], v[120:121]
	v_cvt_pk_bf16_f32 v116, v124, v125
	v_cvt_pk_bf16_f32 v117, v122, v123
	v_lshlrev_b32_e32 v154, 16, v116
	v_and_b32_e32 v155, 0xffff0000, v116
	v_lshlrev_b32_e32 v156, 16, v117
	v_and_b32_e32 v157, 0xffff0000, v117
	v_sub_f32_e32 v121, v122, v156
	v_sub_f32_e32 v122, v123, v157
	v_sub_f32_e32 v120, v124, v154
	v_sub_f32_e32 v123, v125, v155
	v_cvt_pk_bf16_f32 v120, v120, v123
	v_cvt_pk_bf16_f32 v121, v121, v122
	global_store_dwordx4 v[146:147], v[114:117], off offset:256
	global_store_dwordx4 v[148:149], v[118:121], off offset:256
	v_lshlrev_b32_e32 v122, 16, v120
	v_and_b32_e32 v123, 0xffff0000, v120
	v_mul_f32_e32 v114, v129, v129
	v_mul_f32_e32 v115, v127, v127
	v_pk_add_f32 v[122:123], v[154:155], v[122:123]
	v_fmac_f32_e32 v114, v128, v128
	v_fmac_f32_e32 v115, v126, v126
	v_lshlrev_b32_e32 v124, 16, v121
	v_and_b32_e32 v125, 0xffff0000, v121
	v_add_f32_e32 v114, v114, v115
	v_mul_f32_e32 v115, v123, v123
	v_pk_add_f32 v[124:125], v[156:157], v[124:125]
	v_fmac_f32_e32 v115, v122, v122
	v_add_f32_e32 v114, v114, v115
	v_mul_f32_e32 v115, v125, v125
	v_fmac_f32_e32 v115, v124, v124
	v_add_f32_e32 v114, v115, v114
	v_add_f32_e32 v114, v141, v114
	ds_bpermute_b32 v115, v204, v114
	s_waitcnt lgkmcnt(0)
	v_add_f32_e32 v118, v114, v115
	v_add_u32_e32 v114, 16, v144
	v_ashrrev_i32_e32 v115, 31, v114
	v_lshlrev_b64 v[116:117], 11, v[114:115]
	v_lshl_add_u64 v[114:115], s[66:67], 0, v[116:117]
	v_lshl_add_u64 v[114:115], v[114:115], 0, v[142:143]
	v_lshl_add_u64 v[116:117], s[64:65], 0, v[116:117]
	v_lshl_add_u64 v[116:117], v[116:117], 0, v[142:143]
	ds_bpermute_b32 v119, v205, v118
	s_waitcnt vmcnt(12)
	v_lshlrev_b32_e32 v128, 16, v194
	v_and_b32_e32 v129, 0xffff0000, v194
	v_lshlrev_b32_e32 v146, 16, v214
	v_and_b32_e32 v147, 0xffff0000, v214
	v_lshlrev_b32_e32 v120, 16, v195
	v_and_b32_e32 v121, 0xffff0000, v195
	v_lshlrev_b32_e32 v124, 16, v215
	v_and_b32_e32 v125, 0xffff0000, v215
	v_pk_add_f32 v[128:129], v[128:129], v[146:147]
	v_pk_add_f32 v[120:121], v[120:121], v[124:125]
	v_lshlrev_b32_e32 v124, 16, v196
	v_and_b32_e32 v125, 0xffff0000, v196
	v_lshlrev_b32_e32 v146, 16, v216
	v_and_b32_e32 v147, 0xffff0000, v216
	v_lshlrev_b32_e32 v122, 16, v197
	v_and_b32_e32 v123, 0xffff0000, v197
	v_lshlrev_b32_e32 v126, 16, v217
	v_and_b32_e32 v127, 0xffff0000, v217
	v_add_u32_e32 v250, 0x18000, v249
	global_load_dwordx4 v[194:197], v250, s[66:67] offset:256
	global_load_dwordx4 v[214:217], v250, s[64:65] offset:256
	v_pk_add_f32 v[124:125], v[124:125], v[146:147]
	v_pk_add_f32 v[122:123], v[122:123], v[126:127]
	v_pk_add_f32 v[112:113], v[112:113], v[120:121]
	v_pk_add_f32 v[110:111], v[110:111], v[128:129]
	v_pk_add_f32 v[120:121], v[108:109], v[122:123]
	v_pk_add_f32 v[122:123], v[106:107], v[124:125]
	v_cvt_pk_bf16_f32 v106, v110, v111
	v_cvt_pk_bf16_f32 v107, v112, v113
	v_lshlrev_b32_e32 v108, 16, v106
	v_and_b32_e32 v109, 0xffff0000, v106
	v_lshlrev_b32_e32 v124, 16, v107
	v_and_b32_e32 v125, 0xffff0000, v107
	v_sub_f32_e32 v112, v112, v124
	v_sub_f32_e32 v113, v113, v125
	v_sub_f32_e32 v110, v110, v108
	v_sub_f32_e32 v111, v111, v109
	v_cvt_pk_bf16_f32 v110, v110, v111
	v_cvt_pk_bf16_f32 v111, v112, v113
	v_lshlrev_b32_e32 v112, 16, v110
	v_and_b32_e32 v113, 0xffff0000, v110
	v_lshlrev_b32_e32 v126, 16, v111
	v_and_b32_e32 v127, 0xffff0000, v111
	v_pk_add_f32 v[124:125], v[124:125], v[126:127]
	v_pk_add_f32 v[126:127], v[108:109], v[112:113]
	v_cvt_pk_bf16_f32 v108, v122, v123
	v_cvt_pk_bf16_f32 v109, v120, v121
	v_lshlrev_b32_e32 v128, 16, v108
	v_and_b32_e32 v129, 0xffff0000, v108
	v_lshlrev_b32_e32 v146, 16, v109
	v_and_b32_e32 v147, 0xffff0000, v109
	v_sub_f32_e32 v113, v120, v146
	v_sub_f32_e32 v120, v121, v147
	v_sub_f32_e32 v112, v122, v128
	v_sub_f32_e32 v121, v123, v129
	v_cvt_pk_bf16_f32 v112, v112, v121
	v_cvt_pk_bf16_f32 v113, v113, v120
	global_store_dwordx4 v[114:115], v[106:109], off
	global_store_dwordx4 v[116:117], v[110:113], off
	v_lshlrev_b32_e32 v120, 16, v112
	v_and_b32_e32 v121, 0xffff0000, v112
	v_mul_f32_e32 v106, v127, v127
	v_mul_f32_e32 v107, v125, v125
	v_pk_add_f32 v[120:121], v[128:129], v[120:121]
	v_fmac_f32_e32 v106, v126, v126
	v_fmac_f32_e32 v107, v124, v124
	v_lshlrev_b32_e32 v122, 16, v113
	v_and_b32_e32 v123, 0xffff0000, v113
	v_add_f32_e32 v106, v106, v107
	v_mul_f32_e32 v107, v121, v121
	v_pk_add_f32 v[122:123], v[146:147], v[122:123]
	v_fmac_f32_e32 v107, v120, v120
	v_add_f32_e32 v106, v106, v107
	v_mul_f32_e32 v107, v123, v123
	v_fmac_f32_e32 v107, v122, v122
	v_add_f32_e32 v124, v107, v106
	s_waitcnt vmcnt(14)
	v_lshlrev_b32_e32 v120, 16, v218
	v_and_b32_e32 v121, 0xffff0000, v218
	v_lshlrev_b32_e32 v122, 16, v222
	v_and_b32_e32 v123, 0xffff0000, v222
	v_lshlrev_b32_e32 v106, 16, v219
	v_and_b32_e32 v107, 0xffff0000, v219
	v_lshlrev_b32_e32 v110, 16, v223
	v_and_b32_e32 v111, 0xffff0000, v223
	v_pk_add_f32 v[120:121], v[120:121], v[122:123]
	v_pk_add_f32 v[106:107], v[106:107], v[110:111]
	v_lshlrev_b32_e32 v110, 16, v220
	v_and_b32_e32 v111, 0xffff0000, v220
	v_lshlrev_b32_e32 v122, 16, v224
	v_and_b32_e32 v123, 0xffff0000, v224
	v_lshlrev_b32_e32 v108, 16, v221
	v_and_b32_e32 v109, 0xffff0000, v221
	v_lshlrev_b32_e32 v112, 16, v225
	v_and_b32_e32 v113, 0xffff0000, v225
	v_add_u32_e32 v251, 0x40000, v249
	global_load_dwordx4 v[218:221], v251, s[66:67]
	global_load_dwordx4 v[222:225], v251, s[64:65]
	v_pk_add_f32 v[110:111], v[110:111], v[122:123]
	v_pk_add_f32 v[108:109], v[108:109], v[112:113]
	v_pk_add_f32 v[104:105], v[104:105], v[106:107]
	v_pk_add_f32 v[102:103], v[102:103], v[120:121]
	v_pk_add_f32 v[106:107], v[100:101], v[108:109]
	v_pk_add_f32 v[108:109], v[98:99], v[110:111]
	v_cvt_pk_bf16_f32 v98, v102, v103
	v_cvt_pk_bf16_f32 v99, v104, v105
	v_lshlrev_b32_e32 v100, 16, v98
	v_and_b32_e32 v101, 0xffff0000, v98
	v_lshlrev_b32_e32 v110, 16, v99
	v_and_b32_e32 v111, 0xffff0000, v99
	v_sub_f32_e32 v104, v104, v110
	v_sub_f32_e32 v105, v105, v111
	v_sub_f32_e32 v102, v102, v100
	v_sub_f32_e32 v103, v103, v101
	v_cvt_pk_bf16_f32 v102, v102, v103
	v_cvt_pk_bf16_f32 v103, v104, v105
	v_lshlrev_b32_e32 v104, 16, v102
	v_and_b32_e32 v105, 0xffff0000, v102
	v_lshlrev_b32_e32 v112, 16, v103
	v_and_b32_e32 v113, 0xffff0000, v103
	v_pk_add_f32 v[110:111], v[110:111], v[112:113]
	v_pk_add_f32 v[112:113], v[100:101], v[104:105]
	v_cvt_pk_bf16_f32 v100, v108, v109
	v_cvt_pk_bf16_f32 v101, v106, v107
	v_lshlrev_b32_e32 v120, 16, v100
	v_and_b32_e32 v121, 0xffff0000, v100
	v_lshlrev_b32_e32 v122, 16, v101
	v_and_b32_e32 v123, 0xffff0000, v101
	v_sub_f32_e32 v105, v106, v122
	v_sub_f32_e32 v106, v107, v123
	v_sub_f32_e32 v104, v108, v120
	v_sub_f32_e32 v107, v109, v121
	v_cvt_pk_bf16_f32 v104, v104, v107
	v_cvt_pk_bf16_f32 v105, v105, v106
	global_store_dwordx4 v[114:115], v[98:101], off offset:256
	global_store_dwordx4 v[116:117], v[102:105], off offset:256
	v_lshlrev_b32_e32 v106, 16, v104
	v_and_b32_e32 v107, 0xffff0000, v104
	v_mul_f32_e32 v98, v113, v113
	v_mul_f32_e32 v99, v111, v111
	v_pk_add_f32 v[106:107], v[120:121], v[106:107]
	v_fmac_f32_e32 v98, v112, v112
	v_fmac_f32_e32 v99, v110, v110
	v_lshlrev_b32_e32 v108, 16, v105
	v_and_b32_e32 v109, 0xffff0000, v105
	v_add_f32_e32 v98, v98, v99
	v_mul_f32_e32 v99, v107, v107
	v_pk_add_f32 v[108:109], v[122:123], v[108:109]
	v_fmac_f32_e32 v99, v106, v106
	v_add_f32_e32 v98, v98, v99
	v_mul_f32_e32 v99, v109, v109
	v_fmac_f32_e32 v99, v108, v108
	v_add_f32_e32 v98, v99, v98
	v_add_f32_e32 v98, v124, v98
	ds_bpermute_b32 v99, v204, v98
	s_waitcnt lgkmcnt(0)
	v_add_f32_e32 v102, v98, v99
	v_add_u32_e32 v98, 32, v144
	v_ashrrev_i32_e32 v99, 31, v98
	v_lshlrev_b64 v[100:101], 11, v[98:99]
	v_lshl_add_u64 v[98:99], s[66:67], 0, v[100:101]
	v_lshl_add_u64 v[98:99], v[98:99], 0, v[142:143]
	v_lshl_add_u64 v[100:101], s[64:65], 0, v[100:101]
	v_lshl_add_u64 v[100:101], v[100:101], 0, v[142:143]
	ds_bpermute_b32 v103, v205, v102
	s_waitcnt vmcnt(16)
	v_lshlrev_b32_e32 v112, 16, v226
	v_and_b32_e32 v113, 0xffff0000, v226
	v_lshlrev_b32_e32 v114, 16, v230
	v_and_b32_e32 v115, 0xffff0000, v230
	v_lshlrev_b32_e32 v104, 16, v227
	v_and_b32_e32 v105, 0xffff0000, v227
	v_lshlrev_b32_e32 v108, 16, v231
	v_and_b32_e32 v109, 0xffff0000, v231
	v_pk_add_f32 v[112:113], v[112:113], v[114:115]
	v_pk_add_f32 v[104:105], v[104:105], v[108:109]
	v_lshlrev_b32_e32 v108, 16, v228
	v_and_b32_e32 v109, 0xffff0000, v228
	v_lshlrev_b32_e32 v114, 16, v232
	v_and_b32_e32 v115, 0xffff0000, v232
	v_lshlrev_b32_e32 v106, 16, v229
	v_and_b32_e32 v107, 0xffff0000, v229
	v_lshlrev_b32_e32 v110, 16, v233
	v_and_b32_e32 v111, 0xffff0000, v233
	v_add_u32_e32 v250, 0x40000, v249
	global_load_dwordx4 v[226:229], v250, s[66:67] offset:256
	global_load_dwordx4 v[230:233], v250, s[64:65] offset:256
	v_pk_add_f32 v[108:109], v[108:109], v[114:115]
	v_pk_add_f32 v[106:107], v[106:107], v[110:111]
	v_pk_add_f32 v[96:97], v[96:97], v[104:105]
	v_pk_add_f32 v[94:95], v[94:95], v[112:113]
	v_pk_add_f32 v[104:105], v[92:93], v[106:107]
	v_pk_add_f32 v[106:107], v[90:91], v[108:109]
	v_cvt_pk_bf16_f32 v90, v94, v95
	v_cvt_pk_bf16_f32 v91, v96, v97
	v_lshlrev_b32_e32 v92, 16, v90
	v_and_b32_e32 v93, 0xffff0000, v90
	v_lshlrev_b32_e32 v108, 16, v91
	v_and_b32_e32 v109, 0xffff0000, v91
	v_sub_f32_e32 v96, v96, v108
	v_sub_f32_e32 v97, v97, v109
	v_sub_f32_e32 v94, v94, v92
	v_sub_f32_e32 v95, v95, v93
	v_cvt_pk_bf16_f32 v94, v94, v95
	v_cvt_pk_bf16_f32 v95, v96, v97
	v_lshlrev_b32_e32 v96, 16, v94
	v_and_b32_e32 v97, 0xffff0000, v94
	v_lshlrev_b32_e32 v110, 16, v95
	v_and_b32_e32 v111, 0xffff0000, v95
	v_pk_add_f32 v[108:109], v[108:109], v[110:111]
	v_pk_add_f32 v[110:111], v[92:93], v[96:97]
	v_cvt_pk_bf16_f32 v92, v106, v107
	v_cvt_pk_bf16_f32 v93, v104, v105
	v_lshlrev_b32_e32 v112, 16, v92
	v_and_b32_e32 v113, 0xffff0000, v92
	v_lshlrev_b32_e32 v114, 16, v93
	v_and_b32_e32 v115, 0xffff0000, v93
	v_sub_f32_e32 v97, v104, v114
	v_sub_f32_e32 v104, v105, v115
	v_sub_f32_e32 v96, v106, v112
	v_sub_f32_e32 v105, v107, v113
	v_cvt_pk_bf16_f32 v96, v96, v105
	v_cvt_pk_bf16_f32 v97, v97, v104
	global_store_dwordx4 v[98:99], v[90:93], off
	global_store_dwordx4 v[100:101], v[94:97], off
	v_lshlrev_b32_e32 v104, 16, v96
	v_and_b32_e32 v105, 0xffff0000, v96
	v_mul_f32_e32 v90, v111, v111
	v_mul_f32_e32 v91, v109, v109
	v_pk_add_f32 v[104:105], v[112:113], v[104:105]
	v_fmac_f32_e32 v90, v110, v110
	v_fmac_f32_e32 v91, v108, v108
	v_lshlrev_b32_e32 v106, 16, v97
	v_and_b32_e32 v107, 0xffff0000, v97
	v_add_f32_e32 v90, v90, v91
	v_mul_f32_e32 v91, v105, v105
	v_pk_add_f32 v[106:107], v[114:115], v[106:107]
	v_fmac_f32_e32 v91, v104, v104
	v_add_f32_e32 v90, v90, v91
	v_mul_f32_e32 v91, v107, v107
	v_fmac_f32_e32 v91, v106, v106
	v_add_f32_e32 v108, v91, v90
	s_waitcnt vmcnt(18)
	v_lshlrev_b32_e32 v104, 16, v170
	v_and_b32_e32 v105, 0xffff0000, v170
	v_lshlrev_b32_e32 v106, 16, v174
	v_and_b32_e32 v107, 0xffff0000, v174
	v_lshlrev_b32_e32 v90, 16, v171
	v_and_b32_e32 v91, 0xffff0000, v171
	v_lshlrev_b32_e32 v94, 16, v175
	v_and_b32_e32 v95, 0xffff0000, v175
	v_pk_add_f32 v[104:105], v[104:105], v[106:107]
	v_pk_add_f32 v[90:91], v[90:91], v[94:95]
	v_lshlrev_b32_e32 v94, 16, v172
	v_and_b32_e32 v95, 0xffff0000, v172
	v_lshlrev_b32_e32 v106, 16, v176
	v_and_b32_e32 v107, 0xffff0000, v176
	v_lshlrev_b32_e32 v92, 16, v173
	v_and_b32_e32 v93, 0xffff0000, v173
	v_lshlrev_b32_e32 v96, 16, v177
	v_and_b32_e32 v97, 0xffff0000, v177
	v_add_u32_e32 v251, 0x48000, v249
	global_load_dwordx4 v[170:173], v251, s[66:67]
	global_load_dwordx4 v[174:177], v251, s[64:65]
	v_pk_add_f32 v[94:95], v[94:95], v[106:107]
	v_pk_add_f32 v[92:93], v[92:93], v[96:97]
	v_pk_add_f32 v[88:89], v[88:89], v[90:91]
	v_pk_add_f32 v[86:87], v[86:87], v[104:105]
	v_pk_add_f32 v[90:91], v[84:85], v[92:93]
	v_pk_add_f32 v[92:93], v[82:83], v[94:95]
	v_cvt_pk_bf16_f32 v82, v86, v87
	v_cvt_pk_bf16_f32 v83, v88, v89
	v_lshlrev_b32_e32 v84, 16, v82
	v_and_b32_e32 v85, 0xffff0000, v82
	v_lshlrev_b32_e32 v94, 16, v83
	v_and_b32_e32 v95, 0xffff0000, v83
	v_sub_f32_e32 v88, v88, v94
	v_sub_f32_e32 v89, v89, v95
	v_sub_f32_e32 v86, v86, v84
	v_sub_f32_e32 v87, v87, v85
	v_cvt_pk_bf16_f32 v86, v86, v87
	v_cvt_pk_bf16_f32 v87, v88, v89
	v_lshlrev_b32_e32 v88, 16, v86
	v_and_b32_e32 v89, 0xffff0000, v86
	v_lshlrev_b32_e32 v96, 16, v87
	v_and_b32_e32 v97, 0xffff0000, v87
	v_pk_add_f32 v[94:95], v[94:95], v[96:97]
	v_pk_add_f32 v[96:97], v[84:85], v[88:89]
	v_cvt_pk_bf16_f32 v84, v92, v93
	v_cvt_pk_bf16_f32 v85, v90, v91
	v_lshlrev_b32_e32 v104, 16, v84
	v_and_b32_e32 v105, 0xffff0000, v84
	v_lshlrev_b32_e32 v106, 16, v85
	v_and_b32_e32 v107, 0xffff0000, v85
	v_sub_f32_e32 v89, v90, v106
	v_sub_f32_e32 v90, v91, v107
	v_sub_f32_e32 v88, v92, v104
	v_sub_f32_e32 v91, v93, v105
	v_cvt_pk_bf16_f32 v88, v88, v91
	v_cvt_pk_bf16_f32 v89, v89, v90
	global_store_dwordx4 v[98:99], v[82:85], off offset:256
	global_store_dwordx4 v[100:101], v[86:89], off offset:256
	v_lshlrev_b32_e32 v90, 16, v88
	v_and_b32_e32 v91, 0xffff0000, v88
	v_mul_f32_e32 v82, v97, v97
	v_mul_f32_e32 v83, v95, v95
	v_pk_add_f32 v[90:91], v[104:105], v[90:91]
	v_fmac_f32_e32 v82, v96, v96
	v_fmac_f32_e32 v83, v94, v94
	v_lshlrev_b32_e32 v92, 16, v89
	v_and_b32_e32 v93, 0xffff0000, v89
	v_add_f32_e32 v82, v82, v83
	v_mul_f32_e32 v83, v91, v91
	v_pk_add_f32 v[92:93], v[106:107], v[92:93]
	v_fmac_f32_e32 v83, v90, v90
	v_add_f32_e32 v82, v82, v83
	v_mul_f32_e32 v83, v93, v93
	v_fmac_f32_e32 v83, v92, v92
	v_add_f32_e32 v82, v83, v82
	v_add_f32_e32 v82, v108, v82
	ds_bpermute_b32 v83, v204, v82
	s_waitcnt lgkmcnt(0)
	v_add_f32_e32 v86, v82, v83
	v_add_u32_e32 v82, 48, v144
	v_ashrrev_i32_e32 v83, 31, v82
	v_lshlrev_b64 v[84:85], 11, v[82:83]
	v_lshl_add_u64 v[82:83], s[66:67], 0, v[84:85]
	v_lshl_add_u64 v[82:83], v[82:83], 0, v[142:143]
	v_lshl_add_u64 v[84:85], s[64:65], 0, v[84:85]
	v_lshl_add_u64 v[84:85], v[84:85], 0, v[142:143]
	ds_bpermute_b32 v87, v205, v86
	s_waitcnt vmcnt(18)
	v_lshlrev_b32_e32 v96, 16, v178
	v_and_b32_e32 v97, 0xffff0000, v178
	v_lshlrev_b32_e32 v98, 16, v190
	v_and_b32_e32 v99, 0xffff0000, v190
	v_lshlrev_b32_e32 v88, 16, v179
	v_and_b32_e32 v89, 0xffff0000, v179
	v_lshlrev_b32_e32 v92, 16, v191
	v_and_b32_e32 v93, 0xffff0000, v191
	v_pk_add_f32 v[96:97], v[96:97], v[98:99]
	v_pk_add_f32 v[88:89], v[88:89], v[92:93]
	v_lshlrev_b32_e32 v92, 16, v180
	v_and_b32_e32 v93, 0xffff0000, v180
	v_lshlrev_b32_e32 v98, 16, v192
	v_and_b32_e32 v99, 0xffff0000, v192
	v_lshlrev_b32_e32 v90, 16, v181
	v_and_b32_e32 v91, 0xffff0000, v181
	v_lshlrev_b32_e32 v94, 16, v193
	v_and_b32_e32 v95, 0xffff0000, v193
	v_add_u32_e32 v250, 0x48000, v249
	global_load_dwordx4 v[178:181], v250, s[66:67] offset:256
	global_load_dwordx4 v[190:193], v250, s[64:65] offset:256
	v_pk_add_f32 v[92:93], v[92:93], v[98:99]
	v_pk_add_f32 v[90:91], v[90:91], v[94:95]
	v_pk_add_f32 v[80:81], v[80:81], v[88:89]
	v_pk_add_f32 v[78:79], v[78:79], v[96:97]
	v_pk_add_f32 v[88:89], v[76:77], v[90:91]
	v_pk_add_f32 v[90:91], v[74:75], v[92:93]
	v_cvt_pk_bf16_f32 v74, v78, v79
	v_cvt_pk_bf16_f32 v75, v80, v81
	v_lshlrev_b32_e32 v76, 16, v74
	v_and_b32_e32 v77, 0xffff0000, v74
	v_lshlrev_b32_e32 v92, 16, v75
	v_and_b32_e32 v93, 0xffff0000, v75
	v_sub_f32_e32 v80, v80, v92
	v_sub_f32_e32 v81, v81, v93
	v_sub_f32_e32 v78, v78, v76
	v_sub_f32_e32 v79, v79, v77
	v_cvt_pk_bf16_f32 v78, v78, v79
	v_cvt_pk_bf16_f32 v79, v80, v81
	v_lshlrev_b32_e32 v80, 16, v78
	v_and_b32_e32 v81, 0xffff0000, v78
	v_lshlrev_b32_e32 v94, 16, v79
	v_and_b32_e32 v95, 0xffff0000, v79
	v_pk_add_f32 v[92:93], v[92:93], v[94:95]
	v_pk_add_f32 v[94:95], v[76:77], v[80:81]
	v_cvt_pk_bf16_f32 v76, v90, v91
	v_cvt_pk_bf16_f32 v77, v88, v89
	v_lshlrev_b32_e32 v96, 16, v76
	v_and_b32_e32 v97, 0xffff0000, v76
	v_lshlrev_b32_e32 v98, 16, v77
	v_and_b32_e32 v99, 0xffff0000, v77
	v_sub_f32_e32 v81, v88, v98
	v_sub_f32_e32 v88, v89, v99
	v_sub_f32_e32 v80, v90, v96
	v_sub_f32_e32 v89, v91, v97
	v_cvt_pk_bf16_f32 v80, v80, v89
	v_cvt_pk_bf16_f32 v81, v81, v88
	global_store_dwordx4 v[82:83], v[74:77], off
	global_store_dwordx4 v[84:85], v[78:81], off
	v_lshlrev_b32_e32 v88, 16, v80
	v_and_b32_e32 v89, 0xffff0000, v80
	v_mul_f32_e32 v74, v95, v95
	v_mul_f32_e32 v75, v93, v93
	v_pk_add_f32 v[88:89], v[96:97], v[88:89]
	v_fmac_f32_e32 v74, v94, v94
	v_fmac_f32_e32 v75, v92, v92
	v_lshlrev_b32_e32 v90, 16, v81
	v_and_b32_e32 v91, 0xffff0000, v81
	v_add_f32_e32 v74, v74, v75
	v_mul_f32_e32 v75, v89, v89
	v_pk_add_f32 v[90:91], v[98:99], v[90:91]
	v_fmac_f32_e32 v75, v88, v88
	v_add_f32_e32 v74, v74, v75
	v_mul_f32_e32 v75, v91, v91
	v_fmac_f32_e32 v75, v90, v90
	v_add_f32_e32 v92, v75, v74
	s_waitcnt vmcnt(18)
	v_lshlrev_b32_e32 v88, 16, v194
	v_and_b32_e32 v89, 0xffff0000, v194
	v_lshlrev_b32_e32 v90, 16, v214
	v_and_b32_e32 v91, 0xffff0000, v214
	v_lshlrev_b32_e32 v74, 16, v195
	v_and_b32_e32 v75, 0xffff0000, v195
	v_lshlrev_b32_e32 v78, 16, v215
	v_and_b32_e32 v79, 0xffff0000, v215
	v_pk_add_f32 v[88:89], v[88:89], v[90:91]
	v_pk_add_f32 v[74:75], v[74:75], v[78:79]
	v_lshlrev_b32_e32 v78, 16, v196
	v_and_b32_e32 v79, 0xffff0000, v196
	v_lshlrev_b32_e32 v90, 16, v216
	v_and_b32_e32 v91, 0xffff0000, v216
	v_lshlrev_b32_e32 v76, 16, v197
	v_and_b32_e32 v77, 0xffff0000, v197
	v_lshlrev_b32_e32 v80, 16, v217
	v_and_b32_e32 v81, 0xffff0000, v217
	v_add_u32_e32 v251, 0x50000, v249
	global_load_dwordx4 v[194:197], v251, s[66:67]
	global_load_dwordx4 v[214:217], v251, s[64:65]
	v_pk_add_f32 v[78:79], v[78:79], v[90:91]
	v_pk_add_f32 v[76:77], v[76:77], v[80:81]
	v_pk_add_f32 v[72:73], v[72:73], v[74:75]
	v_pk_add_f32 v[70:71], v[70:71], v[88:89]
	v_pk_add_f32 v[74:75], v[68:69], v[76:77]
	v_pk_add_f32 v[76:77], v[66:67], v[78:79]
	v_cvt_pk_bf16_f32 v66, v70, v71
	v_cvt_pk_bf16_f32 v67, v72, v73
	v_lshlrev_b32_e32 v68, 16, v66
	v_and_b32_e32 v69, 0xffff0000, v66
	v_lshlrev_b32_e32 v78, 16, v67
	v_and_b32_e32 v79, 0xffff0000, v67
	v_sub_f32_e32 v72, v72, v78
	v_sub_f32_e32 v73, v73, v79
	v_sub_f32_e32 v70, v70, v68
	v_sub_f32_e32 v71, v71, v69
	v_cvt_pk_bf16_f32 v70, v70, v71
	v_cvt_pk_bf16_f32 v71, v72, v73
	v_lshlrev_b32_e32 v72, 16, v70
	v_and_b32_e32 v73, 0xffff0000, v70
	v_lshlrev_b32_e32 v80, 16, v71
	v_and_b32_e32 v81, 0xffff0000, v71
	v_pk_add_f32 v[78:79], v[78:79], v[80:81]
	v_pk_add_f32 v[80:81], v[68:69], v[72:73]
	v_cvt_pk_bf16_f32 v68, v76, v77
	v_cvt_pk_bf16_f32 v69, v74, v75
	v_lshlrev_b32_e32 v88, 16, v68
	v_and_b32_e32 v89, 0xffff0000, v68
	v_lshlrev_b32_e32 v90, 16, v69
	v_and_b32_e32 v91, 0xffff0000, v69
	v_sub_f32_e32 v73, v74, v90
	v_sub_f32_e32 v74, v75, v91
	v_sub_f32_e32 v72, v76, v88
	v_sub_f32_e32 v75, v77, v89
	v_cvt_pk_bf16_f32 v72, v72, v75
	v_cvt_pk_bf16_f32 v73, v73, v74
	global_store_dwordx4 v[82:83], v[66:69], off offset:256
	global_store_dwordx4 v[84:85], v[70:73], off offset:256
	v_lshlrev_b32_e32 v74, 16, v72
	v_and_b32_e32 v75, 0xffff0000, v72
	v_mul_f32_e32 v66, v81, v81
	v_mul_f32_e32 v67, v79, v79
	v_pk_add_f32 v[74:75], v[88:89], v[74:75]
	v_fmac_f32_e32 v66, v80, v80
	v_fmac_f32_e32 v67, v78, v78
	v_lshlrev_b32_e32 v76, 16, v73
	v_and_b32_e32 v77, 0xffff0000, v73
	v_add_f32_e32 v66, v66, v67
	v_mul_f32_e32 v67, v75, v75
	v_pk_add_f32 v[76:77], v[90:91], v[76:77]
	v_fmac_f32_e32 v67, v74, v74
	v_add_f32_e32 v66, v66, v67
	v_mul_f32_e32 v67, v77, v77
	v_fmac_f32_e32 v67, v76, v76
	v_add_f32_e32 v66, v67, v66
	v_add_f32_e32 v66, v92, v66
	ds_bpermute_b32 v67, v204, v66
	s_waitcnt lgkmcnt(0)
	v_add_f32_e32 v70, v66, v67
	v_add_u32_e32 v66, 0x80, v144
	v_ashrrev_i32_e32 v67, 31, v66
	v_lshlrev_b64 v[68:69], 11, v[66:67]
	v_lshl_add_u64 v[66:67], s[66:67], 0, v[68:69]
	v_lshl_add_u64 v[66:67], v[66:67], 0, v[142:143]
	v_lshl_add_u64 v[68:69], s[64:65], 0, v[68:69]
	v_lshl_add_u64 v[68:69], v[68:69], 0, v[142:143]
	ds_bpermute_b32 v71, v205, v70
	s_waitcnt vmcnt(18)
	v_lshlrev_b32_e32 v80, 16, v218
	v_and_b32_e32 v81, 0xffff0000, v218
	v_lshlrev_b32_e32 v82, 16, v222
	v_and_b32_e32 v83, 0xffff0000, v222
	v_lshlrev_b32_e32 v72, 16, v219
	v_and_b32_e32 v73, 0xffff0000, v219
	v_lshlrev_b32_e32 v76, 16, v223
	v_and_b32_e32 v77, 0xffff0000, v223
	v_pk_add_f32 v[80:81], v[80:81], v[82:83]
	v_pk_add_f32 v[72:73], v[72:73], v[76:77]
	v_lshlrev_b32_e32 v76, 16, v220
	v_and_b32_e32 v77, 0xffff0000, v220
	v_lshlrev_b32_e32 v82, 16, v224
	v_and_b32_e32 v83, 0xffff0000, v224
	v_lshlrev_b32_e32 v74, 16, v221
	v_and_b32_e32 v75, 0xffff0000, v221
	v_lshlrev_b32_e32 v78, 16, v225
	v_and_b32_e32 v79, 0xffff0000, v225
	v_add_u32_e32 v250, 0x50000, v249
	global_load_dwordx4 v[218:221], v250, s[66:67] offset:256
	global_load_dwordx4 v[222:225], v250, s[64:65] offset:256
	v_pk_add_f32 v[76:77], v[76:77], v[82:83]
	v_pk_add_f32 v[74:75], v[74:75], v[78:79]
	v_pk_add_f32 v[64:65], v[64:65], v[72:73]
	v_pk_add_f32 v[62:63], v[62:63], v[80:81]
	v_pk_add_f32 v[72:73], v[60:61], v[74:75]
	v_pk_add_f32 v[74:75], v[58:59], v[76:77]
	v_cvt_pk_bf16_f32 v58, v62, v63
	v_cvt_pk_bf16_f32 v59, v64, v65
	v_lshlrev_b32_e32 v60, 16, v58
	v_and_b32_e32 v61, 0xffff0000, v58
	v_lshlrev_b32_e32 v76, 16, v59
	v_and_b32_e32 v77, 0xffff0000, v59
	v_sub_f32_e32 v64, v64, v76
	v_sub_f32_e32 v65, v65, v77
	v_sub_f32_e32 v62, v62, v60
	v_sub_f32_e32 v63, v63, v61
	v_cvt_pk_bf16_f32 v62, v62, v63
	v_cvt_pk_bf16_f32 v63, v64, v65
	v_lshlrev_b32_e32 v64, 16, v62
	v_and_b32_e32 v65, 0xffff0000, v62
	v_lshlrev_b32_e32 v78, 16, v63
	v_and_b32_e32 v79, 0xffff0000, v63
	v_pk_add_f32 v[76:77], v[76:77], v[78:79]
	v_pk_add_f32 v[78:79], v[60:61], v[64:65]
	v_cvt_pk_bf16_f32 v60, v74, v75
	v_cvt_pk_bf16_f32 v61, v72, v73
	v_lshlrev_b32_e32 v80, 16, v60
	v_and_b32_e32 v81, 0xffff0000, v60
	v_lshlrev_b32_e32 v82, 16, v61
	v_and_b32_e32 v83, 0xffff0000, v61
	v_sub_f32_e32 v65, v72, v82
	v_sub_f32_e32 v72, v73, v83
	v_sub_f32_e32 v64, v74, v80
	v_sub_f32_e32 v73, v75, v81
	v_cvt_pk_bf16_f32 v64, v64, v73
	v_cvt_pk_bf16_f32 v65, v65, v72
	global_store_dwordx4 v[66:67], v[58:61], off
	global_store_dwordx4 v[68:69], v[62:65], off
	v_lshlrev_b32_e32 v72, 16, v64
	v_and_b32_e32 v73, 0xffff0000, v64
	v_mul_f32_e32 v58, v79, v79
	v_mul_f32_e32 v59, v77, v77
	v_pk_add_f32 v[72:73], v[80:81], v[72:73]
	v_fmac_f32_e32 v58, v78, v78
	v_fmac_f32_e32 v59, v76, v76
	v_lshlrev_b32_e32 v74, 16, v65
	v_and_b32_e32 v75, 0xffff0000, v65
	v_add_f32_e32 v58, v58, v59
	v_mul_f32_e32 v59, v73, v73
	v_pk_add_f32 v[74:75], v[82:83], v[74:75]
	v_fmac_f32_e32 v59, v72, v72
	v_add_f32_e32 v58, v58, v59
	v_mul_f32_e32 v59, v75, v75
	v_fmac_f32_e32 v59, v74, v74
	v_add_f32_e32 v76, v59, v58
	s_waitcnt vmcnt(18)
	v_lshlrev_b32_e32 v72, 16, v226
	v_and_b32_e32 v73, 0xffff0000, v226
	v_lshlrev_b32_e32 v74, 16, v230
	v_and_b32_e32 v75, 0xffff0000, v230
	v_lshlrev_b32_e32 v58, 16, v227
	v_and_b32_e32 v59, 0xffff0000, v227
	v_lshlrev_b32_e32 v62, 16, v231
	v_and_b32_e32 v63, 0xffff0000, v231
	v_pk_add_f32 v[72:73], v[72:73], v[74:75]
	v_pk_add_f32 v[58:59], v[58:59], v[62:63]
	v_lshlrev_b32_e32 v62, 16, v228
	v_and_b32_e32 v63, 0xffff0000, v228
	v_lshlrev_b32_e32 v74, 16, v232
	v_and_b32_e32 v75, 0xffff0000, v232
	v_lshlrev_b32_e32 v60, 16, v229
	v_and_b32_e32 v61, 0xffff0000, v229
	v_lshlrev_b32_e32 v64, 16, v233
	v_and_b32_e32 v65, 0xffff0000, v233
	v_add_u32_e32 v251, 0x58000, v249
	global_load_dwordx4 v[226:229], v251, s[66:67]
	global_load_dwordx4 v[230:233], v251, s[64:65]
	v_pk_add_f32 v[62:63], v[62:63], v[74:75]
	v_pk_add_f32 v[60:61], v[60:61], v[64:65]
	v_pk_add_f32 v[56:57], v[56:57], v[58:59]
	v_pk_add_f32 v[54:55], v[54:55], v[72:73]
	v_pk_add_f32 v[58:59], v[52:53], v[60:61]
	v_pk_add_f32 v[60:61], v[50:51], v[62:63]
	v_cvt_pk_bf16_f32 v50, v54, v55
	v_cvt_pk_bf16_f32 v51, v56, v57
	v_lshlrev_b32_e32 v52, 16, v50
	v_and_b32_e32 v53, 0xffff0000, v50
	v_lshlrev_b32_e32 v62, 16, v51
	v_and_b32_e32 v63, 0xffff0000, v51
	v_sub_f32_e32 v56, v56, v62
	v_sub_f32_e32 v57, v57, v63
	v_sub_f32_e32 v54, v54, v52
	v_sub_f32_e32 v55, v55, v53
	v_cvt_pk_bf16_f32 v54, v54, v55
	v_cvt_pk_bf16_f32 v55, v56, v57
	v_lshlrev_b32_e32 v56, 16, v54
	v_and_b32_e32 v57, 0xffff0000, v54
	v_lshlrev_b32_e32 v64, 16, v55
	v_and_b32_e32 v65, 0xffff0000, v55
	v_pk_add_f32 v[62:63], v[62:63], v[64:65]
	v_pk_add_f32 v[64:65], v[52:53], v[56:57]
	v_cvt_pk_bf16_f32 v52, v60, v61
	v_cvt_pk_bf16_f32 v53, v58, v59
	v_lshlrev_b32_e32 v72, 16, v52
	v_and_b32_e32 v73, 0xffff0000, v52
	v_lshlrev_b32_e32 v74, 16, v53
	v_and_b32_e32 v75, 0xffff0000, v53
	v_sub_f32_e32 v57, v58, v74
	v_sub_f32_e32 v58, v59, v75
	v_sub_f32_e32 v56, v60, v72
	v_sub_f32_e32 v59, v61, v73
	v_cvt_pk_bf16_f32 v56, v56, v59
	v_cvt_pk_bf16_f32 v57, v57, v58
	global_store_dwordx4 v[66:67], v[50:53], off offset:256
	global_store_dwordx4 v[68:69], v[54:57], off offset:256
	v_lshlrev_b32_e32 v58, 16, v56
	v_and_b32_e32 v59, 0xffff0000, v56
	v_mul_f32_e32 v50, v65, v65
	v_mul_f32_e32 v51, v63, v63
	v_pk_add_f32 v[58:59], v[72:73], v[58:59]
	v_fmac_f32_e32 v50, v64, v64
	v_fmac_f32_e32 v51, v62, v62
	v_lshlrev_b32_e32 v60, 16, v57
	v_and_b32_e32 v61, 0xffff0000, v57
	v_add_f32_e32 v50, v50, v51
	v_mul_f32_e32 v51, v59, v59
	v_pk_add_f32 v[60:61], v[74:75], v[60:61]
	v_fmac_f32_e32 v51, v58, v58
	v_add_f32_e32 v50, v50, v51
	v_mul_f32_e32 v51, v61, v61
	v_fmac_f32_e32 v51, v60, v60
	v_add_f32_e32 v50, v51, v50
	v_add_f32_e32 v50, v76, v50
	ds_bpermute_b32 v51, v204, v50
	s_waitcnt lgkmcnt(0)
	v_add_f32_e32 v54, v50, v51
	v_add_u32_e32 v50, 0x90, v144
	v_ashrrev_i32_e32 v51, 31, v50
	v_lshlrev_b64 v[52:53], 11, v[50:51]
	v_lshl_add_u64 v[50:51], s[66:67], 0, v[52:53]
	v_lshl_add_u64 v[50:51], v[50:51], 0, v[142:143]
	v_lshl_add_u64 v[52:53], s[64:65], 0, v[52:53]
	v_lshl_add_u64 v[52:53], v[52:53], 0, v[142:143]
	ds_bpermute_b32 v55, v205, v54
	s_waitcnt vmcnt(18)
	v_lshlrev_b32_e32 v64, 16, v170
	v_and_b32_e32 v65, 0xffff0000, v170
	v_lshlrev_b32_e32 v66, 16, v174
	v_and_b32_e32 v67, 0xffff0000, v174
	v_lshlrev_b32_e32 v56, 16, v171
	v_and_b32_e32 v57, 0xffff0000, v171
	v_lshlrev_b32_e32 v60, 16, v175
	v_and_b32_e32 v61, 0xffff0000, v175
	v_pk_add_f32 v[64:65], v[64:65], v[66:67]
	v_pk_add_f32 v[56:57], v[56:57], v[60:61]
	v_lshlrev_b32_e32 v60, 16, v172
	v_and_b32_e32 v61, 0xffff0000, v172
	v_lshlrev_b32_e32 v66, 16, v176
	v_and_b32_e32 v67, 0xffff0000, v176
	v_lshlrev_b32_e32 v58, 16, v173
	v_and_b32_e32 v59, 0xffff0000, v173
	v_lshlrev_b32_e32 v62, 16, v177
	v_and_b32_e32 v63, 0xffff0000, v177
	v_add_u32_e32 v250, 0x58000, v249
	global_load_dwordx4 v[170:173], v250, s[66:67] offset:256
	global_load_dwordx4 v[174:177], v250, s[64:65] offset:256
	v_pk_add_f32 v[60:61], v[60:61], v[66:67]
	v_pk_add_f32 v[58:59], v[58:59], v[62:63]
	v_pk_add_f32 v[48:49], v[48:49], v[56:57]
	v_pk_add_f32 v[46:47], v[46:47], v[64:65]
	v_pk_add_f32 v[56:57], v[44:45], v[58:59]
	v_pk_add_f32 v[58:59], v[42:43], v[60:61]
	v_cvt_pk_bf16_f32 v42, v46, v47
	v_cvt_pk_bf16_f32 v43, v48, v49
	v_lshlrev_b32_e32 v44, 16, v42
	v_and_b32_e32 v45, 0xffff0000, v42
	v_lshlrev_b32_e32 v60, 16, v43
	v_and_b32_e32 v61, 0xffff0000, v43
	v_sub_f32_e32 v48, v48, v60
	v_sub_f32_e32 v49, v49, v61
	v_sub_f32_e32 v46, v46, v44
	v_sub_f32_e32 v47, v47, v45
	v_cvt_pk_bf16_f32 v46, v46, v47
	v_cvt_pk_bf16_f32 v47, v48, v49
	v_lshlrev_b32_e32 v48, 16, v46
	v_and_b32_e32 v49, 0xffff0000, v46
	v_lshlrev_b32_e32 v62, 16, v47
	v_and_b32_e32 v63, 0xffff0000, v47
	v_pk_add_f32 v[60:61], v[60:61], v[62:63]
	v_pk_add_f32 v[62:63], v[44:45], v[48:49]
	v_cvt_pk_bf16_f32 v44, v58, v59
	v_cvt_pk_bf16_f32 v45, v56, v57
	v_lshlrev_b32_e32 v64, 16, v44
	v_and_b32_e32 v65, 0xffff0000, v44
	v_lshlrev_b32_e32 v66, 16, v45
	v_and_b32_e32 v67, 0xffff0000, v45
	v_sub_f32_e32 v49, v56, v66
	v_sub_f32_e32 v56, v57, v67
	v_sub_f32_e32 v48, v58, v64
	v_sub_f32_e32 v57, v59, v65
	v_cvt_pk_bf16_f32 v48, v48, v57
	v_cvt_pk_bf16_f32 v49, v49, v56
	global_store_dwordx4 v[50:51], v[42:45], off
	global_store_dwordx4 v[52:53], v[46:49], off
	v_lshlrev_b32_e32 v56, 16, v48
	v_and_b32_e32 v57, 0xffff0000, v48
	v_mul_f32_e32 v42, v63, v63
	v_mul_f32_e32 v43, v61, v61
	v_pk_add_f32 v[56:57], v[64:65], v[56:57]
	v_fmac_f32_e32 v42, v62, v62
	v_fmac_f32_e32 v43, v60, v60
	v_lshlrev_b32_e32 v58, 16, v49
	v_and_b32_e32 v59, 0xffff0000, v49
	v_add_f32_e32 v42, v42, v43
	v_mul_f32_e32 v43, v57, v57
	v_pk_add_f32 v[58:59], v[66:67], v[58:59]
	v_fmac_f32_e32 v43, v56, v56
	v_add_f32_e32 v42, v42, v43
	v_mul_f32_e32 v43, v59, v59
	v_fmac_f32_e32 v43, v58, v58
	v_add_f32_e32 v60, v43, v42
	s_waitcnt vmcnt(18)
	v_lshlrev_b32_e32 v56, 16, v178
	v_and_b32_e32 v57, 0xffff0000, v178
	v_lshlrev_b32_e32 v58, 16, v190
	v_and_b32_e32 v59, 0xffff0000, v190
	v_lshlrev_b32_e32 v42, 16, v179
	v_and_b32_e32 v43, 0xffff0000, v179
	v_lshlrev_b32_e32 v46, 16, v191
	v_and_b32_e32 v47, 0xffff0000, v191
	v_pk_add_f32 v[56:57], v[56:57], v[58:59]
	v_pk_add_f32 v[42:43], v[42:43], v[46:47]
	v_lshlrev_b32_e32 v46, 16, v180
	v_and_b32_e32 v47, 0xffff0000, v180
	v_lshlrev_b32_e32 v58, 16, v192
	v_and_b32_e32 v59, 0xffff0000, v192
	v_lshlrev_b32_e32 v44, 16, v181
	v_and_b32_e32 v45, 0xffff0000, v181
	v_lshlrev_b32_e32 v48, 16, v193
	v_and_b32_e32 v49, 0xffff0000, v193
	v_pk_add_f32 v[46:47], v[46:47], v[58:59]
	v_pk_add_f32 v[44:45], v[44:45], v[48:49]
	v_pk_add_f32 v[40:41], v[40:41], v[42:43]
	v_pk_add_f32 v[38:39], v[38:39], v[56:57]
	v_pk_add_f32 v[42:43], v[36:37], v[44:45]
	v_pk_add_f32 v[44:45], v[34:35], v[46:47]
	v_cvt_pk_bf16_f32 v34, v38, v39
	v_cvt_pk_bf16_f32 v35, v40, v41
	v_lshlrev_b32_e32 v36, 16, v34
	v_and_b32_e32 v37, 0xffff0000, v34
	v_lshlrev_b32_e32 v46, 16, v35
	v_and_b32_e32 v47, 0xffff0000, v35
	v_sub_f32_e32 v40, v40, v46
	v_sub_f32_e32 v41, v41, v47
	v_sub_f32_e32 v38, v38, v36
	v_sub_f32_e32 v39, v39, v37
	v_cvt_pk_bf16_f32 v38, v38, v39
	v_cvt_pk_bf16_f32 v39, v40, v41
	v_lshlrev_b32_e32 v40, 16, v38
	v_and_b32_e32 v41, 0xffff0000, v38
	v_lshlrev_b32_e32 v48, 16, v39
	v_and_b32_e32 v49, 0xffff0000, v39
	v_pk_add_f32 v[46:47], v[46:47], v[48:49]
	v_pk_add_f32 v[48:49], v[36:37], v[40:41]
	v_cvt_pk_bf16_f32 v36, v44, v45
	v_cvt_pk_bf16_f32 v37, v42, v43
	v_lshlrev_b32_e32 v56, 16, v36
	v_and_b32_e32 v57, 0xffff0000, v36
	v_lshlrev_b32_e32 v58, 16, v37
	v_and_b32_e32 v59, 0xffff0000, v37
	v_sub_f32_e32 v41, v42, v58
	v_sub_f32_e32 v42, v43, v59
	v_sub_f32_e32 v40, v44, v56
	v_sub_f32_e32 v43, v45, v57
	v_cvt_pk_bf16_f32 v40, v40, v43
	v_cvt_pk_bf16_f32 v41, v41, v42
	global_store_dwordx4 v[50:51], v[34:37], off offset:256
	global_store_dwordx4 v[52:53], v[38:41], off offset:256
	v_lshlrev_b32_e32 v42, 16, v40
	v_and_b32_e32 v43, 0xffff0000, v40
	v_mul_f32_e32 v34, v49, v49
	v_mul_f32_e32 v35, v47, v47
	v_pk_add_f32 v[42:43], v[56:57], v[42:43]
	v_fmac_f32_e32 v34, v48, v48
	v_fmac_f32_e32 v35, v46, v46
	v_add_u32_e32 v36, 0xa0, v144
	v_lshlrev_b32_e32 v44, 16, v41
	v_and_b32_e32 v45, 0xffff0000, v41
	v_add_f32_e32 v34, v34, v35
	v_mul_f32_e32 v35, v43, v43
	v_ashrrev_i32_e32 v37, 31, v36
	v_pk_add_f32 v[44:45], v[58:59], v[44:45]
	v_fmac_f32_e32 v35, v42, v42
	v_lshlrev_b64 v[36:37], 11, v[36:37]
	v_add_f32_e32 v34, v34, v35
	v_mul_f32_e32 v35, v45, v45
	v_lshl_add_u64 v[38:39], s[66:67], 0, v[36:37]
	v_fmac_f32_e32 v35, v44, v44
	v_lshl_add_u64 v[44:45], v[38:39], 0, v[142:143]
	v_lshl_add_u64 v[36:37], s[64:65], 0, v[36:37]
	v_lshl_add_u64 v[46:47], v[36:37], 0, v[142:143]
	v_add_f32_e32 v34, v35, v34
	v_add_f32_e32 v34, v60, v34
	ds_bpermute_b32 v35, v204, v34
	s_waitcnt lgkmcnt(0)
	v_add_f32_e32 v34, v34, v35
	ds_bpermute_b32 v35, v205, v34
	s_waitcnt vmcnt(16)
	v_lshlrev_b32_e32 v48, 16, v194
	v_and_b32_e32 v49, 0xffff0000, v194
	v_lshlrev_b32_e32 v50, 16, v214
	v_and_b32_e32 v51, 0xffff0000, v214
	v_lshlrev_b32_e32 v36, 16, v195
	v_and_b32_e32 v37, 0xffff0000, v195
	v_lshlrev_b32_e32 v40, 16, v215
	v_and_b32_e32 v41, 0xffff0000, v215
	v_pk_add_f32 v[48:49], v[48:49], v[50:51]
	v_pk_add_f32 v[36:37], v[36:37], v[40:41]
	v_lshlrev_b32_e32 v40, 16, v196
	v_and_b32_e32 v41, 0xffff0000, v196
	v_lshlrev_b32_e32 v50, 16, v216
	v_and_b32_e32 v51, 0xffff0000, v216
	v_lshlrev_b32_e32 v38, 16, v197
	v_and_b32_e32 v39, 0xffff0000, v197
	v_lshlrev_b32_e32 v42, 16, v217
	v_and_b32_e32 v43, 0xffff0000, v217
	v_pk_add_f32 v[40:41], v[40:41], v[50:51]
	v_pk_add_f32 v[38:39], v[38:39], v[42:43]
	v_pk_add_f32 v[32:33], v[32:33], v[36:37]
	v_pk_add_f32 v[30:31], v[30:31], v[48:49]
	v_pk_add_f32 v[36:37], v[28:29], v[38:39]
	v_pk_add_f32 v[38:39], v[26:27], v[40:41]
	v_cvt_pk_bf16_f32 v26, v30, v31
	v_cvt_pk_bf16_f32 v27, v32, v33
	v_lshlrev_b32_e32 v28, 16, v26
	v_and_b32_e32 v29, 0xffff0000, v26
	v_lshlrev_b32_e32 v40, 16, v27
	v_and_b32_e32 v41, 0xffff0000, v27
	v_sub_f32_e32 v32, v32, v40
	v_sub_f32_e32 v33, v33, v41
	v_sub_f32_e32 v30, v30, v28
	v_sub_f32_e32 v31, v31, v29
	v_cvt_pk_bf16_f32 v30, v30, v31
	v_cvt_pk_bf16_f32 v31, v32, v33
	v_lshlrev_b32_e32 v32, 16, v30
	v_and_b32_e32 v33, 0xffff0000, v30
	v_lshlrev_b32_e32 v42, 16, v31
	v_and_b32_e32 v43, 0xffff0000, v31
	v_pk_add_f32 v[40:41], v[40:41], v[42:43]
	v_pk_add_f32 v[42:43], v[28:29], v[32:33]
	v_cvt_pk_bf16_f32 v28, v38, v39
	v_cvt_pk_bf16_f32 v29, v36, v37
	v_lshlrev_b32_e32 v48, 16, v28
	v_and_b32_e32 v49, 0xffff0000, v28
	v_lshlrev_b32_e32 v50, 16, v29
	v_and_b32_e32 v51, 0xffff0000, v29
	v_sub_f32_e32 v33, v36, v50
	v_sub_f32_e32 v36, v37, v51
	v_sub_f32_e32 v32, v38, v48
	v_sub_f32_e32 v37, v39, v49
	v_cvt_pk_bf16_f32 v32, v32, v37
	v_cvt_pk_bf16_f32 v33, v33, v36
	global_store_dwordx4 v[44:45], v[26:29], off
	global_store_dwordx4 v[46:47], v[30:33], off
	v_lshlrev_b32_e32 v36, 16, v32
	v_and_b32_e32 v37, 0xffff0000, v32
	v_mul_f32_e32 v26, v43, v43
	v_mul_f32_e32 v27, v41, v41
	v_pk_add_f32 v[36:37], v[48:49], v[36:37]
	v_fmac_f32_e32 v26, v42, v42
	v_fmac_f32_e32 v27, v40, v40
	v_lshlrev_b32_e32 v38, 16, v33
	v_and_b32_e32 v39, 0xffff0000, v33
	v_add_f32_e32 v26, v26, v27
	v_mul_f32_e32 v27, v37, v37
	v_pk_add_f32 v[38:39], v[50:51], v[38:39]
	v_fmac_f32_e32 v27, v36, v36
	v_add_f32_e32 v26, v26, v27
	v_mul_f32_e32 v27, v39, v39
	v_fmac_f32_e32 v27, v38, v38
	v_add_f32_e32 v40, v27, v26
	s_waitcnt vmcnt(14)
	v_lshlrev_b32_e32 v36, 16, v218
	v_and_b32_e32 v37, 0xffff0000, v218
	v_lshlrev_b32_e32 v38, 16, v222
	v_and_b32_e32 v39, 0xffff0000, v222
	v_lshlrev_b32_e32 v26, 16, v219
	v_and_b32_e32 v27, 0xffff0000, v219
	v_lshlrev_b32_e32 v30, 16, v223
	v_and_b32_e32 v31, 0xffff0000, v223
	v_pk_add_f32 v[36:37], v[36:37], v[38:39]
	v_pk_add_f32 v[26:27], v[26:27], v[30:31]
	v_lshlrev_b32_e32 v30, 16, v220
	v_and_b32_e32 v31, 0xffff0000, v220
	v_lshlrev_b32_e32 v38, 16, v224
	v_and_b32_e32 v39, 0xffff0000, v224
	v_lshlrev_b32_e32 v28, 16, v221
	v_and_b32_e32 v29, 0xffff0000, v221
	v_lshlrev_b32_e32 v32, 16, v225
	v_and_b32_e32 v33, 0xffff0000, v225
	v_pk_add_f32 v[30:31], v[30:31], v[38:39]
	v_pk_add_f32 v[28:29], v[28:29], v[32:33]
	v_pk_add_f32 v[24:25], v[24:25], v[26:27]
	v_pk_add_f32 v[22:23], v[22:23], v[36:37]
	v_pk_add_f32 v[26:27], v[20:21], v[28:29]
	v_pk_add_f32 v[28:29], v[18:19], v[30:31]
	v_cvt_pk_bf16_f32 v18, v22, v23
	v_cvt_pk_bf16_f32 v19, v24, v25
	v_lshlrev_b32_e32 v20, 16, v18
	v_and_b32_e32 v21, 0xffff0000, v18
	v_lshlrev_b32_e32 v30, 16, v19
	v_and_b32_e32 v31, 0xffff0000, v19
	v_sub_f32_e32 v24, v24, v30
	v_sub_f32_e32 v25, v25, v31
	v_sub_f32_e32 v22, v22, v20
	v_sub_f32_e32 v23, v23, v21
	v_cvt_pk_bf16_f32 v22, v22, v23
	v_cvt_pk_bf16_f32 v23, v24, v25
	v_lshlrev_b32_e32 v24, 16, v22
	v_and_b32_e32 v25, 0xffff0000, v22
	v_lshlrev_b32_e32 v32, 16, v23
	v_and_b32_e32 v33, 0xffff0000, v23
	v_pk_add_f32 v[30:31], v[30:31], v[32:33]
	v_pk_add_f32 v[32:33], v[20:21], v[24:25]
	v_cvt_pk_bf16_f32 v20, v28, v29
	v_cvt_pk_bf16_f32 v21, v26, v27
	v_lshlrev_b32_e32 v36, 16, v20
	v_and_b32_e32 v37, 0xffff0000, v20
	v_lshlrev_b32_e32 v38, 16, v21
	v_and_b32_e32 v39, 0xffff0000, v21
	v_sub_f32_e32 v25, v26, v38
	v_sub_f32_e32 v26, v27, v39
	v_sub_f32_e32 v24, v28, v36
	v_sub_f32_e32 v27, v29, v37
	v_cvt_pk_bf16_f32 v24, v24, v27
	v_cvt_pk_bf16_f32 v25, v25, v26
	global_store_dwordx4 v[44:45], v[18:21], off offset:256
	global_store_dwordx4 v[46:47], v[22:25], off offset:256
	v_lshlrev_b32_e32 v26, 16, v24
	v_and_b32_e32 v27, 0xffff0000, v24
	v_mul_f32_e32 v18, v33, v33
	v_mul_f32_e32 v19, v31, v31
	v_pk_add_f32 v[26:27], v[36:37], v[26:27]
	v_fmac_f32_e32 v18, v32, v32
	v_fmac_f32_e32 v19, v30, v30
	v_lshlrev_b32_e32 v28, 16, v25
	v_and_b32_e32 v29, 0xffff0000, v25
	v_add_f32_e32 v18, v18, v19
	v_mul_f32_e32 v19, v27, v27
	v_pk_add_f32 v[28:29], v[38:39], v[28:29]
	v_fmac_f32_e32 v19, v26, v26
	v_add_f32_e32 v18, v18, v19
	v_mul_f32_e32 v19, v29, v29
	v_fmac_f32_e32 v19, v28, v28
	v_add_f32_e32 v18, v19, v18
	v_add_f32_e32 v18, v40, v18
	ds_bpermute_b32 v19, v204, v18
	s_waitcnt lgkmcnt(0)
	v_add_f32_e32 v30, v18, v19
	v_add_u32_e32 v18, 0xb0, v144
	v_ashrrev_i32_e32 v19, 31, v18
	v_lshlrev_b64 v[18:19], 11, v[18:19]
	v_lshl_add_u64 v[20:21], s[66:67], 0, v[18:19]
	v_lshl_add_u64 v[26:27], v[20:21], 0, v[142:143]
	v_lshl_add_u64 v[18:19], s[64:65], 0, v[18:19]
	v_lshl_add_u64 v[28:29], v[18:19], 0, v[142:143]
	ds_bpermute_b32 v31, v205, v30
	s_waitcnt vmcnt(12)
	v_lshlrev_b32_e32 v32, 16, v226
	v_and_b32_e32 v33, 0xffff0000, v226
	v_lshlrev_b32_e32 v36, 16, v230
	v_and_b32_e32 v37, 0xffff0000, v230
	v_lshlrev_b32_e32 v18, 16, v227
	v_and_b32_e32 v19, 0xffff0000, v227
	v_lshlrev_b32_e32 v22, 16, v231
	v_and_b32_e32 v23, 0xffff0000, v231
	v_pk_add_f32 v[32:33], v[32:33], v[36:37]
	v_pk_add_f32 v[18:19], v[18:19], v[22:23]
	v_lshlrev_b32_e32 v22, 16, v228
	v_and_b32_e32 v23, 0xffff0000, v228
	v_lshlrev_b32_e32 v36, 16, v232
	v_and_b32_e32 v37, 0xffff0000, v232
	v_lshlrev_b32_e32 v20, 16, v229
	v_and_b32_e32 v21, 0xffff0000, v229
	v_lshlrev_b32_e32 v24, 16, v233
	v_and_b32_e32 v25, 0xffff0000, v233
	v_pk_add_f32 v[22:23], v[22:23], v[36:37]
	v_pk_add_f32 v[20:21], v[20:21], v[24:25]
	v_pk_add_f32 v[16:17], v[16:17], v[18:19]
	v_pk_add_f32 v[14:15], v[14:15], v[32:33]
	v_pk_add_f32 v[18:19], v[12:13], v[20:21]
	v_pk_add_f32 v[20:21], v[10:11], v[22:23]
	v_cvt_pk_bf16_f32 v10, v14, v15
	v_cvt_pk_bf16_f32 v11, v16, v17
	v_lshlrev_b32_e32 v12, 16, v10
	v_and_b32_e32 v13, 0xffff0000, v10
	v_lshlrev_b32_e32 v22, 16, v11
	v_and_b32_e32 v23, 0xffff0000, v11
	v_sub_f32_e32 v16, v16, v22
	v_sub_f32_e32 v17, v17, v23
	v_sub_f32_e32 v14, v14, v12
	v_sub_f32_e32 v15, v15, v13
	v_cvt_pk_bf16_f32 v14, v14, v15
	v_cvt_pk_bf16_f32 v15, v16, v17
	v_lshlrev_b32_e32 v16, 16, v14
	v_and_b32_e32 v17, 0xffff0000, v14
	v_lshlrev_b32_e32 v24, 16, v15
	v_and_b32_e32 v25, 0xffff0000, v15
	v_pk_add_f32 v[22:23], v[22:23], v[24:25]
	v_pk_add_f32 v[24:25], v[12:13], v[16:17]
	v_cvt_pk_bf16_f32 v12, v20, v21
	v_cvt_pk_bf16_f32 v13, v18, v19
	v_lshlrev_b32_e32 v32, 16, v12
	v_and_b32_e32 v33, 0xffff0000, v12
	v_lshlrev_b32_e32 v36, 16, v13
	v_and_b32_e32 v37, 0xffff0000, v13
	v_sub_f32_e32 v17, v18, v36
	v_sub_f32_e32 v18, v19, v37
	v_sub_f32_e32 v16, v20, v32
	v_sub_f32_e32 v19, v21, v33
	v_cvt_pk_bf16_f32 v16, v16, v19
	v_cvt_pk_bf16_f32 v17, v17, v18
	global_store_dwordx4 v[26:27], v[10:13], off
	global_store_dwordx4 v[28:29], v[14:17], off
	v_lshlrev_b32_e32 v18, 16, v16
	v_and_b32_e32 v19, 0xffff0000, v16
	v_mul_f32_e32 v10, v25, v25
	v_mul_f32_e32 v11, v23, v23
	v_pk_add_f32 v[18:19], v[32:33], v[18:19]
	v_fmac_f32_e32 v10, v24, v24
	v_fmac_f32_e32 v11, v22, v22
	v_lshlrev_b32_e32 v20, 16, v17
	v_and_b32_e32 v21, 0xffff0000, v17
	v_add_f32_e32 v10, v10, v11
	v_mul_f32_e32 v11, v19, v19
	v_pk_add_f32 v[20:21], v[36:37], v[20:21]
	v_fmac_f32_e32 v11, v18, v18
	v_add_f32_e32 v10, v10, v11
	v_mul_f32_e32 v11, v21, v21
	v_fmac_f32_e32 v11, v20, v20
	v_add_f32_e32 v18, v11, v10
	s_waitcnt vmcnt(10)
	v_lshlrev_b32_e32 v20, 16, v170
	v_and_b32_e32 v21, 0xffff0000, v170
	v_lshlrev_b32_e32 v22, 16, v174
	v_and_b32_e32 v23, 0xffff0000, v174
	v_lshlrev_b32_e32 v10, 16, v171
	v_and_b32_e32 v11, 0xffff0000, v171
	v_lshlrev_b32_e32 v14, 16, v175
	v_and_b32_e32 v15, 0xffff0000, v175
	v_pk_add_f32 v[20:21], v[20:21], v[22:23]
	v_pk_add_f32 v[10:11], v[10:11], v[14:15]
	v_lshlrev_b32_e32 v14, 16, v172
	v_and_b32_e32 v15, 0xffff0000, v172
	v_lshlrev_b32_e32 v22, 16, v176
	v_and_b32_e32 v23, 0xffff0000, v176
	v_lshlrev_b32_e32 v12, 16, v173
	v_and_b32_e32 v13, 0xffff0000, v173
	v_lshlrev_b32_e32 v16, 16, v177
	v_and_b32_e32 v17, 0xffff0000, v177
	v_pk_add_f32 v[14:15], v[14:15], v[22:23]
	v_pk_add_f32 v[12:13], v[12:13], v[16:17]
	v_pk_add_f32 v[8:9], v[8:9], v[10:11]
	v_pk_add_f32 v[6:7], v[6:7], v[20:21]
	v_pk_add_f32 v[10:11], v[4:5], v[12:13]
	v_pk_add_f32 v[12:13], v[2:3], v[14:15]
	v_cvt_pk_bf16_f32 v2, v6, v7
	v_cvt_pk_bf16_f32 v3, v8, v9
	v_lshlrev_b32_e32 v4, 16, v2
	v_and_b32_e32 v5, 0xffff0000, v2
	v_lshlrev_b32_e32 v14, 16, v3
	v_and_b32_e32 v15, 0xffff0000, v3
	v_sub_f32_e32 v8, v8, v14
	v_sub_f32_e32 v9, v9, v15
	v_sub_f32_e32 v6, v6, v4
	v_sub_f32_e32 v7, v7, v5
	v_cvt_pk_bf16_f32 v6, v6, v7
	v_cvt_pk_bf16_f32 v7, v8, v9
	v_lshlrev_b32_e32 v8, 16, v6
	v_and_b32_e32 v9, 0xffff0000, v6
	v_lshlrev_b32_e32 v16, 16, v7
	v_and_b32_e32 v17, 0xffff0000, v7
	v_pk_add_f32 v[14:15], v[14:15], v[16:17]
	v_pk_add_f32 v[16:17], v[4:5], v[8:9]
	v_cvt_pk_bf16_f32 v4, v12, v13
	v_cvt_pk_bf16_f32 v5, v10, v11
	v_lshlrev_b32_e32 v20, 16, v4
	v_and_b32_e32 v21, 0xffff0000, v4
	v_lshlrev_b32_e32 v22, 16, v5
	v_and_b32_e32 v23, 0xffff0000, v5
	v_sub_f32_e32 v9, v10, v22
	v_sub_f32_e32 v10, v11, v23
	v_sub_f32_e32 v8, v12, v20
	v_sub_f32_e32 v11, v13, v21
	v_cvt_pk_bf16_f32 v8, v8, v11
	v_cvt_pk_bf16_f32 v9, v9, v10
	global_store_dwordx4 v[26:27], v[2:5], off offset:256
	global_store_dwordx4 v[28:29], v[6:9], off offset:256
	v_lshlrev_b32_e32 v10, 16, v8
	v_and_b32_e32 v11, 0xffff0000, v8
	v_mul_f32_e32 v2, v17, v17
	v_mul_f32_e32 v3, v15, v15
	v_pk_add_f32 v[10:11], v[20:21], v[10:11]
	v_fmac_f32_e32 v2, v16, v16
	v_fmac_f32_e32 v3, v14, v14
	v_lshlrev_b32_e32 v12, 16, v9
	v_and_b32_e32 v13, 0xffff0000, v9
	v_add_f32_e32 v2, v2, v3
	v_mul_f32_e32 v3, v11, v11
	v_pk_add_f32 v[12:13], v[22:23], v[12:13]
	v_fmac_f32_e32 v3, v10, v10
	v_add_f32_e32 v2, v2, v3
	v_mul_f32_e32 v3, v13, v13
	v_fmac_f32_e32 v3, v12, v12
	v_add_f32_e32 v2, v3, v2
	v_add_f32_e32 v2, v18, v2
	ds_bpermute_b32 v3, v204, v2
	s_waitcnt lgkmcnt(0)
	v_add_f32_e32 v2, v2, v3
	ds_bpermute_b32 v3, v205, v2
	s_and_saveexec_b64 s[24:25], s[10:11]
	s_cbranch_execz .LBB11_1634
	s_ashr_i32 s23, s22, 31
	s_lshl_b64 s[0:1], s[22:23], 2
	s_add_u32 s0, s28, s0
	v_ashrrev_i32_e32 v141, 31, v140
	s_addc_u32 s1, s29, s1
	s_waitcnt lgkmcnt(0)
	v_add_f32_e32 v4, v2, v3
	v_add_f32_e32 v11, v118, v119
	v_lshl_add_u64 v[2:3], v[140:141], 2, s[0:1]
	v_add_f32_e32 v5, v30, v31
	v_add_f32_e32 v6, v34, v35
	v_add_f32_e32 v7, v54, v55
	v_add_f32_e32 v8, v70, v71
	v_add_f32_e32 v9, v86, v87
	v_add_f32_e32 v10, v102, v103
	global_atomic_add_f32 v[2:3], v11, off
	global_atomic_add_f32 v[2:3], v10, off offset:64
	global_atomic_add_f32 v[2:3], v9, off offset:128
	global_atomic_add_f32 v[2:3], v8, off offset:192
	global_atomic_add_f32 v[2:3], v7, off offset:512
	global_atomic_add_f32 v[2:3], v6, off offset:576
	global_atomic_add_f32 v[2:3], v5, off offset:640
	global_atomic_add_f32 v[2:3], v4, off offset:704

.LBB11_1762:
	s_or_b64 exec, exec, s[30:31]
	s_waitcnt lgkmcnt(0)
	s_waitcnt lgkmcnt(0)
	s_barrier
	ds_read_b128 v[140:143], v138
	v_readlane_b32 s0, v243, 0
	s_andn2_b64 vcc, exec, s[2:3]
	s_waitcnt vmcnt(15) lgkmcnt(0)
	v_mfma_f32_16x16x32_bf16 v[94:97], v[140:143], v[94:97], 0
	ds_read_b128 v[140:143], v138 offset:64
	v_add_u32_e32 v0, s0, v118
	s_waitcnt vmcnt(14) lgkmcnt(0)
	v_mfma_f32_16x16x32_bf16 v[90:93], v[140:143], v[90:93], v[94:97]
	s_nop 3
	ds_read_b128 v[94:97], v138 offset:128
	s_waitcnt vmcnt(13) lgkmcnt(0)
	v_mfma_f32_16x16x32_bf16 v[86:89], v[94:97], v[86:89], v[90:93]
	s_nop 2
	ds_read_b128 v[90:93], v138 offset:192
	s_waitcnt vmcnt(12) lgkmcnt(0)
	v_mfma_f32_16x16x32_bf16 v[82:85], v[90:93], v[82:85], v[86:89]
	s_nop 2
	ds_read_b128 v[86:89], v138 offset:256
	s_waitcnt vmcnt(11) lgkmcnt(0)
	v_mfma_f32_16x16x32_bf16 v[78:81], v[86:89], v[78:81], v[82:85]
	s_nop 2
	ds_read_b128 v[82:85], v138 offset:320
	s_waitcnt vmcnt(10) lgkmcnt(0)
	v_mfma_f32_16x16x32_bf16 v[74:77], v[82:85], v[74:77], v[78:81]
	s_nop 2
	ds_read_b128 v[78:81], v138 offset:384
	s_waitcnt vmcnt(9) lgkmcnt(0)
	v_mfma_f32_16x16x32_bf16 v[70:73], v[78:81], v[70:73], v[74:77]
	s_nop 2
	ds_read_b128 v[74:77], v138 offset:448
	s_waitcnt vmcnt(8) lgkmcnt(0)
	v_mfma_f32_16x16x32_bf16 v[66:69], v[74:77], v[66:69], v[70:73]
	s_nop 2
	ds_read_b128 v[70:73], v138 offset:512
	s_waitcnt vmcnt(7) lgkmcnt(0)
	v_mfma_f32_16x16x32_bf16 v[62:65], v[70:73], v[62:65], v[66:69]
	s_nop 2
	ds_read_b128 v[66:69], v138 offset:576
	s_waitcnt vmcnt(6) lgkmcnt(0)
	v_mfma_f32_16x16x32_bf16 v[58:61], v[66:69], v[58:61], v[62:65]
	s_nop 2
	ds_read_b128 v[62:65], v138 offset:640
	s_waitcnt vmcnt(5) lgkmcnt(0)
	v_mfma_f32_16x16x32_bf16 v[54:57], v[62:65], v[54:57], v[58:61]
	s_nop 2
	ds_read_b128 v[58:61], v138 offset:704
	s_waitcnt vmcnt(4) lgkmcnt(0)
	v_mfma_f32_16x16x32_bf16 v[50:53], v[58:61], v[50:53], v[54:57]
	s_nop 2
	ds_read_b128 v[54:57], v138 offset:768
	s_waitcnt vmcnt(3) lgkmcnt(0)
	v_mfma_f32_16x16x32_bf16 v[46:49], v[54:57], v[46:49], v[50:53]
	s_nop 2
	ds_read_b128 v[50:53], v138 offset:832
	s_waitcnt vmcnt(2) lgkmcnt(0)
	v_mfma_f32_16x16x32_bf16 v[42:45], v[50:53], v[42:45], v[46:49]
	s_nop 2
	ds_read_b128 v[46:49], v138 offset:896
	s_waitcnt vmcnt(1) lgkmcnt(0)
	v_mfma_f32_16x16x32_bf16 v[38:41], v[46:49], v[38:41], v[42:45]
	s_nop 2
	ds_read_b128 v[42:45], v138 offset:960
	s_waitcnt vmcnt(0) lgkmcnt(0)
	v_mfma_f32_16x16x32_bf16 v[34:37], v[42:45], v[34:37], v[38:41]
	s_nop 7
	ds_write_b128 v0, v[34:37]
	s_waitcnt lgkmcnt(0)
	s_waitcnt lgkmcnt(0)
	s_barrier
	s_cbranch_vccnz .LBB11_1729
	v_readlane_b32 s0, v245, 40
	s_nop 1
	v_add_u32_e32 v0, s0, v118
	ds_read_b128 v[38:41], v0 offset:2048
	s_lshl_b32 s0, s9, 17
	s_waitcnt lgkmcnt(0)
	v_pk_add_f32 v[40:41], v[36:37], v[40:41]
	v_pk_add_f32 v[38:39], v[34:35], v[38:39]
	ds_read_b128 v[34:37], v0 offset:4096
	s_waitcnt lgkmcnt(0)
	v_pk_add_f32 v[40:41], v[40:41], v[36:37]
	v_pk_add_f32 v[38:39], v[38:39], v[34:35]
	ds_read_b128 v[34:37], v0 offset:6144
	v_subrev_u32_e32 v0, s0, v129
	s_waitcnt lgkmcnt(0)
	v_pk_add_f32 v[34:35], v[38:39], v[34:35]
	v_add_u32_e32 v38, s34, v119
	v_pk_add_f32 v[36:37], v[40:41], v[36:37]
	v_ashrrev_i32_e32 v39, 31, v38
	v_lshlrev_b64 v[40:41], 1, v[0:1]
	v_lshl_add_u64 v[42:43], s[66:67], 0, v[40:41]
	v_lshlrev_b64 v[38:39], 1, v[38:39]
	v_lshl_add_u64 v[42:43], v[42:43], 0, v[38:39]
	v_lshl_add_u64 v[40:41], s[64:65], 0, v[40:41]
	v_lshl_add_u64 v[38:39], v[40:41], 0, v[38:39]
	global_load_dwordx2 v[40:41], v[42:43], off
	global_load_dwordx2 v[44:45], v[38:39], off
	s_waitcnt vmcnt(1)
	v_lshlrev_b32_e32 v46, 16, v40
	v_and_b32_e32 v47, 0xffff0000, v40
	s_waitcnt vmcnt(0)
	v_lshlrev_b32_e32 v48, 16, v44
	v_and_b32_e32 v49, 0xffff0000, v44
	v_lshlrev_b32_e32 v40, 16, v41
	v_and_b32_e32 v41, 0xffff0000, v41
	v_lshlrev_b32_e32 v44, 16, v45
	v_and_b32_e32 v45, 0xffff0000, v45
	v_pk_add_f32 v[46:47], v[46:47], v[48:49]
	v_pk_add_f32 v[40:41], v[40:41], v[44:45]
	v_pk_add_f32 v[34:35], v[34:35], v[46:47]
	v_pk_add_f32 v[36:37], v[36:37], v[40:41]
	v_cvt_pk_bf16_f32 v40, v34, v35
	v_cvt_pk_bf16_f32 v41, v36, v37
	v_lshlrev_b32_e32 v44, 16, v40
	v_and_b32_e32 v45, 0xffff0000, v40
	v_lshlrev_b32_e32 v46, 16, v41
	v_and_b32_e32 v47, 0xffff0000, v41
	v_sub_f32_e32 v0, v36, v46
	v_sub_f32_e32 v36, v37, v47
	v_sub_f32_e32 v34, v34, v44
	v_sub_f32_e32 v35, v35, v45
	v_cvt_pk_bf16_f32 v34, v34, v35
	v_cvt_pk_bf16_f32 v35, v0, v36
	global_store_dwordx2 v[42:43], v[40:41], off sc1
	global_store_dwordx2 v[38:39], v[34:35], off sc1
	v_lshlrev_b32_e32 v36, 16, v34
	v_and_b32_e32 v37, 0xffff0000, v34
	v_lshlrev_b32_e32 v48, 16, v35
	v_and_b32_e32 v49, 0xffff0000, v35
	v_pk_add_f32 v[46:47], v[46:47], v[48:49]
	v_pk_add_f32 v[36:37], v[44:45], v[36:37]
	v_mul_f32_e32 v34, v47, v47
	v_mul_f32_e32 v0, v37, v37
	v_fmac_f32_e32 v0, v36, v36
	v_fmac_f32_e32 v34, v46, v46
	v_add_f32_e32 v0, v0, v34
	ds_bpermute_b32 v34, v204, v0
	s_waitcnt lgkmcnt(0)
	v_add_f32_e32 v34, v0, v34
	ds_bpermute_b32 v35, v205, v34
	s_and_saveexec_b64 s[30:31], s[10:11]
	s_cbranch_execz .LBB11_1728
	v_add_u32_e32 v0, 0x4000, v116
	v_lshl_add_u64 v[36:37], v[0:1], 2, s[28:29]
	s_waitcnt lgkmcnt(0)
	v_add_f32_e32 v0, v34, v35
	global_atomic_add_f32 v[36:37], v0, off
	s_branch .LBB11_1728

.LBB11_1874:
	s_or_b64 exec, exec, s[10:11]
	s_lshl_b32 s0, s39, 10
	v_mov_b32_e32 v140, v145
	v_mov_b32_e32 v142, v147
	s_add_i32 s0, s0, 0
	s_xor_b32 s39, s39, 1
	v_lshl_add_u32 v141, v140, 2, s0
	v_add_u32_e32 v151, 0x22000, v141
	ds_read_b32 v141, v151
	v_readlane_b32 s0, v245, 61
	v_lshl_add_u32 v140, s8, 8, v140
	s_lshl_b32 s0, s0, 8
	s_ashr_i32 s1, s0, 31
	s_waitcnt lgkmcnt(0)
	v_mul_f32_e32 v152, 0x3d800000, v141
	v_ashrrev_i32_e32 v141, 31, v140
	v_lshlrev_b64 v[154:155], 11, v[140:141]
	v_ashrrev_i32_e32 v143, 31, v142
	v_lshl_add_u64 v[154:155], s[78:79], 0, v[154:155]
	s_lshl_b64 s[10:11], s[0:1], 1
	v_lshl_add_u64 v[154:155], v[154:155], 0, s[10:11]
	v_lshlrev_b64 v[142:143], 1, v[142:143]
	v_lshl_add_u64 v[154:155], v[154:155], 0, v[142:143]
	v_pk_mul_f32 v[128:129], v[128:129], v[152:153] op_sel_hi:[1,0]
	v_pk_mul_f32 v[126:127], v[126:127], v[152:153] op_sel_hi:[1,0]
	v_pk_mul_f32 v[156:157], v[124:125], v[152:153] op_sel_hi:[1,0]
	v_pk_mul_f32 v[124:125], v[122:123], v[152:153] op_sel_hi:[1,0]
	v_cvt_pk_bf16_f32 v122, v126, v127
	v_cvt_pk_bf16_f32 v123, v128, v129
	v_pk_mul_f32 v[118:119], v[118:119], v[152:153] op_sel_hi:[1,0]
	v_cvt_pk_bf16_f32 v124, v124, v125
	v_cvt_pk_bf16_f32 v125, v156, v157
	global_store_dwordx4 v[154:155], v[122:125], off
	v_pk_mul_f32 v[120:121], v[120:121], v[152:153] op_sel_hi:[1,0]
	s_nop 0
	v_pk_mul_f32 v[122:123], v[116:117], v[152:153] op_sel_hi:[1,0]
	v_pk_mul_f32 v[116:117], v[114:115], v[152:153] op_sel_hi:[1,0]
	v_cvt_pk_bf16_f32 v114, v118, v119
	v_cvt_pk_bf16_f32 v115, v120, v121
	v_cvt_pk_bf16_f32 v116, v116, v117
	v_cvt_pk_bf16_f32 v117, v122, v123
	ds_read_b32 v118, v151 offset:64
	global_store_dwordx4 v[154:155], v[114:117], off offset:256
	s_nop 1
	v_add_u32_e32 v114, 16, v140
	v_ashrrev_i32_e32 v115, 31, v114
	v_lshlrev_b64 v[114:115], 11, v[114:115]
	v_lshl_add_u64 v[114:115], s[78:79], 0, v[114:115]
	s_waitcnt lgkmcnt(0)
	v_mul_f32_e32 v116, 0x3d800000, v118
	v_lshl_add_u64 v[114:115], v[114:115], 0, s[10:11]
	v_lshl_add_u64 v[114:115], v[114:115], 0, v[142:143]
	v_pk_mul_f32 v[112:113], v[112:113], v[116:117] op_sel_hi:[1,0]
	v_pk_mul_f32 v[110:111], v[110:111], v[116:117] op_sel_hi:[1,0]
	v_pk_mul_f32 v[118:119], v[108:109], v[116:117] op_sel_hi:[1,0]
	v_pk_mul_f32 v[108:109], v[106:107], v[116:117] op_sel_hi:[1,0]
	v_cvt_pk_bf16_f32 v106, v110, v111
	v_cvt_pk_bf16_f32 v107, v112, v113
	v_pk_mul_f32 v[102:103], v[102:103], v[116:117] op_sel_hi:[1,0]
	v_cvt_pk_bf16_f32 v108, v108, v109
	v_cvt_pk_bf16_f32 v109, v118, v119
	global_store_dwordx4 v[114:115], v[106:109], off
	v_pk_mul_f32 v[104:105], v[104:105], v[116:117] op_sel_hi:[1,0]
	s_nop 0
	v_pk_mul_f32 v[106:107], v[100:101], v[116:117] op_sel_hi:[1,0]
	v_pk_mul_f32 v[100:101], v[98:99], v[116:117] op_sel_hi:[1,0]
	v_cvt_pk_bf16_f32 v98, v102, v103
	v_cvt_pk_bf16_f32 v99, v104, v105
	v_cvt_pk_bf16_f32 v100, v100, v101
	v_cvt_pk_bf16_f32 v101, v106, v107
	ds_read_b32 v102, v151 offset:128
	global_store_dwordx4 v[114:115], v[98:101], off offset:256
	s_nop 1
	v_add_u32_e32 v98, 32, v140
	v_ashrrev_i32_e32 v99, 31, v98
	v_lshlrev_b64 v[98:99], 11, v[98:99]
	v_lshl_add_u64 v[98:99], s[78:79], 0, v[98:99]
	s_waitcnt lgkmcnt(0)
	v_mul_f32_e32 v100, 0x3d800000, v102
	v_lshl_add_u64 v[98:99], v[98:99], 0, s[10:11]
	v_lshl_add_u64 v[98:99], v[98:99], 0, v[142:143]
	v_pk_mul_f32 v[96:97], v[96:97], v[100:101] op_sel_hi:[1,0]
	v_pk_mul_f32 v[94:95], v[94:95], v[100:101] op_sel_hi:[1,0]
	v_pk_mul_f32 v[102:103], v[92:93], v[100:101] op_sel_hi:[1,0]
	v_pk_mul_f32 v[92:93], v[90:91], v[100:101] op_sel_hi:[1,0]
	v_cvt_pk_bf16_f32 v90, v94, v95
	v_cvt_pk_bf16_f32 v91, v96, v97
	v_pk_mul_f32 v[86:87], v[86:87], v[100:101] op_sel_hi:[1,0]
	v_cvt_pk_bf16_f32 v92, v92, v93
	v_cvt_pk_bf16_f32 v93, v102, v103
	global_store_dwordx4 v[98:99], v[90:93], off
	v_pk_mul_f32 v[88:89], v[88:89], v[100:101] op_sel_hi:[1,0]
	s_nop 0
	v_pk_mul_f32 v[90:91], v[84:85], v[100:101] op_sel_hi:[1,0]
	v_pk_mul_f32 v[84:85], v[82:83], v[100:101] op_sel_hi:[1,0]
	v_cvt_pk_bf16_f32 v82, v86, v87
	v_cvt_pk_bf16_f32 v83, v88, v89
	v_cvt_pk_bf16_f32 v84, v84, v85
	v_cvt_pk_bf16_f32 v85, v90, v91
	ds_read_b32 v86, v151 offset:192
	global_store_dwordx4 v[98:99], v[82:85], off offset:256
	s_nop 1
	v_add_u32_e32 v82, 48, v140
	v_ashrrev_i32_e32 v83, 31, v82
	v_lshlrev_b64 v[82:83], 11, v[82:83]
	v_lshl_add_u64 v[82:83], s[78:79], 0, v[82:83]
	s_waitcnt lgkmcnt(0)
	v_mul_f32_e32 v84, 0x3d800000, v86
	v_lshl_add_u64 v[82:83], v[82:83], 0, s[10:11]
	v_lshl_add_u64 v[82:83], v[82:83], 0, v[142:143]
	v_pk_mul_f32 v[80:81], v[80:81], v[84:85] op_sel_hi:[1,0]
	v_pk_mul_f32 v[78:79], v[78:79], v[84:85] op_sel_hi:[1,0]
	v_pk_mul_f32 v[86:87], v[76:77], v[84:85] op_sel_hi:[1,0]
	v_pk_mul_f32 v[76:77], v[74:75], v[84:85] op_sel_hi:[1,0]
	v_cvt_pk_bf16_f32 v74, v78, v79
	v_cvt_pk_bf16_f32 v75, v80, v81
	v_pk_mul_f32 v[70:71], v[70:71], v[84:85] op_sel_hi:[1,0]
	v_cvt_pk_bf16_f32 v76, v76, v77
	v_cvt_pk_bf16_f32 v77, v86, v87
	global_store_dwordx4 v[82:83], v[74:77], off
	v_pk_mul_f32 v[72:73], v[72:73], v[84:85] op_sel_hi:[1,0]
	s_nop 0
	v_pk_mul_f32 v[74:75], v[68:69], v[84:85] op_sel_hi:[1,0]
	v_pk_mul_f32 v[68:69], v[66:67], v[84:85] op_sel_hi:[1,0]
	v_cvt_pk_bf16_f32 v66, v70, v71
	v_cvt_pk_bf16_f32 v67, v72, v73
	v_cvt_pk_bf16_f32 v68, v68, v69
	v_cvt_pk_bf16_f32 v69, v74, v75
	ds_read_b32 v70, v151 offset:512
	global_store_dwordx4 v[82:83], v[66:69], off offset:256
	s_nop 1
	v_add_u32_e32 v66, 0x80, v140
	v_ashrrev_i32_e32 v67, 31, v66
	v_lshlrev_b64 v[66:67], 11, v[66:67]
	v_lshl_add_u64 v[66:67], s[78:79], 0, v[66:67]
	s_waitcnt lgkmcnt(0)
	v_mul_f32_e32 v68, 0x3d800000, v70
	v_lshl_add_u64 v[66:67], v[66:67], 0, s[10:11]
	v_lshl_add_u64 v[66:67], v[66:67], 0, v[142:143]
	v_pk_mul_f32 v[64:65], v[64:65], v[68:69] op_sel_hi:[1,0]
	v_pk_mul_f32 v[62:63], v[62:63], v[68:69] op_sel_hi:[1,0]
	v_pk_mul_f32 v[70:71], v[60:61], v[68:69] op_sel_hi:[1,0]
	v_pk_mul_f32 v[60:61], v[58:59], v[68:69] op_sel_hi:[1,0]
	v_cvt_pk_bf16_f32 v58, v62, v63
	v_cvt_pk_bf16_f32 v59, v64, v65
	v_pk_mul_f32 v[54:55], v[54:55], v[68:69] op_sel_hi:[1,0]
	v_cvt_pk_bf16_f32 v60, v60, v61
	v_cvt_pk_bf16_f32 v61, v70, v71
	global_store_dwordx4 v[66:67], v[58:61], off
	v_pk_mul_f32 v[56:57], v[56:57], v[68:69] op_sel_hi:[1,0]
	s_nop 0
	v_pk_mul_f32 v[58:59], v[52:53], v[68:69] op_sel_hi:[1,0]
	v_pk_mul_f32 v[52:53], v[50:51], v[68:69] op_sel_hi:[1,0]
	v_cvt_pk_bf16_f32 v50, v54, v55
	v_cvt_pk_bf16_f32 v51, v56, v57
	v_cvt_pk_bf16_f32 v52, v52, v53
	v_cvt_pk_bf16_f32 v53, v58, v59
	ds_read_b32 v54, v151 offset:576
	global_store_dwordx4 v[66:67], v[50:53], off offset:256
	s_nop 1
	v_add_u32_e32 v50, 0x90, v140
	v_ashrrev_i32_e32 v51, 31, v50
	v_lshlrev_b64 v[50:51], 11, v[50:51]
	v_lshl_add_u64 v[50:51], s[78:79], 0, v[50:51]
	s_waitcnt lgkmcnt(0)
	v_mul_f32_e32 v52, 0x3d800000, v54
	v_lshl_add_u64 v[50:51], v[50:51], 0, s[10:11]
	v_lshl_add_u64 v[50:51], v[50:51], 0, v[142:143]
	v_pk_mul_f32 v[48:49], v[48:49], v[52:53] op_sel_hi:[1,0]
	v_pk_mul_f32 v[46:47], v[46:47], v[52:53] op_sel_hi:[1,0]
	v_pk_mul_f32 v[54:55], v[44:45], v[52:53] op_sel_hi:[1,0]
	v_pk_mul_f32 v[44:45], v[42:43], v[52:53] op_sel_hi:[1,0]
	v_cvt_pk_bf16_f32 v42, v46, v47
	v_cvt_pk_bf16_f32 v43, v48, v49
	v_pk_mul_f32 v[38:39], v[38:39], v[52:53] op_sel_hi:[1,0]
	v_cvt_pk_bf16_f32 v44, v44, v45
	v_cvt_pk_bf16_f32 v45, v54, v55
	global_store_dwordx4 v[50:51], v[42:45], off
	v_pk_mul_f32 v[40:41], v[40:41], v[52:53] op_sel_hi:[1,0]
	s_nop 0
	v_pk_mul_f32 v[42:43], v[36:37], v[52:53] op_sel_hi:[1,0]
	v_pk_mul_f32 v[36:37], v[34:35], v[52:53] op_sel_hi:[1,0]
	v_cvt_pk_bf16_f32 v34, v38, v39
	v_cvt_pk_bf16_f32 v35, v40, v41
	v_cvt_pk_bf16_f32 v36, v36, v37
	v_cvt_pk_bf16_f32 v37, v42, v43
	ds_read_b32 v38, v151 offset:640
	global_store_dwordx4 v[50:51], v[34:37], off offset:256
	s_nop 1
	v_add_u32_e32 v34, 0xa0, v140
	v_ashrrev_i32_e32 v35, 31, v34
	v_lshlrev_b64 v[34:35], 11, v[34:35]
	v_lshl_add_u64 v[34:35], s[78:79], 0, v[34:35]
	s_waitcnt lgkmcnt(0)
	v_mul_f32_e32 v36, 0x3d800000, v38
	v_lshl_add_u64 v[34:35], v[34:35], 0, s[10:11]
	v_lshl_add_u64 v[34:35], v[34:35], 0, v[142:143]
	v_pk_mul_f32 v[32:33], v[32:33], v[36:37] op_sel_hi:[1,0]
	v_pk_mul_f32 v[30:31], v[30:31], v[36:37] op_sel_hi:[1,0]
	v_pk_mul_f32 v[38:39], v[28:29], v[36:37] op_sel_hi:[1,0]
	v_pk_mul_f32 v[28:29], v[26:27], v[36:37] op_sel_hi:[1,0]
	v_cvt_pk_bf16_f32 v26, v30, v31
	v_cvt_pk_bf16_f32 v27, v32, v33
	v_pk_mul_f32 v[22:23], v[22:23], v[36:37] op_sel_hi:[1,0]
	v_cvt_pk_bf16_f32 v28, v28, v29
	v_cvt_pk_bf16_f32 v29, v38, v39
	global_store_dwordx4 v[34:35], v[26:29], off
	v_pk_mul_f32 v[24:25], v[24:25], v[36:37] op_sel_hi:[1,0]
	s_nop 0
	v_pk_mul_f32 v[26:27], v[20:21], v[36:37] op_sel_hi:[1,0]
	v_pk_mul_f32 v[20:21], v[18:19], v[36:37] op_sel_hi:[1,0]
	v_cvt_pk_bf16_f32 v18, v22, v23
	v_cvt_pk_bf16_f32 v19, v24, v25
	v_cvt_pk_bf16_f32 v20, v20, v21
	v_cvt_pk_bf16_f32 v21, v26, v27
	ds_read_b32 v22, v151 offset:704
	global_store_dwordx4 v[34:35], v[18:21], off offset:256
	s_nop 1
	v_add_u32_e32 v18, 0xb0, v140
	v_ashrrev_i32_e32 v19, 31, v18
	v_lshlrev_b64 v[18:19], 11, v[18:19]
	v_lshl_add_u64 v[18:19], s[78:79], 0, v[18:19]
	s_waitcnt lgkmcnt(0)
	v_mul_f32_e32 v20, 0x3d800000, v22
	v_lshl_add_u64 v[18:19], v[18:19], 0, s[10:11]
	v_lshl_add_u64 v[18:19], v[18:19], 0, v[142:143]
	v_pk_mul_f32 v[16:17], v[16:17], v[20:21] op_sel_hi:[1,0]
	v_pk_mul_f32 v[14:15], v[14:15], v[20:21] op_sel_hi:[1,0]
	v_pk_mul_f32 v[22:23], v[12:13], v[20:21] op_sel_hi:[1,0]
	v_pk_mul_f32 v[12:13], v[10:11], v[20:21] op_sel_hi:[1,0]
	v_cvt_pk_bf16_f32 v10, v14, v15
	v_cvt_pk_bf16_f32 v11, v16, v17
	v_pk_mul_f32 v[8:9], v[8:9], v[20:21] op_sel_hi:[1,0]
	v_cvt_pk_bf16_f32 v12, v12, v13
	v_cvt_pk_bf16_f32 v13, v22, v23
	global_store_dwordx4 v[18:19], v[10:13], off
	v_pk_mul_f32 v[6:7], v[6:7], v[20:21] op_sel_hi:[1,0]
	s_nop 0
	v_pk_mul_f32 v[10:11], v[4:5], v[20:21] op_sel_hi:[1,0]
	v_pk_mul_f32 v[4:5], v[2:3], v[20:21] op_sel_hi:[1,0]
	v_cvt_pk_bf16_f32 v2, v6, v7
	v_cvt_pk_bf16_f32 v3, v8, v9
	v_cvt_pk_bf16_f32 v4, v4, v5
	v_cvt_pk_bf16_f32 v5, v10, v11
	global_store_dwordx4 v[18:19], v[2:5], off offset:256
	s_and_saveexec_b64 s[10:11], s[12:13]
	s_cbranch_execz .LBB11_1876
	s_waitcnt vmcnt(16)
	v_fmamk_f32 v150, v150, 0x3a800000, v206
	v_mul_f32_e32 v2, 0x4b800000, v150
	v_cmp_gt_f32_e32 vcc, s77, v150
	s_nop 1
	v_cndmask_b32_e32 v2, v150, v2, vcc
	v_rsq_f32_e32 v2, v2
	s_nop 0
	v_mul_f32_e32 v3, 0x45800000, v2
	v_cndmask_b32_e32 v2, v2, v3, vcc
	v_lshl_add_u32 v3, s39, 10, v148
	ds_write_b32 v3, v2

.LBB11_2080:
	s_or_b64 exec, exec, s[10:11]
	s_add_i32 s8, 0, 0x21000
	s_waitcnt lgkmcnt(0)
	s_barrier
	v_lshl_add_u32 v137, v142, 4, s8
	s_waitcnt lgkmcnt(0)
	ds_read_b128 v[144:147], v137
	s_lshl_b32 s7, s28, 8
	v_ashrrev_i32_e32 v137, 31, v136
	v_lshlrev_b64 v[136:137], 1, v[136:137]
	s_mov_b64 s[10:11], -1
	s_waitcnt lgkmcnt(0)
	v_mov_b32_e32 v148, v145
	v_mov_b32_e32 v149, v146
	v_mov_b32_e32 v145, v147
	v_pk_add_f32 v[144:145], v[148:149], v[144:145]
	s_nop 0
	v_add_f32_e32 v143, v144, v145
	v_div_scale_f32 v144, s[0:1], v143, v143, 1.0
	v_rcp_f32_e32 v145, v144
	v_readlane_b32 s0, v245, 61
	s_lshl_b32 s0, s0, 8
	s_ashr_i32 s1, s0, 31
	v_fma_f32 v146, -v144, v145, 1.0
	v_fmac_f32_e32 v145, v146, v145
	v_div_scale_f32 v146, vcc, 1.0, v143, 1.0
	v_mul_f32_e32 v147, v146, v145
	v_fma_f32 v148, -v144, v147, v146
	v_fmac_f32_e32 v147, v148, v145
	v_fma_f32 v144, -v144, v147, v146
	v_add_u32_e32 v146, s7, v142
	v_div_fmas_f32 v144, v144, v145, v147
	v_ashrrev_i32_e32 v147, 31, v146
	v_lshlrev_b64 v[146:147], 11, v[146:147]
	v_div_fixup_f32 v144, v144, v143, 1.0
	v_lshl_add_u64 v[146:147], s[80:81], 0, v[146:147]
	s_lshl_b64 s[24:25], s[0:1], 1
	v_lshl_add_u64 v[146:147], v[146:147], 0, s[24:25]
	v_pk_mul_f32 v[148:149], v[124:125], v[144:145] op_sel_hi:[1,0]
	v_pk_mul_f32 v[124:125], v[122:123], v[144:145] op_sel_hi:[1,0]
	v_lshl_add_u64 v[146:147], v[146:147], 0, v[136:137]
	v_pk_mul_f32 v[128:129], v[128:129], v[144:145] op_sel_hi:[1,0]
	v_pk_mul_f32 v[126:127], v[126:127], v[144:145] op_sel_hi:[1,0]
	v_pk_mul_f32 v[118:119], v[118:119], v[144:145] op_sel_hi:[1,0]
	v_cvt_pk_bf16_f32 v122, v126, v127
	v_cvt_pk_bf16_f32 v123, v128, v129
	v_cvt_pk_bf16_f32 v124, v124, v125
	v_cvt_pk_bf16_f32 v125, v148, v149
	global_store_dwordx4 v[146:147], v[122:125], off
	v_pk_mul_f32 v[120:121], v[120:121], v[144:145] op_sel_hi:[1,0]
	s_nop 0
	v_add_u32_e32 v124, 16, v142
	v_pk_mul_f32 v[122:123], v[116:117], v[144:145] op_sel_hi:[1,0]
	v_pk_mul_f32 v[116:117], v[114:115], v[144:145] op_sel_hi:[1,0]
	v_cvt_pk_bf16_f32 v114, v118, v119
	v_lshl_add_u32 v118, v124, 4, s8
	v_cvt_pk_bf16_f32 v115, v120, v121
	v_cvt_pk_bf16_f32 v116, v116, v117
	v_cvt_pk_bf16_f32 v117, v122, v123
	ds_read_b128 v[118:121], v118
	global_store_dwordx4 v[146:147], v[114:117], off offset:256
	s_waitcnt lgkmcnt(0)
	v_mov_b32_e32 v122, v119
	v_mov_b32_e32 v123, v120
	v_mov_b32_e32 v119, v121
	v_pk_add_f32 v[118:119], v[122:123], v[118:119]
	s_nop 0
	v_add_f32_e32 v118, v118, v119
	v_div_scale_f32 v119, s[0:1], v118, v118, 1.0
	v_rcp_f32_e32 v120, v119
	s_nop 0
	v_fma_f32 v114, -v119, v120, 1.0
	v_fmac_f32_e32 v120, v114, v120
	v_div_scale_f32 v114, vcc, 1.0, v118, 1.0
	v_mul_f32_e32 v115, v114, v120
	v_fma_f32 v116, -v119, v115, v114
	v_fmac_f32_e32 v115, v116, v120
	v_add_u32_e32 v116, s7, v124
	v_fma_f32 v114, -v119, v115, v114
	v_ashrrev_i32_e32 v117, 31, v116
	v_div_fmas_f32 v114, v114, v120, v115
	v_lshlrev_b64 v[116:117], 11, v[116:117]
	v_div_fixup_f32 v114, v114, v118, 1.0
	v_lshl_add_u64 v[116:117], s[80:81], 0, v[116:117]
	v_lshl_add_u64 v[116:117], v[116:117], 0, s[24:25]
	v_pk_mul_f32 v[118:119], v[108:109], v[114:115] op_sel_hi:[1,0]
	v_pk_mul_f32 v[108:109], v[106:107], v[114:115] op_sel_hi:[1,0]
	v_lshl_add_u64 v[116:117], v[116:117], 0, v[136:137]
	v_pk_mul_f32 v[112:113], v[112:113], v[114:115] op_sel_hi:[1,0]
	v_pk_mul_f32 v[110:111], v[110:111], v[114:115] op_sel_hi:[1,0]
	v_pk_mul_f32 v[102:103], v[102:103], v[114:115] op_sel_hi:[1,0]
	v_cvt_pk_bf16_f32 v106, v110, v111
	v_cvt_pk_bf16_f32 v107, v112, v113
	v_cvt_pk_bf16_f32 v108, v108, v109
	v_cvt_pk_bf16_f32 v109, v118, v119
	global_store_dwordx4 v[116:117], v[106:109], off
	v_pk_mul_f32 v[104:105], v[104:105], v[114:115] op_sel_hi:[1,0]
	s_nop 0
	v_add_u32_e32 v108, 32, v142
	v_pk_mul_f32 v[106:107], v[100:101], v[114:115] op_sel_hi:[1,0]
	v_pk_mul_f32 v[100:101], v[98:99], v[114:115] op_sel_hi:[1,0]
	v_cvt_pk_bf16_f32 v98, v102, v103
	v_lshl_add_u32 v102, v108, 4, s8
	v_cvt_pk_bf16_f32 v99, v104, v105
	v_cvt_pk_bf16_f32 v100, v100, v101
	v_cvt_pk_bf16_f32 v101, v106, v107
	ds_read_b128 v[102:105], v102
	global_store_dwordx4 v[116:117], v[98:101], off offset:256
	s_waitcnt lgkmcnt(0)
	v_mov_b32_e32 v106, v103
	v_mov_b32_e32 v107, v104
	v_mov_b32_e32 v103, v105
	v_pk_add_f32 v[102:103], v[106:107], v[102:103]
	s_nop 0
	v_add_f32_e32 v102, v102, v103
	v_div_scale_f32 v103, s[0:1], v102, v102, 1.0
	v_rcp_f32_e32 v104, v103
	s_nop 0
	v_fma_f32 v98, -v103, v104, 1.0
	v_fmac_f32_e32 v104, v98, v104
	v_div_scale_f32 v98, vcc, 1.0, v102, 1.0
	v_mul_f32_e32 v99, v98, v104
	v_fma_f32 v100, -v103, v99, v98
	v_fmac_f32_e32 v99, v100, v104
	v_add_u32_e32 v100, s7, v108
	v_fma_f32 v98, -v103, v99, v98
	v_ashrrev_i32_e32 v101, 31, v100
	v_div_fmas_f32 v98, v98, v104, v99
	v_lshlrev_b64 v[100:101], 11, v[100:101]
	v_div_fixup_f32 v98, v98, v102, 1.0
	v_lshl_add_u64 v[100:101], s[80:81], 0, v[100:101]
	v_lshl_add_u64 v[100:101], v[100:101], 0, s[24:25]
	v_pk_mul_f32 v[102:103], v[92:93], v[98:99] op_sel_hi:[1,0]
	v_pk_mul_f32 v[92:93], v[90:91], v[98:99] op_sel_hi:[1,0]
	v_lshl_add_u64 v[100:101], v[100:101], 0, v[136:137]
	v_pk_mul_f32 v[96:97], v[96:97], v[98:99] op_sel_hi:[1,0]
	v_pk_mul_f32 v[94:95], v[94:95], v[98:99] op_sel_hi:[1,0]
	v_pk_mul_f32 v[86:87], v[86:87], v[98:99] op_sel_hi:[1,0]
	v_cvt_pk_bf16_f32 v90, v94, v95
	v_cvt_pk_bf16_f32 v91, v96, v97
	v_cvt_pk_bf16_f32 v92, v92, v93
	v_cvt_pk_bf16_f32 v93, v102, v103
	global_store_dwordx4 v[100:101], v[90:93], off
	v_pk_mul_f32 v[88:89], v[88:89], v[98:99] op_sel_hi:[1,0]
	s_nop 0
	v_add_u32_e32 v92, 48, v142
	v_pk_mul_f32 v[90:91], v[84:85], v[98:99] op_sel_hi:[1,0]
	v_pk_mul_f32 v[84:85], v[82:83], v[98:99] op_sel_hi:[1,0]
	v_cvt_pk_bf16_f32 v82, v86, v87
	v_lshl_add_u32 v86, v92, 4, s8
	v_cvt_pk_bf16_f32 v83, v88, v89
	v_cvt_pk_bf16_f32 v84, v84, v85
	v_cvt_pk_bf16_f32 v85, v90, v91
	ds_read_b128 v[86:89], v86
	global_store_dwordx4 v[100:101], v[82:85], off offset:256
	s_waitcnt lgkmcnt(0)
	v_mov_b32_e32 v90, v87
	v_mov_b32_e32 v91, v88
	v_mov_b32_e32 v87, v89
	v_pk_add_f32 v[86:87], v[90:91], v[86:87]
	s_nop 0
	v_add_f32_e32 v86, v86, v87
	v_div_scale_f32 v87, s[0:1], v86, v86, 1.0
	v_rcp_f32_e32 v88, v87
	s_nop 0
	v_fma_f32 v82, -v87, v88, 1.0
	v_fmac_f32_e32 v88, v82, v88
	v_div_scale_f32 v82, vcc, 1.0, v86, 1.0
	v_mul_f32_e32 v83, v82, v88
	v_fma_f32 v84, -v87, v83, v82
	v_fmac_f32_e32 v83, v84, v88
	v_add_u32_e32 v84, s7, v92
	v_fma_f32 v82, -v87, v83, v82
	v_ashrrev_i32_e32 v85, 31, v84
	v_div_fmas_f32 v82, v82, v88, v83
	v_lshlrev_b64 v[84:85], 11, v[84:85]
	v_div_fixup_f32 v82, v82, v86, 1.0
	v_lshl_add_u64 v[84:85], s[80:81], 0, v[84:85]
	v_lshl_add_u64 v[84:85], v[84:85], 0, s[24:25]
	v_pk_mul_f32 v[86:87], v[76:77], v[82:83] op_sel_hi:[1,0]
	v_pk_mul_f32 v[76:77], v[74:75], v[82:83] op_sel_hi:[1,0]
	v_lshl_add_u64 v[84:85], v[84:85], 0, v[136:137]
	v_pk_mul_f32 v[80:81], v[80:81], v[82:83] op_sel_hi:[1,0]
	v_pk_mul_f32 v[78:79], v[78:79], v[82:83] op_sel_hi:[1,0]
	v_pk_mul_f32 v[70:71], v[70:71], v[82:83] op_sel_hi:[1,0]
	v_cvt_pk_bf16_f32 v74, v78, v79
	v_cvt_pk_bf16_f32 v75, v80, v81
	v_cvt_pk_bf16_f32 v76, v76, v77
	v_cvt_pk_bf16_f32 v77, v86, v87
	global_store_dwordx4 v[84:85], v[74:77], off
	v_pk_mul_f32 v[72:73], v[72:73], v[82:83] op_sel_hi:[1,0]
	s_nop 0
	v_add_u32_e32 v76, 0x80, v142
	v_pk_mul_f32 v[74:75], v[68:69], v[82:83] op_sel_hi:[1,0]
	v_pk_mul_f32 v[68:69], v[66:67], v[82:83] op_sel_hi:[1,0]
	v_cvt_pk_bf16_f32 v66, v70, v71
	v_lshl_add_u32 v70, v76, 4, s8
	v_cvt_pk_bf16_f32 v67, v72, v73
	v_cvt_pk_bf16_f32 v68, v68, v69
	v_cvt_pk_bf16_f32 v69, v74, v75
	ds_read_b128 v[70:73], v70
	global_store_dwordx4 v[84:85], v[66:69], off offset:256
	s_waitcnt lgkmcnt(0)
	v_mov_b32_e32 v74, v71
	v_mov_b32_e32 v75, v72
	v_mov_b32_e32 v71, v73
	v_pk_add_f32 v[70:71], v[74:75], v[70:71]
	s_nop 0
	v_add_f32_e32 v70, v70, v71
	v_div_scale_f32 v71, s[0:1], v70, v70, 1.0
	v_rcp_f32_e32 v72, v71
	s_nop 0
	v_fma_f32 v66, -v71, v72, 1.0
	v_fmac_f32_e32 v72, v66, v72
	v_div_scale_f32 v66, vcc, 1.0, v70, 1.0
	v_mul_f32_e32 v67, v66, v72
	v_fma_f32 v68, -v71, v67, v66
	v_fmac_f32_e32 v67, v68, v72
	v_add_u32_e32 v68, s7, v76
	v_fma_f32 v66, -v71, v67, v66
	v_ashrrev_i32_e32 v69, 31, v68
	v_div_fmas_f32 v66, v66, v72, v67
	v_lshlrev_b64 v[68:69], 11, v[68:69]
	v_div_fixup_f32 v66, v66, v70, 1.0
	v_lshl_add_u64 v[68:69], s[80:81], 0, v[68:69]
	v_lshl_add_u64 v[68:69], v[68:69], 0, s[24:25]
	v_pk_mul_f32 v[70:71], v[60:61], v[66:67] op_sel_hi:[1,0]
	v_pk_mul_f32 v[60:61], v[58:59], v[66:67] op_sel_hi:[1,0]
	v_lshl_add_u64 v[68:69], v[68:69], 0, v[136:137]
	v_pk_mul_f32 v[64:65], v[64:65], v[66:67] op_sel_hi:[1,0]
	v_pk_mul_f32 v[62:63], v[62:63], v[66:67] op_sel_hi:[1,0]
	v_pk_mul_f32 v[54:55], v[54:55], v[66:67] op_sel_hi:[1,0]
	v_cvt_pk_bf16_f32 v58, v62, v63
	v_cvt_pk_bf16_f32 v59, v64, v65
	v_cvt_pk_bf16_f32 v60, v60, v61
	v_cvt_pk_bf16_f32 v61, v70, v71
	global_store_dwordx4 v[68:69], v[58:61], off
	v_pk_mul_f32 v[56:57], v[56:57], v[66:67] op_sel_hi:[1,0]
	s_nop 0
	v_add_u32_e32 v60, 0x90, v142
	v_pk_mul_f32 v[58:59], v[52:53], v[66:67] op_sel_hi:[1,0]
	v_pk_mul_f32 v[52:53], v[50:51], v[66:67] op_sel_hi:[1,0]
	v_cvt_pk_bf16_f32 v50, v54, v55
	v_lshl_add_u32 v54, v60, 4, s8
	v_cvt_pk_bf16_f32 v51, v56, v57
	v_cvt_pk_bf16_f32 v52, v52, v53
	v_cvt_pk_bf16_f32 v53, v58, v59
	ds_read_b128 v[54:57], v54
	global_store_dwordx4 v[68:69], v[50:53], off offset:256
	s_waitcnt lgkmcnt(0)
	v_mov_b32_e32 v58, v55
	v_mov_b32_e32 v59, v56
	v_mov_b32_e32 v55, v57
	v_pk_add_f32 v[54:55], v[58:59], v[54:55]
	s_nop 0
	v_add_f32_e32 v54, v54, v55
	v_div_scale_f32 v55, s[0:1], v54, v54, 1.0
	v_rcp_f32_e32 v56, v55
	s_nop 0
	v_fma_f32 v50, -v55, v56, 1.0
	v_fmac_f32_e32 v56, v50, v56
	v_div_scale_f32 v50, vcc, 1.0, v54, 1.0
	v_mul_f32_e32 v51, v50, v56
	v_fma_f32 v52, -v55, v51, v50
	v_fmac_f32_e32 v51, v52, v56
	v_add_u32_e32 v52, s7, v60
	v_fma_f32 v50, -v55, v51, v50
	v_ashrrev_i32_e32 v53, 31, v52
	v_div_fmas_f32 v50, v50, v56, v51
	v_lshlrev_b64 v[52:53], 11, v[52:53]
	v_div_fixup_f32 v50, v50, v54, 1.0
	v_lshl_add_u64 v[52:53], s[80:81], 0, v[52:53]
	v_lshl_add_u64 v[52:53], v[52:53], 0, s[24:25]
	v_pk_mul_f32 v[54:55], v[44:45], v[50:51] op_sel_hi:[1,0]
	v_pk_mul_f32 v[44:45], v[42:43], v[50:51] op_sel_hi:[1,0]
	v_lshl_add_u64 v[52:53], v[52:53], 0, v[136:137]
	v_pk_mul_f32 v[48:49], v[48:49], v[50:51] op_sel_hi:[1,0]
	v_pk_mul_f32 v[46:47], v[46:47], v[50:51] op_sel_hi:[1,0]
	v_pk_mul_f32 v[38:39], v[38:39], v[50:51] op_sel_hi:[1,0]
	v_cvt_pk_bf16_f32 v42, v46, v47
	v_cvt_pk_bf16_f32 v43, v48, v49
	v_cvt_pk_bf16_f32 v44, v44, v45
	v_cvt_pk_bf16_f32 v45, v54, v55
	global_store_dwordx4 v[52:53], v[42:45], off
	v_pk_mul_f32 v[40:41], v[40:41], v[50:51] op_sel_hi:[1,0]
	s_nop 0
	v_add_u32_e32 v44, 0xa0, v142
	v_pk_mul_f32 v[42:43], v[36:37], v[50:51] op_sel_hi:[1,0]
	v_pk_mul_f32 v[36:37], v[34:35], v[50:51] op_sel_hi:[1,0]
	v_cvt_pk_bf16_f32 v34, v38, v39
	v_lshl_add_u32 v38, v44, 4, s8
	v_cvt_pk_bf16_f32 v35, v40, v41
	v_cvt_pk_bf16_f32 v36, v36, v37
	v_cvt_pk_bf16_f32 v37, v42, v43
	ds_read_b128 v[38:41], v38
	global_store_dwordx4 v[52:53], v[34:37], off offset:256
	s_waitcnt lgkmcnt(0)
	v_mov_b32_e32 v42, v39
	v_mov_b32_e32 v43, v40
	v_mov_b32_e32 v39, v41
	v_pk_add_f32 v[38:39], v[42:43], v[38:39]
	s_nop 0
	v_add_f32_e32 v38, v38, v39
	v_div_scale_f32 v39, s[0:1], v38, v38, 1.0
	v_rcp_f32_e32 v40, v39
	s_nop 0
	v_fma_f32 v34, -v39, v40, 1.0
	v_fmac_f32_e32 v40, v34, v40
	v_div_scale_f32 v34, vcc, 1.0, v38, 1.0
	v_mul_f32_e32 v35, v34, v40
	v_fma_f32 v36, -v39, v35, v34
	v_fmac_f32_e32 v35, v36, v40
	v_add_u32_e32 v36, s7, v44
	v_fma_f32 v34, -v39, v35, v34
	v_ashrrev_i32_e32 v37, 31, v36
	v_div_fmas_f32 v34, v34, v40, v35
	v_lshlrev_b64 v[36:37], 11, v[36:37]
	v_div_fixup_f32 v34, v34, v38, 1.0
	v_lshl_add_u64 v[36:37], s[80:81], 0, v[36:37]
	v_lshl_add_u64 v[36:37], v[36:37], 0, s[24:25]
	v_pk_mul_f32 v[38:39], v[28:29], v[34:35] op_sel_hi:[1,0]
	v_pk_mul_f32 v[28:29], v[26:27], v[34:35] op_sel_hi:[1,0]
	v_lshl_add_u64 v[36:37], v[36:37], 0, v[136:137]
	v_pk_mul_f32 v[32:33], v[32:33], v[34:35] op_sel_hi:[1,0]
	v_pk_mul_f32 v[30:31], v[30:31], v[34:35] op_sel_hi:[1,0]
	v_pk_mul_f32 v[22:23], v[22:23], v[34:35] op_sel_hi:[1,0]
	v_cvt_pk_bf16_f32 v26, v30, v31
	v_cvt_pk_bf16_f32 v27, v32, v33
	v_cvt_pk_bf16_f32 v28, v28, v29
	v_cvt_pk_bf16_f32 v29, v38, v39
	global_store_dwordx4 v[36:37], v[26:29], off
	v_pk_mul_f32 v[24:25], v[24:25], v[34:35] op_sel_hi:[1,0]
	s_nop 0
	v_add_u32_e32 v28, 0xb0, v142
	v_pk_mul_f32 v[26:27], v[20:21], v[34:35] op_sel_hi:[1,0]
	v_pk_mul_f32 v[20:21], v[18:19], v[34:35] op_sel_hi:[1,0]
	v_cvt_pk_bf16_f32 v18, v22, v23
	v_lshl_add_u32 v22, v28, 4, s8
	v_cvt_pk_bf16_f32 v19, v24, v25
	v_cvt_pk_bf16_f32 v20, v20, v21
	v_cvt_pk_bf16_f32 v21, v26, v27
	ds_read_b128 v[22:25], v22
	global_store_dwordx4 v[36:37], v[18:21], off offset:256
	s_waitcnt lgkmcnt(0)
	v_mov_b32_e32 v26, v23
	v_mov_b32_e32 v27, v24
	v_mov_b32_e32 v23, v25
	v_pk_add_f32 v[22:23], v[26:27], v[22:23]
	s_nop 0
	v_add_f32_e32 v22, v22, v23
	v_div_scale_f32 v23, s[0:1], v22, v22, 1.0
	v_rcp_f32_e32 v24, v23
	s_nop 0
	v_fma_f32 v18, -v23, v24, 1.0
	v_fmac_f32_e32 v24, v18, v24
	v_div_scale_f32 v18, vcc, 1.0, v22, 1.0
	v_mul_f32_e32 v19, v18, v24
	v_fma_f32 v20, -v23, v19, v18
	v_fmac_f32_e32 v19, v20, v24
	v_add_u32_e32 v20, s7, v28
	v_ashrrev_i32_e32 v21, 31, v20
	v_fma_f32 v18, -v23, v19, v18
	v_lshlrev_b64 v[20:21], 11, v[20:21]
	v_div_fmas_f32 v18, v18, v24, v19
	v_lshl_add_u64 v[20:21], s[80:81], 0, v[20:21]
	v_div_fixup_f32 v18, v18, v22, 1.0
	v_lshl_add_u64 v[20:21], v[20:21], 0, s[24:25]
	v_lshl_add_u64 v[20:21], v[20:21], 0, v[136:137]
	v_pk_mul_f32 v[16:17], v[16:17], v[18:19] op_sel_hi:[1,0]
	v_pk_mul_f32 v[14:15], v[14:15], v[18:19] op_sel_hi:[1,0]
	v_pk_mul_f32 v[22:23], v[12:13], v[18:19] op_sel_hi:[1,0]
	v_pk_mul_f32 v[12:13], v[10:11], v[18:19] op_sel_hi:[1,0]
	v_cvt_pk_bf16_f32 v10, v14, v15
	v_cvt_pk_bf16_f32 v11, v16, v17
	s_andn2_b64 vcc, exec, s[20:21]
	v_cvt_pk_bf16_f32 v12, v12, v13
	v_cvt_pk_bf16_f32 v13, v22, v23
	global_store_dwordx4 v[20:21], v[10:13], off
	v_pk_mul_f32 v[8:9], v[8:9], v[18:19] op_sel_hi:[1,0]
	v_pk_mul_f32 v[6:7], v[6:7], v[18:19] op_sel_hi:[1,0]
	v_pk_mul_f32 v[10:11], v[4:5], v[18:19] op_sel_hi:[1,0]
	v_pk_mul_f32 v[4:5], v[2:3], v[18:19] op_sel_hi:[1,0]
	v_cvt_pk_bf16_f32 v2, v6, v7
	v_cvt_pk_bf16_f32 v3, v8, v9
	v_cvt_pk_bf16_f32 v4, v4, v5
	v_cvt_pk_bf16_f32 v5, v10, v11
	global_store_dwordx4 v[20:21], v[2:5], off offset:256
	s_cbranch_vccnz .LBB11_2041
	s_andn2_b64 vcc, exec, s[14:15]
	s_cbranch_vccnz .LBB11_2040
	s_barrier
	s_branch .LBB11_2040

.LBB11_2332:
	v_mov_b32_e32 v140, v150
	v_mov_b32_e32 v141, v152
	s_lshl_b32 s22, s7, 8
	s_nop 0
	v_add_u32_e32 v144, s22, v140
	v_lshl_add_u32 v142, s6, 8, v141
	v_ashrrev_i32_e32 v145, 31, v144
	v_lshlrev_b64 v[148:149], 11, v[144:145]
	v_ashrrev_i32_e32 v143, 31, v142
	v_lshl_add_u64 v[146:147], s[66:67], 0, v[148:149]
	v_lshlrev_b64 v[142:143], 1, v[142:143]
	v_lshl_add_u64 v[146:147], v[146:147], 0, v[142:143]
	v_lshl_add_u64 v[148:149], s[64:65], 0, v[148:149]
	v_lshl_add_u64 v[148:149], v[148:149], 0, v[142:143]
	v_lshl_add_u32 v249, v144, 11, v142
	global_load_dwordx4 v[170:173], v249, s[66:67]
	global_load_dwordx4 v[174:177], v249, s[64:65]
	global_load_dwordx4 v[178:181], v249, s[66:67] offset:256
	global_load_dwordx4 v[190:193], v249, s[64:65] offset:256
	v_add_u32_e32 v251, 0x8000, v249
	global_load_dwordx4 v[194:197], v251, s[66:67]
	global_load_dwordx4 v[214:217], v251, s[64:65]
	v_add_u32_e32 v250, 0x8000, v249
	global_load_dwordx4 v[218:221], v250, s[66:67] offset:256
	global_load_dwordx4 v[222:225], v250, s[64:65] offset:256
	v_add_u32_e32 v251, 0x10000, v249
	global_load_dwordx4 v[226:229], v251, s[66:67]
	global_load_dwordx4 v[230:233], v251, s[64:65]
	s_waitcnt vmcnt(8)
	v_lshlrev_b32_e32 v162, 16, v170
	v_and_b32_e32 v163, 0xffff0000, v170
	v_lshlrev_b32_e32 v164, 16, v174
	v_and_b32_e32 v165, 0xffff0000, v174
	v_lshlrev_b32_e32 v154, 16, v171
	v_and_b32_e32 v155, 0xffff0000, v171
	v_lshlrev_b32_e32 v158, 16, v175
	v_and_b32_e32 v159, 0xffff0000, v175
	v_pk_add_f32 v[162:163], v[162:163], v[164:165]
	v_pk_add_f32 v[154:155], v[154:155], v[158:159]
	v_lshlrev_b32_e32 v158, 16, v172
	v_and_b32_e32 v159, 0xffff0000, v172
	v_lshlrev_b32_e32 v164, 16, v176
	v_and_b32_e32 v165, 0xffff0000, v176
	v_lshlrev_b32_e32 v156, 16, v173
	v_and_b32_e32 v157, 0xffff0000, v173
	v_lshlrev_b32_e32 v160, 16, v177
	v_and_b32_e32 v161, 0xffff0000, v177
	v_add_u32_e32 v250, 0x10000, v249
	global_load_dwordx4 v[170:173], v250, s[66:67] offset:256
	global_load_dwordx4 v[174:177], v250, s[64:65] offset:256
	v_pk_add_f32 v[158:159], v[158:159], v[164:165]
	v_pk_add_f32 v[156:157], v[156:157], v[160:161]
	v_pk_add_f32 v[128:129], v[128:129], v[154:155]
	v_pk_add_f32 v[126:127], v[126:127], v[162:163]
	v_pk_add_f32 v[154:155], v[124:125], v[156:157]
	v_pk_add_f32 v[156:157], v[122:123], v[158:159]
	v_cvt_pk_bf16_f32 v122, v126, v127
	v_cvt_pk_bf16_f32 v123, v128, v129
	v_lshlrev_b32_e32 v124, 16, v122
	v_and_b32_e32 v125, 0xffff0000, v122
	v_lshlrev_b32_e32 v158, 16, v123
	v_and_b32_e32 v159, 0xffff0000, v123
	v_sub_f32_e32 v128, v128, v158
	v_sub_f32_e32 v129, v129, v159
	v_sub_f32_e32 v126, v126, v124
	v_sub_f32_e32 v127, v127, v125
	v_cvt_pk_bf16_f32 v126, v126, v127
	v_cvt_pk_bf16_f32 v127, v128, v129
	v_lshlrev_b32_e32 v128, 16, v126
	v_and_b32_e32 v129, 0xffff0000, v126
	v_lshlrev_b32_e32 v160, 16, v127
	v_and_b32_e32 v161, 0xffff0000, v127
	v_pk_add_f32 v[158:159], v[158:159], v[160:161]
	v_pk_add_f32 v[160:161], v[124:125], v[128:129]
	v_cvt_pk_bf16_f32 v124, v156, v157
	v_cvt_pk_bf16_f32 v125, v154, v155
	v_lshlrev_b32_e32 v162, 16, v124
	v_lshlrev_b32_e32 v164, 16, v125
	v_and_b32_e32 v163, 0xffff0000, v124
	v_and_b32_e32 v165, 0xffff0000, v125
	v_sub_f32_e32 v129, v154, v164
	v_sub_f32_e32 v128, v156, v162
	v_sub_f32_e32 v141, v155, v165
	v_sub_f32_e32 v145, v157, v163
	v_cvt_pk_bf16_f32 v128, v128, v145
	v_cvt_pk_bf16_f32 v129, v129, v141
	global_store_dwordx4 v[146:147], v[122:125], off
	global_store_dwordx4 v[148:149], v[126:129], off
	v_lshlrev_b32_e32 v154, 16, v128
	v_and_b32_e32 v155, 0xffff0000, v128
	v_mul_f32_e32 v122, v161, v161
	v_mul_f32_e32 v123, v159, v159
	v_pk_add_f32 v[154:155], v[162:163], v[154:155]
	v_fmac_f32_e32 v122, v160, v160
	v_fmac_f32_e32 v123, v158, v158
	v_lshlrev_b32_e32 v156, 16, v129
	v_and_b32_e32 v157, 0xffff0000, v129
	v_add_f32_e32 v122, v122, v123
	v_mul_f32_e32 v123, v155, v155
	v_pk_add_f32 v[156:157], v[164:165], v[156:157]
	v_fmac_f32_e32 v123, v154, v154
	v_add_f32_e32 v122, v122, v123
	v_mul_f32_e32 v123, v157, v157
	v_fmac_f32_e32 v123, v156, v156
	v_add_f32_e32 v141, v123, v122
	s_waitcnt vmcnt(10)
	v_lshlrev_b32_e32 v154, 16, v178
	v_and_b32_e32 v155, 0xffff0000, v178
	v_lshlrev_b32_e32 v156, 16, v190
	v_and_b32_e32 v157, 0xffff0000, v190
	v_lshlrev_b32_e32 v122, 16, v179
	v_and_b32_e32 v123, 0xffff0000, v179
	v_lshlrev_b32_e32 v126, 16, v191
	v_and_b32_e32 v127, 0xffff0000, v191
	v_pk_add_f32 v[154:155], v[154:155], v[156:157]
	v_pk_add_f32 v[122:123], v[122:123], v[126:127]
	v_lshlrev_b32_e32 v126, 16, v180
	v_and_b32_e32 v127, 0xffff0000, v180
	v_lshlrev_b32_e32 v156, 16, v192
	v_and_b32_e32 v157, 0xffff0000, v192
	v_lshlrev_b32_e32 v124, 16, v181
	v_and_b32_e32 v125, 0xffff0000, v181
	v_lshlrev_b32_e32 v128, 16, v193
	v_and_b32_e32 v129, 0xffff0000, v193
	v_add_u32_e32 v251, 0x18000, v249
	global_load_dwordx4 v[178:181], v251, s[66:67]
	global_load_dwordx4 v[190:193], v251, s[64:65]
	v_pk_add_f32 v[126:127], v[126:127], v[156:157]
	v_pk_add_f32 v[124:125], v[124:125], v[128:129]
	v_pk_add_f32 v[120:121], v[120:121], v[122:123]
	v_pk_add_f32 v[118:119], v[118:119], v[154:155]
	v_pk_add_f32 v[122:123], v[116:117], v[124:125]
	v_pk_add_f32 v[124:125], v[114:115], v[126:127]
	v_cvt_pk_bf16_f32 v114, v118, v119
	v_cvt_pk_bf16_f32 v115, v120, v121
	v_lshlrev_b32_e32 v116, 16, v114
	v_and_b32_e32 v117, 0xffff0000, v114
	v_lshlrev_b32_e32 v126, 16, v115
	v_and_b32_e32 v127, 0xffff0000, v115
	v_sub_f32_e32 v120, v120, v126
	v_sub_f32_e32 v121, v121, v127
	v_sub_f32_e32 v118, v118, v116
	v_sub_f32_e32 v119, v119, v117
	v_cvt_pk_bf16_f32 v118, v118, v119
	v_cvt_pk_bf16_f32 v119, v120, v121
	v_lshlrev_b32_e32 v120, 16, v118
	v_and_b32_e32 v121, 0xffff0000, v118
	v_lshlrev_b32_e32 v128, 16, v119
	v_and_b32_e32 v129, 0xffff0000, v119
	v_pk_add_f32 v[126:127], v[126:127], v[128:129]
	v_pk_add_f32 v[128:129], v[116:117], v[120:121]
	v_cvt_pk_bf16_f32 v116, v124, v125
	v_cvt_pk_bf16_f32 v117, v122, v123
	v_lshlrev_b32_e32 v154, 16, v116
	v_and_b32_e32 v155, 0xffff0000, v116
	v_lshlrev_b32_e32 v156, 16, v117
	v_and_b32_e32 v157, 0xffff0000, v117
	v_sub_f32_e32 v121, v122, v156
	v_sub_f32_e32 v122, v123, v157
	v_sub_f32_e32 v120, v124, v154
	v_sub_f32_e32 v123, v125, v155
	v_cvt_pk_bf16_f32 v120, v120, v123
	v_cvt_pk_bf16_f32 v121, v121, v122
	global_store_dwordx4 v[146:147], v[114:117], off offset:256
	global_store_dwordx4 v[148:149], v[118:121], off offset:256
	v_lshlrev_b32_e32 v122, 16, v120
	v_and_b32_e32 v123, 0xffff0000, v120
	v_mul_f32_e32 v114, v129, v129
	v_mul_f32_e32 v115, v127, v127
	v_pk_add_f32 v[122:123], v[154:155], v[122:123]
	v_fmac_f32_e32 v114, v128, v128
	v_fmac_f32_e32 v115, v126, v126
	v_lshlrev_b32_e32 v124, 16, v121
	v_and_b32_e32 v125, 0xffff0000, v121
	v_add_f32_e32 v114, v114, v115
	v_mul_f32_e32 v115, v123, v123
	v_pk_add_f32 v[124:125], v[156:157], v[124:125]
	v_fmac_f32_e32 v115, v122, v122
	v_add_f32_e32 v114, v114, v115
	v_mul_f32_e32 v115, v125, v125
	v_fmac_f32_e32 v115, v124, v124
	v_add_f32_e32 v114, v115, v114
	v_add_f32_e32 v114, v141, v114
	ds_bpermute_b32 v115, v204, v114
	s_waitcnt lgkmcnt(0)
	v_add_f32_e32 v118, v114, v115
	v_add_u32_e32 v114, 16, v144
	v_ashrrev_i32_e32 v115, 31, v114
	v_lshlrev_b64 v[116:117], 11, v[114:115]
	v_lshl_add_u64 v[114:115], s[66:67], 0, v[116:117]
	v_lshl_add_u64 v[114:115], v[114:115], 0, v[142:143]
	v_lshl_add_u64 v[116:117], s[64:65], 0, v[116:117]
	v_lshl_add_u64 v[116:117], v[116:117], 0, v[142:143]
	ds_bpermute_b32 v119, v205, v118
	s_waitcnt vmcnt(12)
	v_lshlrev_b32_e32 v128, 16, v194
	v_and_b32_e32 v129, 0xffff0000, v194
	v_lshlrev_b32_e32 v146, 16, v214
	v_and_b32_e32 v147, 0xffff0000, v214
	v_lshlrev_b32_e32 v120, 16, v195
	v_and_b32_e32 v121, 0xffff0000, v195
	v_lshlrev_b32_e32 v124, 16, v215
	v_and_b32_e32 v125, 0xffff0000, v215
	v_pk_add_f32 v[128:129], v[128:129], v[146:147]
	v_pk_add_f32 v[120:121], v[120:121], v[124:125]
	v_lshlrev_b32_e32 v124, 16, v196
	v_and_b32_e32 v125, 0xffff0000, v196
	v_lshlrev_b32_e32 v146, 16, v216
	v_and_b32_e32 v147, 0xffff0000, v216
	v_lshlrev_b32_e32 v122, 16, v197
	v_and_b32_e32 v123, 0xffff0000, v197
	v_lshlrev_b32_e32 v126, 16, v217
	v_and_b32_e32 v127, 0xffff0000, v217
	v_add_u32_e32 v250, 0x18000, v249
	global_load_dwordx4 v[194:197], v250, s[66:67] offset:256
	global_load_dwordx4 v[214:217], v250, s[64:65] offset:256
	v_pk_add_f32 v[124:125], v[124:125], v[146:147]
	v_pk_add_f32 v[122:123], v[122:123], v[126:127]
	v_pk_add_f32 v[112:113], v[112:113], v[120:121]
	v_pk_add_f32 v[110:111], v[110:111], v[128:129]
	v_pk_add_f32 v[120:121], v[108:109], v[122:123]
	v_pk_add_f32 v[122:123], v[106:107], v[124:125]
	v_cvt_pk_bf16_f32 v106, v110, v111
	v_cvt_pk_bf16_f32 v107, v112, v113
	v_lshlrev_b32_e32 v108, 16, v106
	v_and_b32_e32 v109, 0xffff0000, v106
	v_lshlrev_b32_e32 v124, 16, v107
	v_and_b32_e32 v125, 0xffff0000, v107
	v_sub_f32_e32 v112, v112, v124
	v_sub_f32_e32 v113, v113, v125
	v_sub_f32_e32 v110, v110, v108
	v_sub_f32_e32 v111, v111, v109
	v_cvt_pk_bf16_f32 v110, v110, v111
	v_cvt_pk_bf16_f32 v111, v112, v113
	v_lshlrev_b32_e32 v112, 16, v110
	v_and_b32_e32 v113, 0xffff0000, v110
	v_lshlrev_b32_e32 v126, 16, v111
	v_and_b32_e32 v127, 0xffff0000, v111
	v_pk_add_f32 v[124:125], v[124:125], v[126:127]
	v_pk_add_f32 v[126:127], v[108:109], v[112:113]
	v_cvt_pk_bf16_f32 v108, v122, v123
	v_cvt_pk_bf16_f32 v109, v120, v121
	v_lshlrev_b32_e32 v128, 16, v108
	v_and_b32_e32 v129, 0xffff0000, v108
	v_lshlrev_b32_e32 v146, 16, v109
	v_and_b32_e32 v147, 0xffff0000, v109
	v_sub_f32_e32 v113, v120, v146
	v_sub_f32_e32 v120, v121, v147
	v_sub_f32_e32 v112, v122, v128
	v_sub_f32_e32 v121, v123, v129
	v_cvt_pk_bf16_f32 v112, v112, v121
	v_cvt_pk_bf16_f32 v113, v113, v120
	global_store_dwordx4 v[114:115], v[106:109], off
	global_store_dwordx4 v[116:117], v[110:113], off
	v_lshlrev_b32_e32 v120, 16, v112
	v_and_b32_e32 v121, 0xffff0000, v112
	v_mul_f32_e32 v106, v127, v127
	v_mul_f32_e32 v107, v125, v125
	v_pk_add_f32 v[120:121], v[128:129], v[120:121]
	v_fmac_f32_e32 v106, v126, v126
	v_fmac_f32_e32 v107, v124, v124
	v_lshlrev_b32_e32 v122, 16, v113
	v_and_b32_e32 v123, 0xffff0000, v113
	v_add_f32_e32 v106, v106, v107
	v_mul_f32_e32 v107, v121, v121
	v_pk_add_f32 v[122:123], v[146:147], v[122:123]
	v_fmac_f32_e32 v107, v120, v120
	v_add_f32_e32 v106, v106, v107
	v_mul_f32_e32 v107, v123, v123
	v_fmac_f32_e32 v107, v122, v122
	v_add_f32_e32 v124, v107, v106
	s_waitcnt vmcnt(14)
	v_lshlrev_b32_e32 v120, 16, v218
	v_and_b32_e32 v121, 0xffff0000, v218
	v_lshlrev_b32_e32 v122, 16, v222
	v_and_b32_e32 v123, 0xffff0000, v222
	v_lshlrev_b32_e32 v106, 16, v219
	v_and_b32_e32 v107, 0xffff0000, v219
	v_lshlrev_b32_e32 v110, 16, v223
	v_and_b32_e32 v111, 0xffff0000, v223
	v_pk_add_f32 v[120:121], v[120:121], v[122:123]
	v_pk_add_f32 v[106:107], v[106:107], v[110:111]
	v_lshlrev_b32_e32 v110, 16, v220
	v_and_b32_e32 v111, 0xffff0000, v220
	v_lshlrev_b32_e32 v122, 16, v224
	v_and_b32_e32 v123, 0xffff0000, v224
	v_lshlrev_b32_e32 v108, 16, v221
	v_and_b32_e32 v109, 0xffff0000, v221
	v_lshlrev_b32_e32 v112, 16, v225
	v_and_b32_e32 v113, 0xffff0000, v225
	v_add_u32_e32 v251, 0x40000, v249
	global_load_dwordx4 v[218:221], v251, s[66:67]
	global_load_dwordx4 v[222:225], v251, s[64:65]
	v_pk_add_f32 v[110:111], v[110:111], v[122:123]
	v_pk_add_f32 v[108:109], v[108:109], v[112:113]
	v_pk_add_f32 v[104:105], v[104:105], v[106:107]
	v_pk_add_f32 v[102:103], v[102:103], v[120:121]
	v_pk_add_f32 v[106:107], v[100:101], v[108:109]
	v_pk_add_f32 v[108:109], v[98:99], v[110:111]
	v_cvt_pk_bf16_f32 v98, v102, v103
	v_cvt_pk_bf16_f32 v99, v104, v105
	v_lshlrev_b32_e32 v100, 16, v98
	v_and_b32_e32 v101, 0xffff0000, v98
	v_lshlrev_b32_e32 v110, 16, v99
	v_and_b32_e32 v111, 0xffff0000, v99
	v_sub_f32_e32 v104, v104, v110
	v_sub_f32_e32 v105, v105, v111
	v_sub_f32_e32 v102, v102, v100
	v_sub_f32_e32 v103, v103, v101
	v_cvt_pk_bf16_f32 v102, v102, v103
	v_cvt_pk_bf16_f32 v103, v104, v105
	v_lshlrev_b32_e32 v104, 16, v102
	v_and_b32_e32 v105, 0xffff0000, v102
	v_lshlrev_b32_e32 v112, 16, v103
	v_and_b32_e32 v113, 0xffff0000, v103
	v_pk_add_f32 v[110:111], v[110:111], v[112:113]
	v_pk_add_f32 v[112:113], v[100:101], v[104:105]
	v_cvt_pk_bf16_f32 v100, v108, v109
	v_cvt_pk_bf16_f32 v101, v106, v107
	v_lshlrev_b32_e32 v120, 16, v100
	v_and_b32_e32 v121, 0xffff0000, v100
	v_lshlrev_b32_e32 v122, 16, v101
	v_and_b32_e32 v123, 0xffff0000, v101
	v_sub_f32_e32 v105, v106, v122
	v_sub_f32_e32 v106, v107, v123
	v_sub_f32_e32 v104, v108, v120
	v_sub_f32_e32 v107, v109, v121
	v_cvt_pk_bf16_f32 v104, v104, v107
	v_cvt_pk_bf16_f32 v105, v105, v106
	global_store_dwordx4 v[114:115], v[98:101], off offset:256
	global_store_dwordx4 v[116:117], v[102:105], off offset:256
	v_lshlrev_b32_e32 v106, 16, v104
	v_and_b32_e32 v107, 0xffff0000, v104
	v_mul_f32_e32 v98, v113, v113
	v_mul_f32_e32 v99, v111, v111
	v_pk_add_f32 v[106:107], v[120:121], v[106:107]
	v_fmac_f32_e32 v98, v112, v112
	v_fmac_f32_e32 v99, v110, v110
	v_lshlrev_b32_e32 v108, 16, v105
	v_and_b32_e32 v109, 0xffff0000, v105
	v_add_f32_e32 v98, v98, v99
	v_mul_f32_e32 v99, v107, v107
	v_pk_add_f32 v[108:109], v[122:123], v[108:109]
	v_fmac_f32_e32 v99, v106, v106
	v_add_f32_e32 v98, v98, v99
	v_mul_f32_e32 v99, v109, v109
	v_fmac_f32_e32 v99, v108, v108
	v_add_f32_e32 v98, v99, v98
	v_add_f32_e32 v98, v124, v98
	ds_bpermute_b32 v99, v204, v98
	s_waitcnt lgkmcnt(0)
	v_add_f32_e32 v102, v98, v99
	v_add_u32_e32 v98, 32, v144
	v_ashrrev_i32_e32 v99, 31, v98
	v_lshlrev_b64 v[100:101], 11, v[98:99]
	v_lshl_add_u64 v[98:99], s[66:67], 0, v[100:101]
	v_lshl_add_u64 v[98:99], v[98:99], 0, v[142:143]
	v_lshl_add_u64 v[100:101], s[64:65], 0, v[100:101]
	v_lshl_add_u64 v[100:101], v[100:101], 0, v[142:143]
	ds_bpermute_b32 v103, v205, v102
	s_waitcnt vmcnt(16)
	v_lshlrev_b32_e32 v112, 16, v226
	v_and_b32_e32 v113, 0xffff0000, v226
	v_lshlrev_b32_e32 v114, 16, v230
	v_and_b32_e32 v115, 0xffff0000, v230
	v_lshlrev_b32_e32 v104, 16, v227
	v_and_b32_e32 v105, 0xffff0000, v227
	v_lshlrev_b32_e32 v108, 16, v231
	v_and_b32_e32 v109, 0xffff0000, v231
	v_pk_add_f32 v[112:113], v[112:113], v[114:115]
	v_pk_add_f32 v[104:105], v[104:105], v[108:109]
	v_lshlrev_b32_e32 v108, 16, v228
	v_and_b32_e32 v109, 0xffff0000, v228
	v_lshlrev_b32_e32 v114, 16, v232
	v_and_b32_e32 v115, 0xffff0000, v232
	v_lshlrev_b32_e32 v106, 16, v229
	v_and_b32_e32 v107, 0xffff0000, v229
	v_lshlrev_b32_e32 v110, 16, v233
	v_and_b32_e32 v111, 0xffff0000, v233
	v_add_u32_e32 v250, 0x40000, v249
	global_load_dwordx4 v[226:229], v250, s[66:67] offset:256
	global_load_dwordx4 v[230:233], v250, s[64:65] offset:256
	v_pk_add_f32 v[108:109], v[108:109], v[114:115]
	v_pk_add_f32 v[106:107], v[106:107], v[110:111]
	v_pk_add_f32 v[96:97], v[96:97], v[104:105]
	v_pk_add_f32 v[94:95], v[94:95], v[112:113]
	v_pk_add_f32 v[104:105], v[92:93], v[106:107]
	v_pk_add_f32 v[106:107], v[90:91], v[108:109]
	v_cvt_pk_bf16_f32 v90, v94, v95
	v_cvt_pk_bf16_f32 v91, v96, v97
	v_lshlrev_b32_e32 v92, 16, v90
	v_and_b32_e32 v93, 0xffff0000, v90
	v_lshlrev_b32_e32 v108, 16, v91
	v_and_b32_e32 v109, 0xffff0000, v91
	v_sub_f32_e32 v96, v96, v108
	v_sub_f32_e32 v97, v97, v109
	v_sub_f32_e32 v94, v94, v92
	v_sub_f32_e32 v95, v95, v93
	v_cvt_pk_bf16_f32 v94, v94, v95
	v_cvt_pk_bf16_f32 v95, v96, v97
	v_lshlrev_b32_e32 v96, 16, v94
	v_and_b32_e32 v97, 0xffff0000, v94
	v_lshlrev_b32_e32 v110, 16, v95
	v_and_b32_e32 v111, 0xffff0000, v95
	v_pk_add_f32 v[108:109], v[108:109], v[110:111]
	v_pk_add_f32 v[110:111], v[92:93], v[96:97]
	v_cvt_pk_bf16_f32 v92, v106, v107
	v_cvt_pk_bf16_f32 v93, v104, v105
	v_lshlrev_b32_e32 v112, 16, v92
	v_and_b32_e32 v113, 0xffff0000, v92
	v_lshlrev_b32_e32 v114, 16, v93
	v_and_b32_e32 v115, 0xffff0000, v93
	v_sub_f32_e32 v97, v104, v114
	v_sub_f32_e32 v104, v105, v115
	v_sub_f32_e32 v96, v106, v112
	v_sub_f32_e32 v105, v107, v113
	v_cvt_pk_bf16_f32 v96, v96, v105
	v_cvt_pk_bf16_f32 v97, v97, v104
	global_store_dwordx4 v[98:99], v[90:93], off
	global_store_dwordx4 v[100:101], v[94:97], off
	v_lshlrev_b32_e32 v104, 16, v96
	v_and_b32_e32 v105, 0xffff0000, v96
	v_mul_f32_e32 v90, v111, v111
	v_mul_f32_e32 v91, v109, v109
	v_pk_add_f32 v[104:105], v[112:113], v[104:105]
	v_fmac_f32_e32 v90, v110, v110
	v_fmac_f32_e32 v91, v108, v108
	v_lshlrev_b32_e32 v106, 16, v97
	v_and_b32_e32 v107, 0xffff0000, v97
	v_add_f32_e32 v90, v90, v91
	v_mul_f32_e32 v91, v105, v105
	v_pk_add_f32 v[106:107], v[114:115], v[106:107]
	v_fmac_f32_e32 v91, v104, v104
	v_add_f32_e32 v90, v90, v91
	v_mul_f32_e32 v91, v107, v107
	v_fmac_f32_e32 v91, v106, v106
	v_add_f32_e32 v108, v91, v90
	s_waitcnt vmcnt(18)
	v_lshlrev_b32_e32 v104, 16, v170
	v_and_b32_e32 v105, 0xffff0000, v170
	v_lshlrev_b32_e32 v106, 16, v174
	v_and_b32_e32 v107, 0xffff0000, v174
	v_lshlrev_b32_e32 v90, 16, v171
	v_and_b32_e32 v91, 0xffff0000, v171
	v_lshlrev_b32_e32 v94, 16, v175
	v_and_b32_e32 v95, 0xffff0000, v175
	v_pk_add_f32 v[104:105], v[104:105], v[106:107]
	v_pk_add_f32 v[90:91], v[90:91], v[94:95]
	v_lshlrev_b32_e32 v94, 16, v172
	v_and_b32_e32 v95, 0xffff0000, v172
	v_lshlrev_b32_e32 v106, 16, v176
	v_and_b32_e32 v107, 0xffff0000, v176
	v_lshlrev_b32_e32 v92, 16, v173
	v_and_b32_e32 v93, 0xffff0000, v173
	v_lshlrev_b32_e32 v96, 16, v177
	v_and_b32_e32 v97, 0xffff0000, v177
	v_add_u32_e32 v251, 0x48000, v249
	global_load_dwordx4 v[170:173], v251, s[66:67]
	global_load_dwordx4 v[174:177], v251, s[64:65]
	v_pk_add_f32 v[94:95], v[94:95], v[106:107]
	v_pk_add_f32 v[92:93], v[92:93], v[96:97]
	v_pk_add_f32 v[88:89], v[88:89], v[90:91]
	v_pk_add_f32 v[86:87], v[86:87], v[104:105]
	v_pk_add_f32 v[90:91], v[84:85], v[92:93]
	v_pk_add_f32 v[92:93], v[82:83], v[94:95]
	v_cvt_pk_bf16_f32 v82, v86, v87
	v_cvt_pk_bf16_f32 v83, v88, v89
	v_lshlrev_b32_e32 v84, 16, v82
	v_and_b32_e32 v85, 0xffff0000, v82
	v_lshlrev_b32_e32 v94, 16, v83
	v_and_b32_e32 v95, 0xffff0000, v83
	v_sub_f32_e32 v88, v88, v94
	v_sub_f32_e32 v89, v89, v95
	v_sub_f32_e32 v86, v86, v84
	v_sub_f32_e32 v87, v87, v85
	v_cvt_pk_bf16_f32 v86, v86, v87
	v_cvt_pk_bf16_f32 v87, v88, v89
	v_lshlrev_b32_e32 v88, 16, v86
	v_and_b32_e32 v89, 0xffff0000, v86
	v_lshlrev_b32_e32 v96, 16, v87
	v_and_b32_e32 v97, 0xffff0000, v87
	v_pk_add_f32 v[94:95], v[94:95], v[96:97]
	v_pk_add_f32 v[96:97], v[84:85], v[88:89]
	v_cvt_pk_bf16_f32 v84, v92, v93
	v_cvt_pk_bf16_f32 v85, v90, v91
	v_lshlrev_b32_e32 v104, 16, v84
	v_and_b32_e32 v105, 0xffff0000, v84
	v_lshlrev_b32_e32 v106, 16, v85
	v_and_b32_e32 v107, 0xffff0000, v85
	v_sub_f32_e32 v89, v90, v106
	v_sub_f32_e32 v90, v91, v107
	v_sub_f32_e32 v88, v92, v104
	v_sub_f32_e32 v91, v93, v105
	v_cvt_pk_bf16_f32 v88, v88, v91
	v_cvt_pk_bf16_f32 v89, v89, v90
	global_store_dwordx4 v[98:99], v[82:85], off offset:256
	global_store_dwordx4 v[100:101], v[86:89], off offset:256
	v_lshlrev_b32_e32 v90, 16, v88
	v_and_b32_e32 v91, 0xffff0000, v88
	v_mul_f32_e32 v82, v97, v97
	v_mul_f32_e32 v83, v95, v95
	v_pk_add_f32 v[90:91], v[104:105], v[90:91]
	v_fmac_f32_e32 v82, v96, v96
	v_fmac_f32_e32 v83, v94, v94
	v_lshlrev_b32_e32 v92, 16, v89
	v_and_b32_e32 v93, 0xffff0000, v89
	v_add_f32_e32 v82, v82, v83
	v_mul_f32_e32 v83, v91, v91
	v_pk_add_f32 v[92:93], v[106:107], v[92:93]
	v_fmac_f32_e32 v83, v90, v90
	v_add_f32_e32 v82, v82, v83
	v_mul_f32_e32 v83, v93, v93
	v_fmac_f32_e32 v83, v92, v92
	v_add_f32_e32 v82, v83, v82
	v_add_f32_e32 v82, v108, v82
	ds_bpermute_b32 v83, v204, v82
	s_waitcnt lgkmcnt(0)
	v_add_f32_e32 v86, v82, v83
	v_add_u32_e32 v82, 48, v144
	v_ashrrev_i32_e32 v83, 31, v82
	v_lshlrev_b64 v[84:85], 11, v[82:83]
	v_lshl_add_u64 v[82:83], s[66:67], 0, v[84:85]
	v_lshl_add_u64 v[82:83], v[82:83], 0, v[142:143]
	v_lshl_add_u64 v[84:85], s[64:65], 0, v[84:85]
	v_lshl_add_u64 v[84:85], v[84:85], 0, v[142:143]
	ds_bpermute_b32 v87, v205, v86
	s_waitcnt vmcnt(18)
	v_lshlrev_b32_e32 v96, 16, v178
	v_and_b32_e32 v97, 0xffff0000, v178
	v_lshlrev_b32_e32 v98, 16, v190
	v_and_b32_e32 v99, 0xffff0000, v190
	v_lshlrev_b32_e32 v88, 16, v179
	v_and_b32_e32 v89, 0xffff0000, v179
	v_lshlrev_b32_e32 v92, 16, v191
	v_and_b32_e32 v93, 0xffff0000, v191
	v_pk_add_f32 v[96:97], v[96:97], v[98:99]
	v_pk_add_f32 v[88:89], v[88:89], v[92:93]
	v_lshlrev_b32_e32 v92, 16, v180
	v_and_b32_e32 v93, 0xffff0000, v180
	v_lshlrev_b32_e32 v98, 16, v192
	v_and_b32_e32 v99, 0xffff0000, v192
	v_lshlrev_b32_e32 v90, 16, v181
	v_and_b32_e32 v91, 0xffff0000, v181
	v_lshlrev_b32_e32 v94, 16, v193
	v_and_b32_e32 v95, 0xffff0000, v193
	v_add_u32_e32 v250, 0x48000, v249
	global_load_dwordx4 v[178:181], v250, s[66:67] offset:256
	global_load_dwordx4 v[190:193], v250, s[64:65] offset:256
	v_pk_add_f32 v[92:93], v[92:93], v[98:99]
	v_pk_add_f32 v[90:91], v[90:91], v[94:95]
	v_pk_add_f32 v[80:81], v[80:81], v[88:89]
	v_pk_add_f32 v[78:79], v[78:79], v[96:97]
	v_pk_add_f32 v[88:89], v[76:77], v[90:91]
	v_pk_add_f32 v[90:91], v[74:75], v[92:93]
	v_cvt_pk_bf16_f32 v74, v78, v79
	v_cvt_pk_bf16_f32 v75, v80, v81
	v_lshlrev_b32_e32 v76, 16, v74
	v_and_b32_e32 v77, 0xffff0000, v74
	v_lshlrev_b32_e32 v92, 16, v75
	v_and_b32_e32 v93, 0xffff0000, v75
	v_sub_f32_e32 v80, v80, v92
	v_sub_f32_e32 v81, v81, v93
	v_sub_f32_e32 v78, v78, v76
	v_sub_f32_e32 v79, v79, v77
	v_cvt_pk_bf16_f32 v78, v78, v79
	v_cvt_pk_bf16_f32 v79, v80, v81
	v_lshlrev_b32_e32 v80, 16, v78
	v_and_b32_e32 v81, 0xffff0000, v78
	v_lshlrev_b32_e32 v94, 16, v79
	v_and_b32_e32 v95, 0xffff0000, v79
	v_pk_add_f32 v[92:93], v[92:93], v[94:95]
	v_pk_add_f32 v[94:95], v[76:77], v[80:81]
	v_cvt_pk_bf16_f32 v76, v90, v91
	v_cvt_pk_bf16_f32 v77, v88, v89
	v_lshlrev_b32_e32 v96, 16, v76
	v_and_b32_e32 v97, 0xffff0000, v76
	v_lshlrev_b32_e32 v98, 16, v77
	v_and_b32_e32 v99, 0xffff0000, v77
	v_sub_f32_e32 v81, v88, v98
	v_sub_f32_e32 v88, v89, v99
	v_sub_f32_e32 v80, v90, v96
	v_sub_f32_e32 v89, v91, v97
	v_cvt_pk_bf16_f32 v80, v80, v89
	v_cvt_pk_bf16_f32 v81, v81, v88
	global_store_dwordx4 v[82:83], v[74:77], off
	global_store_dwordx4 v[84:85], v[78:81], off
	v_lshlrev_b32_e32 v88, 16, v80
	v_and_b32_e32 v89, 0xffff0000, v80
	v_mul_f32_e32 v74, v95, v95
	v_mul_f32_e32 v75, v93, v93
	v_pk_add_f32 v[88:89], v[96:97], v[88:89]
	v_fmac_f32_e32 v74, v94, v94
	v_fmac_f32_e32 v75, v92, v92
	v_lshlrev_b32_e32 v90, 16, v81
	v_and_b32_e32 v91, 0xffff0000, v81
	v_add_f32_e32 v74, v74, v75
	v_mul_f32_e32 v75, v89, v89
	v_pk_add_f32 v[90:91], v[98:99], v[90:91]
	v_fmac_f32_e32 v75, v88, v88
	v_add_f32_e32 v74, v74, v75
	v_mul_f32_e32 v75, v91, v91
	v_fmac_f32_e32 v75, v90, v90
	v_add_f32_e32 v92, v75, v74
	s_waitcnt vmcnt(18)
	v_lshlrev_b32_e32 v88, 16, v194
	v_and_b32_e32 v89, 0xffff0000, v194
	v_lshlrev_b32_e32 v90, 16, v214
	v_and_b32_e32 v91, 0xffff0000, v214
	v_lshlrev_b32_e32 v74, 16, v195
	v_and_b32_e32 v75, 0xffff0000, v195
	v_lshlrev_b32_e32 v78, 16, v215
	v_and_b32_e32 v79, 0xffff0000, v215
	v_pk_add_f32 v[88:89], v[88:89], v[90:91]
	v_pk_add_f32 v[74:75], v[74:75], v[78:79]
	v_lshlrev_b32_e32 v78, 16, v196
	v_and_b32_e32 v79, 0xffff0000, v196
	v_lshlrev_b32_e32 v90, 16, v216
	v_and_b32_e32 v91, 0xffff0000, v216
	v_lshlrev_b32_e32 v76, 16, v197
	v_and_b32_e32 v77, 0xffff0000, v197
	v_lshlrev_b32_e32 v80, 16, v217
	v_and_b32_e32 v81, 0xffff0000, v217
	v_add_u32_e32 v251, 0x50000, v249
	global_load_dwordx4 v[194:197], v251, s[66:67]
	global_load_dwordx4 v[214:217], v251, s[64:65]
	v_pk_add_f32 v[78:79], v[78:79], v[90:91]
	v_pk_add_f32 v[76:77], v[76:77], v[80:81]
	v_pk_add_f32 v[72:73], v[72:73], v[74:75]
	v_pk_add_f32 v[70:71], v[70:71], v[88:89]
	v_pk_add_f32 v[74:75], v[68:69], v[76:77]
	v_pk_add_f32 v[76:77], v[66:67], v[78:79]
	v_cvt_pk_bf16_f32 v66, v70, v71
	v_cvt_pk_bf16_f32 v67, v72, v73
	v_lshlrev_b32_e32 v68, 16, v66
	v_and_b32_e32 v69, 0xffff0000, v66
	v_lshlrev_b32_e32 v78, 16, v67
	v_and_b32_e32 v79, 0xffff0000, v67
	v_sub_f32_e32 v72, v72, v78
	v_sub_f32_e32 v73, v73, v79
	v_sub_f32_e32 v70, v70, v68
	v_sub_f32_e32 v71, v71, v69
	v_cvt_pk_bf16_f32 v70, v70, v71
	v_cvt_pk_bf16_f32 v71, v72, v73
	v_lshlrev_b32_e32 v72, 16, v70
	v_and_b32_e32 v73, 0xffff0000, v70
	v_lshlrev_b32_e32 v80, 16, v71
	v_and_b32_e32 v81, 0xffff0000, v71
	v_pk_add_f32 v[78:79], v[78:79], v[80:81]
	v_pk_add_f32 v[80:81], v[68:69], v[72:73]
	v_cvt_pk_bf16_f32 v68, v76, v77
	v_cvt_pk_bf16_f32 v69, v74, v75
	v_lshlrev_b32_e32 v88, 16, v68
	v_and_b32_e32 v89, 0xffff0000, v68
	v_lshlrev_b32_e32 v90, 16, v69
	v_and_b32_e32 v91, 0xffff0000, v69
	v_sub_f32_e32 v73, v74, v90
	v_sub_f32_e32 v74, v75, v91
	v_sub_f32_e32 v72, v76, v88
	v_sub_f32_e32 v75, v77, v89
	v_cvt_pk_bf16_f32 v72, v72, v75
	v_cvt_pk_bf16_f32 v73, v73, v74
	global_store_dwordx4 v[82:83], v[66:69], off offset:256
	global_store_dwordx4 v[84:85], v[70:73], off offset:256
	v_lshlrev_b32_e32 v74, 16, v72
	v_and_b32_e32 v75, 0xffff0000, v72
	v_mul_f32_e32 v66, v81, v81
	v_mul_f32_e32 v67, v79, v79
	v_pk_add_f32 v[74:75], v[88:89], v[74:75]
	v_fmac_f32_e32 v66, v80, v80
	v_fmac_f32_e32 v67, v78, v78
	v_lshlrev_b32_e32 v76, 16, v73
	v_and_b32_e32 v77, 0xffff0000, v73
	v_add_f32_e32 v66, v66, v67
	v_mul_f32_e32 v67, v75, v75
	v_pk_add_f32 v[76:77], v[90:91], v[76:77]
	v_fmac_f32_e32 v67, v74, v74
	v_add_f32_e32 v66, v66, v67
	v_mul_f32_e32 v67, v77, v77
	v_fmac_f32_e32 v67, v76, v76
	v_add_f32_e32 v66, v67, v66
	v_add_f32_e32 v66, v92, v66
	ds_bpermute_b32 v67, v204, v66
	s_waitcnt lgkmcnt(0)
	v_add_f32_e32 v70, v66, v67
	v_add_u32_e32 v66, 0x80, v144
	v_ashrrev_i32_e32 v67, 31, v66
	v_lshlrev_b64 v[68:69], 11, v[66:67]
	v_lshl_add_u64 v[66:67], s[66:67], 0, v[68:69]
	v_lshl_add_u64 v[66:67], v[66:67], 0, v[142:143]
	v_lshl_add_u64 v[68:69], s[64:65], 0, v[68:69]
	v_lshl_add_u64 v[68:69], v[68:69], 0, v[142:143]
	ds_bpermute_b32 v71, v205, v70
	s_waitcnt vmcnt(18)
	v_lshlrev_b32_e32 v80, 16, v218
	v_and_b32_e32 v81, 0xffff0000, v218
	v_lshlrev_b32_e32 v82, 16, v222
	v_and_b32_e32 v83, 0xffff0000, v222
	v_lshlrev_b32_e32 v72, 16, v219
	v_and_b32_e32 v73, 0xffff0000, v219
	v_lshlrev_b32_e32 v76, 16, v223
	v_and_b32_e32 v77, 0xffff0000, v223
	v_pk_add_f32 v[80:81], v[80:81], v[82:83]
	v_pk_add_f32 v[72:73], v[72:73], v[76:77]
	v_lshlrev_b32_e32 v76, 16, v220
	v_and_b32_e32 v77, 0xffff0000, v220
	v_lshlrev_b32_e32 v82, 16, v224
	v_and_b32_e32 v83, 0xffff0000, v224
	v_lshlrev_b32_e32 v74, 16, v221
	v_and_b32_e32 v75, 0xffff0000, v221
	v_lshlrev_b32_e32 v78, 16, v225
	v_and_b32_e32 v79, 0xffff0000, v225
	v_add_u32_e32 v250, 0x50000, v249
	global_load_dwordx4 v[218:221], v250, s[66:67] offset:256
	global_load_dwordx4 v[222:225], v250, s[64:65] offset:256
	v_pk_add_f32 v[76:77], v[76:77], v[82:83]
	v_pk_add_f32 v[74:75], v[74:75], v[78:79]
	v_pk_add_f32 v[64:65], v[64:65], v[72:73]
	v_pk_add_f32 v[62:63], v[62:63], v[80:81]
	v_pk_add_f32 v[72:73], v[60:61], v[74:75]
	v_pk_add_f32 v[74:75], v[58:59], v[76:77]
	v_cvt_pk_bf16_f32 v58, v62, v63
	v_cvt_pk_bf16_f32 v59, v64, v65
	v_lshlrev_b32_e32 v60, 16, v58
	v_and_b32_e32 v61, 0xffff0000, v58
	v_lshlrev_b32_e32 v76, 16, v59
	v_and_b32_e32 v77, 0xffff0000, v59
	v_sub_f32_e32 v64, v64, v76
	v_sub_f32_e32 v65, v65, v77
	v_sub_f32_e32 v62, v62, v60
	v_sub_f32_e32 v63, v63, v61
	v_cvt_pk_bf16_f32 v62, v62, v63
	v_cvt_pk_bf16_f32 v63, v64, v65
	v_lshlrev_b32_e32 v64, 16, v62
	v_and_b32_e32 v65, 0xffff0000, v62
	v_lshlrev_b32_e32 v78, 16, v63
	v_and_b32_e32 v79, 0xffff0000, v63
	v_pk_add_f32 v[76:77], v[76:77], v[78:79]
	v_pk_add_f32 v[78:79], v[60:61], v[64:65]
	v_cvt_pk_bf16_f32 v60, v74, v75
	v_cvt_pk_bf16_f32 v61, v72, v73
	v_lshlrev_b32_e32 v80, 16, v60
	v_and_b32_e32 v81, 0xffff0000, v60
	v_lshlrev_b32_e32 v82, 16, v61
	v_and_b32_e32 v83, 0xffff0000, v61
	v_sub_f32_e32 v65, v72, v82
	v_sub_f32_e32 v72, v73, v83
	v_sub_f32_e32 v64, v74, v80
	v_sub_f32_e32 v73, v75, v81
	v_cvt_pk_bf16_f32 v64, v64, v73
	v_cvt_pk_bf16_f32 v65, v65, v72
	global_store_dwordx4 v[66:67], v[58:61], off
	global_store_dwordx4 v[68:69], v[62:65], off
	v_lshlrev_b32_e32 v72, 16, v64
	v_and_b32_e32 v73, 0xffff0000, v64
	v_mul_f32_e32 v58, v79, v79
	v_mul_f32_e32 v59, v77, v77
	v_pk_add_f32 v[72:73], v[80:81], v[72:73]
	v_fmac_f32_e32 v58, v78, v78
	v_fmac_f32_e32 v59, v76, v76
	v_lshlrev_b32_e32 v74, 16, v65
	v_and_b32_e32 v75, 0xffff0000, v65
	v_add_f32_e32 v58, v58, v59
	v_mul_f32_e32 v59, v73, v73
	v_pk_add_f32 v[74:75], v[82:83], v[74:75]
	v_fmac_f32_e32 v59, v72, v72
	v_add_f32_e32 v58, v58, v59
	v_mul_f32_e32 v59, v75, v75
	v_fmac_f32_e32 v59, v74, v74
	v_add_f32_e32 v76, v59, v58
	s_waitcnt vmcnt(18)
	v_lshlrev_b32_e32 v72, 16, v226
	v_and_b32_e32 v73, 0xffff0000, v226
	v_lshlrev_b32_e32 v74, 16, v230
	v_and_b32_e32 v75, 0xffff0000, v230
	v_lshlrev_b32_e32 v58, 16, v227
	v_and_b32_e32 v59, 0xffff0000, v227
	v_lshlrev_b32_e32 v62, 16, v231
	v_and_b32_e32 v63, 0xffff0000, v231
	v_pk_add_f32 v[72:73], v[72:73], v[74:75]
	v_pk_add_f32 v[58:59], v[58:59], v[62:63]
	v_lshlrev_b32_e32 v62, 16, v228
	v_and_b32_e32 v63, 0xffff0000, v228
	v_lshlrev_b32_e32 v74, 16, v232
	v_and_b32_e32 v75, 0xffff0000, v232
	v_lshlrev_b32_e32 v60, 16, v229
	v_and_b32_e32 v61, 0xffff0000, v229
	v_lshlrev_b32_e32 v64, 16, v233
	v_and_b32_e32 v65, 0xffff0000, v233
	v_add_u32_e32 v251, 0x58000, v249
	global_load_dwordx4 v[226:229], v251, s[66:67]
	global_load_dwordx4 v[230:233], v251, s[64:65]
	v_pk_add_f32 v[62:63], v[62:63], v[74:75]
	v_pk_add_f32 v[60:61], v[60:61], v[64:65]
	v_pk_add_f32 v[56:57], v[56:57], v[58:59]
	v_pk_add_f32 v[54:55], v[54:55], v[72:73]
	v_pk_add_f32 v[58:59], v[52:53], v[60:61]
	v_pk_add_f32 v[60:61], v[50:51], v[62:63]
	v_cvt_pk_bf16_f32 v50, v54, v55
	v_cvt_pk_bf16_f32 v51, v56, v57
	v_lshlrev_b32_e32 v52, 16, v50
	v_and_b32_e32 v53, 0xffff0000, v50
	v_lshlrev_b32_e32 v62, 16, v51
	v_and_b32_e32 v63, 0xffff0000, v51
	v_sub_f32_e32 v56, v56, v62
	v_sub_f32_e32 v57, v57, v63
	v_sub_f32_e32 v54, v54, v52
	v_sub_f32_e32 v55, v55, v53
	v_cvt_pk_bf16_f32 v54, v54, v55
	v_cvt_pk_bf16_f32 v55, v56, v57
	v_lshlrev_b32_e32 v56, 16, v54
	v_and_b32_e32 v57, 0xffff0000, v54
	v_lshlrev_b32_e32 v64, 16, v55
	v_and_b32_e32 v65, 0xffff0000, v55
	v_pk_add_f32 v[62:63], v[62:63], v[64:65]
	v_pk_add_f32 v[64:65], v[52:53], v[56:57]
	v_cvt_pk_bf16_f32 v52, v60, v61
	v_cvt_pk_bf16_f32 v53, v58, v59
	v_lshlrev_b32_e32 v72, 16, v52
	v_and_b32_e32 v73, 0xffff0000, v52
	v_lshlrev_b32_e32 v74, 16, v53
	v_and_b32_e32 v75, 0xffff0000, v53
	v_sub_f32_e32 v57, v58, v74
	v_sub_f32_e32 v58, v59, v75
	v_sub_f32_e32 v56, v60, v72
	v_sub_f32_e32 v59, v61, v73
	v_cvt_pk_bf16_f32 v56, v56, v59
	v_cvt_pk_bf16_f32 v57, v57, v58
	global_store_dwordx4 v[66:67], v[50:53], off offset:256
	global_store_dwordx4 v[68:69], v[54:57], off offset:256
	v_lshlrev_b32_e32 v58, 16, v56
	v_and_b32_e32 v59, 0xffff0000, v56
	v_mul_f32_e32 v50, v65, v65
	v_mul_f32_e32 v51, v63, v63
	v_pk_add_f32 v[58:59], v[72:73], v[58:59]
	v_fmac_f32_e32 v50, v64, v64
	v_fmac_f32_e32 v51, v62, v62
	v_lshlrev_b32_e32 v60, 16, v57
	v_and_b32_e32 v61, 0xffff0000, v57
	v_add_f32_e32 v50, v50, v51
	v_mul_f32_e32 v51, v59, v59
	v_pk_add_f32 v[60:61], v[74:75], v[60:61]
	v_fmac_f32_e32 v51, v58, v58
	v_add_f32_e32 v50, v50, v51
	v_mul_f32_e32 v51, v61, v61
	v_fmac_f32_e32 v51, v60, v60
	v_add_f32_e32 v50, v51, v50
	v_add_f32_e32 v50, v76, v50
	ds_bpermute_b32 v51, v204, v50
	s_waitcnt lgkmcnt(0)
	v_add_f32_e32 v54, v50, v51
	v_add_u32_e32 v50, 0x90, v144
	v_ashrrev_i32_e32 v51, 31, v50
	v_lshlrev_b64 v[52:53], 11, v[50:51]
	v_lshl_add_u64 v[50:51], s[66:67], 0, v[52:53]
	v_lshl_add_u64 v[50:51], v[50:51], 0, v[142:143]
	v_lshl_add_u64 v[52:53], s[64:65], 0, v[52:53]
	v_lshl_add_u64 v[52:53], v[52:53], 0, v[142:143]
	ds_bpermute_b32 v55, v205, v54
	s_waitcnt vmcnt(18)
	v_lshlrev_b32_e32 v64, 16, v170
	v_and_b32_e32 v65, 0xffff0000, v170
	v_lshlrev_b32_e32 v66, 16, v174
	v_and_b32_e32 v67, 0xffff0000, v174
	v_lshlrev_b32_e32 v56, 16, v171
	v_and_b32_e32 v57, 0xffff0000, v171
	v_lshlrev_b32_e32 v60, 16, v175
	v_and_b32_e32 v61, 0xffff0000, v175
	v_pk_add_f32 v[64:65], v[64:65], v[66:67]
	v_pk_add_f32 v[56:57], v[56:57], v[60:61]
	v_lshlrev_b32_e32 v60, 16, v172
	v_and_b32_e32 v61, 0xffff0000, v172
	v_lshlrev_b32_e32 v66, 16, v176
	v_and_b32_e32 v67, 0xffff0000, v176
	v_lshlrev_b32_e32 v58, 16, v173
	v_and_b32_e32 v59, 0xffff0000, v173
	v_lshlrev_b32_e32 v62, 16, v177
	v_and_b32_e32 v63, 0xffff0000, v177
	v_add_u32_e32 v250, 0x58000, v249
	global_load_dwordx4 v[170:173], v250, s[66:67] offset:256
	global_load_dwordx4 v[174:177], v250, s[64:65] offset:256
	v_pk_add_f32 v[60:61], v[60:61], v[66:67]
	v_pk_add_f32 v[58:59], v[58:59], v[62:63]
	v_pk_add_f32 v[48:49], v[48:49], v[56:57]
	v_pk_add_f32 v[46:47], v[46:47], v[64:65]
	v_pk_add_f32 v[56:57], v[44:45], v[58:59]
	v_pk_add_f32 v[58:59], v[42:43], v[60:61]
	v_cvt_pk_bf16_f32 v42, v46, v47
	v_cvt_pk_bf16_f32 v43, v48, v49
	v_lshlrev_b32_e32 v44, 16, v42
	v_and_b32_e32 v45, 0xffff0000, v42
	v_lshlrev_b32_e32 v60, 16, v43
	v_and_b32_e32 v61, 0xffff0000, v43
	v_sub_f32_e32 v48, v48, v60
	v_sub_f32_e32 v49, v49, v61
	v_sub_f32_e32 v46, v46, v44
	v_sub_f32_e32 v47, v47, v45
	v_cvt_pk_bf16_f32 v46, v46, v47
	v_cvt_pk_bf16_f32 v47, v48, v49
	v_lshlrev_b32_e32 v48, 16, v46
	v_and_b32_e32 v49, 0xffff0000, v46
	v_lshlrev_b32_e32 v62, 16, v47
	v_and_b32_e32 v63, 0xffff0000, v47
	v_pk_add_f32 v[60:61], v[60:61], v[62:63]
	v_pk_add_f32 v[62:63], v[44:45], v[48:49]
	v_cvt_pk_bf16_f32 v44, v58, v59
	v_cvt_pk_bf16_f32 v45, v56, v57
	v_lshlrev_b32_e32 v64, 16, v44
	v_and_b32_e32 v65, 0xffff0000, v44
	v_lshlrev_b32_e32 v66, 16, v45
	v_and_b32_e32 v67, 0xffff0000, v45
	v_sub_f32_e32 v49, v56, v66
	v_sub_f32_e32 v56, v57, v67
	v_sub_f32_e32 v48, v58, v64
	v_sub_f32_e32 v57, v59, v65
	v_cvt_pk_bf16_f32 v48, v48, v57
	v_cvt_pk_bf16_f32 v49, v49, v56
	global_store_dwordx4 v[50:51], v[42:45], off
	global_store_dwordx4 v[52:53], v[46:49], off
	v_lshlrev_b32_e32 v56, 16, v48
	v_and_b32_e32 v57, 0xffff0000, v48
	v_mul_f32_e32 v42, v63, v63
	v_mul_f32_e32 v43, v61, v61
	v_pk_add_f32 v[56:57], v[64:65], v[56:57]
	v_fmac_f32_e32 v42, v62, v62
	v_fmac_f32_e32 v43, v60, v60
	v_lshlrev_b32_e32 v58, 16, v49
	v_and_b32_e32 v59, 0xffff0000, v49
	v_add_f32_e32 v42, v42, v43
	v_mul_f32_e32 v43, v57, v57
	v_pk_add_f32 v[58:59], v[66:67], v[58:59]
	v_fmac_f32_e32 v43, v56, v56
	v_add_f32_e32 v42, v42, v43
	v_mul_f32_e32 v43, v59, v59
	v_fmac_f32_e32 v43, v58, v58
	v_add_f32_e32 v60, v43, v42
	s_waitcnt vmcnt(18)
	v_lshlrev_b32_e32 v56, 16, v178
	v_and_b32_e32 v57, 0xffff0000, v178
	v_lshlrev_b32_e32 v58, 16, v190
	v_and_b32_e32 v59, 0xffff0000, v190
	v_lshlrev_b32_e32 v42, 16, v179
	v_and_b32_e32 v43, 0xffff0000, v179
	v_lshlrev_b32_e32 v46, 16, v191
	v_and_b32_e32 v47, 0xffff0000, v191
	v_pk_add_f32 v[56:57], v[56:57], v[58:59]
	v_pk_add_f32 v[42:43], v[42:43], v[46:47]
	v_lshlrev_b32_e32 v46, 16, v180
	v_and_b32_e32 v47, 0xffff0000, v180
	v_lshlrev_b32_e32 v58, 16, v192
	v_and_b32_e32 v59, 0xffff0000, v192
	v_lshlrev_b32_e32 v44, 16, v181
	v_and_b32_e32 v45, 0xffff0000, v181
	v_lshlrev_b32_e32 v48, 16, v193
	v_and_b32_e32 v49, 0xffff0000, v193
	v_pk_add_f32 v[46:47], v[46:47], v[58:59]
	v_pk_add_f32 v[44:45], v[44:45], v[48:49]
	v_pk_add_f32 v[40:41], v[40:41], v[42:43]
	v_pk_add_f32 v[38:39], v[38:39], v[56:57]
	v_pk_add_f32 v[42:43], v[36:37], v[44:45]
	v_pk_add_f32 v[44:45], v[34:35], v[46:47]
	v_cvt_pk_bf16_f32 v34, v38, v39
	v_cvt_pk_bf16_f32 v35, v40, v41
	v_lshlrev_b32_e32 v36, 16, v34
	v_and_b32_e32 v37, 0xffff0000, v34
	v_lshlrev_b32_e32 v46, 16, v35
	v_and_b32_e32 v47, 0xffff0000, v35
	v_sub_f32_e32 v40, v40, v46
	v_sub_f32_e32 v41, v41, v47
	v_sub_f32_e32 v38, v38, v36
	v_sub_f32_e32 v39, v39, v37
	v_cvt_pk_bf16_f32 v38, v38, v39
	v_cvt_pk_bf16_f32 v39, v40, v41
	v_lshlrev_b32_e32 v40, 16, v38
	v_and_b32_e32 v41, 0xffff0000, v38
	v_lshlrev_b32_e32 v48, 16, v39
	v_and_b32_e32 v49, 0xffff0000, v39
	v_pk_add_f32 v[46:47], v[46:47], v[48:49]
	v_pk_add_f32 v[48:49], v[36:37], v[40:41]
	v_cvt_pk_bf16_f32 v36, v44, v45
	v_cvt_pk_bf16_f32 v37, v42, v43
	v_lshlrev_b32_e32 v56, 16, v36
	v_and_b32_e32 v57, 0xffff0000, v36
	v_lshlrev_b32_e32 v58, 16, v37
	v_and_b32_e32 v59, 0xffff0000, v37
	v_sub_f32_e32 v41, v42, v58
	v_sub_f32_e32 v42, v43, v59
	v_sub_f32_e32 v40, v44, v56
	v_sub_f32_e32 v43, v45, v57
	v_cvt_pk_bf16_f32 v40, v40, v43
	v_cvt_pk_bf16_f32 v41, v41, v42
	global_store_dwordx4 v[50:51], v[34:37], off offset:256
	global_store_dwordx4 v[52:53], v[38:41], off offset:256
	v_lshlrev_b32_e32 v42, 16, v40
	v_and_b32_e32 v43, 0xffff0000, v40
	v_mul_f32_e32 v34, v49, v49
	v_mul_f32_e32 v35, v47, v47
	v_pk_add_f32 v[42:43], v[56:57], v[42:43]
	v_fmac_f32_e32 v34, v48, v48
	v_fmac_f32_e32 v35, v46, v46
	v_add_u32_e32 v36, 0xa0, v144
	v_lshlrev_b32_e32 v44, 16, v41
	v_and_b32_e32 v45, 0xffff0000, v41
	v_add_f32_e32 v34, v34, v35
	v_mul_f32_e32 v35, v43, v43
	v_ashrrev_i32_e32 v37, 31, v36
	v_pk_add_f32 v[44:45], v[58:59], v[44:45]
	v_fmac_f32_e32 v35, v42, v42
	v_lshlrev_b64 v[36:37], 11, v[36:37]
	v_add_f32_e32 v34, v34, v35
	v_mul_f32_e32 v35, v45, v45
	v_lshl_add_u64 v[38:39], s[66:67], 0, v[36:37]
	v_fmac_f32_e32 v35, v44, v44
	v_lshl_add_u64 v[44:45], v[38:39], 0, v[142:143]
	v_lshl_add_u64 v[36:37], s[64:65], 0, v[36:37]
	v_lshl_add_u64 v[46:47], v[36:37], 0, v[142:143]
	v_add_f32_e32 v34, v35, v34
	v_add_f32_e32 v34, v60, v34
	ds_bpermute_b32 v35, v204, v34
	s_waitcnt lgkmcnt(0)
	v_add_f32_e32 v34, v34, v35
	ds_bpermute_b32 v35, v205, v34
	s_waitcnt vmcnt(16)
	v_lshlrev_b32_e32 v48, 16, v194
	v_and_b32_e32 v49, 0xffff0000, v194
	v_lshlrev_b32_e32 v50, 16, v214
	v_and_b32_e32 v51, 0xffff0000, v214
	v_lshlrev_b32_e32 v36, 16, v195
	v_and_b32_e32 v37, 0xffff0000, v195
	v_lshlrev_b32_e32 v40, 16, v215
	v_and_b32_e32 v41, 0xffff0000, v215
	v_pk_add_f32 v[48:49], v[48:49], v[50:51]
	v_pk_add_f32 v[36:37], v[36:37], v[40:41]
	v_lshlrev_b32_e32 v40, 16, v196
	v_and_b32_e32 v41, 0xffff0000, v196
	v_lshlrev_b32_e32 v50, 16, v216
	v_and_b32_e32 v51, 0xffff0000, v216
	v_lshlrev_b32_e32 v38, 16, v197
	v_and_b32_e32 v39, 0xffff0000, v197
	v_lshlrev_b32_e32 v42, 16, v217
	v_and_b32_e32 v43, 0xffff0000, v217
	v_pk_add_f32 v[40:41], v[40:41], v[50:51]
	v_pk_add_f32 v[38:39], v[38:39], v[42:43]
	v_pk_add_f32 v[32:33], v[32:33], v[36:37]
	v_pk_add_f32 v[30:31], v[30:31], v[48:49]
	v_pk_add_f32 v[36:37], v[28:29], v[38:39]
	v_pk_add_f32 v[38:39], v[26:27], v[40:41]
	v_cvt_pk_bf16_f32 v26, v30, v31
	v_cvt_pk_bf16_f32 v27, v32, v33
	v_lshlrev_b32_e32 v28, 16, v26
	v_and_b32_e32 v29, 0xffff0000, v26
	v_lshlrev_b32_e32 v40, 16, v27
	v_and_b32_e32 v41, 0xffff0000, v27
	v_sub_f32_e32 v32, v32, v40
	v_sub_f32_e32 v33, v33, v41
	v_sub_f32_e32 v30, v30, v28
	v_sub_f32_e32 v31, v31, v29
	v_cvt_pk_bf16_f32 v30, v30, v31
	v_cvt_pk_bf16_f32 v31, v32, v33
	v_lshlrev_b32_e32 v32, 16, v30
	v_and_b32_e32 v33, 0xffff0000, v30
	v_lshlrev_b32_e32 v42, 16, v31
	v_and_b32_e32 v43, 0xffff0000, v31
	v_pk_add_f32 v[40:41], v[40:41], v[42:43]
	v_pk_add_f32 v[42:43], v[28:29], v[32:33]
	v_cvt_pk_bf16_f32 v28, v38, v39
	v_cvt_pk_bf16_f32 v29, v36, v37
	v_lshlrev_b32_e32 v48, 16, v28
	v_and_b32_e32 v49, 0xffff0000, v28
	v_lshlrev_b32_e32 v50, 16, v29
	v_and_b32_e32 v51, 0xffff0000, v29
	v_sub_f32_e32 v33, v36, v50
	v_sub_f32_e32 v36, v37, v51
	v_sub_f32_e32 v32, v38, v48
	v_sub_f32_e32 v37, v39, v49
	v_cvt_pk_bf16_f32 v32, v32, v37
	v_cvt_pk_bf16_f32 v33, v33, v36
	global_store_dwordx4 v[44:45], v[26:29], off
	global_store_dwordx4 v[46:47], v[30:33], off
	v_lshlrev_b32_e32 v36, 16, v32
	v_and_b32_e32 v37, 0xffff0000, v32
	v_mul_f32_e32 v26, v43, v43
	v_mul_f32_e32 v27, v41, v41
	v_pk_add_f32 v[36:37], v[48:49], v[36:37]
	v_fmac_f32_e32 v26, v42, v42
	v_fmac_f32_e32 v27, v40, v40
	v_lshlrev_b32_e32 v38, 16, v33
	v_and_b32_e32 v39, 0xffff0000, v33
	v_add_f32_e32 v26, v26, v27
	v_mul_f32_e32 v27, v37, v37
	v_pk_add_f32 v[38:39], v[50:51], v[38:39]
	v_fmac_f32_e32 v27, v36, v36
	v_add_f32_e32 v26, v26, v27
	v_mul_f32_e32 v27, v39, v39
	v_fmac_f32_e32 v27, v38, v38
	v_add_f32_e32 v40, v27, v26
	s_waitcnt vmcnt(14)
	v_lshlrev_b32_e32 v36, 16, v218
	v_and_b32_e32 v37, 0xffff0000, v218
	v_lshlrev_b32_e32 v38, 16, v222
	v_and_b32_e32 v39, 0xffff0000, v222
	v_lshlrev_b32_e32 v26, 16, v219
	v_and_b32_e32 v27, 0xffff0000, v219
	v_lshlrev_b32_e32 v30, 16, v223
	v_and_b32_e32 v31, 0xffff0000, v223
	v_pk_add_f32 v[36:37], v[36:37], v[38:39]
	v_pk_add_f32 v[26:27], v[26:27], v[30:31]
	v_lshlrev_b32_e32 v30, 16, v220
	v_and_b32_e32 v31, 0xffff0000, v220
	v_lshlrev_b32_e32 v38, 16, v224
	v_and_b32_e32 v39, 0xffff0000, v224
	v_lshlrev_b32_e32 v28, 16, v221
	v_and_b32_e32 v29, 0xffff0000, v221
	v_lshlrev_b32_e32 v32, 16, v225
	v_and_b32_e32 v33, 0xffff0000, v225
	v_pk_add_f32 v[30:31], v[30:31], v[38:39]
	v_pk_add_f32 v[28:29], v[28:29], v[32:33]
	v_pk_add_f32 v[24:25], v[24:25], v[26:27]
	v_pk_add_f32 v[22:23], v[22:23], v[36:37]
	v_pk_add_f32 v[26:27], v[20:21], v[28:29]
	v_pk_add_f32 v[28:29], v[18:19], v[30:31]
	v_cvt_pk_bf16_f32 v18, v22, v23
	v_cvt_pk_bf16_f32 v19, v24, v25
	v_lshlrev_b32_e32 v20, 16, v18
	v_and_b32_e32 v21, 0xffff0000, v18
	v_lshlrev_b32_e32 v30, 16, v19
	v_and_b32_e32 v31, 0xffff0000, v19
	v_sub_f32_e32 v24, v24, v30
	v_sub_f32_e32 v25, v25, v31
	v_sub_f32_e32 v22, v22, v20
	v_sub_f32_e32 v23, v23, v21
	v_cvt_pk_bf16_f32 v22, v22, v23
	v_cvt_pk_bf16_f32 v23, v24, v25
	v_lshlrev_b32_e32 v24, 16, v22
	v_and_b32_e32 v25, 0xffff0000, v22
	v_lshlrev_b32_e32 v32, 16, v23
	v_and_b32_e32 v33, 0xffff0000, v23
	v_pk_add_f32 v[30:31], v[30:31], v[32:33]
	v_pk_add_f32 v[32:33], v[20:21], v[24:25]
	v_cvt_pk_bf16_f32 v20, v28, v29
	v_cvt_pk_bf16_f32 v21, v26, v27
	v_lshlrev_b32_e32 v36, 16, v20
	v_and_b32_e32 v37, 0xffff0000, v20
	v_lshlrev_b32_e32 v38, 16, v21
	v_and_b32_e32 v39, 0xffff0000, v21
	v_sub_f32_e32 v25, v26, v38
	v_sub_f32_e32 v26, v27, v39
	v_sub_f32_e32 v24, v28, v36
	v_sub_f32_e32 v27, v29, v37
	v_cvt_pk_bf16_f32 v24, v24, v27
	v_cvt_pk_bf16_f32 v25, v25, v26
	global_store_dwordx4 v[44:45], v[18:21], off offset:256
	global_store_dwordx4 v[46:47], v[22:25], off offset:256
	v_lshlrev_b32_e32 v26, 16, v24
	v_and_b32_e32 v27, 0xffff0000, v24
	v_mul_f32_e32 v18, v33, v33
	v_mul_f32_e32 v19, v31, v31
	v_pk_add_f32 v[26:27], v[36:37], v[26:27]
	v_fmac_f32_e32 v18, v32, v32
	v_fmac_f32_e32 v19, v30, v30
	v_lshlrev_b32_e32 v28, 16, v25
	v_and_b32_e32 v29, 0xffff0000, v25
	v_add_f32_e32 v18, v18, v19
	v_mul_f32_e32 v19, v27, v27
	v_pk_add_f32 v[28:29], v[38:39], v[28:29]
	v_fmac_f32_e32 v19, v26, v26
	v_add_f32_e32 v18, v18, v19
	v_mul_f32_e32 v19, v29, v29
	v_fmac_f32_e32 v19, v28, v28
	v_add_f32_e32 v18, v19, v18
	v_add_f32_e32 v18, v40, v18
	ds_bpermute_b32 v19, v204, v18
	s_waitcnt lgkmcnt(0)
	v_add_f32_e32 v30, v18, v19
	v_add_u32_e32 v18, 0xb0, v144
	v_ashrrev_i32_e32 v19, 31, v18
	v_lshlrev_b64 v[18:19], 11, v[18:19]
	v_lshl_add_u64 v[20:21], s[66:67], 0, v[18:19]
	v_lshl_add_u64 v[26:27], v[20:21], 0, v[142:143]
	v_lshl_add_u64 v[18:19], s[64:65], 0, v[18:19]
	v_lshl_add_u64 v[28:29], v[18:19], 0, v[142:143]
	ds_bpermute_b32 v31, v205, v30
	s_waitcnt vmcnt(12)
	v_lshlrev_b32_e32 v32, 16, v226
	v_and_b32_e32 v33, 0xffff0000, v226
	v_lshlrev_b32_e32 v36, 16, v230
	v_and_b32_e32 v37, 0xffff0000, v230
	v_lshlrev_b32_e32 v18, 16, v227
	v_and_b32_e32 v19, 0xffff0000, v227
	v_lshlrev_b32_e32 v22, 16, v231
	v_and_b32_e32 v23, 0xffff0000, v231
	v_pk_add_f32 v[32:33], v[32:33], v[36:37]
	v_pk_add_f32 v[18:19], v[18:19], v[22:23]
	v_lshlrev_b32_e32 v22, 16, v228
	v_and_b32_e32 v23, 0xffff0000, v228
	v_lshlrev_b32_e32 v36, 16, v232
	v_and_b32_e32 v37, 0xffff0000, v232
	v_lshlrev_b32_e32 v20, 16, v229
	v_and_b32_e32 v21, 0xffff0000, v229
	v_lshlrev_b32_e32 v24, 16, v233
	v_and_b32_e32 v25, 0xffff0000, v233
	v_pk_add_f32 v[22:23], v[22:23], v[36:37]
	v_pk_add_f32 v[20:21], v[20:21], v[24:25]
	v_pk_add_f32 v[16:17], v[16:17], v[18:19]
	v_pk_add_f32 v[14:15], v[14:15], v[32:33]
	v_pk_add_f32 v[18:19], v[12:13], v[20:21]
	v_pk_add_f32 v[20:21], v[10:11], v[22:23]
	v_cvt_pk_bf16_f32 v10, v14, v15
	v_cvt_pk_bf16_f32 v11, v16, v17
	v_lshlrev_b32_e32 v12, 16, v10
	v_and_b32_e32 v13, 0xffff0000, v10
	v_lshlrev_b32_e32 v22, 16, v11
	v_and_b32_e32 v23, 0xffff0000, v11
	v_sub_f32_e32 v16, v16, v22
	v_sub_f32_e32 v17, v17, v23
	v_sub_f32_e32 v14, v14, v12
	v_sub_f32_e32 v15, v15, v13
	v_cvt_pk_bf16_f32 v14, v14, v15
	v_cvt_pk_bf16_f32 v15, v16, v17
	v_lshlrev_b32_e32 v16, 16, v14
	v_and_b32_e32 v17, 0xffff0000, v14
	v_lshlrev_b32_e32 v24, 16, v15
	v_and_b32_e32 v25, 0xffff0000, v15
	v_pk_add_f32 v[22:23], v[22:23], v[24:25]
	v_pk_add_f32 v[24:25], v[12:13], v[16:17]
	v_cvt_pk_bf16_f32 v12, v20, v21
	v_cvt_pk_bf16_f32 v13, v18, v19
	v_lshlrev_b32_e32 v32, 16, v12
	v_and_b32_e32 v33, 0xffff0000, v12
	v_lshlrev_b32_e32 v36, 16, v13
	v_and_b32_e32 v37, 0xffff0000, v13
	v_sub_f32_e32 v17, v18, v36
	v_sub_f32_e32 v18, v19, v37
	v_sub_f32_e32 v16, v20, v32
	v_sub_f32_e32 v19, v21, v33
	v_cvt_pk_bf16_f32 v16, v16, v19
	v_cvt_pk_bf16_f32 v17, v17, v18
	global_store_dwordx4 v[26:27], v[10:13], off
	global_store_dwordx4 v[28:29], v[14:17], off
	v_lshlrev_b32_e32 v18, 16, v16
	v_and_b32_e32 v19, 0xffff0000, v16
	v_mul_f32_e32 v10, v25, v25
	v_mul_f32_e32 v11, v23, v23
	v_pk_add_f32 v[18:19], v[32:33], v[18:19]
	v_fmac_f32_e32 v10, v24, v24
	v_fmac_f32_e32 v11, v22, v22
	v_lshlrev_b32_e32 v20, 16, v17
	v_and_b32_e32 v21, 0xffff0000, v17
	v_add_f32_e32 v10, v10, v11
	v_mul_f32_e32 v11, v19, v19
	v_pk_add_f32 v[20:21], v[36:37], v[20:21]
	v_fmac_f32_e32 v11, v18, v18
	v_add_f32_e32 v10, v10, v11
	v_mul_f32_e32 v11, v21, v21
	v_fmac_f32_e32 v11, v20, v20
	v_add_f32_e32 v18, v11, v10
	s_waitcnt vmcnt(10)
	v_lshlrev_b32_e32 v20, 16, v170
	v_and_b32_e32 v21, 0xffff0000, v170
	v_lshlrev_b32_e32 v22, 16, v174
	v_and_b32_e32 v23, 0xffff0000, v174
	v_lshlrev_b32_e32 v10, 16, v171
	v_and_b32_e32 v11, 0xffff0000, v171
	v_lshlrev_b32_e32 v14, 16, v175
	v_and_b32_e32 v15, 0xffff0000, v175
	v_pk_add_f32 v[20:21], v[20:21], v[22:23]
	v_pk_add_f32 v[10:11], v[10:11], v[14:15]
	v_lshlrev_b32_e32 v14, 16, v172
	v_and_b32_e32 v15, 0xffff0000, v172
	v_lshlrev_b32_e32 v22, 16, v176
	v_and_b32_e32 v23, 0xffff0000, v176
	v_lshlrev_b32_e32 v12, 16, v173
	v_and_b32_e32 v13, 0xffff0000, v173
	v_lshlrev_b32_e32 v16, 16, v177
	v_and_b32_e32 v17, 0xffff0000, v177
	v_pk_add_f32 v[14:15], v[14:15], v[22:23]
	v_pk_add_f32 v[12:13], v[12:13], v[16:17]
	v_pk_add_f32 v[8:9], v[8:9], v[10:11]
	v_pk_add_f32 v[6:7], v[6:7], v[20:21]
	v_pk_add_f32 v[10:11], v[4:5], v[12:13]
	v_pk_add_f32 v[12:13], v[2:3], v[14:15]
	v_cvt_pk_bf16_f32 v2, v6, v7
	v_cvt_pk_bf16_f32 v3, v8, v9
	v_lshlrev_b32_e32 v4, 16, v2
	v_and_b32_e32 v5, 0xffff0000, v2
	v_lshlrev_b32_e32 v14, 16, v3
	v_and_b32_e32 v15, 0xffff0000, v3
	v_sub_f32_e32 v8, v8, v14
	v_sub_f32_e32 v9, v9, v15
	v_sub_f32_e32 v6, v6, v4
	v_sub_f32_e32 v7, v7, v5
	v_cvt_pk_bf16_f32 v6, v6, v7
	v_cvt_pk_bf16_f32 v7, v8, v9
	v_lshlrev_b32_e32 v8, 16, v6
	v_and_b32_e32 v9, 0xffff0000, v6
	v_lshlrev_b32_e32 v16, 16, v7
	v_and_b32_e32 v17, 0xffff0000, v7
	v_pk_add_f32 v[14:15], v[14:15], v[16:17]
	v_pk_add_f32 v[16:17], v[4:5], v[8:9]
	v_cvt_pk_bf16_f32 v4, v12, v13
	v_cvt_pk_bf16_f32 v5, v10, v11
	v_lshlrev_b32_e32 v20, 16, v4
	v_and_b32_e32 v21, 0xffff0000, v4
	v_lshlrev_b32_e32 v22, 16, v5
	v_and_b32_e32 v23, 0xffff0000, v5
	v_sub_f32_e32 v9, v10, v22
	v_sub_f32_e32 v10, v11, v23
	v_sub_f32_e32 v8, v12, v20
	v_sub_f32_e32 v11, v13, v21
	v_cvt_pk_bf16_f32 v8, v8, v11
	v_cvt_pk_bf16_f32 v9, v9, v10
	global_store_dwordx4 v[26:27], v[2:5], off offset:256
	global_store_dwordx4 v[28:29], v[6:9], off offset:256
	v_lshlrev_b32_e32 v10, 16, v8
	v_and_b32_e32 v11, 0xffff0000, v8
	v_mul_f32_e32 v2, v17, v17
	v_mul_f32_e32 v3, v15, v15
	v_pk_add_f32 v[10:11], v[20:21], v[10:11]
	v_fmac_f32_e32 v2, v16, v16
	v_fmac_f32_e32 v3, v14, v14
	v_lshlrev_b32_e32 v12, 16, v9
	v_and_b32_e32 v13, 0xffff0000, v9
	v_add_f32_e32 v2, v2, v3
	v_mul_f32_e32 v3, v11, v11
	v_pk_add_f32 v[12:13], v[22:23], v[12:13]
	v_fmac_f32_e32 v3, v10, v10
	v_add_f32_e32 v2, v2, v3
	v_mul_f32_e32 v3, v13, v13
	v_fmac_f32_e32 v3, v12, v12
	v_add_f32_e32 v2, v3, v2
	v_add_f32_e32 v2, v18, v2
	ds_bpermute_b32 v3, v204, v2
	s_waitcnt lgkmcnt(0)
	v_add_f32_e32 v2, v2, v3
	ds_bpermute_b32 v3, v205, v2
	s_and_saveexec_b64 s[24:25], s[10:11]
	s_cbranch_execz .LBB11_2334
	s_ashr_i32 s23, s22, 31
	s_lshl_b64 s[0:1], s[22:23], 2
	s_add_u32 s0, s28, s0
	v_ashrrev_i32_e32 v141, 31, v140
	s_addc_u32 s1, s29, s1
	s_waitcnt lgkmcnt(0)
	v_add_f32_e32 v4, v2, v3
	v_add_f32_e32 v11, v118, v119
	v_lshl_add_u64 v[2:3], v[140:141], 2, s[0:1]
	v_add_f32_e32 v5, v30, v31
	v_add_f32_e32 v6, v34, v35
	v_add_f32_e32 v7, v54, v55
	v_add_f32_e32 v8, v70, v71
	v_add_f32_e32 v9, v86, v87
	v_add_f32_e32 v10, v102, v103
	global_atomic_add_f32 v[2:3], v11, off
	global_atomic_add_f32 v[2:3], v10, off offset:64
	global_atomic_add_f32 v[2:3], v9, off offset:128
	global_atomic_add_f32 v[2:3], v8, off offset:192
	global_atomic_add_f32 v[2:3], v7, off offset:512
	global_atomic_add_f32 v[2:3], v6, off offset:576
	global_atomic_add_f32 v[2:3], v5, off offset:640
	global_atomic_add_f32 v[2:3], v4, off offset:704

.LBB11_2462:
	s_or_b64 exec, exec, s[30:31]
	s_waitcnt lgkmcnt(0)
	s_waitcnt lgkmcnt(0)
	s_barrier
	ds_read_b128 v[108:111], v106
	ds_read_b128 v[112:115], v106 offset:33024
	v_readlane_b32 s0, v245, 5
	s_andn2_b64 vcc, exec, s[2:3]
	s_waitcnt vmcnt(7) lgkmcnt(1)
	v_mfma_f32_16x16x32_bf16 v[108:111], v[108:111], v[62:65], 0
	v_add_u32_e32 v0, s0, v86
	s_waitcnt lgkmcnt(0)
	v_mfma_f32_16x16x32_bf16 v[62:65], v[112:115], v[62:65], 0
	ds_read_b128 v[112:115], v106 offset:64
	s_waitcnt vmcnt(6) lgkmcnt(0)
	v_mfma_f32_16x16x32_bf16 v[108:111], v[112:115], v[58:61], v[108:111]
	ds_read_b128 v[112:115], v106 offset:33088
	s_waitcnt lgkmcnt(0)
	v_mfma_f32_16x16x32_bf16 v[58:61], v[112:115], v[58:61], v[62:65]
	s_nop 2
	ds_read_b128 v[62:65], v106 offset:128
	s_waitcnt vmcnt(5) lgkmcnt(0)
	v_mfma_f32_16x16x32_bf16 v[62:65], v[62:65], v[54:57], v[108:111]
	s_nop 2
	ds_read_b128 v[108:111], v106 offset:33152
	s_waitcnt lgkmcnt(0)
	v_mfma_f32_16x16x32_bf16 v[54:57], v[108:111], v[54:57], v[58:61]
	s_nop 2
	ds_read_b128 v[58:61], v106 offset:192
	s_waitcnt vmcnt(4) lgkmcnt(0)
	v_mfma_f32_16x16x32_bf16 v[58:61], v[58:61], v[50:53], v[62:65]
	s_nop 2
	ds_read_b128 v[62:65], v106 offset:33216
	s_waitcnt lgkmcnt(0)
	v_mfma_f32_16x16x32_bf16 v[50:53], v[62:65], v[50:53], v[54:57]
	s_nop 2
	ds_read_b128 v[54:57], v106 offset:256
	s_waitcnt vmcnt(3) lgkmcnt(0)
	v_mfma_f32_16x16x32_bf16 v[54:57], v[54:57], v[46:49], v[58:61]
	s_nop 2
	ds_read_b128 v[58:61], v106 offset:33280
	s_waitcnt lgkmcnt(0)
	v_mfma_f32_16x16x32_bf16 v[46:49], v[58:61], v[46:49], v[50:53]
	s_nop 2
	ds_read_b128 v[50:53], v106 offset:320
	s_waitcnt vmcnt(2) lgkmcnt(0)
	v_mfma_f32_16x16x32_bf16 v[50:53], v[50:53], v[42:45], v[54:57]
	s_nop 2
	ds_read_b128 v[54:57], v106 offset:33344
	s_waitcnt lgkmcnt(0)
	v_mfma_f32_16x16x32_bf16 v[42:45], v[54:57], v[42:45], v[46:49]
	s_nop 2
	ds_read_b128 v[46:49], v106 offset:384
	s_waitcnt vmcnt(1) lgkmcnt(0)
	v_mfma_f32_16x16x32_bf16 v[46:49], v[46:49], v[38:41], v[50:53]
	s_nop 2
	ds_read_b128 v[50:53], v106 offset:33408
	s_waitcnt lgkmcnt(0)
	v_mfma_f32_16x16x32_bf16 v[42:45], v[50:53], v[38:41], v[42:45]
	ds_read_b128 v[38:41], v106 offset:448
	s_waitcnt vmcnt(0) lgkmcnt(0)
	v_mfma_f32_16x16x32_bf16 v[38:41], v[38:41], v[34:37], v[46:49]
	s_nop 2
	ds_read_b128 v[46:49], v106 offset:33472
	s_waitcnt lgkmcnt(0)
	v_mfma_f32_16x16x32_bf16 v[34:37], v[46:49], v[34:37], v[42:45]
	s_nop 1
	ds_write_b128 v0, v[38:41]
	s_nop 4
	ds_write_b128 v0, v[34:37] offset:1024
	s_waitcnt lgkmcnt(0)
	s_waitcnt lgkmcnt(0)
	s_barrier
	s_cbranch_vccnz .LBB11_2429
	v_readlane_b32 s0, v245, 6
	s_nop 1
	v_add_u32_e32 v0, s0, v86
	ds_read_b128 v[42:45], v0 offset:4096
	s_lshl_b32 s0, s9, 17
	s_waitcnt lgkmcnt(0)
	v_pk_add_f32 v[44:45], v[40:41], v[44:45]
	v_pk_add_f32 v[42:43], v[38:39], v[42:43]
	ds_read_b128 v[38:41], v0 offset:5120
	s_waitcnt lgkmcnt(0)
	v_pk_add_f32 v[40:41], v[36:37], v[40:41]
	v_pk_add_f32 v[38:39], v[34:35], v[38:39]
	ds_read_b128 v[34:37], v0 offset:8192
	s_waitcnt lgkmcnt(0)
	v_pk_add_f32 v[44:45], v[44:45], v[36:37]
	v_pk_add_f32 v[42:43], v[42:43], v[34:35]
	ds_read_b128 v[34:37], v0 offset:9216
	s_waitcnt lgkmcnt(0)
	v_pk_add_f32 v[40:41], v[40:41], v[36:37]
	v_pk_add_f32 v[46:47], v[38:39], v[34:35]
	ds_read_b128 v[34:37], v0 offset:12288
	s_waitcnt lgkmcnt(0)
	v_pk_add_f32 v[44:45], v[44:45], v[36:37]
	ds_read_b128 v[36:39], v0 offset:13312
	v_pk_add_f32 v[42:43], v[42:43], v[34:35]
	v_subrev_u32_e32 v0, s0, v97
	s_waitcnt lgkmcnt(0)
	v_pk_add_f32 v[34:35], v[40:41], v[38:39]
	v_add_u32_e32 v38, s34, v87
	v_lshlrev_b64 v[40:41], 1, v[0:1]
	v_ashrrev_i32_e32 v39, 31, v38
	v_pk_add_f32 v[36:37], v[46:47], v[36:37]
	v_lshl_add_u64 v[46:47], s[66:67], 0, v[40:41]
	v_lshlrev_b64 v[48:49], 1, v[38:39]
	v_lshl_add_u64 v[38:39], v[46:47], 0, v[48:49]
	v_lshl_add_u64 v[40:41], s[64:65], 0, v[40:41]
	v_lshl_add_u64 v[40:41], v[40:41], 0, v[48:49]
	global_load_dwordx2 v[46:47], v[38:39], off
	global_load_dwordx2 v[48:49], v[40:41], off
	s_waitcnt vmcnt(1)
	v_lshlrev_b32_e32 v50, 16, v46
	v_and_b32_e32 v51, 0xffff0000, v46
	s_waitcnt vmcnt(0)
	v_lshlrev_b32_e32 v52, 16, v48
	v_and_b32_e32 v53, 0xffff0000, v48
	v_lshlrev_b32_e32 v46, 16, v47
	v_and_b32_e32 v47, 0xffff0000, v47
	v_lshlrev_b32_e32 v48, 16, v49
	v_and_b32_e32 v49, 0xffff0000, v49
	v_pk_add_f32 v[50:51], v[50:51], v[52:53]
	v_pk_add_f32 v[46:47], v[46:47], v[48:49]
	v_pk_add_f32 v[42:43], v[42:43], v[50:51]
	v_pk_add_f32 v[44:45], v[44:45], v[46:47]
	v_cvt_pk_bf16_f32 v46, v42, v43
	v_cvt_pk_bf16_f32 v47, v44, v45
	v_lshlrev_b32_e32 v48, 16, v46
	v_and_b32_e32 v49, 0xffff0000, v46
	v_lshlrev_b32_e32 v50, 16, v47
	v_and_b32_e32 v51, 0xffff0000, v47
	v_sub_f32_e32 v0, v44, v50
	v_sub_f32_e32 v44, v45, v51
	v_sub_f32_e32 v42, v42, v48
	v_sub_f32_e32 v43, v43, v49
	v_cvt_pk_bf16_f32 v42, v42, v43
	v_cvt_pk_bf16_f32 v43, v0, v44
	global_store_dwordx2 v[38:39], v[46:47], off sc1
	global_store_dwordx2 v[40:41], v[42:43], off sc1
	v_lshlrev_b32_e32 v44, 16, v42
	v_and_b32_e32 v45, 0xffff0000, v42
	v_lshlrev_b32_e32 v52, 16, v43
	v_and_b32_e32 v53, 0xffff0000, v43
	v_pk_add_f32 v[50:51], v[50:51], v[52:53]
	v_pk_add_f32 v[44:45], v[48:49], v[44:45]
	v_mul_f32_e32 v42, v51, v51
	v_mul_f32_e32 v0, v45, v45
	v_fmac_f32_e32 v0, v44, v44
	v_fmac_f32_e32 v42, v50, v50
	v_add_f32_e32 v0, v0, v42
	global_load_dwordx2 v[42:43], v[38:39], off offset:32
	global_load_dwordx2 v[44:45], v[40:41], off offset:32
	s_waitcnt vmcnt(1)
	v_lshlrev_b32_e32 v46, 16, v42
	v_and_b32_e32 v47, 0xffff0000, v42
	s_waitcnt vmcnt(0)
	v_lshlrev_b32_e32 v48, 16, v44
	v_and_b32_e32 v49, 0xffff0000, v44
	v_lshlrev_b32_e32 v42, 16, v43
	v_and_b32_e32 v43, 0xffff0000, v43
	v_lshlrev_b32_e32 v44, 16, v45
	v_and_b32_e32 v45, 0xffff0000, v45
	v_pk_add_f32 v[46:47], v[46:47], v[48:49]
	v_pk_add_f32 v[42:43], v[42:43], v[44:45]
	v_pk_add_f32 v[36:37], v[36:37], v[46:47]
	v_pk_add_f32 v[34:35], v[34:35], v[42:43]
	v_cvt_pk_bf16_f32 v42, v36, v37
	v_cvt_pk_bf16_f32 v43, v34, v35
	v_lshlrev_b32_e32 v44, 16, v42
	v_and_b32_e32 v45, 0xffff0000, v42
	v_lshlrev_b32_e32 v46, 16, v43
	v_and_b32_e32 v47, 0xffff0000, v43
	v_sub_f32_e32 v48, v34, v46
	v_sub_f32_e32 v35, v35, v47
	v_sub_f32_e32 v34, v36, v44
	v_sub_f32_e32 v36, v37, v45
	v_cvt_pk_bf16_f32 v34, v34, v36
	v_cvt_pk_bf16_f32 v35, v48, v35
	global_store_dwordx2 v[38:39], v[42:43], off offset:32 sc1
	global_store_dwordx2 v[40:41], v[34:35], off offset:32 sc1
	v_lshlrev_b32_e32 v36, 16, v34
	v_and_b32_e32 v37, 0xffff0000, v34
	v_lshlrev_b32_e32 v48, 16, v35
	v_and_b32_e32 v49, 0xffff0000, v35
	v_pk_add_f32 v[46:47], v[46:47], v[48:49]
	v_pk_add_f32 v[36:37], v[44:45], v[36:37]
	v_mul_f32_e32 v35, v47, v47
	v_mul_f32_e32 v34, v37, v37
	v_fmac_f32_e32 v34, v36, v36
	v_fmac_f32_e32 v35, v46, v46
	v_add_f32_e32 v34, v34, v35
	v_add_f32_e32 v0, v0, v34
	ds_bpermute_b32 v34, v204, v0
	s_waitcnt lgkmcnt(0)
	v_add_f32_e32 v34, v0, v34
	ds_bpermute_b32 v35, v205, v34
	s_and_saveexec_b64 s[30:31], s[10:11]
	s_cbranch_execz .LBB11_2428
	v_add_u32_e32 v0, 0x4000, v84
	v_lshl_add_u64 v[36:37], v[0:1], 2, s[28:29]
	s_waitcnt lgkmcnt(0)
	v_add_f32_e32 v0, v34, v35
	global_atomic_add_f32 v[36:37], v0, off
	s_branch .LBB11_2428

.LBB11_2773:
	v_mov_b32_e32 v140, v150
	v_mov_b32_e32 v141, v152
	s_lshl_b32 s22, s7, 8
	s_nop 0
	v_add_u32_e32 v144, s22, v140
	v_lshl_add_u32 v142, s6, 8, v141
	v_ashrrev_i32_e32 v145, 31, v144
	v_lshlrev_b64 v[148:149], 11, v[144:145]
	v_ashrrev_i32_e32 v143, 31, v142
	v_lshl_add_u64 v[146:147], s[66:67], 0, v[148:149]
	v_lshlrev_b64 v[142:143], 1, v[142:143]
	v_lshl_add_u64 v[146:147], v[146:147], 0, v[142:143]
	v_lshl_add_u64 v[148:149], s[64:65], 0, v[148:149]
	v_lshl_add_u64 v[148:149], v[148:149], 0, v[142:143]
	v_lshl_add_u32 v249, v144, 11, v142
	global_load_dwordx4 v[170:173], v249, s[66:67]
	global_load_dwordx4 v[174:177], v249, s[64:65]
	global_load_dwordx4 v[178:181], v249, s[66:67] offset:256
	global_load_dwordx4 v[190:193], v249, s[64:65] offset:256
	v_add_u32_e32 v251, 0x8000, v249
	global_load_dwordx4 v[194:197], v251, s[66:67]
	global_load_dwordx4 v[214:217], v251, s[64:65]
	v_add_u32_e32 v250, 0x8000, v249
	global_load_dwordx4 v[218:221], v250, s[66:67] offset:256
	global_load_dwordx4 v[222:225], v250, s[64:65] offset:256
	v_add_u32_e32 v251, 0x10000, v249
	global_load_dwordx4 v[226:229], v251, s[66:67]
	global_load_dwordx4 v[230:233], v251, s[64:65]
	s_waitcnt vmcnt(8)
	v_lshlrev_b32_e32 v162, 16, v170
	v_and_b32_e32 v163, 0xffff0000, v170
	v_lshlrev_b32_e32 v164, 16, v174
	v_and_b32_e32 v165, 0xffff0000, v174
	v_lshlrev_b32_e32 v154, 16, v171
	v_and_b32_e32 v155, 0xffff0000, v171
	v_lshlrev_b32_e32 v158, 16, v175
	v_and_b32_e32 v159, 0xffff0000, v175
	v_pk_add_f32 v[162:163], v[162:163], v[164:165]
	v_pk_add_f32 v[154:155], v[154:155], v[158:159]
	v_lshlrev_b32_e32 v158, 16, v172
	v_and_b32_e32 v159, 0xffff0000, v172
	v_lshlrev_b32_e32 v164, 16, v176
	v_and_b32_e32 v165, 0xffff0000, v176
	v_lshlrev_b32_e32 v156, 16, v173
	v_and_b32_e32 v157, 0xffff0000, v173
	v_lshlrev_b32_e32 v160, 16, v177
	v_and_b32_e32 v161, 0xffff0000, v177
	v_add_u32_e32 v250, 0x10000, v249
	global_load_dwordx4 v[170:173], v250, s[66:67] offset:256
	global_load_dwordx4 v[174:177], v250, s[64:65] offset:256
	v_pk_add_f32 v[158:159], v[158:159], v[164:165]
	v_pk_add_f32 v[156:157], v[156:157], v[160:161]
	v_pk_fma_f32 v[128:129], v[128:129], 0.5, v[154:155] op_sel_hi:[1,0,1]
	v_pk_fma_f32 v[126:127], v[126:127], 0.5, v[162:163] op_sel_hi:[1,0,1]
	v_pk_fma_f32 v[154:155], v[124:125], 0.5, v[156:157] op_sel_hi:[1,0,1]
	v_pk_fma_f32 v[156:157], v[122:123], 0.5, v[158:159] op_sel_hi:[1,0,1]
	v_cvt_pk_bf16_f32 v122, v126, v127
	v_cvt_pk_bf16_f32 v123, v128, v129
	v_lshlrev_b32_e32 v124, 16, v122
	v_and_b32_e32 v125, 0xffff0000, v122
	v_lshlrev_b32_e32 v158, 16, v123
	v_and_b32_e32 v159, 0xffff0000, v123
	v_sub_f32_e32 v128, v128, v158
	v_sub_f32_e32 v129, v129, v159
	v_sub_f32_e32 v126, v126, v124
	v_sub_f32_e32 v127, v127, v125
	v_cvt_pk_bf16_f32 v126, v126, v127
	v_cvt_pk_bf16_f32 v127, v128, v129
	v_lshlrev_b32_e32 v128, 16, v126
	v_and_b32_e32 v129, 0xffff0000, v126
	v_lshlrev_b32_e32 v160, 16, v127
	v_and_b32_e32 v161, 0xffff0000, v127
	v_pk_add_f32 v[158:159], v[158:159], v[160:161]
	v_pk_add_f32 v[160:161], v[124:125], v[128:129]
	v_cvt_pk_bf16_f32 v124, v156, v157
	v_cvt_pk_bf16_f32 v125, v154, v155
	v_lshlrev_b32_e32 v162, 16, v124
	v_lshlrev_b32_e32 v164, 16, v125
	v_and_b32_e32 v163, 0xffff0000, v124
	v_and_b32_e32 v165, 0xffff0000, v125
	v_sub_f32_e32 v129, v154, v164
	v_sub_f32_e32 v128, v156, v162
	v_sub_f32_e32 v141, v155, v165
	v_sub_f32_e32 v145, v157, v163
	v_cvt_pk_bf16_f32 v128, v128, v145
	v_cvt_pk_bf16_f32 v129, v129, v141
	global_store_dwordx4 v[146:147], v[122:125], off
	global_store_dwordx4 v[148:149], v[126:129], off
	v_lshlrev_b32_e32 v154, 16, v128
	v_and_b32_e32 v155, 0xffff0000, v128
	v_mul_f32_e32 v122, v161, v161
	v_mul_f32_e32 v123, v159, v159
	v_pk_add_f32 v[154:155], v[162:163], v[154:155]
	v_fmac_f32_e32 v122, v160, v160
	v_fmac_f32_e32 v123, v158, v158
	v_lshlrev_b32_e32 v156, 16, v129
	v_and_b32_e32 v157, 0xffff0000, v129
	v_add_f32_e32 v122, v122, v123
	v_mul_f32_e32 v123, v155, v155
	v_pk_add_f32 v[156:157], v[164:165], v[156:157]
	v_fmac_f32_e32 v123, v154, v154
	v_add_f32_e32 v122, v122, v123
	v_mul_f32_e32 v123, v157, v157
	v_fmac_f32_e32 v123, v156, v156
	v_add_f32_e32 v141, v123, v122
	s_waitcnt vmcnt(10)
	v_lshlrev_b32_e32 v154, 16, v178
	v_and_b32_e32 v155, 0xffff0000, v178
	v_lshlrev_b32_e32 v156, 16, v190
	v_and_b32_e32 v157, 0xffff0000, v190
	v_lshlrev_b32_e32 v122, 16, v179
	v_and_b32_e32 v123, 0xffff0000, v179
	v_lshlrev_b32_e32 v126, 16, v191
	v_and_b32_e32 v127, 0xffff0000, v191
	v_pk_add_f32 v[154:155], v[154:155], v[156:157]
	v_pk_add_f32 v[122:123], v[122:123], v[126:127]
	v_lshlrev_b32_e32 v126, 16, v180
	v_and_b32_e32 v127, 0xffff0000, v180
	v_lshlrev_b32_e32 v156, 16, v192
	v_and_b32_e32 v157, 0xffff0000, v192
	v_lshlrev_b32_e32 v124, 16, v181
	v_and_b32_e32 v125, 0xffff0000, v181
	v_lshlrev_b32_e32 v128, 16, v193
	v_and_b32_e32 v129, 0xffff0000, v193
	v_add_u32_e32 v251, 0x18000, v249
	global_load_dwordx4 v[178:181], v251, s[66:67]
	global_load_dwordx4 v[190:193], v251, s[64:65]
	v_pk_add_f32 v[126:127], v[126:127], v[156:157]
	v_pk_add_f32 v[124:125], v[124:125], v[128:129]
	v_pk_fma_f32 v[120:121], v[120:121], 0.5, v[122:123] op_sel_hi:[1,0,1]
	v_pk_fma_f32 v[118:119], v[118:119], 0.5, v[154:155] op_sel_hi:[1,0,1]
	v_pk_fma_f32 v[122:123], v[116:117], 0.5, v[124:125] op_sel_hi:[1,0,1]
	v_pk_fma_f32 v[124:125], v[114:115], 0.5, v[126:127] op_sel_hi:[1,0,1]
	v_cvt_pk_bf16_f32 v114, v118, v119
	v_cvt_pk_bf16_f32 v115, v120, v121
	v_lshlrev_b32_e32 v116, 16, v114
	v_and_b32_e32 v117, 0xffff0000, v114
	v_lshlrev_b32_e32 v126, 16, v115
	v_and_b32_e32 v127, 0xffff0000, v115
	v_sub_f32_e32 v120, v120, v126
	v_sub_f32_e32 v121, v121, v127
	v_sub_f32_e32 v118, v118, v116
	v_sub_f32_e32 v119, v119, v117
	v_cvt_pk_bf16_f32 v118, v118, v119
	v_cvt_pk_bf16_f32 v119, v120, v121
	v_lshlrev_b32_e32 v120, 16, v118
	v_and_b32_e32 v121, 0xffff0000, v118
	v_lshlrev_b32_e32 v128, 16, v119
	v_and_b32_e32 v129, 0xffff0000, v119
	v_pk_add_f32 v[126:127], v[126:127], v[128:129]
	v_pk_add_f32 v[128:129], v[116:117], v[120:121]
	v_cvt_pk_bf16_f32 v116, v124, v125
	v_cvt_pk_bf16_f32 v117, v122, v123
	v_lshlrev_b32_e32 v154, 16, v116
	v_and_b32_e32 v155, 0xffff0000, v116
	v_lshlrev_b32_e32 v156, 16, v117
	v_and_b32_e32 v157, 0xffff0000, v117
	v_sub_f32_e32 v121, v122, v156
	v_sub_f32_e32 v122, v123, v157
	v_sub_f32_e32 v120, v124, v154
	v_sub_f32_e32 v123, v125, v155
	v_cvt_pk_bf16_f32 v120, v120, v123
	v_cvt_pk_bf16_f32 v121, v121, v122
	global_store_dwordx4 v[146:147], v[114:117], off offset:256
	global_store_dwordx4 v[148:149], v[118:121], off offset:256
	v_lshlrev_b32_e32 v122, 16, v120
	v_and_b32_e32 v123, 0xffff0000, v120
	v_mul_f32_e32 v114, v129, v129
	v_mul_f32_e32 v115, v127, v127
	v_pk_add_f32 v[122:123], v[154:155], v[122:123]
	v_fmac_f32_e32 v114, v128, v128
	v_fmac_f32_e32 v115, v126, v126
	v_lshlrev_b32_e32 v124, 16, v121
	v_and_b32_e32 v125, 0xffff0000, v121
	v_add_f32_e32 v114, v114, v115
	v_mul_f32_e32 v115, v123, v123
	v_pk_add_f32 v[124:125], v[156:157], v[124:125]
	v_fmac_f32_e32 v115, v122, v122
	v_add_f32_e32 v114, v114, v115
	v_mul_f32_e32 v115, v125, v125
	v_fmac_f32_e32 v115, v124, v124
	v_add_f32_e32 v114, v115, v114
	v_add_f32_e32 v114, v141, v114
	ds_bpermute_b32 v115, v204, v114
	s_waitcnt lgkmcnt(0)
	v_add_f32_e32 v118, v114, v115
	v_add_u32_e32 v114, 16, v144
	v_ashrrev_i32_e32 v115, 31, v114
	v_lshlrev_b64 v[116:117], 11, v[114:115]
	v_lshl_add_u64 v[114:115], s[66:67], 0, v[116:117]
	v_lshl_add_u64 v[114:115], v[114:115], 0, v[142:143]
	v_lshl_add_u64 v[116:117], s[64:65], 0, v[116:117]
	v_lshl_add_u64 v[116:117], v[116:117], 0, v[142:143]
	ds_bpermute_b32 v119, v205, v118
	s_waitcnt vmcnt(12)
	v_lshlrev_b32_e32 v128, 16, v194
	v_and_b32_e32 v129, 0xffff0000, v194
	v_lshlrev_b32_e32 v146, 16, v214
	v_and_b32_e32 v147, 0xffff0000, v214
	v_lshlrev_b32_e32 v120, 16, v195
	v_and_b32_e32 v121, 0xffff0000, v195
	v_lshlrev_b32_e32 v124, 16, v215
	v_and_b32_e32 v125, 0xffff0000, v215
	v_pk_add_f32 v[128:129], v[128:129], v[146:147]
	v_pk_add_f32 v[120:121], v[120:121], v[124:125]
	v_lshlrev_b32_e32 v124, 16, v196
	v_and_b32_e32 v125, 0xffff0000, v196
	v_lshlrev_b32_e32 v146, 16, v216
	v_and_b32_e32 v147, 0xffff0000, v216
	v_lshlrev_b32_e32 v122, 16, v197
	v_and_b32_e32 v123, 0xffff0000, v197
	v_lshlrev_b32_e32 v126, 16, v217
	v_and_b32_e32 v127, 0xffff0000, v217
	v_add_u32_e32 v250, 0x18000, v249
	global_load_dwordx4 v[194:197], v250, s[66:67] offset:256
	global_load_dwordx4 v[214:217], v250, s[64:65] offset:256
	v_pk_add_f32 v[124:125], v[124:125], v[146:147]
	v_pk_add_f32 v[122:123], v[122:123], v[126:127]
	v_pk_fma_f32 v[112:113], v[112:113], 0.5, v[120:121] op_sel_hi:[1,0,1]
	v_pk_fma_f32 v[110:111], v[110:111], 0.5, v[128:129] op_sel_hi:[1,0,1]
	v_pk_fma_f32 v[120:121], v[108:109], 0.5, v[122:123] op_sel_hi:[1,0,1]
	v_pk_fma_f32 v[122:123], v[106:107], 0.5, v[124:125] op_sel_hi:[1,0,1]
	v_cvt_pk_bf16_f32 v106, v110, v111
	v_cvt_pk_bf16_f32 v107, v112, v113
	v_lshlrev_b32_e32 v108, 16, v106
	v_and_b32_e32 v109, 0xffff0000, v106
	v_lshlrev_b32_e32 v124, 16, v107
	v_and_b32_e32 v125, 0xffff0000, v107
	v_sub_f32_e32 v112, v112, v124
	v_sub_f32_e32 v113, v113, v125
	v_sub_f32_e32 v110, v110, v108
	v_sub_f32_e32 v111, v111, v109
	v_cvt_pk_bf16_f32 v110, v110, v111
	v_cvt_pk_bf16_f32 v111, v112, v113
	v_lshlrev_b32_e32 v112, 16, v110
	v_and_b32_e32 v113, 0xffff0000, v110
	v_lshlrev_b32_e32 v126, 16, v111
	v_and_b32_e32 v127, 0xffff0000, v111
	v_pk_add_f32 v[124:125], v[124:125], v[126:127]
	v_pk_add_f32 v[126:127], v[108:109], v[112:113]
	v_cvt_pk_bf16_f32 v108, v122, v123
	v_cvt_pk_bf16_f32 v109, v120, v121
	v_lshlrev_b32_e32 v128, 16, v108
	v_and_b32_e32 v129, 0xffff0000, v108
	v_lshlrev_b32_e32 v146, 16, v109
	v_and_b32_e32 v147, 0xffff0000, v109
	v_sub_f32_e32 v113, v120, v146
	v_sub_f32_e32 v120, v121, v147
	v_sub_f32_e32 v112, v122, v128
	v_sub_f32_e32 v121, v123, v129
	v_cvt_pk_bf16_f32 v112, v112, v121
	v_cvt_pk_bf16_f32 v113, v113, v120
	global_store_dwordx4 v[114:115], v[106:109], off
	global_store_dwordx4 v[116:117], v[110:113], off
	v_lshlrev_b32_e32 v120, 16, v112
	v_and_b32_e32 v121, 0xffff0000, v112
	v_mul_f32_e32 v106, v127, v127
	v_mul_f32_e32 v107, v125, v125
	v_pk_add_f32 v[120:121], v[128:129], v[120:121]
	v_fmac_f32_e32 v106, v126, v126
	v_fmac_f32_e32 v107, v124, v124
	v_lshlrev_b32_e32 v122, 16, v113
	v_and_b32_e32 v123, 0xffff0000, v113
	v_add_f32_e32 v106, v106, v107
	v_mul_f32_e32 v107, v121, v121
	v_pk_add_f32 v[122:123], v[146:147], v[122:123]
	v_fmac_f32_e32 v107, v120, v120
	v_add_f32_e32 v106, v106, v107
	v_mul_f32_e32 v107, v123, v123
	v_fmac_f32_e32 v107, v122, v122
	v_add_f32_e32 v124, v107, v106
	s_waitcnt vmcnt(14)
	v_lshlrev_b32_e32 v120, 16, v218
	v_and_b32_e32 v121, 0xffff0000, v218
	v_lshlrev_b32_e32 v122, 16, v222
	v_and_b32_e32 v123, 0xffff0000, v222
	v_lshlrev_b32_e32 v106, 16, v219
	v_and_b32_e32 v107, 0xffff0000, v219
	v_lshlrev_b32_e32 v110, 16, v223
	v_and_b32_e32 v111, 0xffff0000, v223
	v_pk_add_f32 v[120:121], v[120:121], v[122:123]
	v_pk_add_f32 v[106:107], v[106:107], v[110:111]
	v_lshlrev_b32_e32 v110, 16, v220
	v_and_b32_e32 v111, 0xffff0000, v220
	v_lshlrev_b32_e32 v122, 16, v224
	v_and_b32_e32 v123, 0xffff0000, v224
	v_lshlrev_b32_e32 v108, 16, v221
	v_and_b32_e32 v109, 0xffff0000, v221
	v_lshlrev_b32_e32 v112, 16, v225
	v_and_b32_e32 v113, 0xffff0000, v225
	v_add_u32_e32 v251, 0x40000, v249
	global_load_dwordx4 v[218:221], v251, s[66:67]
	global_load_dwordx4 v[222:225], v251, s[64:65]
	v_pk_add_f32 v[110:111], v[110:111], v[122:123]
	v_pk_add_f32 v[108:109], v[108:109], v[112:113]
	v_pk_fma_f32 v[104:105], v[104:105], 0.5, v[106:107] op_sel_hi:[1,0,1]
	v_pk_fma_f32 v[102:103], v[102:103], 0.5, v[120:121] op_sel_hi:[1,0,1]
	v_pk_fma_f32 v[106:107], v[100:101], 0.5, v[108:109] op_sel_hi:[1,0,1]
	v_pk_fma_f32 v[108:109], v[98:99], 0.5, v[110:111] op_sel_hi:[1,0,1]
	v_cvt_pk_bf16_f32 v98, v102, v103
	v_cvt_pk_bf16_f32 v99, v104, v105
	v_lshlrev_b32_e32 v100, 16, v98
	v_and_b32_e32 v101, 0xffff0000, v98
	v_lshlrev_b32_e32 v110, 16, v99
	v_and_b32_e32 v111, 0xffff0000, v99
	v_sub_f32_e32 v104, v104, v110
	v_sub_f32_e32 v105, v105, v111
	v_sub_f32_e32 v102, v102, v100
	v_sub_f32_e32 v103, v103, v101
	v_cvt_pk_bf16_f32 v102, v102, v103
	v_cvt_pk_bf16_f32 v103, v104, v105
	v_lshlrev_b32_e32 v104, 16, v102
	v_and_b32_e32 v105, 0xffff0000, v102
	v_lshlrev_b32_e32 v112, 16, v103
	v_and_b32_e32 v113, 0xffff0000, v103
	v_pk_add_f32 v[110:111], v[110:111], v[112:113]
	v_pk_add_f32 v[112:113], v[100:101], v[104:105]
	v_cvt_pk_bf16_f32 v100, v108, v109
	v_cvt_pk_bf16_f32 v101, v106, v107
	v_lshlrev_b32_e32 v120, 16, v100
	v_and_b32_e32 v121, 0xffff0000, v100
	v_lshlrev_b32_e32 v122, 16, v101
	v_and_b32_e32 v123, 0xffff0000, v101
	v_sub_f32_e32 v105, v106, v122
	v_sub_f32_e32 v106, v107, v123
	v_sub_f32_e32 v104, v108, v120
	v_sub_f32_e32 v107, v109, v121
	v_cvt_pk_bf16_f32 v104, v104, v107
	v_cvt_pk_bf16_f32 v105, v105, v106
	global_store_dwordx4 v[114:115], v[98:101], off offset:256
	global_store_dwordx4 v[116:117], v[102:105], off offset:256
	v_lshlrev_b32_e32 v106, 16, v104
	v_and_b32_e32 v107, 0xffff0000, v104
	v_mul_f32_e32 v98, v113, v113
	v_mul_f32_e32 v99, v111, v111
	v_pk_add_f32 v[106:107], v[120:121], v[106:107]
	v_fmac_f32_e32 v98, v112, v112
	v_fmac_f32_e32 v99, v110, v110
	v_lshlrev_b32_e32 v108, 16, v105
	v_and_b32_e32 v109, 0xffff0000, v105
	v_add_f32_e32 v98, v98, v99
	v_mul_f32_e32 v99, v107, v107
	v_pk_add_f32 v[108:109], v[122:123], v[108:109]
	v_fmac_f32_e32 v99, v106, v106
	v_add_f32_e32 v98, v98, v99
	v_mul_f32_e32 v99, v109, v109
	v_fmac_f32_e32 v99, v108, v108
	v_add_f32_e32 v98, v99, v98
	v_add_f32_e32 v98, v124, v98
	ds_bpermute_b32 v99, v204, v98
	s_waitcnt lgkmcnt(0)
	v_add_f32_e32 v102, v98, v99
	v_add_u32_e32 v98, 32, v144
	v_ashrrev_i32_e32 v99, 31, v98
	v_lshlrev_b64 v[100:101], 11, v[98:99]
	v_lshl_add_u64 v[98:99], s[66:67], 0, v[100:101]
	v_lshl_add_u64 v[98:99], v[98:99], 0, v[142:143]
	v_lshl_add_u64 v[100:101], s[64:65], 0, v[100:101]
	v_lshl_add_u64 v[100:101], v[100:101], 0, v[142:143]
	ds_bpermute_b32 v103, v205, v102
	s_waitcnt vmcnt(16)
	v_lshlrev_b32_e32 v112, 16, v226
	v_and_b32_e32 v113, 0xffff0000, v226
	v_lshlrev_b32_e32 v114, 16, v230
	v_and_b32_e32 v115, 0xffff0000, v230
	v_lshlrev_b32_e32 v104, 16, v227
	v_and_b32_e32 v105, 0xffff0000, v227
	v_lshlrev_b32_e32 v108, 16, v231
	v_and_b32_e32 v109, 0xffff0000, v231
	v_pk_add_f32 v[112:113], v[112:113], v[114:115]
	v_pk_add_f32 v[104:105], v[104:105], v[108:109]
	v_lshlrev_b32_e32 v108, 16, v228
	v_and_b32_e32 v109, 0xffff0000, v228
	v_lshlrev_b32_e32 v114, 16, v232
	v_and_b32_e32 v115, 0xffff0000, v232
	v_lshlrev_b32_e32 v106, 16, v229
	v_and_b32_e32 v107, 0xffff0000, v229
	v_lshlrev_b32_e32 v110, 16, v233
	v_and_b32_e32 v111, 0xffff0000, v233
	v_add_u32_e32 v250, 0x40000, v249
	global_load_dwordx4 v[226:229], v250, s[66:67] offset:256
	global_load_dwordx4 v[230:233], v250, s[64:65] offset:256
	v_pk_add_f32 v[108:109], v[108:109], v[114:115]
	v_pk_add_f32 v[106:107], v[106:107], v[110:111]
	v_pk_fma_f32 v[96:97], v[96:97], 0.5, v[104:105] op_sel_hi:[1,0,1]
	v_pk_fma_f32 v[94:95], v[94:95], 0.5, v[112:113] op_sel_hi:[1,0,1]
	v_pk_fma_f32 v[104:105], v[92:93], 0.5, v[106:107] op_sel_hi:[1,0,1]
	v_pk_fma_f32 v[106:107], v[90:91], 0.5, v[108:109] op_sel_hi:[1,0,1]
	v_cvt_pk_bf16_f32 v90, v94, v95
	v_cvt_pk_bf16_f32 v91, v96, v97
	v_lshlrev_b32_e32 v92, 16, v90
	v_and_b32_e32 v93, 0xffff0000, v90
	v_lshlrev_b32_e32 v108, 16, v91
	v_and_b32_e32 v109, 0xffff0000, v91
	v_sub_f32_e32 v96, v96, v108
	v_sub_f32_e32 v97, v97, v109
	v_sub_f32_e32 v94, v94, v92
	v_sub_f32_e32 v95, v95, v93
	v_cvt_pk_bf16_f32 v94, v94, v95
	v_cvt_pk_bf16_f32 v95, v96, v97
	v_lshlrev_b32_e32 v96, 16, v94
	v_and_b32_e32 v97, 0xffff0000, v94
	v_lshlrev_b32_e32 v110, 16, v95
	v_and_b32_e32 v111, 0xffff0000, v95
	v_pk_add_f32 v[108:109], v[108:109], v[110:111]
	v_pk_add_f32 v[110:111], v[92:93], v[96:97]
	v_cvt_pk_bf16_f32 v92, v106, v107
	v_cvt_pk_bf16_f32 v93, v104, v105
	v_lshlrev_b32_e32 v112, 16, v92
	v_and_b32_e32 v113, 0xffff0000, v92
	v_lshlrev_b32_e32 v114, 16, v93
	v_and_b32_e32 v115, 0xffff0000, v93
	v_sub_f32_e32 v97, v104, v114
	v_sub_f32_e32 v104, v105, v115
	v_sub_f32_e32 v96, v106, v112
	v_sub_f32_e32 v105, v107, v113
	v_cvt_pk_bf16_f32 v96, v96, v105
	v_cvt_pk_bf16_f32 v97, v97, v104
	global_store_dwordx4 v[98:99], v[90:93], off
	global_store_dwordx4 v[100:101], v[94:97], off
	v_lshlrev_b32_e32 v104, 16, v96
	v_and_b32_e32 v105, 0xffff0000, v96
	v_mul_f32_e32 v90, v111, v111
	v_mul_f32_e32 v91, v109, v109
	v_pk_add_f32 v[104:105], v[112:113], v[104:105]
	v_fmac_f32_e32 v90, v110, v110
	v_fmac_f32_e32 v91, v108, v108
	v_lshlrev_b32_e32 v106, 16, v97
	v_and_b32_e32 v107, 0xffff0000, v97
	v_add_f32_e32 v90, v90, v91
	v_mul_f32_e32 v91, v105, v105
	v_pk_add_f32 v[106:107], v[114:115], v[106:107]
	v_fmac_f32_e32 v91, v104, v104
	v_add_f32_e32 v90, v90, v91
	v_mul_f32_e32 v91, v107, v107
	v_fmac_f32_e32 v91, v106, v106
	v_add_f32_e32 v108, v91, v90
	s_waitcnt vmcnt(18)
	v_lshlrev_b32_e32 v104, 16, v170
	v_and_b32_e32 v105, 0xffff0000, v170
	v_lshlrev_b32_e32 v106, 16, v174
	v_and_b32_e32 v107, 0xffff0000, v174
	v_lshlrev_b32_e32 v90, 16, v171
	v_and_b32_e32 v91, 0xffff0000, v171
	v_lshlrev_b32_e32 v94, 16, v175
	v_and_b32_e32 v95, 0xffff0000, v175
	v_pk_add_f32 v[104:105], v[104:105], v[106:107]
	v_pk_add_f32 v[90:91], v[90:91], v[94:95]
	v_lshlrev_b32_e32 v94, 16, v172
	v_and_b32_e32 v95, 0xffff0000, v172
	v_lshlrev_b32_e32 v106, 16, v176
	v_and_b32_e32 v107, 0xffff0000, v176
	v_lshlrev_b32_e32 v92, 16, v173
	v_and_b32_e32 v93, 0xffff0000, v173
	v_lshlrev_b32_e32 v96, 16, v177
	v_and_b32_e32 v97, 0xffff0000, v177
	v_add_u32_e32 v251, 0x48000, v249
	global_load_dwordx4 v[170:173], v251, s[66:67]
	global_load_dwordx4 v[174:177], v251, s[64:65]
	v_pk_add_f32 v[94:95], v[94:95], v[106:107]
	v_pk_add_f32 v[92:93], v[92:93], v[96:97]
	v_pk_fma_f32 v[88:89], v[88:89], 0.5, v[90:91] op_sel_hi:[1,0,1]
	v_pk_fma_f32 v[86:87], v[86:87], 0.5, v[104:105] op_sel_hi:[1,0,1]
	v_pk_fma_f32 v[90:91], v[84:85], 0.5, v[92:93] op_sel_hi:[1,0,1]
	v_pk_fma_f32 v[92:93], v[82:83], 0.5, v[94:95] op_sel_hi:[1,0,1]
	v_cvt_pk_bf16_f32 v82, v86, v87
	v_cvt_pk_bf16_f32 v83, v88, v89
	v_lshlrev_b32_e32 v84, 16, v82
	v_and_b32_e32 v85, 0xffff0000, v82
	v_lshlrev_b32_e32 v94, 16, v83
	v_and_b32_e32 v95, 0xffff0000, v83
	v_sub_f32_e32 v88, v88, v94
	v_sub_f32_e32 v89, v89, v95
	v_sub_f32_e32 v86, v86, v84
	v_sub_f32_e32 v87, v87, v85
	v_cvt_pk_bf16_f32 v86, v86, v87
	v_cvt_pk_bf16_f32 v87, v88, v89
	v_lshlrev_b32_e32 v88, 16, v86
	v_and_b32_e32 v89, 0xffff0000, v86
	v_lshlrev_b32_e32 v96, 16, v87
	v_and_b32_e32 v97, 0xffff0000, v87
	v_pk_add_f32 v[94:95], v[94:95], v[96:97]
	v_pk_add_f32 v[96:97], v[84:85], v[88:89]
	v_cvt_pk_bf16_f32 v84, v92, v93
	v_cvt_pk_bf16_f32 v85, v90, v91
	v_lshlrev_b32_e32 v104, 16, v84
	v_and_b32_e32 v105, 0xffff0000, v84
	v_lshlrev_b32_e32 v106, 16, v85
	v_and_b32_e32 v107, 0xffff0000, v85
	v_sub_f32_e32 v89, v90, v106
	v_sub_f32_e32 v90, v91, v107
	v_sub_f32_e32 v88, v92, v104
	v_sub_f32_e32 v91, v93, v105
	v_cvt_pk_bf16_f32 v88, v88, v91
	v_cvt_pk_bf16_f32 v89, v89, v90
	global_store_dwordx4 v[98:99], v[82:85], off offset:256
	global_store_dwordx4 v[100:101], v[86:89], off offset:256
	v_lshlrev_b32_e32 v90, 16, v88
	v_and_b32_e32 v91, 0xffff0000, v88
	v_mul_f32_e32 v82, v97, v97
	v_mul_f32_e32 v83, v95, v95
	v_pk_add_f32 v[90:91], v[104:105], v[90:91]
	v_fmac_f32_e32 v82, v96, v96
	v_fmac_f32_e32 v83, v94, v94
	v_lshlrev_b32_e32 v92, 16, v89
	v_and_b32_e32 v93, 0xffff0000, v89
	v_add_f32_e32 v82, v82, v83
	v_mul_f32_e32 v83, v91, v91
	v_pk_add_f32 v[92:93], v[106:107], v[92:93]
	v_fmac_f32_e32 v83, v90, v90
	v_add_f32_e32 v82, v82, v83
	v_mul_f32_e32 v83, v93, v93
	v_fmac_f32_e32 v83, v92, v92
	v_add_f32_e32 v82, v83, v82
	v_add_f32_e32 v82, v108, v82
	ds_bpermute_b32 v83, v204, v82
	s_waitcnt lgkmcnt(0)
	v_add_f32_e32 v86, v82, v83
	v_add_u32_e32 v82, 48, v144
	v_ashrrev_i32_e32 v83, 31, v82
	v_lshlrev_b64 v[84:85], 11, v[82:83]
	v_lshl_add_u64 v[82:83], s[66:67], 0, v[84:85]
	v_lshl_add_u64 v[82:83], v[82:83], 0, v[142:143]
	v_lshl_add_u64 v[84:85], s[64:65], 0, v[84:85]
	v_lshl_add_u64 v[84:85], v[84:85], 0, v[142:143]
	ds_bpermute_b32 v87, v205, v86
	s_waitcnt vmcnt(18)
	v_lshlrev_b32_e32 v96, 16, v178
	v_and_b32_e32 v97, 0xffff0000, v178
	v_lshlrev_b32_e32 v98, 16, v190
	v_and_b32_e32 v99, 0xffff0000, v190
	v_lshlrev_b32_e32 v88, 16, v179
	v_and_b32_e32 v89, 0xffff0000, v179
	v_lshlrev_b32_e32 v92, 16, v191
	v_and_b32_e32 v93, 0xffff0000, v191
	v_pk_add_f32 v[96:97], v[96:97], v[98:99]
	v_pk_add_f32 v[88:89], v[88:89], v[92:93]
	v_lshlrev_b32_e32 v92, 16, v180
	v_and_b32_e32 v93, 0xffff0000, v180
	v_lshlrev_b32_e32 v98, 16, v192
	v_and_b32_e32 v99, 0xffff0000, v192
	v_lshlrev_b32_e32 v90, 16, v181
	v_and_b32_e32 v91, 0xffff0000, v181
	v_lshlrev_b32_e32 v94, 16, v193
	v_and_b32_e32 v95, 0xffff0000, v193
	v_add_u32_e32 v250, 0x48000, v249
	global_load_dwordx4 v[178:181], v250, s[66:67] offset:256
	global_load_dwordx4 v[190:193], v250, s[64:65] offset:256
	v_pk_add_f32 v[92:93], v[92:93], v[98:99]
	v_pk_add_f32 v[90:91], v[90:91], v[94:95]
	v_pk_fma_f32 v[80:81], v[80:81], 0.5, v[88:89] op_sel_hi:[1,0,1]
	v_pk_fma_f32 v[78:79], v[78:79], 0.5, v[96:97] op_sel_hi:[1,0,1]
	v_pk_fma_f32 v[88:89], v[76:77], 0.5, v[90:91] op_sel_hi:[1,0,1]
	v_pk_fma_f32 v[90:91], v[74:75], 0.5, v[92:93] op_sel_hi:[1,0,1]
	v_cvt_pk_bf16_f32 v74, v78, v79
	v_cvt_pk_bf16_f32 v75, v80, v81
	v_lshlrev_b32_e32 v76, 16, v74
	v_and_b32_e32 v77, 0xffff0000, v74
	v_lshlrev_b32_e32 v92, 16, v75
	v_and_b32_e32 v93, 0xffff0000, v75
	v_sub_f32_e32 v80, v80, v92
	v_sub_f32_e32 v81, v81, v93
	v_sub_f32_e32 v78, v78, v76
	v_sub_f32_e32 v79, v79, v77
	v_cvt_pk_bf16_f32 v78, v78, v79
	v_cvt_pk_bf16_f32 v79, v80, v81
	v_lshlrev_b32_e32 v80, 16, v78
	v_and_b32_e32 v81, 0xffff0000, v78
	v_lshlrev_b32_e32 v94, 16, v79
	v_and_b32_e32 v95, 0xffff0000, v79
	v_pk_add_f32 v[92:93], v[92:93], v[94:95]
	v_pk_add_f32 v[94:95], v[76:77], v[80:81]
	v_cvt_pk_bf16_f32 v76, v90, v91
	v_cvt_pk_bf16_f32 v77, v88, v89
	v_lshlrev_b32_e32 v96, 16, v76
	v_and_b32_e32 v97, 0xffff0000, v76
	v_lshlrev_b32_e32 v98, 16, v77
	v_and_b32_e32 v99, 0xffff0000, v77
	v_sub_f32_e32 v81, v88, v98
	v_sub_f32_e32 v88, v89, v99
	v_sub_f32_e32 v80, v90, v96
	v_sub_f32_e32 v89, v91, v97
	v_cvt_pk_bf16_f32 v80, v80, v89
	v_cvt_pk_bf16_f32 v81, v81, v88
	global_store_dwordx4 v[82:83], v[74:77], off
	global_store_dwordx4 v[84:85], v[78:81], off
	v_lshlrev_b32_e32 v88, 16, v80
	v_and_b32_e32 v89, 0xffff0000, v80
	v_mul_f32_e32 v74, v95, v95
	v_mul_f32_e32 v75, v93, v93
	v_pk_add_f32 v[88:89], v[96:97], v[88:89]
	v_fmac_f32_e32 v74, v94, v94
	v_fmac_f32_e32 v75, v92, v92
	v_lshlrev_b32_e32 v90, 16, v81
	v_and_b32_e32 v91, 0xffff0000, v81
	v_add_f32_e32 v74, v74, v75
	v_mul_f32_e32 v75, v89, v89
	v_pk_add_f32 v[90:91], v[98:99], v[90:91]
	v_fmac_f32_e32 v75, v88, v88
	v_add_f32_e32 v74, v74, v75
	v_mul_f32_e32 v75, v91, v91
	v_fmac_f32_e32 v75, v90, v90
	v_add_f32_e32 v92, v75, v74
	s_waitcnt vmcnt(18)
	v_lshlrev_b32_e32 v88, 16, v194
	v_and_b32_e32 v89, 0xffff0000, v194
	v_lshlrev_b32_e32 v90, 16, v214
	v_and_b32_e32 v91, 0xffff0000, v214
	v_lshlrev_b32_e32 v74, 16, v195
	v_and_b32_e32 v75, 0xffff0000, v195
	v_lshlrev_b32_e32 v78, 16, v215
	v_and_b32_e32 v79, 0xffff0000, v215
	v_pk_add_f32 v[88:89], v[88:89], v[90:91]
	v_pk_add_f32 v[74:75], v[74:75], v[78:79]
	v_lshlrev_b32_e32 v78, 16, v196
	v_and_b32_e32 v79, 0xffff0000, v196
	v_lshlrev_b32_e32 v90, 16, v216
	v_and_b32_e32 v91, 0xffff0000, v216
	v_lshlrev_b32_e32 v76, 16, v197
	v_and_b32_e32 v77, 0xffff0000, v197
	v_lshlrev_b32_e32 v80, 16, v217
	v_and_b32_e32 v81, 0xffff0000, v217
	v_add_u32_e32 v251, 0x50000, v249
	global_load_dwordx4 v[194:197], v251, s[66:67]
	global_load_dwordx4 v[214:217], v251, s[64:65]
	v_pk_add_f32 v[78:79], v[78:79], v[90:91]
	v_pk_add_f32 v[76:77], v[76:77], v[80:81]
	v_pk_fma_f32 v[72:73], v[72:73], 0.5, v[74:75] op_sel_hi:[1,0,1]
	v_pk_fma_f32 v[70:71], v[70:71], 0.5, v[88:89] op_sel_hi:[1,0,1]
	v_pk_fma_f32 v[74:75], v[68:69], 0.5, v[76:77] op_sel_hi:[1,0,1]
	v_pk_fma_f32 v[76:77], v[66:67], 0.5, v[78:79] op_sel_hi:[1,0,1]
	v_cvt_pk_bf16_f32 v66, v70, v71
	v_cvt_pk_bf16_f32 v67, v72, v73
	v_lshlrev_b32_e32 v68, 16, v66
	v_and_b32_e32 v69, 0xffff0000, v66
	v_lshlrev_b32_e32 v78, 16, v67
	v_and_b32_e32 v79, 0xffff0000, v67
	v_sub_f32_e32 v72, v72, v78
	v_sub_f32_e32 v73, v73, v79
	v_sub_f32_e32 v70, v70, v68
	v_sub_f32_e32 v71, v71, v69
	v_cvt_pk_bf16_f32 v70, v70, v71
	v_cvt_pk_bf16_f32 v71, v72, v73
	v_lshlrev_b32_e32 v72, 16, v70
	v_and_b32_e32 v73, 0xffff0000, v70
	v_lshlrev_b32_e32 v80, 16, v71
	v_and_b32_e32 v81, 0xffff0000, v71
	v_pk_add_f32 v[78:79], v[78:79], v[80:81]
	v_pk_add_f32 v[80:81], v[68:69], v[72:73]
	v_cvt_pk_bf16_f32 v68, v76, v77
	v_cvt_pk_bf16_f32 v69, v74, v75
	v_lshlrev_b32_e32 v88, 16, v68
	v_and_b32_e32 v89, 0xffff0000, v68
	v_lshlrev_b32_e32 v90, 16, v69
	v_and_b32_e32 v91, 0xffff0000, v69
	v_sub_f32_e32 v73, v74, v90
	v_sub_f32_e32 v74, v75, v91
	v_sub_f32_e32 v72, v76, v88
	v_sub_f32_e32 v75, v77, v89
	v_cvt_pk_bf16_f32 v72, v72, v75
	v_cvt_pk_bf16_f32 v73, v73, v74
	global_store_dwordx4 v[82:83], v[66:69], off offset:256
	global_store_dwordx4 v[84:85], v[70:73], off offset:256
	v_lshlrev_b32_e32 v74, 16, v72
	v_and_b32_e32 v75, 0xffff0000, v72
	v_mul_f32_e32 v66, v81, v81
	v_mul_f32_e32 v67, v79, v79
	v_pk_add_f32 v[74:75], v[88:89], v[74:75]
	v_fmac_f32_e32 v66, v80, v80
	v_fmac_f32_e32 v67, v78, v78
	v_lshlrev_b32_e32 v76, 16, v73
	v_and_b32_e32 v77, 0xffff0000, v73
	v_add_f32_e32 v66, v66, v67
	v_mul_f32_e32 v67, v75, v75
	v_pk_add_f32 v[76:77], v[90:91], v[76:77]
	v_fmac_f32_e32 v67, v74, v74
	v_add_f32_e32 v66, v66, v67
	v_mul_f32_e32 v67, v77, v77
	v_fmac_f32_e32 v67, v76, v76
	v_add_f32_e32 v66, v67, v66
	v_add_f32_e32 v66, v92, v66
	ds_bpermute_b32 v67, v204, v66
	s_waitcnt lgkmcnt(0)
	v_add_f32_e32 v70, v66, v67
	v_add_u32_e32 v66, 0x80, v144
	v_ashrrev_i32_e32 v67, 31, v66
	v_lshlrev_b64 v[68:69], 11, v[66:67]
	v_lshl_add_u64 v[66:67], s[66:67], 0, v[68:69]
	v_lshl_add_u64 v[66:67], v[66:67], 0, v[142:143]
	v_lshl_add_u64 v[68:69], s[64:65], 0, v[68:69]
	v_lshl_add_u64 v[68:69], v[68:69], 0, v[142:143]
	ds_bpermute_b32 v71, v205, v70
	s_waitcnt vmcnt(18)
	v_lshlrev_b32_e32 v80, 16, v218
	v_and_b32_e32 v81, 0xffff0000, v218
	v_lshlrev_b32_e32 v82, 16, v222
	v_and_b32_e32 v83, 0xffff0000, v222
	v_lshlrev_b32_e32 v72, 16, v219
	v_and_b32_e32 v73, 0xffff0000, v219
	v_lshlrev_b32_e32 v76, 16, v223
	v_and_b32_e32 v77, 0xffff0000, v223
	v_pk_add_f32 v[80:81], v[80:81], v[82:83]
	v_pk_add_f32 v[72:73], v[72:73], v[76:77]
	v_lshlrev_b32_e32 v76, 16, v220
	v_and_b32_e32 v77, 0xffff0000, v220
	v_lshlrev_b32_e32 v82, 16, v224
	v_and_b32_e32 v83, 0xffff0000, v224
	v_lshlrev_b32_e32 v74, 16, v221
	v_and_b32_e32 v75, 0xffff0000, v221
	v_lshlrev_b32_e32 v78, 16, v225
	v_and_b32_e32 v79, 0xffff0000, v225
	v_add_u32_e32 v250, 0x50000, v249
	global_load_dwordx4 v[218:221], v250, s[66:67] offset:256
	global_load_dwordx4 v[222:225], v250, s[64:65] offset:256
	v_pk_add_f32 v[76:77], v[76:77], v[82:83]
	v_pk_add_f32 v[74:75], v[74:75], v[78:79]
	v_pk_fma_f32 v[64:65], v[64:65], 0.5, v[72:73] op_sel_hi:[1,0,1]
	v_pk_fma_f32 v[62:63], v[62:63], 0.5, v[80:81] op_sel_hi:[1,0,1]
	v_pk_fma_f32 v[72:73], v[60:61], 0.5, v[74:75] op_sel_hi:[1,0,1]
	v_pk_fma_f32 v[74:75], v[58:59], 0.5, v[76:77] op_sel_hi:[1,0,1]
	v_cvt_pk_bf16_f32 v58, v62, v63
	v_cvt_pk_bf16_f32 v59, v64, v65
	v_lshlrev_b32_e32 v60, 16, v58
	v_and_b32_e32 v61, 0xffff0000, v58
	v_lshlrev_b32_e32 v76, 16, v59
	v_and_b32_e32 v77, 0xffff0000, v59
	v_sub_f32_e32 v64, v64, v76
	v_sub_f32_e32 v65, v65, v77
	v_sub_f32_e32 v62, v62, v60
	v_sub_f32_e32 v63, v63, v61
	v_cvt_pk_bf16_f32 v62, v62, v63
	v_cvt_pk_bf16_f32 v63, v64, v65
	v_lshlrev_b32_e32 v64, 16, v62
	v_and_b32_e32 v65, 0xffff0000, v62
	v_lshlrev_b32_e32 v78, 16, v63
	v_and_b32_e32 v79, 0xffff0000, v63
	v_pk_add_f32 v[76:77], v[76:77], v[78:79]
	v_pk_add_f32 v[78:79], v[60:61], v[64:65]
	v_cvt_pk_bf16_f32 v60, v74, v75
	v_cvt_pk_bf16_f32 v61, v72, v73
	v_lshlrev_b32_e32 v80, 16, v60
	v_and_b32_e32 v81, 0xffff0000, v60
	v_lshlrev_b32_e32 v82, 16, v61
	v_and_b32_e32 v83, 0xffff0000, v61
	v_sub_f32_e32 v65, v72, v82
	v_sub_f32_e32 v72, v73, v83
	v_sub_f32_e32 v64, v74, v80
	v_sub_f32_e32 v73, v75, v81
	v_cvt_pk_bf16_f32 v64, v64, v73
	v_cvt_pk_bf16_f32 v65, v65, v72
	global_store_dwordx4 v[66:67], v[58:61], off
	global_store_dwordx4 v[68:69], v[62:65], off
	v_lshlrev_b32_e32 v72, 16, v64
	v_and_b32_e32 v73, 0xffff0000, v64
	v_mul_f32_e32 v58, v79, v79
	v_mul_f32_e32 v59, v77, v77
	v_pk_add_f32 v[72:73], v[80:81], v[72:73]
	v_fmac_f32_e32 v58, v78, v78
	v_fmac_f32_e32 v59, v76, v76
	v_lshlrev_b32_e32 v74, 16, v65
	v_and_b32_e32 v75, 0xffff0000, v65
	v_add_f32_e32 v58, v58, v59
	v_mul_f32_e32 v59, v73, v73
	v_pk_add_f32 v[74:75], v[82:83], v[74:75]
	v_fmac_f32_e32 v59, v72, v72
	v_add_f32_e32 v58, v58, v59
	v_mul_f32_e32 v59, v75, v75
	v_fmac_f32_e32 v59, v74, v74
	v_add_f32_e32 v76, v59, v58
	s_waitcnt vmcnt(18)
	v_lshlrev_b32_e32 v72, 16, v226
	v_and_b32_e32 v73, 0xffff0000, v226
	v_lshlrev_b32_e32 v74, 16, v230
	v_and_b32_e32 v75, 0xffff0000, v230
	v_lshlrev_b32_e32 v58, 16, v227
	v_and_b32_e32 v59, 0xffff0000, v227
	v_lshlrev_b32_e32 v62, 16, v231
	v_and_b32_e32 v63, 0xffff0000, v231
	v_pk_add_f32 v[72:73], v[72:73], v[74:75]
	v_pk_add_f32 v[58:59], v[58:59], v[62:63]
	v_lshlrev_b32_e32 v62, 16, v228
	v_and_b32_e32 v63, 0xffff0000, v228
	v_lshlrev_b32_e32 v74, 16, v232
	v_and_b32_e32 v75, 0xffff0000, v232
	v_lshlrev_b32_e32 v60, 16, v229
	v_and_b32_e32 v61, 0xffff0000, v229
	v_lshlrev_b32_e32 v64, 16, v233
	v_and_b32_e32 v65, 0xffff0000, v233
	v_add_u32_e32 v251, 0x58000, v249
	global_load_dwordx4 v[226:229], v251, s[66:67]
	global_load_dwordx4 v[230:233], v251, s[64:65]
	v_pk_add_f32 v[62:63], v[62:63], v[74:75]
	v_pk_add_f32 v[60:61], v[60:61], v[64:65]
	v_pk_fma_f32 v[56:57], v[56:57], 0.5, v[58:59] op_sel_hi:[1,0,1]
	v_pk_fma_f32 v[54:55], v[54:55], 0.5, v[72:73] op_sel_hi:[1,0,1]
	v_pk_fma_f32 v[58:59], v[52:53], 0.5, v[60:61] op_sel_hi:[1,0,1]
	v_pk_fma_f32 v[60:61], v[50:51], 0.5, v[62:63] op_sel_hi:[1,0,1]
	v_cvt_pk_bf16_f32 v50, v54, v55
	v_cvt_pk_bf16_f32 v51, v56, v57
	v_lshlrev_b32_e32 v52, 16, v50
	v_and_b32_e32 v53, 0xffff0000, v50
	v_lshlrev_b32_e32 v62, 16, v51
	v_and_b32_e32 v63, 0xffff0000, v51
	v_sub_f32_e32 v56, v56, v62
	v_sub_f32_e32 v57, v57, v63
	v_sub_f32_e32 v54, v54, v52
	v_sub_f32_e32 v55, v55, v53
	v_cvt_pk_bf16_f32 v54, v54, v55
	v_cvt_pk_bf16_f32 v55, v56, v57
	v_lshlrev_b32_e32 v56, 16, v54
	v_and_b32_e32 v57, 0xffff0000, v54
	v_lshlrev_b32_e32 v64, 16, v55
	v_and_b32_e32 v65, 0xffff0000, v55
	v_pk_add_f32 v[62:63], v[62:63], v[64:65]
	v_pk_add_f32 v[64:65], v[52:53], v[56:57]
	v_cvt_pk_bf16_f32 v52, v60, v61
	v_cvt_pk_bf16_f32 v53, v58, v59
	v_lshlrev_b32_e32 v72, 16, v52
	v_and_b32_e32 v73, 0xffff0000, v52
	v_lshlrev_b32_e32 v74, 16, v53
	v_and_b32_e32 v75, 0xffff0000, v53
	v_sub_f32_e32 v57, v58, v74
	v_sub_f32_e32 v58, v59, v75
	v_sub_f32_e32 v56, v60, v72
	v_sub_f32_e32 v59, v61, v73
	v_cvt_pk_bf16_f32 v56, v56, v59
	v_cvt_pk_bf16_f32 v57, v57, v58
	global_store_dwordx4 v[66:67], v[50:53], off offset:256
	global_store_dwordx4 v[68:69], v[54:57], off offset:256
	v_lshlrev_b32_e32 v58, 16, v56
	v_and_b32_e32 v59, 0xffff0000, v56
	v_mul_f32_e32 v50, v65, v65
	v_mul_f32_e32 v51, v63, v63
	v_pk_add_f32 v[58:59], v[72:73], v[58:59]
	v_fmac_f32_e32 v50, v64, v64
	v_fmac_f32_e32 v51, v62, v62
	v_lshlrev_b32_e32 v60, 16, v57
	v_and_b32_e32 v61, 0xffff0000, v57
	v_add_f32_e32 v50, v50, v51
	v_mul_f32_e32 v51, v59, v59
	v_pk_add_f32 v[60:61], v[74:75], v[60:61]
	v_fmac_f32_e32 v51, v58, v58
	v_add_f32_e32 v50, v50, v51
	v_mul_f32_e32 v51, v61, v61
	v_fmac_f32_e32 v51, v60, v60
	v_add_f32_e32 v50, v51, v50
	v_add_f32_e32 v50, v76, v50
	ds_bpermute_b32 v51, v204, v50
	s_waitcnt lgkmcnt(0)
	v_add_f32_e32 v54, v50, v51
	v_add_u32_e32 v50, 0x90, v144
	v_ashrrev_i32_e32 v51, 31, v50
	v_lshlrev_b64 v[52:53], 11, v[50:51]
	v_lshl_add_u64 v[50:51], s[66:67], 0, v[52:53]
	v_lshl_add_u64 v[50:51], v[50:51], 0, v[142:143]
	v_lshl_add_u64 v[52:53], s[64:65], 0, v[52:53]
	v_lshl_add_u64 v[52:53], v[52:53], 0, v[142:143]
	ds_bpermute_b32 v55, v205, v54
	s_waitcnt vmcnt(18)
	v_lshlrev_b32_e32 v64, 16, v170
	v_and_b32_e32 v65, 0xffff0000, v170
	v_lshlrev_b32_e32 v66, 16, v174
	v_and_b32_e32 v67, 0xffff0000, v174
	v_lshlrev_b32_e32 v56, 16, v171
	v_and_b32_e32 v57, 0xffff0000, v171
	v_lshlrev_b32_e32 v60, 16, v175
	v_and_b32_e32 v61, 0xffff0000, v175
	v_pk_add_f32 v[64:65], v[64:65], v[66:67]
	v_pk_add_f32 v[56:57], v[56:57], v[60:61]
	v_lshlrev_b32_e32 v60, 16, v172
	v_and_b32_e32 v61, 0xffff0000, v172
	v_lshlrev_b32_e32 v66, 16, v176
	v_and_b32_e32 v67, 0xffff0000, v176
	v_lshlrev_b32_e32 v58, 16, v173
	v_and_b32_e32 v59, 0xffff0000, v173
	v_lshlrev_b32_e32 v62, 16, v177
	v_and_b32_e32 v63, 0xffff0000, v177
	v_add_u32_e32 v250, 0x58000, v249
	global_load_dwordx4 v[170:173], v250, s[66:67] offset:256
	global_load_dwordx4 v[174:177], v250, s[64:65] offset:256
	v_pk_add_f32 v[60:61], v[60:61], v[66:67]
	v_pk_add_f32 v[58:59], v[58:59], v[62:63]
	v_pk_fma_f32 v[48:49], v[48:49], 0.5, v[56:57] op_sel_hi:[1,0,1]
	v_pk_fma_f32 v[46:47], v[46:47], 0.5, v[64:65] op_sel_hi:[1,0,1]
	v_pk_fma_f32 v[56:57], v[44:45], 0.5, v[58:59] op_sel_hi:[1,0,1]
	v_pk_fma_f32 v[58:59], v[42:43], 0.5, v[60:61] op_sel_hi:[1,0,1]
	v_cvt_pk_bf16_f32 v42, v46, v47
	v_cvt_pk_bf16_f32 v43, v48, v49
	v_lshlrev_b32_e32 v44, 16, v42
	v_and_b32_e32 v45, 0xffff0000, v42
	v_lshlrev_b32_e32 v60, 16, v43
	v_and_b32_e32 v61, 0xffff0000, v43
	v_sub_f32_e32 v48, v48, v60
	v_sub_f32_e32 v49, v49, v61
	v_sub_f32_e32 v46, v46, v44
	v_sub_f32_e32 v47, v47, v45
	v_cvt_pk_bf16_f32 v46, v46, v47
	v_cvt_pk_bf16_f32 v47, v48, v49
	v_lshlrev_b32_e32 v48, 16, v46
	v_and_b32_e32 v49, 0xffff0000, v46
	v_lshlrev_b32_e32 v62, 16, v47
	v_and_b32_e32 v63, 0xffff0000, v47
	v_pk_add_f32 v[60:61], v[60:61], v[62:63]
	v_pk_add_f32 v[62:63], v[44:45], v[48:49]
	v_cvt_pk_bf16_f32 v44, v58, v59
	v_cvt_pk_bf16_f32 v45, v56, v57
	v_lshlrev_b32_e32 v64, 16, v44
	v_and_b32_e32 v65, 0xffff0000, v44
	v_lshlrev_b32_e32 v66, 16, v45
	v_and_b32_e32 v67, 0xffff0000, v45
	v_sub_f32_e32 v49, v56, v66
	v_sub_f32_e32 v56, v57, v67
	v_sub_f32_e32 v48, v58, v64
	v_sub_f32_e32 v57, v59, v65
	v_cvt_pk_bf16_f32 v48, v48, v57
	v_cvt_pk_bf16_f32 v49, v49, v56
	global_store_dwordx4 v[50:51], v[42:45], off
	global_store_dwordx4 v[52:53], v[46:49], off
	v_lshlrev_b32_e32 v56, 16, v48
	v_and_b32_e32 v57, 0xffff0000, v48
	v_mul_f32_e32 v42, v63, v63
	v_mul_f32_e32 v43, v61, v61
	v_pk_add_f32 v[56:57], v[64:65], v[56:57]
	v_fmac_f32_e32 v42, v62, v62
	v_fmac_f32_e32 v43, v60, v60
	v_lshlrev_b32_e32 v58, 16, v49
	v_and_b32_e32 v59, 0xffff0000, v49
	v_add_f32_e32 v42, v42, v43
	v_mul_f32_e32 v43, v57, v57
	v_pk_add_f32 v[58:59], v[66:67], v[58:59]
	v_fmac_f32_e32 v43, v56, v56
	v_add_f32_e32 v42, v42, v43
	v_mul_f32_e32 v43, v59, v59
	v_fmac_f32_e32 v43, v58, v58
	v_add_f32_e32 v60, v43, v42
	s_waitcnt vmcnt(18)
	v_lshlrev_b32_e32 v56, 16, v178
	v_and_b32_e32 v57, 0xffff0000, v178
	v_lshlrev_b32_e32 v58, 16, v190
	v_and_b32_e32 v59, 0xffff0000, v190
	v_lshlrev_b32_e32 v42, 16, v179
	v_and_b32_e32 v43, 0xffff0000, v179
	v_lshlrev_b32_e32 v46, 16, v191
	v_and_b32_e32 v47, 0xffff0000, v191
	v_pk_add_f32 v[56:57], v[56:57], v[58:59]
	v_pk_add_f32 v[42:43], v[42:43], v[46:47]
	v_lshlrev_b32_e32 v46, 16, v180
	v_and_b32_e32 v47, 0xffff0000, v180
	v_lshlrev_b32_e32 v58, 16, v192
	v_and_b32_e32 v59, 0xffff0000, v192
	v_lshlrev_b32_e32 v44, 16, v181
	v_and_b32_e32 v45, 0xffff0000, v181
	v_lshlrev_b32_e32 v48, 16, v193
	v_and_b32_e32 v49, 0xffff0000, v193
	v_pk_add_f32 v[46:47], v[46:47], v[58:59]
	v_pk_add_f32 v[44:45], v[44:45], v[48:49]
	v_pk_fma_f32 v[40:41], v[40:41], 0.5, v[42:43] op_sel_hi:[1,0,1]
	v_pk_fma_f32 v[38:39], v[38:39], 0.5, v[56:57] op_sel_hi:[1,0,1]
	v_pk_fma_f32 v[42:43], v[36:37], 0.5, v[44:45] op_sel_hi:[1,0,1]
	v_pk_fma_f32 v[44:45], v[34:35], 0.5, v[46:47] op_sel_hi:[1,0,1]
	v_cvt_pk_bf16_f32 v34, v38, v39
	v_cvt_pk_bf16_f32 v35, v40, v41
	v_lshlrev_b32_e32 v36, 16, v34
	v_and_b32_e32 v37, 0xffff0000, v34
	v_lshlrev_b32_e32 v46, 16, v35
	v_and_b32_e32 v47, 0xffff0000, v35
	v_sub_f32_e32 v40, v40, v46
	v_sub_f32_e32 v41, v41, v47
	v_sub_f32_e32 v38, v38, v36
	v_sub_f32_e32 v39, v39, v37
	v_cvt_pk_bf16_f32 v38, v38, v39
	v_cvt_pk_bf16_f32 v39, v40, v41
	v_lshlrev_b32_e32 v40, 16, v38
	v_and_b32_e32 v41, 0xffff0000, v38
	v_lshlrev_b32_e32 v48, 16, v39
	v_and_b32_e32 v49, 0xffff0000, v39
	v_pk_add_f32 v[46:47], v[46:47], v[48:49]
	v_pk_add_f32 v[48:49], v[36:37], v[40:41]
	v_cvt_pk_bf16_f32 v36, v44, v45
	v_cvt_pk_bf16_f32 v37, v42, v43
	v_lshlrev_b32_e32 v56, 16, v36
	v_and_b32_e32 v57, 0xffff0000, v36
	v_lshlrev_b32_e32 v58, 16, v37
	v_and_b32_e32 v59, 0xffff0000, v37
	v_sub_f32_e32 v41, v42, v58
	v_sub_f32_e32 v42, v43, v59
	v_sub_f32_e32 v40, v44, v56
	v_sub_f32_e32 v43, v45, v57
	v_cvt_pk_bf16_f32 v40, v40, v43
	v_cvt_pk_bf16_f32 v41, v41, v42
	global_store_dwordx4 v[50:51], v[34:37], off offset:256
	global_store_dwordx4 v[52:53], v[38:41], off offset:256
	v_lshlrev_b32_e32 v42, 16, v40
	v_and_b32_e32 v43, 0xffff0000, v40
	v_mul_f32_e32 v34, v49, v49
	v_mul_f32_e32 v35, v47, v47
	v_pk_add_f32 v[42:43], v[56:57], v[42:43]
	v_fmac_f32_e32 v34, v48, v48
	v_fmac_f32_e32 v35, v46, v46
	v_add_u32_e32 v36, 0xa0, v144
	v_lshlrev_b32_e32 v44, 16, v41
	v_and_b32_e32 v45, 0xffff0000, v41
	v_add_f32_e32 v34, v34, v35
	v_mul_f32_e32 v35, v43, v43
	v_ashrrev_i32_e32 v37, 31, v36
	v_pk_add_f32 v[44:45], v[58:59], v[44:45]
	v_fmac_f32_e32 v35, v42, v42
	v_lshlrev_b64 v[36:37], 11, v[36:37]
	v_add_f32_e32 v34, v34, v35
	v_mul_f32_e32 v35, v45, v45
	v_lshl_add_u64 v[38:39], s[66:67], 0, v[36:37]
	v_fmac_f32_e32 v35, v44, v44
	v_lshl_add_u64 v[44:45], v[38:39], 0, v[142:143]
	v_lshl_add_u64 v[36:37], s[64:65], 0, v[36:37]
	v_lshl_add_u64 v[46:47], v[36:37], 0, v[142:143]
	v_add_f32_e32 v34, v35, v34
	v_add_f32_e32 v34, v60, v34
	ds_bpermute_b32 v35, v204, v34
	s_waitcnt lgkmcnt(0)
	v_add_f32_e32 v34, v34, v35
	ds_bpermute_b32 v35, v205, v34
	s_waitcnt vmcnt(16)
	v_lshlrev_b32_e32 v48, 16, v194
	v_and_b32_e32 v49, 0xffff0000, v194
	v_lshlrev_b32_e32 v50, 16, v214
	v_and_b32_e32 v51, 0xffff0000, v214
	v_lshlrev_b32_e32 v36, 16, v195
	v_and_b32_e32 v37, 0xffff0000, v195
	v_lshlrev_b32_e32 v40, 16, v215
	v_and_b32_e32 v41, 0xffff0000, v215
	v_pk_add_f32 v[48:49], v[48:49], v[50:51]
	v_pk_add_f32 v[36:37], v[36:37], v[40:41]
	v_lshlrev_b32_e32 v40, 16, v196
	v_and_b32_e32 v41, 0xffff0000, v196
	v_lshlrev_b32_e32 v50, 16, v216
	v_and_b32_e32 v51, 0xffff0000, v216
	v_lshlrev_b32_e32 v38, 16, v197
	v_and_b32_e32 v39, 0xffff0000, v197
	v_lshlrev_b32_e32 v42, 16, v217
	v_and_b32_e32 v43, 0xffff0000, v217
	v_pk_add_f32 v[40:41], v[40:41], v[50:51]
	v_pk_add_f32 v[38:39], v[38:39], v[42:43]
	v_pk_fma_f32 v[32:33], v[32:33], 0.5, v[36:37] op_sel_hi:[1,0,1]
	v_pk_fma_f32 v[30:31], v[30:31], 0.5, v[48:49] op_sel_hi:[1,0,1]
	v_pk_fma_f32 v[36:37], v[28:29], 0.5, v[38:39] op_sel_hi:[1,0,1]
	v_pk_fma_f32 v[38:39], v[26:27], 0.5, v[40:41] op_sel_hi:[1,0,1]
	v_cvt_pk_bf16_f32 v26, v30, v31
	v_cvt_pk_bf16_f32 v27, v32, v33
	v_lshlrev_b32_e32 v28, 16, v26
	v_and_b32_e32 v29, 0xffff0000, v26
	v_lshlrev_b32_e32 v40, 16, v27
	v_and_b32_e32 v41, 0xffff0000, v27
	v_sub_f32_e32 v32, v32, v40
	v_sub_f32_e32 v33, v33, v41
	v_sub_f32_e32 v30, v30, v28
	v_sub_f32_e32 v31, v31, v29
	v_cvt_pk_bf16_f32 v30, v30, v31
	v_cvt_pk_bf16_f32 v31, v32, v33
	v_lshlrev_b32_e32 v32, 16, v30
	v_and_b32_e32 v33, 0xffff0000, v30
	v_lshlrev_b32_e32 v42, 16, v31
	v_and_b32_e32 v43, 0xffff0000, v31
	v_pk_add_f32 v[40:41], v[40:41], v[42:43]
	v_pk_add_f32 v[42:43], v[28:29], v[32:33]
	v_cvt_pk_bf16_f32 v28, v38, v39
	v_cvt_pk_bf16_f32 v29, v36, v37
	v_lshlrev_b32_e32 v48, 16, v28
	v_and_b32_e32 v49, 0xffff0000, v28
	v_lshlrev_b32_e32 v50, 16, v29
	v_and_b32_e32 v51, 0xffff0000, v29
	v_sub_f32_e32 v33, v36, v50
	v_sub_f32_e32 v36, v37, v51
	v_sub_f32_e32 v32, v38, v48
	v_sub_f32_e32 v37, v39, v49
	v_cvt_pk_bf16_f32 v32, v32, v37
	v_cvt_pk_bf16_f32 v33, v33, v36
	global_store_dwordx4 v[44:45], v[26:29], off
	global_store_dwordx4 v[46:47], v[30:33], off
	v_lshlrev_b32_e32 v36, 16, v32
	v_and_b32_e32 v37, 0xffff0000, v32
	v_mul_f32_e32 v26, v43, v43
	v_mul_f32_e32 v27, v41, v41
	v_pk_add_f32 v[36:37], v[48:49], v[36:37]
	v_fmac_f32_e32 v26, v42, v42
	v_fmac_f32_e32 v27, v40, v40
	v_lshlrev_b32_e32 v38, 16, v33
	v_and_b32_e32 v39, 0xffff0000, v33
	v_add_f32_e32 v26, v26, v27
	v_mul_f32_e32 v27, v37, v37
	v_pk_add_f32 v[38:39], v[50:51], v[38:39]
	v_fmac_f32_e32 v27, v36, v36
	v_add_f32_e32 v26, v26, v27
	v_mul_f32_e32 v27, v39, v39
	v_fmac_f32_e32 v27, v38, v38
	v_add_f32_e32 v40, v27, v26
	s_waitcnt vmcnt(14)
	v_lshlrev_b32_e32 v36, 16, v218
	v_and_b32_e32 v37, 0xffff0000, v218
	v_lshlrev_b32_e32 v38, 16, v222
	v_and_b32_e32 v39, 0xffff0000, v222
	v_lshlrev_b32_e32 v26, 16, v219
	v_and_b32_e32 v27, 0xffff0000, v219
	v_lshlrev_b32_e32 v30, 16, v223
	v_and_b32_e32 v31, 0xffff0000, v223
	v_pk_add_f32 v[36:37], v[36:37], v[38:39]
	v_pk_add_f32 v[26:27], v[26:27], v[30:31]
	v_lshlrev_b32_e32 v30, 16, v220
	v_and_b32_e32 v31, 0xffff0000, v220
	v_lshlrev_b32_e32 v38, 16, v224
	v_and_b32_e32 v39, 0xffff0000, v224
	v_lshlrev_b32_e32 v28, 16, v221
	v_and_b32_e32 v29, 0xffff0000, v221
	v_lshlrev_b32_e32 v32, 16, v225
	v_and_b32_e32 v33, 0xffff0000, v225
	v_pk_add_f32 v[30:31], v[30:31], v[38:39]
	v_pk_add_f32 v[28:29], v[28:29], v[32:33]
	v_pk_fma_f32 v[24:25], v[24:25], 0.5, v[26:27] op_sel_hi:[1,0,1]
	v_pk_fma_f32 v[22:23], v[22:23], 0.5, v[36:37] op_sel_hi:[1,0,1]
	v_pk_fma_f32 v[26:27], v[20:21], 0.5, v[28:29] op_sel_hi:[1,0,1]
	v_pk_fma_f32 v[28:29], v[18:19], 0.5, v[30:31] op_sel_hi:[1,0,1]
	v_cvt_pk_bf16_f32 v18, v22, v23
	v_cvt_pk_bf16_f32 v19, v24, v25
	v_lshlrev_b32_e32 v20, 16, v18
	v_and_b32_e32 v21, 0xffff0000, v18
	v_lshlrev_b32_e32 v30, 16, v19
	v_and_b32_e32 v31, 0xffff0000, v19
	v_sub_f32_e32 v24, v24, v30
	v_sub_f32_e32 v25, v25, v31
	v_sub_f32_e32 v22, v22, v20
	v_sub_f32_e32 v23, v23, v21
	v_cvt_pk_bf16_f32 v22, v22, v23
	v_cvt_pk_bf16_f32 v23, v24, v25
	v_lshlrev_b32_e32 v24, 16, v22
	v_and_b32_e32 v25, 0xffff0000, v22
	v_lshlrev_b32_e32 v32, 16, v23
	v_and_b32_e32 v33, 0xffff0000, v23
	v_pk_add_f32 v[30:31], v[30:31], v[32:33]
	v_pk_add_f32 v[32:33], v[20:21], v[24:25]
	v_cvt_pk_bf16_f32 v20, v28, v29
	v_cvt_pk_bf16_f32 v21, v26, v27
	v_lshlrev_b32_e32 v36, 16, v20
	v_and_b32_e32 v37, 0xffff0000, v20
	v_lshlrev_b32_e32 v38, 16, v21
	v_and_b32_e32 v39, 0xffff0000, v21
	v_sub_f32_e32 v25, v26, v38
	v_sub_f32_e32 v26, v27, v39
	v_sub_f32_e32 v24, v28, v36
	v_sub_f32_e32 v27, v29, v37
	v_cvt_pk_bf16_f32 v24, v24, v27
	v_cvt_pk_bf16_f32 v25, v25, v26
	global_store_dwordx4 v[44:45], v[18:21], off offset:256
	global_store_dwordx4 v[46:47], v[22:25], off offset:256
	v_lshlrev_b32_e32 v26, 16, v24
	v_and_b32_e32 v27, 0xffff0000, v24
	v_mul_f32_e32 v18, v33, v33
	v_mul_f32_e32 v19, v31, v31
	v_pk_add_f32 v[26:27], v[36:37], v[26:27]
	v_fmac_f32_e32 v18, v32, v32
	v_fmac_f32_e32 v19, v30, v30
	v_lshlrev_b32_e32 v28, 16, v25
	v_and_b32_e32 v29, 0xffff0000, v25
	v_add_f32_e32 v18, v18, v19
	v_mul_f32_e32 v19, v27, v27
	v_pk_add_f32 v[28:29], v[38:39], v[28:29]
	v_fmac_f32_e32 v19, v26, v26
	v_add_f32_e32 v18, v18, v19
	v_mul_f32_e32 v19, v29, v29
	v_fmac_f32_e32 v19, v28, v28
	v_add_f32_e32 v18, v19, v18
	v_add_f32_e32 v18, v40, v18
	ds_bpermute_b32 v19, v204, v18
	s_waitcnt lgkmcnt(0)
	v_add_f32_e32 v30, v18, v19
	v_add_u32_e32 v18, 0xb0, v144
	v_ashrrev_i32_e32 v19, 31, v18
	v_lshlrev_b64 v[18:19], 11, v[18:19]
	v_lshl_add_u64 v[20:21], s[66:67], 0, v[18:19]
	v_lshl_add_u64 v[26:27], v[20:21], 0, v[142:143]
	v_lshl_add_u64 v[18:19], s[64:65], 0, v[18:19]
	v_lshl_add_u64 v[28:29], v[18:19], 0, v[142:143]
	ds_bpermute_b32 v31, v205, v30
	s_waitcnt vmcnt(12)
	v_lshlrev_b32_e32 v32, 16, v226
	v_and_b32_e32 v33, 0xffff0000, v226
	v_lshlrev_b32_e32 v36, 16, v230
	v_and_b32_e32 v37, 0xffff0000, v230
	v_lshlrev_b32_e32 v18, 16, v227
	v_and_b32_e32 v19, 0xffff0000, v227
	v_lshlrev_b32_e32 v22, 16, v231
	v_and_b32_e32 v23, 0xffff0000, v231
	v_pk_add_f32 v[32:33], v[32:33], v[36:37]
	v_pk_add_f32 v[18:19], v[18:19], v[22:23]
	v_lshlrev_b32_e32 v22, 16, v228
	v_and_b32_e32 v23, 0xffff0000, v228
	v_lshlrev_b32_e32 v36, 16, v232
	v_and_b32_e32 v37, 0xffff0000, v232
	v_lshlrev_b32_e32 v20, 16, v229
	v_and_b32_e32 v21, 0xffff0000, v229
	v_lshlrev_b32_e32 v24, 16, v233
	v_and_b32_e32 v25, 0xffff0000, v233
	v_pk_add_f32 v[22:23], v[22:23], v[36:37]
	v_pk_add_f32 v[20:21], v[20:21], v[24:25]
	v_pk_fma_f32 v[16:17], v[16:17], 0.5, v[18:19] op_sel_hi:[1,0,1]
	v_pk_fma_f32 v[14:15], v[14:15], 0.5, v[32:33] op_sel_hi:[1,0,1]
	v_pk_fma_f32 v[18:19], v[12:13], 0.5, v[20:21] op_sel_hi:[1,0,1]
	v_pk_fma_f32 v[20:21], v[10:11], 0.5, v[22:23] op_sel_hi:[1,0,1]
	v_cvt_pk_bf16_f32 v10, v14, v15
	v_cvt_pk_bf16_f32 v11, v16, v17
	v_lshlrev_b32_e32 v12, 16, v10
	v_and_b32_e32 v13, 0xffff0000, v10
	v_lshlrev_b32_e32 v22, 16, v11
	v_and_b32_e32 v23, 0xffff0000, v11
	v_sub_f32_e32 v16, v16, v22
	v_sub_f32_e32 v17, v17, v23
	v_sub_f32_e32 v14, v14, v12
	v_sub_f32_e32 v15, v15, v13
	v_cvt_pk_bf16_f32 v14, v14, v15
	v_cvt_pk_bf16_f32 v15, v16, v17
	v_lshlrev_b32_e32 v16, 16, v14
	v_and_b32_e32 v17, 0xffff0000, v14
	v_lshlrev_b32_e32 v24, 16, v15
	v_and_b32_e32 v25, 0xffff0000, v15
	v_pk_add_f32 v[22:23], v[22:23], v[24:25]
	v_pk_add_f32 v[24:25], v[12:13], v[16:17]
	v_cvt_pk_bf16_f32 v12, v20, v21
	v_cvt_pk_bf16_f32 v13, v18, v19
	v_lshlrev_b32_e32 v32, 16, v12
	v_and_b32_e32 v33, 0xffff0000, v12
	v_lshlrev_b32_e32 v36, 16, v13
	v_and_b32_e32 v37, 0xffff0000, v13
	v_sub_f32_e32 v17, v18, v36
	v_sub_f32_e32 v18, v19, v37
	v_sub_f32_e32 v16, v20, v32
	v_sub_f32_e32 v19, v21, v33
	v_cvt_pk_bf16_f32 v16, v16, v19
	v_cvt_pk_bf16_f32 v17, v17, v18
	global_store_dwordx4 v[26:27], v[10:13], off
	global_store_dwordx4 v[28:29], v[14:17], off
	v_lshlrev_b32_e32 v18, 16, v16
	v_and_b32_e32 v19, 0xffff0000, v16
	v_mul_f32_e32 v10, v25, v25
	v_mul_f32_e32 v11, v23, v23
	v_pk_add_f32 v[18:19], v[32:33], v[18:19]
	v_fmac_f32_e32 v10, v24, v24
	v_fmac_f32_e32 v11, v22, v22
	v_lshlrev_b32_e32 v20, 16, v17
	v_and_b32_e32 v21, 0xffff0000, v17
	v_add_f32_e32 v10, v10, v11
	v_mul_f32_e32 v11, v19, v19
	v_pk_add_f32 v[20:21], v[36:37], v[20:21]
	v_fmac_f32_e32 v11, v18, v18
	v_add_f32_e32 v10, v10, v11
	v_mul_f32_e32 v11, v21, v21
	v_fmac_f32_e32 v11, v20, v20
	v_add_f32_e32 v18, v11, v10
	s_waitcnt vmcnt(10)
	v_lshlrev_b32_e32 v20, 16, v170
	v_and_b32_e32 v21, 0xffff0000, v170
	v_lshlrev_b32_e32 v22, 16, v174
	v_and_b32_e32 v23, 0xffff0000, v174
	v_lshlrev_b32_e32 v10, 16, v171
	v_and_b32_e32 v11, 0xffff0000, v171
	v_lshlrev_b32_e32 v14, 16, v175
	v_and_b32_e32 v15, 0xffff0000, v175
	v_pk_add_f32 v[20:21], v[20:21], v[22:23]
	v_pk_add_f32 v[10:11], v[10:11], v[14:15]
	v_lshlrev_b32_e32 v14, 16, v172
	v_and_b32_e32 v15, 0xffff0000, v172
	v_lshlrev_b32_e32 v22, 16, v176
	v_and_b32_e32 v23, 0xffff0000, v176
	v_lshlrev_b32_e32 v12, 16, v173
	v_and_b32_e32 v13, 0xffff0000, v173
	v_lshlrev_b32_e32 v16, 16, v177
	v_and_b32_e32 v17, 0xffff0000, v177
	v_pk_add_f32 v[14:15], v[14:15], v[22:23]
	v_pk_add_f32 v[12:13], v[12:13], v[16:17]
	v_pk_fma_f32 v[8:9], v[8:9], 0.5, v[10:11] op_sel_hi:[1,0,1]
	v_pk_fma_f32 v[6:7], v[6:7], 0.5, v[20:21] op_sel_hi:[1,0,1]
	v_pk_fma_f32 v[10:11], v[4:5], 0.5, v[12:13] op_sel_hi:[1,0,1]
	v_pk_fma_f32 v[12:13], v[2:3], 0.5, v[14:15] op_sel_hi:[1,0,1]
	v_cvt_pk_bf16_f32 v2, v6, v7
	v_cvt_pk_bf16_f32 v3, v8, v9
	v_lshlrev_b32_e32 v4, 16, v2
	v_and_b32_e32 v5, 0xffff0000, v2
	v_lshlrev_b32_e32 v14, 16, v3
	v_and_b32_e32 v15, 0xffff0000, v3
	v_sub_f32_e32 v8, v8, v14
	v_sub_f32_e32 v9, v9, v15
	v_sub_f32_e32 v6, v6, v4
	v_sub_f32_e32 v7, v7, v5
	v_cvt_pk_bf16_f32 v6, v6, v7
	v_cvt_pk_bf16_f32 v7, v8, v9
	v_lshlrev_b32_e32 v8, 16, v6
	v_and_b32_e32 v9, 0xffff0000, v6
	v_lshlrev_b32_e32 v16, 16, v7
	v_and_b32_e32 v17, 0xffff0000, v7
	v_pk_add_f32 v[14:15], v[14:15], v[16:17]
	v_pk_add_f32 v[16:17], v[4:5], v[8:9]
	v_cvt_pk_bf16_f32 v4, v12, v13
	v_cvt_pk_bf16_f32 v5, v10, v11
	v_lshlrev_b32_e32 v20, 16, v4
	v_and_b32_e32 v21, 0xffff0000, v4
	v_lshlrev_b32_e32 v22, 16, v5
	v_and_b32_e32 v23, 0xffff0000, v5
	v_sub_f32_e32 v9, v10, v22
	v_sub_f32_e32 v10, v11, v23
	v_sub_f32_e32 v8, v12, v20
	v_sub_f32_e32 v11, v13, v21
	v_cvt_pk_bf16_f32 v8, v8, v11
	v_cvt_pk_bf16_f32 v9, v9, v10
	global_store_dwordx4 v[26:27], v[2:5], off offset:256
	global_store_dwordx4 v[28:29], v[6:9], off offset:256
	v_lshlrev_b32_e32 v10, 16, v8
	v_and_b32_e32 v11, 0xffff0000, v8
	v_mul_f32_e32 v2, v17, v17
	v_mul_f32_e32 v3, v15, v15
	v_pk_add_f32 v[10:11], v[20:21], v[10:11]
	v_fmac_f32_e32 v2, v16, v16
	v_fmac_f32_e32 v3, v14, v14
	v_lshlrev_b32_e32 v12, 16, v9
	v_and_b32_e32 v13, 0xffff0000, v9
	v_add_f32_e32 v2, v2, v3
	v_mul_f32_e32 v3, v11, v11
	v_pk_add_f32 v[12:13], v[22:23], v[12:13]
	v_fmac_f32_e32 v3, v10, v10
	v_add_f32_e32 v2, v2, v3
	v_mul_f32_e32 v3, v13, v13
	v_fmac_f32_e32 v3, v12, v12
	v_add_f32_e32 v2, v3, v2
	v_add_f32_e32 v2, v18, v2
	ds_bpermute_b32 v3, v204, v2
	s_waitcnt lgkmcnt(0)
	v_add_f32_e32 v2, v2, v3
	ds_bpermute_b32 v3, v205, v2
	s_and_saveexec_b64 s[24:25], s[10:11]
	s_cbranch_execz .LBB11_2775
	s_ashr_i32 s23, s22, 31
	s_lshl_b64 s[0:1], s[22:23], 2
	s_add_u32 s0, s36, s0
	v_ashrrev_i32_e32 v141, 31, v140
	s_addc_u32 s1, s37, s1
	s_waitcnt lgkmcnt(0)
	v_add_f32_e32 v4, v2, v3
	v_add_f32_e32 v11, v118, v119
	v_lshl_add_u64 v[2:3], v[140:141], 2, s[0:1]
	v_add_f32_e32 v5, v30, v31
	v_add_f32_e32 v6, v34, v35
	v_add_f32_e32 v7, v54, v55
	v_add_f32_e32 v8, v70, v71
	v_add_f32_e32 v9, v86, v87
	v_add_f32_e32 v10, v102, v103
	global_atomic_add_f32 v[2:3], v11, off
	global_atomic_add_f32 v[2:3], v10, off offset:64
	global_atomic_add_f32 v[2:3], v9, off offset:128
	global_atomic_add_f32 v[2:3], v8, off offset:192
	global_atomic_add_f32 v[2:3], v7, off offset:512
	global_atomic_add_f32 v[2:3], v6, off offset:576
	global_atomic_add_f32 v[2:3], v5, off offset:640
	global_atomic_add_f32 v[2:3], v4, off offset:704

.LBB11_2915:
	s_or_b64 exec, exec, s[38:39]
	s_waitcnt lgkmcnt(0)
	s_waitcnt lgkmcnt(0)
	s_barrier
	ds_read_b128 v[192:195], v191
	v_readlane_b32 s0, v243, 0
	s_andn2_b64 vcc, exec, s[2:3]
	s_waitcnt vmcnt(21) lgkmcnt(0)
	v_mfma_f32_16x16x32_bf16 v[130:133], v[192:195], v[130:133], 0
	ds_read_b128 v[192:195], v191 offset:64
	v_add_u32_e32 v0, s0, v158
	s_waitcnt vmcnt(20) lgkmcnt(0)
	v_mfma_f32_16x16x32_bf16 v[126:129], v[192:195], v[126:129], v[130:133]
	s_nop 3
	ds_read_b128 v[130:133], v191 offset:128
	s_waitcnt vmcnt(19) lgkmcnt(0)
	v_mfma_f32_16x16x32_bf16 v[122:125], v[130:133], v[122:125], v[126:129]
	s_nop 2
	ds_read_b128 v[126:129], v191 offset:192
	s_waitcnt vmcnt(18) lgkmcnt(0)
	v_mfma_f32_16x16x32_bf16 v[118:121], v[126:129], v[118:121], v[122:125]
	s_nop 2
	ds_read_b128 v[122:125], v191 offset:256
	s_waitcnt vmcnt(17) lgkmcnt(0)
	v_mfma_f32_16x16x32_bf16 v[114:117], v[122:125], v[114:117], v[118:121]
	s_nop 2
	ds_read_b128 v[118:121], v191 offset:320
	s_waitcnt vmcnt(16) lgkmcnt(0)
	v_mfma_f32_16x16x32_bf16 v[110:113], v[118:121], v[110:113], v[114:117]
	s_nop 2
	ds_read_b128 v[114:117], v191 offset:384
	s_waitcnt vmcnt(15) lgkmcnt(0)
	v_mfma_f32_16x16x32_bf16 v[106:109], v[114:117], v[106:109], v[110:113]
	s_nop 2
	ds_read_b128 v[110:113], v191 offset:448
	s_waitcnt vmcnt(14) lgkmcnt(0)
	v_mfma_f32_16x16x32_bf16 v[102:105], v[110:113], v[102:105], v[106:109]
	s_nop 2
	ds_read_b128 v[106:109], v191 offset:512
	s_waitcnt vmcnt(13) lgkmcnt(0)
	v_mfma_f32_16x16x32_bf16 v[98:101], v[106:109], v[98:101], v[102:105]
	s_nop 2
	ds_read_b128 v[102:105], v191 offset:576
	s_waitcnt vmcnt(12) lgkmcnt(0)
	v_mfma_f32_16x16x32_bf16 v[94:97], v[102:105], v[94:97], v[98:101]
	s_nop 2
	ds_read_b128 v[98:101], v191 offset:640
	s_waitcnt vmcnt(11) lgkmcnt(0)
	v_mfma_f32_16x16x32_bf16 v[90:93], v[98:101], v[90:93], v[94:97]
	s_nop 2
	ds_read_b128 v[94:97], v191 offset:704
	s_waitcnt vmcnt(10) lgkmcnt(0)
	v_mfma_f32_16x16x32_bf16 v[86:89], v[94:97], v[86:89], v[90:93]
	s_nop 2
	ds_read_b128 v[90:93], v191 offset:768
	s_waitcnt vmcnt(9) lgkmcnt(0)
	v_mfma_f32_16x16x32_bf16 v[82:85], v[90:93], v[82:85], v[86:89]
	s_nop 2
	ds_read_b128 v[86:89], v191 offset:832
	s_waitcnt vmcnt(8) lgkmcnt(0)
	v_mfma_f32_16x16x32_bf16 v[78:81], v[86:89], v[78:81], v[82:85]
	s_nop 2
	ds_read_b128 v[82:85], v191 offset:896
	s_waitcnt vmcnt(7) lgkmcnt(0)
	v_mfma_f32_16x16x32_bf16 v[74:77], v[82:85], v[74:77], v[78:81]
	s_nop 2
	ds_read_b128 v[78:81], v191 offset:960
	s_waitcnt vmcnt(6) lgkmcnt(0)
	v_mfma_f32_16x16x32_bf16 v[70:73], v[78:81], v[70:73], v[74:77]
	s_nop 2
	ds_read_b128 v[74:77], v191 offset:1024
	s_waitcnt vmcnt(5) lgkmcnt(0)
	v_mfma_f32_16x16x32_bf16 v[66:69], v[74:77], v[66:69], v[70:73]
	s_nop 2
	ds_read_b128 v[70:73], v191 offset:1088
	s_waitcnt vmcnt(4) lgkmcnt(0)
	v_mfma_f32_16x16x32_bf16 v[62:65], v[70:73], v[62:65], v[66:69]
	s_nop 2
	ds_read_b128 v[66:69], v191 offset:1152
	s_waitcnt vmcnt(3) lgkmcnt(0)
	v_mfma_f32_16x16x32_bf16 v[58:61], v[66:69], v[58:61], v[62:65]
	s_nop 2
	ds_read_b128 v[62:65], v191 offset:1216
	s_waitcnt vmcnt(2) lgkmcnt(0)
	v_mfma_f32_16x16x32_bf16 v[54:57], v[62:65], v[54:57], v[58:61]
	s_nop 2
	ds_read_b128 v[58:61], v191 offset:1280
	s_waitcnt vmcnt(1) lgkmcnt(0)
	v_mfma_f32_16x16x32_bf16 v[50:53], v[58:61], v[50:53], v[54:57]
	s_nop 2
	ds_read_b128 v[54:57], v191 offset:1344
	s_waitcnt vmcnt(0) lgkmcnt(0)
	v_mfma_f32_16x16x32_bf16 v[46:49], v[54:57], v[46:49], v[50:53]
	s_nop 7
	ds_write_b128 v0, v[46:49]
	s_waitcnt lgkmcnt(0)
	s_waitcnt lgkmcnt(0)
	s_barrier
	s_cbranch_vccnz .LBB11_2870
	v_readlane_b32 s0, v245, 40
	s_nop 1
	v_add_u32_e32 v0, s0, v158
	ds_read_b128 v[50:53], v0 offset:2048
	s_lshl_b32 s0, s9, 17
	s_waitcnt lgkmcnt(0)
	v_pk_add_f32 v[52:53], v[48:49], v[52:53]
	v_pk_add_f32 v[50:51], v[46:47], v[50:51]
	ds_read_b128 v[46:49], v0 offset:4096
	s_waitcnt lgkmcnt(0)
	v_pk_add_f32 v[52:53], v[52:53], v[48:49]
	v_pk_add_f32 v[50:51], v[50:51], v[46:47]
	ds_read_b128 v[46:49], v0 offset:6144
	v_subrev_u32_e32 v0, s0, v173
	s_waitcnt lgkmcnt(0)
	v_pk_add_f32 v[46:47], v[50:51], v[46:47]
	v_add_u32_e32 v50, s40, v159
	v_pk_add_f32 v[48:49], v[52:53], v[48:49]
	v_ashrrev_i32_e32 v51, 31, v50
	v_lshlrev_b64 v[52:53], 1, v[0:1]
	v_lshl_add_u64 v[54:55], s[66:67], 0, v[52:53]
	v_lshlrev_b64 v[50:51], 1, v[50:51]
	v_lshl_add_u64 v[54:55], v[54:55], 0, v[50:51]
	v_lshl_add_u64 v[52:53], s[64:65], 0, v[52:53]
	v_lshl_add_u64 v[50:51], v[52:53], 0, v[50:51]
	global_load_dwordx2 v[52:53], v[54:55], off
	global_load_dwordx2 v[56:57], v[50:51], off
	s_waitcnt vmcnt(1)
	v_lshlrev_b32_e32 v58, 16, v52
	v_and_b32_e32 v59, 0xffff0000, v52
	s_waitcnt vmcnt(0)
	v_lshlrev_b32_e32 v60, 16, v56
	v_and_b32_e32 v61, 0xffff0000, v56
	v_lshlrev_b32_e32 v52, 16, v53
	v_and_b32_e32 v53, 0xffff0000, v53
	v_lshlrev_b32_e32 v56, 16, v57
	v_and_b32_e32 v57, 0xffff0000, v57
	v_pk_add_f32 v[58:59], v[58:59], v[60:61]
	v_pk_add_f32 v[52:53], v[52:53], v[56:57]
	v_pk_fma_f32 v[46:47], v[46:47], 0.5, v[58:59] op_sel_hi:[1,0,1]
	v_pk_fma_f32 v[48:49], v[48:49], 0.5, v[52:53] op_sel_hi:[1,0,1]
	v_cvt_pk_bf16_f32 v52, v46, v47
	v_cvt_pk_bf16_f32 v53, v48, v49
	v_lshlrev_b32_e32 v56, 16, v52
	v_and_b32_e32 v57, 0xffff0000, v52
	v_lshlrev_b32_e32 v58, 16, v53
	v_and_b32_e32 v59, 0xffff0000, v53
	v_sub_f32_e32 v0, v48, v58
	v_sub_f32_e32 v48, v49, v59
	v_sub_f32_e32 v46, v46, v56
	v_sub_f32_e32 v47, v47, v57
	v_cvt_pk_bf16_f32 v46, v46, v47
	v_cvt_pk_bf16_f32 v47, v0, v48
	global_store_dwordx2 v[54:55], v[52:53], off sc1
	global_store_dwordx2 v[50:51], v[46:47], off sc1
	v_lshlrev_b32_e32 v48, 16, v46
	v_and_b32_e32 v49, 0xffff0000, v46
	v_lshlrev_b32_e32 v60, 16, v47
	v_and_b32_e32 v61, 0xffff0000, v47
	v_pk_add_f32 v[58:59], v[58:59], v[60:61]
	v_pk_add_f32 v[48:49], v[56:57], v[48:49]
	v_mul_f32_e32 v46, v59, v59
	v_mul_f32_e32 v0, v49, v49
	v_fmac_f32_e32 v0, v48, v48
	v_fmac_f32_e32 v46, v58, v58
	v_add_f32_e32 v0, v0, v46
	ds_bpermute_b32 v46, v204, v0
	s_waitcnt lgkmcnt(0)
	v_add_f32_e32 v46, v0, v46
	ds_bpermute_b32 v47, v205, v46
	s_and_saveexec_b64 s[38:39], s[10:11]
	s_cbranch_execz .LBB11_2869
	s_lshl_b32 s0, s9, 7
	v_subrev_u32_e32 v0, s0, v172
	v_lshl_add_u64 v[48:49], v[0:1], 2, s[36:37]
	s_waitcnt lgkmcnt(0)
	v_add_f32_e32 v0, v46, v47
	global_atomic_add_f32 v[48:49], v0, off
	s_branch .LBB11_2869

.LBB11_3038:
	s_cmpk_lt_i32 s18, 0x400
	s_cselect_b64 s[2:3], -1, 0
	s_or_b64 s[8:9], s[0:1], s[2:3]
	s_andn2_b64 vcc, exec, s[8:9]
	s_cbranch_vccnz .LBB11_3037
	s_and_b64 s[2:3], s[2:3], exec
	s_cselect_b32 s2, s19, 0x3c00
	s_add_i32 s12, s18, s2
	s_ashr_i32 s3, s2, 31
	s_add_u32 s2, s18, s2
	s_addc_u32 s3, s6, s3
	s_lshl_b64 s[8:9], s[2:3], 2
	s_add_u32 s8, s4, s8
	s_addc_u32 s9, s5, s9
	global_load_dword v22, v6, s[8:9]
	s_load_dwordx4 s[8:11], s[16:17], 0x128
	s_add_i32 s14, s12, 0xffffc000
	s_cmpk_lt_i32 s12, 0x4000
	s_cselect_b32 s12, s2, s14
	s_cselect_b32 s14, 0, 0x4000000
	s_cselect_b32 s13, s3, 0
	s_waitcnt lgkmcnt(0)
	s_add_u32 s14, s10, s14
	s_addc_u32 s15, s11, 0
	s_lshl_b64 s[10:11], s[12:13], 12
	s_add_u32 s10, s14, s10
	s_addc_u32 s11, s15, s11
	s_lshl_b64 s[2:3], s[2:3], 11
	v_lshl_add_u64 v[12:13], v[0:1], 0, s[2:3]
	v_lshl_add_u64 v[16:17], v[2:3], 0, s[2:3]
	global_load_dwordx2 v[14:15], v[12:13], off
	global_load_dwordx2 v[18:19], v[16:17], off
	v_lshl_add_u64 v[20:21], s[8:9], 0, v[4:5]
	global_load_dwordx4 v[8:11], v[20:21], off
	global_load_dword v250, v[12:13], off offset:512
	global_load_dword v250, v[16:17], off offset:512
	global_load_dword v250, v[12:13], off offset:1024
	global_load_dword v250, v[16:17], off offset:1024
	global_load_dword v250, v[12:13], off offset:1536
	global_load_dword v250, v[16:17], off offset:1536
	s_waitcnt vmcnt(9)
	v_fmamk_f32 v22, v22, 0x3a800000, v7
	v_mul_f32_e32 v23, 0x4b800000, v22
	v_cmp_gt_f32_e32 vcc, s7, v22
	s_waitcnt vmcnt(8)
	v_lshlrev_b32_e32 v24, 16, v14
	v_cndmask_b32_e32 v22, v22, v23, vcc
	v_rsq_f32_e32 v28, v22
	v_and_b32_e32 v25, 0xffff0000, v14
	s_waitcnt vmcnt(7)
	v_lshlrev_b32_e32 v26, 16, v18
	v_and_b32_e32 v27, 0xffff0000, v18
	v_mul_f32_e32 v29, 0x45800000, v28
	v_lshlrev_b32_e32 v14, 16, v15
	v_and_b32_e32 v15, 0xffff0000, v15
	v_lshlrev_b32_e32 v18, 16, v19
	v_and_b32_e32 v19, 0xffff0000, v19
	v_cndmask_b32_e32 v28, v28, v29, vcc
	v_pk_add_f32 v[24:25], v[24:25], v[26:27]
	v_pk_add_f32 v[14:15], v[14:15], v[18:19]
	v_pk_mul_f32 v[18:19], v[28:29], v[24:25] op_sel_hi:[0,1]
	v_pk_mul_f32 v[14:15], v[28:29], v[14:15] op_sel_hi:[0,1]
	v_lshl_add_u64 v[22:23], s[10:11], 0, v[4:5]
	s_waitcnt vmcnt(6)
	v_pk_mul_f32 v[10:11], v[10:11], v[14:15]
	v_pk_mul_f32 v[8:9], v[8:9], v[18:19]
	global_store_dwordx4 v[22:23], v[8:11], off nt
	global_load_dwordx2 v[14:15], v[12:13], off offset:512
	global_load_dwordx2 v[18:19], v[16:17], off offset:512
	s_nop 0
	global_load_dwordx4 v[8:11], v[20:21], off offset:1024
	s_waitcnt vmcnt(2)
	v_lshlrev_b32_e32 v24, 16, v14
	v_and_b32_e32 v25, 0xffff0000, v14
	s_waitcnt vmcnt(1)
	v_lshlrev_b32_e32 v26, 16, v18
	v_and_b32_e32 v27, 0xffff0000, v18
	v_lshlrev_b32_e32 v14, 16, v15
	v_and_b32_e32 v15, 0xffff0000, v15
	v_lshlrev_b32_e32 v18, 16, v19
	v_and_b32_e32 v19, 0xffff0000, v19
	v_pk_add_f32 v[24:25], v[24:25], v[26:27]
	v_pk_add_f32 v[14:15], v[14:15], v[18:19]
	v_pk_mul_f32 v[18:19], v[28:29], v[24:25] op_sel_hi:[0,1]
	v_pk_mul_f32 v[14:15], v[28:29], v[14:15] op_sel_hi:[0,1]
	s_waitcnt vmcnt(0)
	v_pk_mul_f32 v[10:11], v[10:11], v[14:15]
	v_pk_mul_f32 v[8:9], v[8:9], v[18:19]
	global_store_dwordx4 v[22:23], v[8:11], off offset:1024 nt
	global_load_dwordx2 v[14:15], v[12:13], off offset:1024
	global_load_dwordx2 v[18:19], v[16:17], off offset:1024
	s_nop 0
	global_load_dwordx4 v[8:11], v[20:21], off offset:2048
	s_waitcnt vmcnt(2)
	v_lshlrev_b32_e32 v24, 16, v14
	v_and_b32_e32 v25, 0xffff0000, v14
	s_waitcnt vmcnt(1)
	v_lshlrev_b32_e32 v26, 16, v18
	v_and_b32_e32 v27, 0xffff0000, v18
	v_lshlrev_b32_e32 v14, 16, v15
	v_and_b32_e32 v15, 0xffff0000, v15
	v_lshlrev_b32_e32 v18, 16, v19
	v_and_b32_e32 v19, 0xffff0000, v19
	v_pk_add_f32 v[24:25], v[24:25], v[26:27]
	v_pk_add_f32 v[14:15], v[14:15], v[18:19]
	v_pk_mul_f32 v[18:19], v[28:29], v[24:25] op_sel_hi:[0,1]
	v_pk_mul_f32 v[14:15], v[28:29], v[14:15] op_sel_hi:[0,1]
	s_waitcnt vmcnt(0)
	v_pk_mul_f32 v[10:11], v[10:11], v[14:15]
	v_pk_mul_f32 v[8:9], v[8:9], v[18:19]
	global_store_dwordx4 v[22:23], v[8:11], off offset:2048 nt
	global_load_dwordx2 v[14:15], v[12:13], off offset:1536
	global_load_dwordx2 v[18:19], v[16:17], off offset:1536
	s_nop 0
	global_load_dwordx4 v[8:11], v[20:21], off offset:3072
	s_waitcnt vmcnt(2)
	v_lshlrev_b32_e32 v12, 16, v14
	v_and_b32_e32 v13, 0xffff0000, v14
	s_waitcnt vmcnt(1)
	v_lshlrev_b32_e32 v16, 16, v18
	v_and_b32_e32 v17, 0xffff0000, v18
	v_lshlrev_b32_e32 v14, 16, v15
	v_and_b32_e32 v15, 0xffff0000, v15
	v_lshlrev_b32_e32 v18, 16, v19
	v_and_b32_e32 v19, 0xffff0000, v19
	v_pk_add_f32 v[12:13], v[12:13], v[16:17]
	v_pk_add_f32 v[14:15], v[14:15], v[18:19]
	v_pk_mul_f32 v[12:13], v[28:29], v[12:13] op_sel_hi:[0,1]
	v_pk_mul_f32 v[14:15], v[28:29], v[14:15] op_sel_hi:[0,1]
	s_waitcnt vmcnt(0)
	v_pk_mul_f32 v[10:11], v[10:11], v[14:15]
	v_pk_mul_f32 v[8:9], v[8:9], v[12:13]
	global_store_dwordx4 v[22:23], v[8:11], off offset:3072 nt
	s_branch .LBB11_3037
